# MLA: O accumulators scaled in place and PV writes home registers (32 fewer v_mov_b64 per chunk); NT=4 loops skip accumulator copy round trip; max canonicalisation dropped
# speedup vs baseline: 1.0141x; 1.0098x over previous
; #define LAS __attribute__((address_space(3)))
; __device__ __forceinline__ float ex2(float x) { return __builtin_amdgcn_exp2f(x); }
; __device__ __forceinline__ f32x4 mfma16(bf16x8 a, bf16x8 b, f32x4 c) { return __builtin_amdgcn_mfma_f32_16x16x32_bf16(a, b, c, 0, 0, 0); }
; template <int NT, int NKK, int NDT, int MODE, bool MASK> ...
;   const int r = lane & 15, lg = lane >> 4, vq = (lane & 15) >> 2, vp = lane & 3;
;   f32x4 s[NT][4];
;   __builtin_amdgcn_s_setprio(1);
; #pragma unroll
;   for (int t = 0; t < 4; ++t)
; #pragma unroll
;     for (int kk = 0; kk < NKK; ++kk) {
;       const bf16x8 kf = *(LAS const bf16x8*)(Kl + (16 * t + r) * KSTR + (32 * kk + 8 * lg) * 2);
; #pragma unroll
;       for (int j = 0; j < NT; ++j) s[j][t] = mfma16(kf, qf[j][kk], kk == 0 ? (f32x4){0.f, 0.f, 0.f, 0.f} : s[j][t]);
;     }
;   __builtin_amdgcn_s_setprio(0);
;   bf16x8 pf[NT][2];
; #pragma unroll
;   for (int j = 0; j < NT; ++j) {
;     float mx = -INFINITY;
; #pragma unroll
;     for (int t = 0; t < 4; ++t)
; #pragma unroll
;       for (int i = 0; i < 4; ++i) {
;         if (MASK) { const int kp = kpos0 + 16 * t + 4 * lg + i; if (!mask_ok<MODE>(tq[j], kp, W)) s[j][t][i] = -INFINITY; }
;         mx = fmaxf(mx, s[j][t][i]);
;       }
;     mx = max_x16_x32(mx);
;     if (__any(mx > m[j] + 8.0f / c)) {
;       const float mnew = fmaxf(m[j], mx);
;       const float ms2 = (mnew == -INFINITY) ? 0.f : mnew;
;       const float alpha = ex2((m[j] - ms2) * c);
;       m[j] = mnew; l[j] *= alpha;
; #pragma unroll
;       for (int dt = 0; dt < NDT; ++dt) o[j][dt] *= alpha;
;     }
; template <int NT, int DQK, int DV, int MODE, int PD, class Src> ...
;     ...
;         const int lo = kbase + 64 * kc, hi = lo + 63;
;         bool rel = true, full = true;
;         if (MODE == MODE_CAUSAL) { rel = lo <= tq_max; full = hi <= tq_min; }
;         if (MODE == MODE_WINDOW) { rel = (lo <= tq_max) && (hi > tq_min - W); full = (hi <= tq_min) && (lo > tq_max - W); }
;         if (MODE == MODE_CMP) { rel = 16 * lo + 31 <= tq_max; full = 16 * hi + 31 <= tq_min; }
;         if (rel) {
;           if (NT <= 2) {
;             if (full) attn_chunk_wide<NT, DQK / 32, DV / 16, MODE, false>(o, m, l, qf, buf, KSTR, buf + KB, VSTR, lo, tq, c, W, lane);
;             else attn_chunk_wide<NT, DQK / 32, DV / 16, MODE, true>(o, m, l, qf, buf, KSTR, buf + KB, VSTR, lo, tq, c, W, lane);
.LBB0_768:
	s_waitcnt lgkmcnt(0)
	s_barrier
	s_add_i32 s8, s69, 0xffffff41
	s_cmp_gt_i32 s8, s68
	s_cbranch_scc1 .LBB0_797
	s_add_i32 s8, s69, 0xffffff80
	s_cmp_gt_i32 s8, s59
	s_setprio 1
	v_add_u32_e32 v1, s71, v236
	s_waitcnt lgkmcnt(0)
	v_add_u32_e32 v94, v1, v237
	ds_read_b128 v[134:137], v94
	ds_read_b128 v[130:133], v94 offset:64
	ds_read_b128 v[126:129], v94 offset:128
	ds_read_b128 v[122:125], v94 offset:3328
	ds_read_b128 v[118:121], v94 offset:3392
	ds_read_b128 v[114:117], v94 offset:3456
	ds_read_b128 v[106:109], v94 offset:6656
	ds_read_b128 v[98:101], v94 offset:6720
	v_add_u32_e32 v201, v1, v238
	ds_read_b128 v[110:113], v94 offset:6784
	ds_read_b128 v[102:105], v201
	ds_read_b128 v[94:97], v201 offset:64
	s_mov_b64 s[20:21], -1
	v_add_f32_e32 v1, 0x4259535f, v220
	s_cbranch_scc1 .LBB0_788
	s_waitcnt lgkmcnt(10)
	v_mfma_f32_16x16x32_bf16 v[138:141], v[134:137], v[18:21], 0
	ds_read_b128 v[146:149], v201 offset:128
	v_mov_b32_e32 v234, 0x260
	v_mfma_f32_16x16x32_bf16 v[142:145], v[134:137], v[10:13], 0
	s_waitcnt lgkmcnt(10)
	v_mfma_f32_16x16x32_bf16 v[138:141], v[130:133], v[2:5], v[138:141]
	v_mfma_f32_16x16x32_bf16 v[142:145], v[130:133], v[14:17], v[142:145]
	s_waitcnt lgkmcnt(9)
	v_mfma_f32_16x16x32_bf16 v[182:185], v[126:129], v[6:9], v[138:141]
	v_mfma_f32_16x16x32_bf16 v[166:169], v[126:129], v[22:25], v[142:145]
	s_waitcnt lgkmcnt(8)
	v_mfma_f32_16x16x32_bf16 v[138:141], v[122:125], v[18:21], 0
	v_mfma_f32_16x16x32_bf16 v[142:145], v[122:125], v[10:13], 0
	s_waitcnt lgkmcnt(7)
	v_mfma_f32_16x16x32_bf16 v[138:141], v[118:121], v[2:5], v[138:141]
	v_mfma_f32_16x16x32_bf16 v[142:145], v[118:121], v[14:17], v[142:145]
	s_waitcnt lgkmcnt(6)
	v_mfma_f32_16x16x32_bf16 v[178:181], v[114:117], v[6:9], v[138:141]
	v_mfma_f32_16x16x32_bf16 v[154:157], v[114:117], v[22:25], v[142:145]
	s_waitcnt lgkmcnt(5)
	v_mfma_f32_16x16x32_bf16 v[138:141], v[106:109], v[18:21], 0
	v_mfma_f32_16x16x32_bf16 v[142:145], v[106:109], v[10:13], 0
	s_waitcnt lgkmcnt(4)
	v_mfma_f32_16x16x32_bf16 v[138:141], v[98:101], v[2:5], v[138:141]
	v_mfma_f32_16x16x32_bf16 v[142:145], v[98:101], v[14:17], v[142:145]
	s_waitcnt lgkmcnt(3)
	v_mfma_f32_16x16x32_bf16 v[174:177], v[110:113], v[6:9], v[138:141]
	v_mfma_f32_16x16x32_bf16 v[150:153], v[110:113], v[22:25], v[142:145]
	s_waitcnt lgkmcnt(2)
	v_mfma_f32_16x16x32_bf16 v[138:141], v[102:105], v[18:21], 0
	v_mfma_f32_16x16x32_bf16 v[142:145], v[102:105], v[10:13], 0
	s_waitcnt lgkmcnt(1)
	v_mfma_f32_16x16x32_bf16 v[138:141], v[94:97], v[2:5], v[138:141]
	v_mfma_f32_16x16x32_bf16 v[142:145], v[94:97], v[14:17], v[142:145]
	s_waitcnt lgkmcnt(0)
	v_mfma_f32_16x16x32_bf16 v[170:173], v[146:149], v[6:9], v[138:141]
	v_mfma_f32_16x16x32_bf16 v[142:145], v[146:149], v[22:25], v[142:145]
	s_setprio 0
	s_nop 2
	v_max3_f32 v138, v182, s81, v183
	v_max3_f32 v138, v138, v184, v185
	v_max3_f32 v138, v138, v178, v179
	v_max3_f32 v138, v138, v180, v181
	v_max3_f32 v138, v138, v174, v175
	v_max3_f32 v138, v138, v176, v177
	v_max3_f32 v138, v138, v170, v171
	v_max3_f32 v138, v138, v172, v173
	v_mov_b32_e32 v139, v138
	s_nop 1
	v_permlane16_swap_b32_e32 v138, v139
	v_max_f32_e32 v138, v138, v139
	v_mov_b32_e32 v139, v138
	s_nop 1
	v_permlane32_swap_b32_e32 v138, v139
	v_max_f32_e32 v186, v138, v139
	v_cmp_gt_f32_e32 vcc, v186, v1
	v_mov_b64_e32 v[222:223], v[220:221]
	v_mov_b64_e32 v[224:225], v[218:219]
	v_mov_b32_e32 v187, v220
	s_cbranch_vccz .LBB0_772
	v_max_f32_e32 v138, v186, v186
	v_max_f32_e32 v139, v220, v220
	v_max_f32_e32 v222, v139, v138
	v_cmp_neq_f32_e32 vcc, s81, v222
	v_mov_b32_e32 v223, v221
	v_mov_b32_e32 v225, v219
	v_cndmask_b32_e32 v138, 0, v222, vcc
	v_sub_f32_e32 v138, v220, v138
	v_mul_f32_e32 v138, 0x3e16c740, v138
	v_exp_f32_e32 v138, v138
	v_mov_b32_e32 v187, v222
	v_mul_f32_e32 v224, v218, v138
	v_pk_mul_f32 v[92:93], v[92:93], v[138:139] op_sel_hi:[1,0]
	v_pk_mul_f32 v[90:91], v[90:91], v[138:139] op_sel_hi:[1,0]
	v_pk_mul_f32 v[88:89], v[88:89], v[138:139] op_sel_hi:[1,0]
	v_pk_mul_f32 v[86:87], v[86:87], v[138:139] op_sel_hi:[1,0]
	v_pk_mul_f32 v[76:77], v[76:77], v[138:139] op_sel_hi:[1,0]
	v_pk_mul_f32 v[74:75], v[74:75], v[138:139] op_sel_hi:[1,0]
	v_pk_mul_f32 v[68:69], v[68:69], v[138:139] op_sel_hi:[1,0]
	v_pk_mul_f32 v[66:67], v[66:67], v[138:139] op_sel_hi:[1,0]
; __device__ __forceinline__ float ex2(float x) { return __builtin_amdgcn_exp2f(x); }
;   __device__ __forceinline__ bf16_t* W() const { return (bf16_t*)(ws + WS_W); }
; template <int NT, int NKK, int NDT, int MODE, bool MASK> ...
;     ...
;   for (int j = 0; j < NT; ++j) {
;     float mx = -INFINITY;
; #pragma unroll
;     for (int t = 0; t < 4; ++t)
; #pragma unroll
;       for (int i = 0; i < 4; ++i) {
;         if (MASK) { const int kp = kpos0 + 16 * t + 4 * lg + i; if (!mask_ok<MODE>(tq[j], kp, W)) s[j][t][i] = -INFINITY; }
;         mx = fmaxf(mx, s[j][t][i]);
;       }
;     mx = max_x16_x32(mx);
;     if (__any(mx > m[j] + 8.0f / c)) {
;       const float mnew = fmaxf(m[j], mx);
;       const float ms2 = (mnew == -INFINITY) ? 0.f : mnew;
;       const float alpha = ex2((m[j] - ms2) * c);
;       m[j] = mnew; l[j] *= alpha;
; #pragma unroll
;       for (int dt = 0; dt < NDT; ++dt) o[j][dt] *= alpha;
;     }
;     const float mc = ((m[j] == -INFINITY) ? 0.f : m[j]) * c;
;     float p[4][4], ps = 0.f;
; #pragma unroll
;     for (int t = 0; t < 4; ++t)
; #pragma unroll
;       for (int i = 0; i < 4; ++i) { p[t][i] = ex2(s[j][t][i] * c - mc); ps += p[t][i]; }
;     l[j] += ps;
;     pf[j][0] = pack8(p[0], p[1]); pf[j][1] = pack8(p[2], p[3]);
.LBB0_772:
	v_mul_f32_e32 v186, 0x3e16c740, v187
	v_cmp_neq_f32_e32 vcc, s81, v187
	s_nop 1
	v_cndmask_b32_e32 v186, 0, v186, vcc
	v_fma_f32 v182, v182, s88, -v186
	v_exp_f32_e32 v205, v182
	v_fma_f32 v182, v183, s88, -v186
	v_exp_f32_e32 v207, v182
	v_fma_f32 v182, v184, s88, -v186
	v_exp_f32_e32 v246, v182
	v_fma_f32 v182, v185, s88, -v186
	v_exp_f32_e32 v247, v182
	v_fma_f32 v178, v178, s88, -v186
	v_add_f32_e32 v182, 0, v205
	v_exp_f32_e32 v248, v178
	v_fma_f32 v178, v179, s88, -v186
	v_add_f32_e32 v182, v207, v182
	v_exp_f32_e32 v249, v178
	v_fma_f32 v178, v180, s88, -v186
	v_add_f32_e32 v182, v246, v182
	v_exp_f32_e32 v250, v178
	v_fma_f32 v178, v181, s88, -v186
	v_add_f32_e32 v182, v247, v182
	v_exp_f32_e32 v251, v178
	v_fma_f32 v174, v174, s88, -v186
	v_add_f32_e32 v178, v248, v182
	v_exp_f32_e32 v252, v174
	v_fma_f32 v174, v175, s88, -v186
	v_add_f32_e32 v178, v249, v178
	v_exp_f32_e32 v231, v174
	v_fma_f32 v174, v176, s88, -v186
	v_add_f32_e32 v178, v250, v178
	v_exp_f32_e32 v229, v174
	v_fma_f32 v174, v177, s88, -v186
	v_add_f32_e32 v178, v251, v178
	v_exp_f32_e32 v230, v174
	v_fma_f32 v170, v170, s88, -v186
	v_add_f32_e32 v174, v252, v178
	v_exp_f32_e32 v232, v170
	v_fma_f32 v170, v171, s88, -v186
	v_add_f32_e32 v174, v231, v174
	v_exp_f32_e32 v228, v170
	v_fma_f32 v170, v172, s88, -v186
	v_add_f32_e32 v174, v229, v174
	v_exp_f32_e32 v196, v170
	v_fma_f32 v170, v173, s88, -v186
	v_add_f32_e32 v174, v230, v174
	v_exp_f32_e32 v173, v170
	v_add_f32_e32 v170, v232, v174
	v_add_f32_e32 v170, v228, v170
	v_add_f32_e32 v170, v196, v170
	v_add_f32_e32 v170, v173, v170
	v_add_f32_e32 v224, v224, v170
	v_max3_f32 v170, v166, s81, v167
	v_max3_f32 v170, v170, v168, v169
	v_max3_f32 v170, v170, v154, v155
	v_max3_f32 v170, v170, v156, v157
	v_max3_f32 v170, v170, v150, v151
	v_max3_f32 v170, v170, v152, v153
	v_max3_f32 v170, v170, v142, v143
	v_max3_f32 v170, v170, v144, v145
	v_mov_b32_e32 v171, v170
	s_nop 1
	v_permlane16_swap_b32_e32 v170, v171
	v_max_f32_e32 v170, v170, v171
	v_mov_b32_e32 v171, v170
	s_nop 1
	v_permlane32_swap_b32_e32 v170, v171
	v_max_f32_e32 v170, v170, v171
	v_add_f32_e32 v171, 0x4259535f, v223
	v_cmp_gt_f32_e32 vcc, v170, v171
	s_cbranch_vccz .LBB0_786
	v_max_f32_e32 v170, v170, v170
	v_max_f32_e32 v171, v223, v223
	v_max_f32_e32 v197, v171, v170
	v_cmp_neq_f32_e32 vcc, s81, v197
	s_nop 1
	v_cndmask_b32_e32 v170, 0, v197, vcc
	v_sub_f32_e32 v170, v223, v170
	v_mul_f32_e32 v170, 0x3e16c740, v170
	v_exp_f32_e32 v170, v170
	v_mov_b32_e32 v223, v197
	v_mul_f32_e32 v225, v225, v170
	v_pk_mul_f32 v[84:85], v[84:85], v[170:171] op_sel_hi:[1,0]
	v_pk_mul_f32 v[82:83], v[82:83], v[170:171] op_sel_hi:[1,0]
	v_pk_mul_f32 v[80:81], v[80:81], v[170:171] op_sel_hi:[1,0]
	v_pk_mul_f32 v[78:79], v[78:79], v[170:171] op_sel_hi:[1,0]
	v_pk_mul_f32 v[72:73], v[72:73], v[170:171] op_sel_hi:[1,0]
	v_pk_mul_f32 v[70:71], v[70:71], v[170:171] op_sel_hi:[1,0]
	v_pk_mul_f32 v[64:65], v[64:65], v[170:171] op_sel_hi:[1,0]
	v_pk_mul_f32 v[62:63], v[62:63], v[170:171] op_sel_hi:[1,0]
	s_branch .LBB0_787

; __device__ __forceinline__ float ex2(float x) { return __builtin_amdgcn_exp2f(x); }
; __device__ __forceinline__ f32x4 mfma16(bf16x8 a, bf16x8 b, f32x4 c) { return __builtin_amdgcn_mfma_f32_16x16x32_bf16(a, b, c, 0, 0, 0); }
; __device__ __forceinline__ s16x4 ds_tr(LAS const unsigned char* p) { return __builtin_bit_cast(s16x4, __builtin_amdgcn_ds_read_tr16_b64_v4i16((LAS v4i16_t*)p)); }
; template <int NT, int NKK, int NDT, int MODE, bool MASK> ...
;     ...
;     const float mc = ((m[j] == -INFINITY) ? 0.f : m[j]) * c;
;     float p[4][4], ps = 0.f;
; #pragma unroll
;     for (int t = 0; t < 4; ++t)
; #pragma unroll
;       for (int i = 0; i < 4; ++i) { p[t][i] = ex2(s[j][t][i] * c - mc); ps += p[t][i]; }
;     l[j] += ps;
;     pf[j][0] = pack8(p[0], p[1]); pf[j][1] = pack8(p[2], p[3]);
;   }
;   __builtin_amdgcn_s_setprio(1);
; #pragma unroll
;   for (int st = 0; st < 2; ++st)
; #pragma unroll
;     for (int dt = 0; dt < NDT; ++dt) {
;       const s16x4 v0 = ds_tr(Vl + (32 * st + 4 * lg + vq) * VSTR + (16 * dt + 4 * vp) * 2);
;       const s16x4 v1 = ds_tr(Vl + (32 * st + 16 + 4 * lg + vq) * VSTR + (16 * dt + 4 * vp) * 2);
;       const bf16x8 vf = (bf16x8){v0[0], v0[1], v0[2], v0[3], v1[0], v1[1], v1[2], v1[3]};
; #pragma unroll
;       for (int j = 0; j < NT; ++j) o[j][dt] = mfma16(vf, pf[j][st], o[j][dt]);
;     }
;   __builtin_amdgcn_s_setprio(0);
.LBB0_786:
	v_mov_b32_e32 v197, v223
.LBB0_787:
	v_cvt_pk_bf16_f32 v173, v196, v173
	v_mul_f32_e32 v196, 0x3e16c740, v197
	v_cmp_neq_f32_e32 vcc, s81, v197
	v_cvt_pk_bf16_f32 v172, v232, v228
	v_cvt_pk_bf16_f32 v228, v205, v207
	v_cndmask_b32_e32 v196, 0, v196, vcc
	v_fma_f32 v166, v166, s88, -v196
	v_exp_f32_e32 v166, v166
	v_fma_f32 v167, v167, s88, -v196
	v_exp_f32_e32 v167, v167
	v_fma_f32 v168, v168, s88, -v196
	v_exp_f32_e32 v168, v168
	v_fma_f32 v169, v169, s88, -v196
	v_exp_f32_e32 v169, v169
	v_fma_f32 v154, v154, s88, -v196
	v_add_f32_e32 v197, 0, v166
	v_exp_f32_e32 v154, v154
	v_fma_f32 v155, v155, s88, -v196
	v_add_f32_e32 v197, v167, v197
	v_exp_f32_e32 v155, v155
	v_fma_f32 v156, v156, s88, -v196
	v_add_f32_e32 v197, v168, v197
	v_exp_f32_e32 v156, v156
	v_fma_f32 v157, v157, s88, -v196
	v_add_f32_e32 v197, v169, v197
	v_exp_f32_e32 v157, v157
	v_fma_f32 v150, v150, s88, -v196
	v_add_f32_e32 v197, v154, v197
	v_exp_f32_e32 v150, v150
	v_fma_f32 v151, v151, s88, -v196
	v_add_f32_e32 v197, v155, v197
	v_exp_f32_e32 v151, v151
	v_fma_f32 v152, v152, s88, -v196
	v_add_f32_e32 v197, v156, v197
	v_exp_f32_e32 v152, v152
	v_fma_f32 v153, v153, s88, -v196
	v_add_f32_e32 v197, v157, v197
	v_exp_f32_e32 v153, v153
	v_fma_f32 v142, v142, s88, -v196
	v_add_f32_e32 v197, v150, v197
	v_exp_f32_e32 v198, v142
	v_fma_f32 v142, v143, s88, -v196
	v_add_f32_e32 v197, v151, v197
	v_exp_f32_e32 v199, v142
	v_fma_f32 v142, v144, s88, -v196
	v_add_f32_e32 v197, v152, v197
	v_exp_f32_e32 v205, v142
	v_fma_f32 v142, v145, s88, -v196
	v_add_f32_e32 v197, v153, v197
	v_exp_f32_e32 v196, v142
	v_add_f32_e32 v142, v198, v197
	v_add_f32_e32 v142, v199, v142
	v_add_f32_e32 v142, v205, v142
	v_add_f32_e32 v142, v196, v142
	v_add_f32_e32 v225, v225, v142
	v_cvt_pk_bf16_f32 v142, v166, v167
	v_cvt_pk_bf16_f32 v143, v168, v169
	v_cvt_pk_bf16_f32 v144, v154, v155
	v_cvt_pk_bf16_f32 v145, v156, v157
	v_cvt_pk_bf16_f32 v170, v252, v231
	v_cvt_pk_bf16_f32 v171, v229, v230
	v_cvt_pk_bf16_f32 v229, v246, v247
	v_cvt_pk_bf16_f32 v230, v248, v249
	v_cvt_pk_bf16_f32 v231, v250, v251
	v_cvt_pk_bf16_f32 v246, v150, v151
	v_cvt_pk_bf16_f32 v247, v152, v153
	v_cvt_pk_bf16_f32 v248, v198, v199
	v_cvt_pk_bf16_f32 v249, v205, v196
	s_setprio 1
	v_add3_u32 v196, s71, v240, v239
	ds_read_b64_tr_b16 v[152:153], v196 offset:15872
	ds_read_b64_tr_b16 v[150:151], v196 offset:13312
	ds_read_b64_tr_b16 v[154:155], v196 offset:13344
	ds_read_b64_tr_b16 v[156:157], v196 offset:15904
	ds_read_b64_tr_b16 v[166:167], v196 offset:13376
	ds_read_b64_tr_b16 v[168:169], v196 offset:15936
	s_mov_b64 s[20:21], 0
	s_waitcnt lgkmcnt(4)
	v_mfma_f32_16x16x32_bf16 v[158:161], v[150:153], v[228:231], v[90:93]
	v_mfma_f32_16x16x32_bf16 v[150:153], v[150:153], v[142:145], v[82:85]
	s_waitcnt lgkmcnt(0)
	v_mfma_f32_16x16x32_bf16 v[182:185], v[166:169], v[228:231], v[74:77]
	s_nop 2
	ds_read_b64_tr_b16 v[146:147], v196 offset:13408
	ds_read_b64_tr_b16 v[148:149], v196 offset:15968
	v_mfma_f32_16x16x32_bf16 v[162:165], v[154:157], v[228:231], v[86:89]
	v_mfma_f32_16x16x32_bf16 v[154:157], v[154:157], v[142:145], v[78:81]
	v_mfma_f32_16x16x32_bf16 v[166:169], v[166:169], v[142:145], v[70:73]
	s_waitcnt lgkmcnt(0)
	v_mfma_f32_16x16x32_bf16 v[174:177], v[146:149], v[142:145], v[62:65]
	ds_read_b64_tr_b16 v[142:143], v196 offset:18432
	ds_read_b64_tr_b16 v[144:145], v196 offset:20992
	v_mfma_f32_16x16x32_bf16 v[178:181], v[146:149], v[228:231], v[66:69]
	s_waitcnt lgkmcnt(0)
	v_mfma_f32_16x16x32_bf16 v[90:93], v[142:145], v[170:173], v[158:161]
	v_mfma_f32_16x16x32_bf16 v[82:85], v[142:145], v[246:249], v[150:153]
	s_nop 2
	ds_read_b64_tr_b16 v[150:151], v196 offset:18464
	ds_read_b64_tr_b16 v[152:153], v196 offset:21024
	ds_read_b64_tr_b16 v[158:159], v196 offset:18496
	ds_read_b64_tr_b16 v[160:161], v196 offset:21056
	s_waitcnt lgkmcnt(2)
	v_mfma_f32_16x16x32_bf16 v[86:89], v[150:153], v[170:173], v[162:165]
	s_nop 2
	ds_read_b64_tr_b16 v[162:163], v196 offset:18528
	ds_read_b64_tr_b16 v[164:165], v196 offset:21088
	v_mfma_f32_16x16x32_bf16 v[78:81], v[150:153], v[246:249], v[154:157]
	s_waitcnt lgkmcnt(2)
	v_mfma_f32_16x16x32_bf16 v[74:77], v[158:161], v[170:173], v[182:185]
	v_mfma_f32_16x16x32_bf16 v[70:73], v[158:161], v[246:249], v[166:169]
	s_waitcnt lgkmcnt(0)
	v_mfma_f32_16x16x32_bf16 v[66:69], v[162:165], v[170:173], v[178:181]
	v_mfma_f32_16x16x32_bf16 v[62:65], v[162:165], v[246:249], v[174:177]
	s_setprio 0
	s_branch .Lmla_post_0
; #define LAS __attribute__((address_space(3)))
; __device__ __forceinline__ float ex2(float x) { return __builtin_amdgcn_exp2f(x); }
; __device__ __forceinline__ f32x4 mfma16(bf16x8 a, bf16x8 b, f32x4 c) { return __builtin_amdgcn_mfma_f32_16x16x32_bf16(a, b, c, 0, 0, 0); }
;   __device__ __forceinline__ bf16_t* W() const { return (bf16_t*)(ws + WS_W); }
; template <int NT, int NKK, int NDT, int MODE, bool MASK> ...
;   const int r = lane & 15, lg = lane >> 4, vq = (lane & 15) >> 2, vp = lane & 3;
;   f32x4 s[NT][4];
;   __builtin_amdgcn_s_setprio(1);
; #pragma unroll
;   for (int t = 0; t < 4; ++t)
; #pragma unroll
;     for (int kk = 0; kk < NKK; ++kk) {
;       const bf16x8 kf = *(LAS const bf16x8*)(Kl + (16 * t + r) * KSTR + (32 * kk + 8 * lg) * 2);
; #pragma unroll
;       for (int j = 0; j < NT; ++j) s[j][t] = mfma16(kf, qf[j][kk], kk == 0 ? (f32x4){0.f, 0.f, 0.f, 0.f} : s[j][t]);
;     }
;   __builtin_amdgcn_s_setprio(0);
;   bf16x8 pf[NT][2];
; #pragma unroll
;   for (int j = 0; j < NT; ++j) {
;     float mx = -INFINITY;
; #pragma unroll
;     for (int t = 0; t < 4; ++t)
; #pragma unroll
;       for (int i = 0; i < 4; ++i) {
;         if (MASK) { const int kp = kpos0 + 16 * t + 4 * lg + i; if (!mask_ok<MODE>(tq[j], kp, W)) s[j][t][i] = -INFINITY; }
;         mx = fmaxf(mx, s[j][t][i]);
;       }
;     mx = max_x16_x32(mx);
;     if (__any(mx > m[j] + 8.0f / c)) {
;       const float mnew = fmaxf(m[j], mx);
;       const float ms2 = (mnew == -INFINITY) ? 0.f : mnew;
;       const float alpha = ex2((m[j] - ms2) * c);
;       m[j] = mnew; l[j] *= alpha;
; #pragma unroll
;       for (int dt = 0; dt < NDT; ++dt) o[j][dt] *= alpha;
;     }
.LBB0_788:
	s_and_b64 vcc, exec, s[20:21]
	s_cbranch_vccz .LBB0_796
	s_waitcnt lgkmcnt(10)
	v_mfma_f32_16x16x32_bf16 v[138:141], v[134:137], v[18:21], 0
	v_mfma_f32_16x16x32_bf16 v[134:137], v[134:137], v[10:13], 0
	s_waitcnt lgkmcnt(9)
	v_mfma_f32_16x16x32_bf16 v[138:141], v[130:133], v[2:5], v[138:141]
	v_mfma_f32_16x16x32_bf16 v[134:137], v[130:133], v[14:17], v[134:137]
	s_waitcnt lgkmcnt(8)
	v_mfma_f32_16x16x32_bf16 v[130:133], v[126:129], v[6:9], v[138:141]
	v_mfma_f32_16x16x32_bf16 v[126:129], v[126:129], v[22:25], v[134:137]
	s_waitcnt lgkmcnt(7)
	v_mfma_f32_16x16x32_bf16 v[134:137], v[122:125], v[18:21], 0
	v_mfma_f32_16x16x32_bf16 v[122:125], v[122:125], v[10:13], 0
	s_waitcnt lgkmcnt(6)
	v_mfma_f32_16x16x32_bf16 v[134:137], v[118:121], v[2:5], v[134:137]
	v_mfma_f32_16x16x32_bf16 v[118:121], v[118:121], v[14:17], v[122:125]
	s_waitcnt lgkmcnt(5)
	v_mfma_f32_16x16x32_bf16 v[134:137], v[114:117], v[6:9], v[134:137]
	v_mfma_f32_16x16x32_bf16 v[114:117], v[114:117], v[22:25], v[118:121]
	s_waitcnt lgkmcnt(4)
	v_mfma_f32_16x16x32_bf16 v[118:121], v[106:109], v[18:21], 0
	v_mfma_f32_16x16x32_bf16 v[106:109], v[106:109], v[10:13], 0
	s_waitcnt lgkmcnt(3)
	v_mfma_f32_16x16x32_bf16 v[118:121], v[98:101], v[2:5], v[118:121]
	v_mfma_f32_16x16x32_bf16 v[98:101], v[98:101], v[14:17], v[106:109]
	s_waitcnt lgkmcnt(1)
	v_mfma_f32_16x16x32_bf16 v[106:109], v[102:105], v[18:21], 0
	v_mfma_f32_16x16x32_bf16 v[102:105], v[102:105], v[10:13], 0
	s_waitcnt lgkmcnt(0)
	v_mfma_f32_16x16x32_bf16 v[106:109], v[94:97], v[2:5], v[106:109]
	v_mfma_f32_16x16x32_bf16 v[94:97], v[94:97], v[14:17], v[102:105]
	s_nop 4
	ds_read_b128 v[102:105], v201 offset:128
	v_mfma_f32_16x16x32_bf16 v[118:121], v[110:113], v[6:9], v[118:121]
	v_mfma_f32_16x16x32_bf16 v[98:101], v[110:113], v[22:25], v[98:101]
	s_waitcnt lgkmcnt(0)
	v_mfma_f32_16x16x32_bf16 v[94:97], v[102:105], v[22:25], v[94:97]
	v_mfma_f32_16x16x32_bf16 v[144:147], v[102:105], v[6:9], v[106:109]
	s_setprio 0
	v_add_u32_e32 v103, s69, v241
	v_add_u32_e32 v104, 0xffffff41, v103
	v_add_u32_e32 v105, 0xffffff43, v103
	v_mov_b32_e32 v102, s81
	v_cmp_gt_i32_e64 s[20:21], v104, v194
	v_cmp_lt_i32_e64 s[22:23], v104, v194
	v_cmp_le_i32_e32 vcc, v105, v194
	v_add_u32_e32 v106, 0xffffff44, v103
	v_cndmask_b32_e64 v142, v130, v102, s[20:21]
	v_cndmask_b32_e64 v122, v200, v131, s[22:23]
	v_cndmask_b32_e32 v124, v200, v132, vcc
	v_cmp_le_i32_e32 vcc, v106, v194
	v_max3_f32 v102, v142, s81, v122
	v_add_u32_e32 v107, 0xffffff51, v103
	v_cndmask_b32_e32 v123, v200, v133, vcc
	v_max3_f32 v108, v102, v124, v123
	v_mov_b32_e32 v102, s81
	v_cmp_gt_i32_e32 vcc, v107, v194
	v_add_u32_e32 v107, 0xffffff52, v103
	v_add_u32_e32 v110, 0xffffff54, v103
	v_cndmask_b32_e32 v125, v134, v102, vcc
	v_cmp_le_i32_e32 vcc, v107, v194
	v_add_u32_e32 v109, 0xffffff61, v103
	v_add_u32_e32 v111, 0xffffff62, v103
	v_cndmask_b32_e32 v131, v200, v135, vcc
	v_max3_f32 v102, v108, v125, v131
	v_add_u32_e32 v108, 0xffffff53, v103
	v_cmp_le_i32_e32 vcc, v108, v194
	v_add_u32_e32 v113, 0xffffff71, v103
	s_nop 0
	v_cndmask_b32_e32 v133, v200, v136, vcc
	v_cmp_le_i32_e32 vcc, v110, v194
	s_nop 1
	v_cndmask_b32_e32 v132, v200, v137, vcc
	v_max3_f32 v112, v102, v133, v132
	v_mov_b32_e32 v102, s81
	v_cmp_gt_i32_e32 vcc, v109, v194
	s_nop 1
	v_cndmask_b32_e32 v134, v118, v102, vcc
	v_cmp_le_i32_e32 vcc, v111, v194
	v_add_u32_e32 v118, 0xffffff64, v103
	s_nop 0
	v_cndmask_b32_e32 v135, v200, v119, vcc
	v_max3_f32 v102, v112, v134, v135
	v_add_u32_e32 v112, 0xffffff63, v103
	v_cmp_le_i32_e32 vcc, v112, v194
	v_add_u32_e32 v119, 0xffffff72, v103
	s_nop 0
	v_cndmask_b32_e32 v137, v200, v120, vcc
	v_cmp_le_i32_e32 vcc, v118, v194
	s_nop 1
	v_cndmask_b32_e32 v136, v200, v121, vcc
	v_max3_f32 v120, v102, v137, v136
	v_mov_b32_e32 v102, s81
	v_cmp_gt_i32_e32 vcc, v113, v194
	v_add_u32_e32 v121, 0xffffff74, v103
	s_nop 0
	v_cndmask_b32_e32 v138, v144, v102, vcc
	v_cmp_le_i32_e32 vcc, v119, v194
	s_nop 1
	v_cndmask_b32_e32 v139, v200, v145, vcc
	v_max3_f32 v102, v120, v138, v139
	v_add_u32_e32 v120, 0xffffff73, v103
	v_cmp_le_i32_e32 vcc, v120, v194
	s_nop 1
	v_cndmask_b32_e32 v141, v200, v146, vcc
	v_cmp_le_i32_e32 vcc, v121, v194
	s_nop 1
	v_cndmask_b32_e32 v140, v200, v147, vcc
	v_max3_f32 v102, v102, v141, v140
	v_mov_b32_e32 v103, v102
	s_nop 1
	v_permlane16_swap_b32_e32 v102, v103
	v_max_f32_e32 v102, v102, v103
	v_mov_b32_e32 v103, v102
	s_nop 1
	v_permlane32_swap_b32_e32 v102, v103
	v_max_f32_e32 v102, v102, v103
	v_cmp_gt_f32_e32 vcc, v102, v1
	s_cbranch_vccz .LBB0_791
	v_max_f32_e32 v1, v102, v102
	v_max_f32_e32 v102, v220, v220
	v_max_f32_e32 v102, v102, v1
	v_cmp_neq_f32_e32 vcc, s81, v102
	v_mov_b32_e32 v103, v221
	s_nop 0
	v_cndmask_b32_e32 v1, 0, v102, vcc
	v_sub_f32_e32 v1, v220, v1
	v_mul_f32_e32 v1, 0x3e16c740, v1
	v_exp_f32_e32 v144, v1
	v_mov_b64_e32 v[220:221], v[102:103]
	v_mul_f32_e32 v218, v218, v144
	v_pk_mul_f32 v[92:93], v[92:93], v[144:145] op_sel_hi:[1,0]
	v_pk_mul_f32 v[90:91], v[90:91], v[144:145] op_sel_hi:[1,0]
	v_pk_mul_f32 v[88:89], v[88:89], v[144:145] op_sel_hi:[1,0]
	v_pk_mul_f32 v[86:87], v[86:87], v[144:145] op_sel_hi:[1,0]
	v_pk_mul_f32 v[76:77], v[76:77], v[144:145] op_sel_hi:[1,0]
	v_pk_mul_f32 v[74:75], v[74:75], v[144:145] op_sel_hi:[1,0]
	v_pk_mul_f32 v[68:69], v[68:69], v[144:145] op_sel_hi:[1,0]
	v_pk_mul_f32 v[66:67], v[66:67], v[144:145] op_sel_hi:[1,0]
	s_branch .LBB0_792

; __device__ __forceinline__ float ex2(float x) { return __builtin_amdgcn_exp2f(x); }
;   __device__ __forceinline__ bf16_t* W() const { return (bf16_t*)(ws + WS_W); }
; template <int NT, int NKK, int NDT, int MODE, bool MASK> ...
;     ...
;   for (int j = 0; j < NT; ++j) {
;     float mx = -INFINITY;
; #pragma unroll
;     for (int t = 0; t < 4; ++t)
; #pragma unroll
;       for (int i = 0; i < 4; ++i) {
;         if (MASK) { const int kp = kpos0 + 16 * t + 4 * lg + i; if (!mask_ok<MODE>(tq[j], kp, W)) s[j][t][i] = -INFINITY; }
;         mx = fmaxf(mx, s[j][t][i]);
;       }
;     mx = max_x16_x32(mx);
;     if (__any(mx > m[j] + 8.0f / c)) {
;       const float mnew = fmaxf(m[j], mx);
;       const float ms2 = (mnew == -INFINITY) ? 0.f : mnew;
;       const float alpha = ex2((m[j] - ms2) * c);
;       m[j] = mnew; l[j] *= alpha;
; #pragma unroll
;       for (int dt = 0; dt < NDT; ++dt) o[j][dt] *= alpha;
;     }
;     const float mc = ((m[j] == -INFINITY) ? 0.f : m[j]) * c;
;     float p[4][4], ps = 0.f;
; #pragma unroll
;     for (int t = 0; t < 4; ++t)
; #pragma unroll
;       for (int i = 0; i < 4; ++i) { p[t][i] = ex2(s[j][t][i] * c - mc); ps += p[t][i]; }
.LBB0_792:
	v_mul_f32_e32 v103, 0x3e16c740, v102
	v_cmp_neq_f32_e32 vcc, s81, v102
	v_cndmask_b32_e64 v1, v142, v130, s[22:23]
	v_cmp_lt_i32_e64 s[22:23], v104, v202
	v_cndmask_b32_e32 v142, 0, v103, vcc
	v_fma_f32 v1, v1, s88, -v142
	v_exp_f32_e32 v1, v1
	v_fma_f32 v102, v122, s88, -v142
	v_exp_f32_e32 v102, v102
	v_fma_f32 v103, v124, s88, -v142
	v_exp_f32_e32 v103, v103
	v_fma_f32 v122, v123, s88, -v142
	v_exp_f32_e32 v122, v122
	v_add_f32_e32 v123, 0, v1
	v_add_f32_e32 v123, v102, v123
	v_add_f32_e32 v123, v103, v123
	v_add_f32_e32 v143, v122, v123
	v_fma_f32 v123, v125, s88, -v142
	v_exp_f32_e32 v123, v123
	v_fma_f32 v124, v131, s88, -v142
	v_exp_f32_e32 v124, v124
	v_fma_f32 v125, v133, s88, -v142
	v_exp_f32_e32 v125, v125
	v_fma_f32 v130, v132, s88, -v142
	v_exp_f32_e32 v130, v130
	v_add_f32_e32 v131, v123, v143
	v_add_f32_e32 v131, v124, v131
	v_add_f32_e32 v131, v125, v131
	v_add_f32_e32 v143, v130, v131
	v_fma_f32 v131, v134, s88, -v142
	v_exp_f32_e32 v131, v131
	v_fma_f32 v132, v135, s88, -v142
	v_exp_f32_e32 v132, v132
	v_fma_f32 v133, v137, s88, -v142
	v_exp_f32_e32 v133, v133
	v_fma_f32 v134, v136, s88, -v142
	v_exp_f32_e32 v134, v134
	v_add_f32_e32 v135, v131, v143
	v_add_f32_e32 v135, v132, v135
	v_add_f32_e32 v135, v133, v135
	v_add_f32_e32 v136, v134, v135
	v_fma_f32 v135, v138, s88, -v142
	v_exp_f32_e32 v135, v135
	v_fma_f32 v137, v139, s88, -v142
	v_exp_f32_e32 v138, v137
	v_fma_f32 v137, v141, s88, -v142
	v_exp_f32_e32 v139, v137
	v_fma_f32 v137, v140, s88, -v142
	v_exp_f32_e32 v140, v137
	v_add_f32_e32 v136, v135, v136
	v_add_f32_e32 v136, v138, v136
	v_add_f32_e32 v136, v139, v136
	v_add_f32_e32 v136, v140, v136
	v_add_f32_e32 v218, v218, v136
	v_mov_b32_e32 v136, s81
	v_cmp_gt_i32_e32 vcc, v104, v202
	s_nop 1
	v_cndmask_b32_e32 v141, v126, v136, vcc
	v_cmp_le_i32_e32 vcc, v105, v202
	v_cndmask_b32_e64 v136, v200, v127, s[22:23]
	v_max3_f32 v104, v141, s81, v136
	v_cndmask_b32_e32 v137, v200, v128, vcc
	v_cmp_le_i32_e32 vcc, v106, v202
	s_nop 1
	v_cndmask_b32_e32 v128, v200, v129, vcc
	v_max3_f32 v105, v104, v137, v128
	v_mov_b32_e32 v104, s81
	v_cmp_le_i32_e32 vcc, v107, v202
	v_cndmask_b32_e64 v127, v114, v104, s[20:21]
	s_nop 0
	v_cndmask_b32_e32 v114, v200, v115, vcc
	v_cmp_le_i32_e32 vcc, v108, v202
	v_max3_f32 v104, v105, v127, v114
	s_nop 0
	v_cndmask_b32_e32 v115, v200, v116, vcc
	v_cmp_le_i32_e32 vcc, v110, v202
	s_nop 1
	v_cndmask_b32_e32 v108, v200, v117, vcc
	v_max3_f32 v106, v104, v115, v108
	v_mov_b32_e32 v104, s81
	v_cmp_gt_i32_e32 vcc, v109, v202
	s_nop 1
	v_cndmask_b32_e32 v107, v98, v104, vcc
	v_cmp_le_i32_e32 vcc, v111, v202
	s_nop 1
	v_cndmask_b32_e32 v105, v200, v99, vcc
	v_cmp_le_i32_e32 vcc, v112, v202
	v_max3_f32 v98, v106, v107, v105
	s_nop 0
	v_cndmask_b32_e32 v106, v200, v100, vcc
	v_cmp_le_i32_e32 vcc, v118, v202
	s_nop 1
	v_cndmask_b32_e32 v104, v200, v101, vcc
	v_max3_f32 v100, v98, v106, v104
	v_mov_b32_e32 v98, s81
	v_cmp_gt_i32_e32 vcc, v113, v202
	s_nop 1
	v_cndmask_b32_e32 v101, v94, v98, vcc
	v_cmp_le_i32_e32 vcc, v119, v202
	s_nop 1
	v_cndmask_b32_e32 v99, v200, v95, vcc
	v_cmp_le_i32_e32 vcc, v120, v202
	v_max3_f32 v94, v100, v101, v99
	s_nop 0
	v_cndmask_b32_e32 v100, v200, v96, vcc
	v_cmp_le_i32_e32 vcc, v121, v202
	s_nop 1
	v_cndmask_b32_e32 v98, v200, v97, vcc
	v_max3_f32 v94, v94, v100, v98
	v_mov_b32_e32 v95, v94
	s_nop 1
	v_permlane16_swap_b32_e32 v94, v95
	v_max_f32_e32 v94, v94, v95
	v_mov_b32_e32 v95, v94
	s_nop 1
	v_permlane32_swap_b32_e32 v94, v95
	v_max_f32_e32 v94, v94, v95
	v_add_f32_e32 v95, 0x4259535f, v221
	v_cmp_gt_f32_e32 vcc, v94, v95
	s_cbranch_vccz .LBB0_794
	v_max_f32_e32 v94, v94, v94
	v_max_f32_e32 v95, v221, v221
	v_max_f32_e32 v109, v95, v94
	v_cmp_neq_f32_e32 vcc, s81, v109
	s_nop 1
	v_cndmask_b32_e32 v94, 0, v109, vcc
	v_sub_f32_e32 v94, v221, v94
	v_mul_f32_e32 v94, 0x3e16c740, v94
	v_exp_f32_e32 v94, v94
	v_mov_b32_e32 v221, v109
	v_mul_f32_e32 v219, v219, v94
	v_pk_mul_f32 v[84:85], v[84:85], v[94:95] op_sel_hi:[1,0]
	v_pk_mul_f32 v[82:83], v[82:83], v[94:95] op_sel_hi:[1,0]
	v_pk_mul_f32 v[80:81], v[80:81], v[94:95] op_sel_hi:[1,0]
	v_pk_mul_f32 v[78:79], v[78:79], v[94:95] op_sel_hi:[1,0]
	v_pk_mul_f32 v[72:73], v[72:73], v[94:95] op_sel_hi:[1,0]
	v_pk_mul_f32 v[70:71], v[70:71], v[94:95] op_sel_hi:[1,0]
	v_pk_mul_f32 v[64:65], v[64:65], v[94:95] op_sel_hi:[1,0]
	v_pk_mul_f32 v[62:63], v[62:63], v[94:95] op_sel_hi:[1,0]
	s_branch .LBB0_795

; __device__ __forceinline__ float ex2(float x) { return __builtin_amdgcn_exp2f(x); }
; template <int NT, int NKK, int NDT, int MODE, bool MASK> ...
;     ...
;     if (__any(mx > m[j] + 8.0f / c)) {
;       const float mnew = fmaxf(m[j], mx);
;       const float ms2 = (mnew == -INFINITY) ? 0.f : mnew;
;       const float alpha = ex2((m[j] - ms2) * c);
;       m[j] = mnew; l[j] *= alpha;
; #pragma unroll
;       for (int dt = 0; dt < NDT; ++dt) o[j][dt] *= alpha;
;     }
.LBB0_796:
	s_setprio 0
	s_nop 1
	v_mov_b64_e32 v[90:91], v[138:139]
	v_mov_b64_e32 v[86:87], v[146:147]
	v_mov_b64_e32 v[74:75], v[154:155]
	s_nop 0
	v_mov_b64_e32 v[66:67], v[166:167]
	v_mov_b64_e32 v[82:83], v[142:143]
	v_mov_b64_e32 v[78:79], v[150:151]
	v_mov_b64_e32 v[70:71], v[158:159]
	v_mov_b64_e32 v[62:63], v[162:163]
	v_mov_b64_e32 v[92:93], v[140:141]
	v_mov_b64_e32 v[88:89], v[148:149]
	v_mov_b64_e32 v[76:77], v[156:157]
	v_mov_b64_e32 v[68:69], v[168:169]
	v_mov_b64_e32 v[84:85], v[144:145]
	v_mov_b64_e32 v[80:81], v[152:153]
	v_mov_b64_e32 v[72:73], v[160:161]
	v_mov_b64_e32 v[64:65], v[164:165]
.Lmla_post_0:
	v_mov_b64_e32 v[218:219], v[224:225]
	v_mov_b64_e32 v[220:221], v[222:223]

; #define LAS __attribute__((address_space(3)))
; __device__ __forceinline__ float ex2(float x) { return __builtin_amdgcn_exp2f(x); }
; __device__ __forceinline__ f32x4 mfma16(bf16x8 a, bf16x8 b, f32x4 c) { return __builtin_amdgcn_mfma_f32_16x16x32_bf16(a, b, c, 0, 0, 0); }
; template <int NT, int NKK, int NDT, int MODE, bool MASK> ...
;   const int r = lane & 15, lg = lane >> 4, vq = (lane & 15) >> 2, vp = lane & 3;
;   f32x4 s[NT][4];
;   __builtin_amdgcn_s_setprio(1);
; #pragma unroll
;   for (int t = 0; t < 4; ++t)
; #pragma unroll
;     for (int kk = 0; kk < NKK; ++kk) {
;       const bf16x8 kf = *(LAS const bf16x8*)(Kl + (16 * t + r) * KSTR + (32 * kk + 8 * lg) * 2);
; #pragma unroll
;       for (int j = 0; j < NT; ++j) s[j][t] = mfma16(kf, qf[j][kk], kk == 0 ? (f32x4){0.f, 0.f, 0.f, 0.f} : s[j][t]);
;     }
;   __builtin_amdgcn_s_setprio(0);
;   bf16x8 pf[NT][2];
; #pragma unroll
;   for (int j = 0; j < NT; ++j) {
;     float mx = -INFINITY;
; #pragma unroll
;     for (int t = 0; t < 4; ++t)
; #pragma unroll
;       for (int i = 0; i < 4; ++i) {
;         if (MASK) { const int kp = kpos0 + 16 * t + 4 * lg + i; if (!mask_ok<MODE>(tq[j], kp, W)) s[j][t][i] = -INFINITY; }
;         mx = fmaxf(mx, s[j][t][i]);
;       }
;     mx = max_x16_x32(mx);
;     if (__any(mx > m[j] + 8.0f / c)) {
;       const float mnew = fmaxf(m[j], mx);
;       const float ms2 = (mnew == -INFINITY) ? 0.f : mnew;
;       const float alpha = ex2((m[j] - ms2) * c);
;       m[j] = mnew; l[j] *= alpha;
; #pragma unroll
;       for (int dt = 0; dt < NDT; ++dt) o[j][dt] *= alpha;
;     }
; template <int NT, int DQK, int DV, int MODE, int PD, class Src> ...
;     ...
;         const int lo = kbase + 64 * kc, hi = lo + 63;
;         bool rel = true, full = true;
;         if (MODE == MODE_CAUSAL) { rel = lo <= tq_max; full = hi <= tq_min; }
;         if (MODE == MODE_WINDOW) { rel = (lo <= tq_max) && (hi > tq_min - W); full = (hi <= tq_min) && (lo > tq_max - W); }
;         if (MODE == MODE_CMP) { rel = 16 * lo + 31 <= tq_max; full = 16 * hi + 31 <= tq_min; }
;         if (rel) {
;           if (NT <= 2) {
;             if (full) attn_chunk_wide<NT, DQK / 32, DV / 16, MODE, false>(o, m, l, qf, buf, KSTR, buf + KB, VSTR, lo, tq, c, W, lane);
;             else attn_chunk_wide<NT, DQK / 32, DV / 16, MODE, true>(o, m, l, qf, buf, KSTR, buf + KB, VSTR, lo, tq, c, W, lane);
.LBB0_810:
	s_waitcnt lgkmcnt(0)
	s_barrier
	s_add_i32 s8, s69, 0xffffff81
	s_cmp_gt_i32 s8, s68
	s_cbranch_scc1 .LBB0_837
	s_sub_i32 s8, s69, 64
	s_cmp_gt_i32 s8, s59
	s_setprio 1
	v_add_u32_e32 v1, s73, v236
	s_waitcnt lgkmcnt(0)
	v_add_u32_e32 v94, v1, v237
	ds_read_b128 v[134:137], v94
	ds_read_b128 v[130:133], v94 offset:64
	ds_read_b128 v[126:129], v94 offset:128
	ds_read_b128 v[122:125], v94 offset:3328
	ds_read_b128 v[118:121], v94 offset:3392
	ds_read_b128 v[114:117], v94 offset:3456
	ds_read_b128 v[106:109], v94 offset:6656
	ds_read_b128 v[98:101], v94 offset:6720
	v_add_u32_e32 v201, v1, v238
	ds_read_b128 v[110:113], v94 offset:6784
	ds_read_b128 v[102:105], v201
	ds_read_b128 v[94:97], v201 offset:64
	s_mov_b64 s[20:21], -1
	v_add_f32_e32 v1, 0x4259535f, v220
	s_cbranch_scc1 .LBB0_828
	s_waitcnt lgkmcnt(10)
	v_mfma_f32_16x16x32_bf16 v[138:141], v[134:137], v[18:21], 0
	ds_read_b128 v[146:149], v201 offset:128
	v_mov_b32_e32 v234, 0x260
	v_mfma_f32_16x16x32_bf16 v[142:145], v[134:137], v[10:13], 0
	s_waitcnt lgkmcnt(10)
	v_mfma_f32_16x16x32_bf16 v[138:141], v[130:133], v[2:5], v[138:141]
	v_mfma_f32_16x16x32_bf16 v[142:145], v[130:133], v[14:17], v[142:145]
	s_waitcnt lgkmcnt(9)
	v_mfma_f32_16x16x32_bf16 v[182:185], v[126:129], v[6:9], v[138:141]
	v_mfma_f32_16x16x32_bf16 v[166:169], v[126:129], v[22:25], v[142:145]
	s_waitcnt lgkmcnt(8)
	v_mfma_f32_16x16x32_bf16 v[138:141], v[122:125], v[18:21], 0
	v_mfma_f32_16x16x32_bf16 v[142:145], v[122:125], v[10:13], 0
	s_waitcnt lgkmcnt(7)
	v_mfma_f32_16x16x32_bf16 v[138:141], v[118:121], v[2:5], v[138:141]
	v_mfma_f32_16x16x32_bf16 v[142:145], v[118:121], v[14:17], v[142:145]
	s_waitcnt lgkmcnt(6)
	v_mfma_f32_16x16x32_bf16 v[178:181], v[114:117], v[6:9], v[138:141]
	v_mfma_f32_16x16x32_bf16 v[154:157], v[114:117], v[22:25], v[142:145]
	s_waitcnt lgkmcnt(5)
	v_mfma_f32_16x16x32_bf16 v[138:141], v[106:109], v[18:21], 0
	v_mfma_f32_16x16x32_bf16 v[142:145], v[106:109], v[10:13], 0
	s_waitcnt lgkmcnt(4)
	v_mfma_f32_16x16x32_bf16 v[138:141], v[98:101], v[2:5], v[138:141]
	v_mfma_f32_16x16x32_bf16 v[142:145], v[98:101], v[14:17], v[142:145]
	s_waitcnt lgkmcnt(3)
	v_mfma_f32_16x16x32_bf16 v[174:177], v[110:113], v[6:9], v[138:141]
	v_mfma_f32_16x16x32_bf16 v[150:153], v[110:113], v[22:25], v[142:145]
	s_waitcnt lgkmcnt(2)
	v_mfma_f32_16x16x32_bf16 v[138:141], v[102:105], v[18:21], 0
	v_mfma_f32_16x16x32_bf16 v[142:145], v[102:105], v[10:13], 0
	s_waitcnt lgkmcnt(1)
	v_mfma_f32_16x16x32_bf16 v[138:141], v[94:97], v[2:5], v[138:141]
	v_mfma_f32_16x16x32_bf16 v[142:145], v[94:97], v[14:17], v[142:145]
	s_waitcnt lgkmcnt(0)
	v_mfma_f32_16x16x32_bf16 v[170:173], v[146:149], v[6:9], v[138:141]
	v_mfma_f32_16x16x32_bf16 v[142:145], v[146:149], v[22:25], v[142:145]
	s_setprio 0
	s_nop 2
	v_max3_f32 v138, v182, s81, v183
	v_max3_f32 v138, v138, v184, v185
	v_max3_f32 v138, v138, v178, v179
	v_max3_f32 v138, v138, v180, v181
	v_max3_f32 v138, v138, v174, v175
	v_max3_f32 v138, v138, v176, v177
	v_max3_f32 v138, v138, v170, v171
	v_max3_f32 v138, v138, v172, v173
	v_mov_b32_e32 v139, v138
	s_nop 1
	v_permlane16_swap_b32_e32 v138, v139
	v_max_f32_e32 v138, v138, v139
	v_mov_b32_e32 v139, v138
	s_nop 1
	v_permlane32_swap_b32_e32 v138, v139
	v_max_f32_e32 v186, v138, v139
	v_cmp_gt_f32_e32 vcc, v186, v1
	v_mov_b64_e32 v[222:223], v[220:221]
	v_mov_b64_e32 v[224:225], v[218:219]
	v_mov_b32_e32 v187, v220
	s_cbranch_vccz .LBB0_814
	v_max_f32_e32 v138, v186, v186
	v_max_f32_e32 v139, v220, v220
	v_max_f32_e32 v222, v139, v138
	v_cmp_neq_f32_e32 vcc, s81, v222
	v_mov_b32_e32 v223, v221
	v_mov_b32_e32 v225, v219
	v_cndmask_b32_e32 v138, 0, v222, vcc
	v_sub_f32_e32 v138, v220, v138
	v_mul_f32_e32 v138, 0x3e16c740, v138
	v_exp_f32_e32 v138, v138
	v_mov_b32_e32 v187, v222
	v_mul_f32_e32 v224, v218, v138
	v_pk_mul_f32 v[92:93], v[92:93], v[138:139] op_sel_hi:[1,0]
	v_pk_mul_f32 v[90:91], v[90:91], v[138:139] op_sel_hi:[1,0]
	v_pk_mul_f32 v[88:89], v[88:89], v[138:139] op_sel_hi:[1,0]
	v_pk_mul_f32 v[86:87], v[86:87], v[138:139] op_sel_hi:[1,0]
	v_pk_mul_f32 v[76:77], v[76:77], v[138:139] op_sel_hi:[1,0]
	v_pk_mul_f32 v[74:75], v[74:75], v[138:139] op_sel_hi:[1,0]
	v_pk_mul_f32 v[68:69], v[68:69], v[138:139] op_sel_hi:[1,0]
	v_pk_mul_f32 v[66:67], v[66:67], v[138:139] op_sel_hi:[1,0]

; __device__ __forceinline__ float ex2(float x) { return __builtin_amdgcn_exp2f(x); }
; __device__ __forceinline__ f32x4 mfma16(bf16x8 a, bf16x8 b, f32x4 c) { return __builtin_amdgcn_mfma_f32_16x16x32_bf16(a, b, c, 0, 0, 0); }
; __device__ __forceinline__ s16x4 ds_tr(LAS const unsigned char* p) { return __builtin_bit_cast(s16x4, __builtin_amdgcn_ds_read_tr16_b64_v4i16((LAS v4i16_t*)p)); }
; template <int NT, int NKK, int NDT, int MODE, bool MASK> ...
;     ...
;     const float mc = ((m[j] == -INFINITY) ? 0.f : m[j]) * c;
;     float p[4][4], ps = 0.f;
; #pragma unroll
;     for (int t = 0; t < 4; ++t)
; #pragma unroll
;       for (int i = 0; i < 4; ++i) { p[t][i] = ex2(s[j][t][i] * c - mc); ps += p[t][i]; }
;     l[j] += ps;
;     pf[j][0] = pack8(p[0], p[1]); pf[j][1] = pack8(p[2], p[3]);
;   }
;   __builtin_amdgcn_s_setprio(1);
; #pragma unroll
;   for (int st = 0; st < 2; ++st)
; #pragma unroll
;     for (int dt = 0; dt < NDT; ++dt) {
;       const s16x4 v0 = ds_tr(Vl + (32 * st + 4 * lg + vq) * VSTR + (16 * dt + 4 * vp) * 2);
;       const s16x4 v1 = ds_tr(Vl + (32 * st + 16 + 4 * lg + vq) * VSTR + (16 * dt + 4 * vp) * 2);
;       const bf16x8 vf = (bf16x8){v0[0], v0[1], v0[2], v0[3], v1[0], v1[1], v1[2], v1[3]};
; #pragma unroll
;       for (int j = 0; j < NT; ++j) o[j][dt] = mfma16(vf, pf[j][st], o[j][dt]);
;     }
;   __builtin_amdgcn_s_setprio(0);
.LBB0_827:
	v_cvt_pk_bf16_f32 v173, v196, v173
	v_mul_f32_e32 v196, 0x3e16c740, v197
	v_cmp_neq_f32_e32 vcc, s81, v197
	v_cvt_pk_bf16_f32 v172, v232, v228
	v_cvt_pk_bf16_f32 v228, v205, v207
	v_cndmask_b32_e32 v196, 0, v196, vcc
	v_fma_f32 v166, v166, s88, -v196
	v_exp_f32_e32 v166, v166
	v_fma_f32 v167, v167, s88, -v196
	v_exp_f32_e32 v167, v167
	v_fma_f32 v168, v168, s88, -v196
	v_exp_f32_e32 v168, v168
	v_fma_f32 v169, v169, s88, -v196
	v_exp_f32_e32 v169, v169
	v_fma_f32 v154, v154, s88, -v196
	v_add_f32_e32 v197, 0, v166
	v_exp_f32_e32 v154, v154
	v_fma_f32 v155, v155, s88, -v196
	v_add_f32_e32 v197, v167, v197
	v_exp_f32_e32 v155, v155
	v_fma_f32 v156, v156, s88, -v196
	v_add_f32_e32 v197, v168, v197
	v_exp_f32_e32 v156, v156
	v_fma_f32 v157, v157, s88, -v196
	v_add_f32_e32 v197, v169, v197
	v_exp_f32_e32 v157, v157
	v_fma_f32 v150, v150, s88, -v196
	v_add_f32_e32 v197, v154, v197
	v_exp_f32_e32 v150, v150
	v_fma_f32 v151, v151, s88, -v196
	v_add_f32_e32 v197, v155, v197
	v_exp_f32_e32 v151, v151
	v_fma_f32 v152, v152, s88, -v196
	v_add_f32_e32 v197, v156, v197
	v_exp_f32_e32 v152, v152
	v_fma_f32 v153, v153, s88, -v196
	v_add_f32_e32 v197, v157, v197
	v_exp_f32_e32 v153, v153
	v_fma_f32 v142, v142, s88, -v196
	v_add_f32_e32 v197, v150, v197
	v_exp_f32_e32 v198, v142
	v_fma_f32 v142, v143, s88, -v196
	v_add_f32_e32 v197, v151, v197
	v_exp_f32_e32 v199, v142
	v_fma_f32 v142, v144, s88, -v196
	v_add_f32_e32 v197, v152, v197
	v_exp_f32_e32 v205, v142
	v_fma_f32 v142, v145, s88, -v196
	v_add_f32_e32 v197, v153, v197
	v_exp_f32_e32 v196, v142
	v_add_f32_e32 v142, v198, v197
	v_add_f32_e32 v142, v199, v142
	v_add_f32_e32 v142, v205, v142
	v_add_f32_e32 v142, v196, v142
	v_add_f32_e32 v225, v225, v142
	v_cvt_pk_bf16_f32 v142, v166, v167
	v_cvt_pk_bf16_f32 v143, v168, v169
	v_cvt_pk_bf16_f32 v144, v154, v155
	v_cvt_pk_bf16_f32 v145, v156, v157
	v_cvt_pk_bf16_f32 v170, v252, v231
	v_cvt_pk_bf16_f32 v171, v229, v230
	v_cvt_pk_bf16_f32 v229, v246, v247
	v_cvt_pk_bf16_f32 v230, v248, v249
	v_cvt_pk_bf16_f32 v231, v250, v251
	v_cvt_pk_bf16_f32 v246, v150, v151
	v_cvt_pk_bf16_f32 v247, v152, v153
	v_cvt_pk_bf16_f32 v248, v198, v199
	v_cvt_pk_bf16_f32 v249, v205, v196
	s_setprio 1
	v_add3_u32 v196, s73, v240, v239
	ds_read_b64_tr_b16 v[152:153], v196 offset:15872
	ds_read_b64_tr_b16 v[150:151], v196 offset:13312
	ds_read_b64_tr_b16 v[154:155], v196 offset:13344
	ds_read_b64_tr_b16 v[156:157], v196 offset:15904
	ds_read_b64_tr_b16 v[166:167], v196 offset:13376
	ds_read_b64_tr_b16 v[168:169], v196 offset:15936
	s_mov_b64 s[20:21], 0
	s_waitcnt lgkmcnt(4)
	v_mfma_f32_16x16x32_bf16 v[158:161], v[150:153], v[228:231], v[90:93]
	v_mfma_f32_16x16x32_bf16 v[150:153], v[150:153], v[142:145], v[82:85]
	s_waitcnt lgkmcnt(0)
	v_mfma_f32_16x16x32_bf16 v[182:185], v[166:169], v[228:231], v[74:77]
	s_nop 2
	ds_read_b64_tr_b16 v[146:147], v196 offset:13408
	ds_read_b64_tr_b16 v[148:149], v196 offset:15968
	v_mfma_f32_16x16x32_bf16 v[162:165], v[154:157], v[228:231], v[86:89]
	v_mfma_f32_16x16x32_bf16 v[154:157], v[154:157], v[142:145], v[78:81]
	v_mfma_f32_16x16x32_bf16 v[166:169], v[166:169], v[142:145], v[70:73]
	s_waitcnt lgkmcnt(0)
	v_mfma_f32_16x16x32_bf16 v[174:177], v[146:149], v[142:145], v[62:65]
	ds_read_b64_tr_b16 v[142:143], v196 offset:18432
	ds_read_b64_tr_b16 v[144:145], v196 offset:20992
	v_mfma_f32_16x16x32_bf16 v[178:181], v[146:149], v[228:231], v[66:69]
	s_waitcnt lgkmcnt(0)
	v_mfma_f32_16x16x32_bf16 v[90:93], v[142:145], v[170:173], v[158:161]
	v_mfma_f32_16x16x32_bf16 v[82:85], v[142:145], v[246:249], v[150:153]
	s_nop 2
	ds_read_b64_tr_b16 v[150:151], v196 offset:18464
	ds_read_b64_tr_b16 v[152:153], v196 offset:21024
	ds_read_b64_tr_b16 v[158:159], v196 offset:18496
	ds_read_b64_tr_b16 v[160:161], v196 offset:21056
	s_waitcnt lgkmcnt(2)
	v_mfma_f32_16x16x32_bf16 v[86:89], v[150:153], v[170:173], v[162:165]
	s_nop 2
	ds_read_b64_tr_b16 v[162:163], v196 offset:18528
	ds_read_b64_tr_b16 v[164:165], v196 offset:21088
	v_mfma_f32_16x16x32_bf16 v[78:81], v[150:153], v[246:249], v[154:157]
	s_waitcnt lgkmcnt(2)
	v_mfma_f32_16x16x32_bf16 v[74:77], v[158:161], v[170:173], v[182:185]
	v_mfma_f32_16x16x32_bf16 v[70:73], v[158:161], v[246:249], v[166:169]
	s_waitcnt lgkmcnt(0)
	v_mfma_f32_16x16x32_bf16 v[66:69], v[162:165], v[170:173], v[178:181]
	v_mfma_f32_16x16x32_bf16 v[62:65], v[162:165], v[246:249], v[174:177]
	s_setprio 0
	s_branch .Lmla_post_1
; #define LAS __attribute__((address_space(3)))
; __device__ __forceinline__ float ex2(float x) { return __builtin_amdgcn_exp2f(x); }
; __device__ __forceinline__ f32x4 mfma16(bf16x8 a, bf16x8 b, f32x4 c) { return __builtin_amdgcn_mfma_f32_16x16x32_bf16(a, b, c, 0, 0, 0); }
;   __device__ __forceinline__ bf16_t* W() const { return (bf16_t*)(ws + WS_W); }
; template <int NT, int NKK, int NDT, int MODE, bool MASK> ...
;   const int r = lane & 15, lg = lane >> 4, vq = (lane & 15) >> 2, vp = lane & 3;
;   f32x4 s[NT][4];
;   __builtin_amdgcn_s_setprio(1);
; #pragma unroll
;   for (int t = 0; t < 4; ++t)
; #pragma unroll
;     for (int kk = 0; kk < NKK; ++kk) {
;       const bf16x8 kf = *(LAS const bf16x8*)(Kl + (16 * t + r) * KSTR + (32 * kk + 8 * lg) * 2);
; #pragma unroll
;       for (int j = 0; j < NT; ++j) s[j][t] = mfma16(kf, qf[j][kk], kk == 0 ? (f32x4){0.f, 0.f, 0.f, 0.f} : s[j][t]);
;     }
;   __builtin_amdgcn_s_setprio(0);
;   bf16x8 pf[NT][2];
; #pragma unroll
;   for (int j = 0; j < NT; ++j) {
;     float mx = -INFINITY;
; #pragma unroll
;     for (int t = 0; t < 4; ++t)
; #pragma unroll
;       for (int i = 0; i < 4; ++i) {
;         if (MASK) { const int kp = kpos0 + 16 * t + 4 * lg + i; if (!mask_ok<MODE>(tq[j], kp, W)) s[j][t][i] = -INFINITY; }
;         mx = fmaxf(mx, s[j][t][i]);
;       }
;     mx = max_x16_x32(mx);
;     if (__any(mx > m[j] + 8.0f / c)) {
;       const float mnew = fmaxf(m[j], mx);
;       const float ms2 = (mnew == -INFINITY) ? 0.f : mnew;
;       const float alpha = ex2((m[j] - ms2) * c);
;       m[j] = mnew; l[j] *= alpha;
; #pragma unroll
;       for (int dt = 0; dt < NDT; ++dt) o[j][dt] *= alpha;
;     }
.LBB0_828:
	s_and_b64 vcc, exec, s[20:21]
	s_cbranch_vccz .LBB0_836
	s_waitcnt lgkmcnt(10)
	v_mfma_f32_16x16x32_bf16 v[138:141], v[134:137], v[18:21], 0
	v_mfma_f32_16x16x32_bf16 v[134:137], v[134:137], v[10:13], 0
	s_waitcnt lgkmcnt(9)
	v_mfma_f32_16x16x32_bf16 v[138:141], v[130:133], v[2:5], v[138:141]
	v_mfma_f32_16x16x32_bf16 v[134:137], v[130:133], v[14:17], v[134:137]
	s_waitcnt lgkmcnt(8)
	v_mfma_f32_16x16x32_bf16 v[130:133], v[126:129], v[6:9], v[138:141]
	v_mfma_f32_16x16x32_bf16 v[126:129], v[126:129], v[22:25], v[134:137]
	s_waitcnt lgkmcnt(7)
	v_mfma_f32_16x16x32_bf16 v[134:137], v[122:125], v[18:21], 0
	v_mfma_f32_16x16x32_bf16 v[122:125], v[122:125], v[10:13], 0
	s_waitcnt lgkmcnt(6)
	v_mfma_f32_16x16x32_bf16 v[134:137], v[118:121], v[2:5], v[134:137]
	v_mfma_f32_16x16x32_bf16 v[118:121], v[118:121], v[14:17], v[122:125]
	s_waitcnt lgkmcnt(5)
	v_mfma_f32_16x16x32_bf16 v[134:137], v[114:117], v[6:9], v[134:137]
	v_mfma_f32_16x16x32_bf16 v[114:117], v[114:117], v[22:25], v[118:121]
	s_waitcnt lgkmcnt(4)
	v_mfma_f32_16x16x32_bf16 v[118:121], v[106:109], v[18:21], 0
	v_mfma_f32_16x16x32_bf16 v[106:109], v[106:109], v[10:13], 0
	s_waitcnt lgkmcnt(3)
	v_mfma_f32_16x16x32_bf16 v[118:121], v[98:101], v[2:5], v[118:121]
	v_mfma_f32_16x16x32_bf16 v[98:101], v[98:101], v[14:17], v[106:109]
	s_waitcnt lgkmcnt(1)
	v_mfma_f32_16x16x32_bf16 v[106:109], v[102:105], v[18:21], 0
	v_mfma_f32_16x16x32_bf16 v[102:105], v[102:105], v[10:13], 0
	s_waitcnt lgkmcnt(0)
	v_mfma_f32_16x16x32_bf16 v[106:109], v[94:97], v[2:5], v[106:109]
	v_mfma_f32_16x16x32_bf16 v[94:97], v[94:97], v[14:17], v[102:105]
	s_nop 4
	ds_read_b128 v[102:105], v201 offset:128
	v_mfma_f32_16x16x32_bf16 v[118:121], v[110:113], v[6:9], v[118:121]
	v_mfma_f32_16x16x32_bf16 v[98:101], v[110:113], v[22:25], v[98:101]
	s_waitcnt lgkmcnt(0)
	v_mfma_f32_16x16x32_bf16 v[94:97], v[102:105], v[22:25], v[94:97]
	v_mfma_f32_16x16x32_bf16 v[144:147], v[102:105], v[6:9], v[106:109]
	s_setprio 0
	v_add_u32_e32 v103, s69, v241
	v_add_u32_e32 v104, 0xffffff81, v103
	v_add_u32_e32 v105, 0xffffff83, v103
	v_mov_b32_e32 v102, s81
	v_cmp_gt_i32_e64 s[20:21], v104, v194
	v_cmp_lt_i32_e64 s[22:23], v104, v194
	v_cmp_le_i32_e32 vcc, v105, v194
	v_add_u32_e32 v106, 0xffffff84, v103
	v_cndmask_b32_e64 v142, v130, v102, s[20:21]
	v_cndmask_b32_e64 v122, v200, v131, s[22:23]
	v_cndmask_b32_e32 v124, v200, v132, vcc
	v_cmp_le_i32_e32 vcc, v106, v194
	v_max3_f32 v102, v142, s81, v122
	v_add_u32_e32 v107, 0xffffff91, v103
	v_cndmask_b32_e32 v123, v200, v133, vcc
	v_max3_f32 v108, v102, v124, v123
	v_mov_b32_e32 v102, s81
	v_cmp_gt_i32_e32 vcc, v107, v194
	v_add_u32_e32 v107, 0xffffff92, v103
	v_add_u32_e32 v110, 0xffffff94, v103
	v_cndmask_b32_e32 v125, v134, v102, vcc
	v_cmp_le_i32_e32 vcc, v107, v194
	v_add_u32_e32 v109, 0xffffffa1, v103
	v_add_u32_e32 v111, 0xffffffa2, v103
	v_cndmask_b32_e32 v131, v200, v135, vcc
	v_max3_f32 v102, v108, v125, v131
	v_add_u32_e32 v108, 0xffffff93, v103
	v_cmp_le_i32_e32 vcc, v108, v194
	v_add_u32_e32 v113, 0xffffffb1, v103
	s_nop 0
	v_cndmask_b32_e32 v133, v200, v136, vcc
	v_cmp_le_i32_e32 vcc, v110, v194
	s_nop 1
	v_cndmask_b32_e32 v132, v200, v137, vcc
	v_max3_f32 v112, v102, v133, v132
	v_mov_b32_e32 v102, s81
	v_cmp_gt_i32_e32 vcc, v109, v194
	s_nop 1
	v_cndmask_b32_e32 v134, v118, v102, vcc
	v_cmp_le_i32_e32 vcc, v111, v194
	v_add_u32_e32 v118, 0xffffffa4, v103
	s_nop 0
	v_cndmask_b32_e32 v135, v200, v119, vcc
	v_max3_f32 v102, v112, v134, v135
	v_add_u32_e32 v112, 0xffffffa3, v103
	v_cmp_le_i32_e32 vcc, v112, v194
	v_add_u32_e32 v119, 0xffffffb2, v103
	s_nop 0
	v_cndmask_b32_e32 v137, v200, v120, vcc
	v_cmp_le_i32_e32 vcc, v118, v194
	s_nop 1
	v_cndmask_b32_e32 v136, v200, v121, vcc
	v_max3_f32 v120, v102, v137, v136
	v_mov_b32_e32 v102, s81
	v_cmp_gt_i32_e32 vcc, v113, v194
	v_add_u32_e32 v121, 0xffffffb4, v103
	s_nop 0
	v_cndmask_b32_e32 v138, v144, v102, vcc
	v_cmp_le_i32_e32 vcc, v119, v194
	s_nop 1
	v_cndmask_b32_e32 v139, v200, v145, vcc
	v_max3_f32 v102, v120, v138, v139
	v_add_u32_e32 v120, 0xffffffb3, v103
	v_cmp_le_i32_e32 vcc, v120, v194
	s_nop 1
	v_cndmask_b32_e32 v141, v200, v146, vcc
	v_cmp_le_i32_e32 vcc, v121, v194
	s_nop 1
	v_cndmask_b32_e32 v140, v200, v147, vcc
	v_max3_f32 v102, v102, v141, v140
	v_mov_b32_e32 v103, v102
	s_nop 1
	v_permlane16_swap_b32_e32 v102, v103
	v_max_f32_e32 v102, v102, v103
	v_mov_b32_e32 v103, v102
	s_nop 1
	v_permlane32_swap_b32_e32 v102, v103
	v_max_f32_e32 v102, v102, v103
	v_cmp_gt_f32_e32 vcc, v102, v1
	s_cbranch_vccz .LBB0_831
	v_max_f32_e32 v1, v102, v102
	v_max_f32_e32 v102, v220, v220
	v_max_f32_e32 v102, v102, v1
	v_cmp_neq_f32_e32 vcc, s81, v102
	v_mov_b32_e32 v103, v221
	s_nop 0
	v_cndmask_b32_e32 v1, 0, v102, vcc
	v_sub_f32_e32 v1, v220, v1
	v_mul_f32_e32 v1, 0x3e16c740, v1
	v_exp_f32_e32 v144, v1
	v_mov_b64_e32 v[220:221], v[102:103]
	v_mul_f32_e32 v218, v218, v144
	v_pk_mul_f32 v[92:93], v[92:93], v[144:145] op_sel_hi:[1,0]
	v_pk_mul_f32 v[90:91], v[90:91], v[144:145] op_sel_hi:[1,0]
	v_pk_mul_f32 v[88:89], v[88:89], v[144:145] op_sel_hi:[1,0]
	v_pk_mul_f32 v[86:87], v[86:87], v[144:145] op_sel_hi:[1,0]
	v_pk_mul_f32 v[76:77], v[76:77], v[144:145] op_sel_hi:[1,0]
	v_pk_mul_f32 v[74:75], v[74:75], v[144:145] op_sel_hi:[1,0]
	v_pk_mul_f32 v[68:69], v[68:69], v[144:145] op_sel_hi:[1,0]
	v_pk_mul_f32 v[66:67], v[66:67], v[144:145] op_sel_hi:[1,0]
	s_branch .LBB0_832

; #define LAS __attribute__((address_space(3)))
; __device__ __forceinline__ float ex2(float x) { return __builtin_amdgcn_exp2f(x); }
; __device__ __forceinline__ f32x4 mfma16(bf16x8 a, bf16x8 b, f32x4 c) { return __builtin_amdgcn_mfma_f32_16x16x32_bf16(a, b, c, 0, 0, 0); }
; template <int NT, int NKK, int NDT, int MODE, bool MASK> ...
;   const int r = lane & 15, lg = lane >> 4, vq = (lane & 15) >> 2, vp = lane & 3;
;   f32x4 s[NT][4];
;   __builtin_amdgcn_s_setprio(1);
; #pragma unroll
;   for (int t = 0; t < 4; ++t)
; #pragma unroll
;     for (int kk = 0; kk < NKK; ++kk) {
;       const bf16x8 kf = *(LAS const bf16x8*)(Kl + (16 * t + r) * KSTR + (32 * kk + 8 * lg) * 2);
; #pragma unroll
;       for (int j = 0; j < NT; ++j) s[j][t] = mfma16(kf, qf[j][kk], kk == 0 ? (f32x4){0.f, 0.f, 0.f, 0.f} : s[j][t]);
;     }
;   __builtin_amdgcn_s_setprio(0);
;   bf16x8 pf[NT][2];
; #pragma unroll
;   for (int j = 0; j < NT; ++j) {
;     float mx = -INFINITY;
; #pragma unroll
;     for (int t = 0; t < 4; ++t)
; #pragma unroll
;       for (int i = 0; i < 4; ++i) {
;         if (MASK) { const int kp = kpos0 + 16 * t + 4 * lg + i; if (!mask_ok<MODE>(tq[j], kp, W)) s[j][t][i] = -INFINITY; }
;         mx = fmaxf(mx, s[j][t][i]);
;       }
;     mx = max_x16_x32(mx);
;     if (__any(mx > m[j] + 8.0f / c)) {
;       const float mnew = fmaxf(m[j], mx);
;       const float ms2 = (mnew == -INFINITY) ? 0.f : mnew;
;       const float alpha = ex2((m[j] - ms2) * c);
;       m[j] = mnew; l[j] *= alpha;
; #pragma unroll
;       for (int dt = 0; dt < NDT; ++dt) o[j][dt] *= alpha;
;     }
; template <int NT, int DQK, int DV, int MODE, int PD, class Src> ...
;     ...
;         const int lo = kbase + 64 * kc, hi = lo + 63;
;         bool rel = true, full = true;
;         if (MODE == MODE_CAUSAL) { rel = lo <= tq_max; full = hi <= tq_min; }
;         if (MODE == MODE_WINDOW) { rel = (lo <= tq_max) && (hi > tq_min - W); full = (hi <= tq_min) && (lo > tq_max - W); }
;         if (MODE == MODE_CMP) { rel = 16 * lo + 31 <= tq_max; full = 16 * hi + 31 <= tq_min; }
;         if (rel) {
;           if (NT <= 2) {
;             if (full) attn_chunk_wide<NT, DQK / 32, DV / 16, MODE, false>(o, m, l, qf, buf, KSTR, buf + KB, VSTR, lo, tq, c, W, lane);
;             else attn_chunk_wide<NT, DQK / 32, DV / 16, MODE, true>(o, m, l, qf, buf, KSTR, buf + KB, VSTR, lo, tq, c, W, lane);
.LBB0_850:
	s_waitcnt lgkmcnt(0)
	s_barrier
	s_sub_i32 s8, s69, 63
	s_cmp_gt_i32 s8, s68
	s_cbranch_scc1 .LBB0_877
	s_cmp_gt_i32 s69, s59
	s_setprio 1
	v_add_u32_e32 v1, s71, v236
	s_waitcnt lgkmcnt(0)
	v_add_u32_e32 v94, v1, v237
	ds_read_b128 v[134:137], v94
	ds_read_b128 v[130:133], v94 offset:64
	ds_read_b128 v[126:129], v94 offset:128
	ds_read_b128 v[122:125], v94 offset:3328
	ds_read_b128 v[118:121], v94 offset:3392
	ds_read_b128 v[114:117], v94 offset:3456
	ds_read_b128 v[106:109], v94 offset:6656
	ds_read_b128 v[98:101], v94 offset:6720
	v_add_u32_e32 v201, v1, v238
	ds_read_b128 v[110:113], v94 offset:6784
	ds_read_b128 v[102:105], v201
	ds_read_b128 v[94:97], v201 offset:64
	s_mov_b64 s[20:21], -1
	v_add_f32_e32 v1, 0x4259535f, v220
	s_cbranch_scc1 .LBB0_868
	s_waitcnt lgkmcnt(10)
	v_mfma_f32_16x16x32_bf16 v[138:141], v[134:137], v[18:21], 0
	ds_read_b128 v[146:149], v201 offset:128
	v_mov_b32_e32 v234, 0x260
	v_mfma_f32_16x16x32_bf16 v[142:145], v[134:137], v[10:13], 0
	s_waitcnt lgkmcnt(10)
	v_mfma_f32_16x16x32_bf16 v[138:141], v[130:133], v[2:5], v[138:141]
	v_mfma_f32_16x16x32_bf16 v[142:145], v[130:133], v[14:17], v[142:145]
	s_waitcnt lgkmcnt(9)
	v_mfma_f32_16x16x32_bf16 v[182:185], v[126:129], v[6:9], v[138:141]
	v_mfma_f32_16x16x32_bf16 v[166:169], v[126:129], v[22:25], v[142:145]
	s_waitcnt lgkmcnt(8)
	v_mfma_f32_16x16x32_bf16 v[138:141], v[122:125], v[18:21], 0
	v_mfma_f32_16x16x32_bf16 v[142:145], v[122:125], v[10:13], 0
	s_waitcnt lgkmcnt(7)
	v_mfma_f32_16x16x32_bf16 v[138:141], v[118:121], v[2:5], v[138:141]
	v_mfma_f32_16x16x32_bf16 v[142:145], v[118:121], v[14:17], v[142:145]
	s_waitcnt lgkmcnt(6)
	v_mfma_f32_16x16x32_bf16 v[178:181], v[114:117], v[6:9], v[138:141]
	v_mfma_f32_16x16x32_bf16 v[154:157], v[114:117], v[22:25], v[142:145]
	s_waitcnt lgkmcnt(5)
	v_mfma_f32_16x16x32_bf16 v[138:141], v[106:109], v[18:21], 0
	v_mfma_f32_16x16x32_bf16 v[142:145], v[106:109], v[10:13], 0
	s_waitcnt lgkmcnt(4)
	v_mfma_f32_16x16x32_bf16 v[138:141], v[98:101], v[2:5], v[138:141]
	v_mfma_f32_16x16x32_bf16 v[142:145], v[98:101], v[14:17], v[142:145]
	s_waitcnt lgkmcnt(3)
	v_mfma_f32_16x16x32_bf16 v[174:177], v[110:113], v[6:9], v[138:141]
	v_mfma_f32_16x16x32_bf16 v[150:153], v[110:113], v[22:25], v[142:145]
	s_waitcnt lgkmcnt(2)
	v_mfma_f32_16x16x32_bf16 v[138:141], v[102:105], v[18:21], 0
	v_mfma_f32_16x16x32_bf16 v[142:145], v[102:105], v[10:13], 0
	s_waitcnt lgkmcnt(1)
	v_mfma_f32_16x16x32_bf16 v[138:141], v[94:97], v[2:5], v[138:141]
	v_mfma_f32_16x16x32_bf16 v[142:145], v[94:97], v[14:17], v[142:145]
	s_waitcnt lgkmcnt(0)
	v_mfma_f32_16x16x32_bf16 v[170:173], v[146:149], v[6:9], v[138:141]
	v_mfma_f32_16x16x32_bf16 v[142:145], v[146:149], v[22:25], v[142:145]
	s_setprio 0
	s_nop 2
	v_max3_f32 v138, v182, s81, v183
	v_max3_f32 v138, v138, v184, v185
	v_max3_f32 v138, v138, v178, v179
	v_max3_f32 v138, v138, v180, v181
	v_max3_f32 v138, v138, v174, v175
	v_max3_f32 v138, v138, v176, v177
	v_max3_f32 v138, v138, v170, v171
	v_max3_f32 v138, v138, v172, v173
	v_mov_b32_e32 v139, v138
	s_nop 1
	v_permlane16_swap_b32_e32 v138, v139
	v_max_f32_e32 v138, v138, v139
	v_mov_b32_e32 v139, v138
	s_nop 1
	v_permlane32_swap_b32_e32 v138, v139
	v_max_f32_e32 v186, v138, v139
	v_cmp_gt_f32_e32 vcc, v186, v1
	v_mov_b64_e32 v[222:223], v[220:221]
	v_mov_b64_e32 v[224:225], v[218:219]
	v_mov_b32_e32 v187, v220
	s_cbranch_vccz .LBB0_854
	v_max_f32_e32 v138, v186, v186
	v_max_f32_e32 v139, v220, v220
	v_max_f32_e32 v222, v139, v138
	v_cmp_neq_f32_e32 vcc, s81, v222
	v_mov_b32_e32 v223, v221
	v_mov_b32_e32 v225, v219
	v_cndmask_b32_e32 v138, 0, v222, vcc
	v_sub_f32_e32 v138, v220, v138
	v_mul_f32_e32 v138, 0x3e16c740, v138
	v_exp_f32_e32 v138, v138
	v_mov_b32_e32 v187, v222
	v_mul_f32_e32 v224, v218, v138
	v_pk_mul_f32 v[92:93], v[92:93], v[138:139] op_sel_hi:[1,0]
	v_pk_mul_f32 v[90:91], v[90:91], v[138:139] op_sel_hi:[1,0]
	v_pk_mul_f32 v[88:89], v[88:89], v[138:139] op_sel_hi:[1,0]
	v_pk_mul_f32 v[86:87], v[86:87], v[138:139] op_sel_hi:[1,0]
	v_pk_mul_f32 v[76:77], v[76:77], v[138:139] op_sel_hi:[1,0]
	v_pk_mul_f32 v[74:75], v[74:75], v[138:139] op_sel_hi:[1,0]
	v_pk_mul_f32 v[68:69], v[68:69], v[138:139] op_sel_hi:[1,0]
	v_pk_mul_f32 v[66:67], v[66:67], v[138:139] op_sel_hi:[1,0]

; #define LAS __attribute__((address_space(3)))
; __device__ __forceinline__ float ex2(float x) { return __builtin_amdgcn_exp2f(x); }
; __device__ __forceinline__ f32x4 mfma16(bf16x8 a, bf16x8 b, f32x4 c) { return __builtin_amdgcn_mfma_f32_16x16x32_bf16(a, b, c, 0, 0, 0); }
;   __device__ __forceinline__ bf16_t* W() const { return (bf16_t*)(ws + WS_W); }
; template <int NT, int NKK, int NDT, int MODE, bool MASK> ...
;   const int r = lane & 15, lg = lane >> 4, vq = (lane & 15) >> 2, vp = lane & 3;
;   f32x4 s[NT][4];
;   __builtin_amdgcn_s_setprio(1);
; #pragma unroll
;   for (int t = 0; t < 4; ++t)
; #pragma unroll
;     for (int kk = 0; kk < NKK; ++kk) {
;       const bf16x8 kf = *(LAS const bf16x8*)(Kl + (16 * t + r) * KSTR + (32 * kk + 8 * lg) * 2);
; #pragma unroll
;       for (int j = 0; j < NT; ++j) s[j][t] = mfma16(kf, qf[j][kk], kk == 0 ? (f32x4){0.f, 0.f, 0.f, 0.f} : s[j][t]);
;     }
;   __builtin_amdgcn_s_setprio(0);
;   bf16x8 pf[NT][2];
; #pragma unroll
;   for (int j = 0; j < NT; ++j) {
;     float mx = -INFINITY;
; #pragma unroll
;     for (int t = 0; t < 4; ++t)
; #pragma unroll
;       for (int i = 0; i < 4; ++i) {
;         if (MASK) { const int kp = kpos0 + 16 * t + 4 * lg + i; if (!mask_ok<MODE>(tq[j], kp, W)) s[j][t][i] = -INFINITY; }
;         mx = fmaxf(mx, s[j][t][i]);
;       }
;     mx = max_x16_x32(mx);
;     if (__any(mx > m[j] + 8.0f / c)) {
;       const float mnew = fmaxf(m[j], mx);
;       const float ms2 = (mnew == -INFINITY) ? 0.f : mnew;
;       const float alpha = ex2((m[j] - ms2) * c);
;       m[j] = mnew; l[j] *= alpha;
; #pragma unroll
;       for (int dt = 0; dt < NDT; ++dt) o[j][dt] *= alpha;
;     }
.LBB0_868:
	s_and_b64 vcc, exec, s[20:21]
	s_cbranch_vccz .LBB0_876
	s_waitcnt lgkmcnt(10)
	v_mfma_f32_16x16x32_bf16 v[138:141], v[134:137], v[18:21], 0
	v_mfma_f32_16x16x32_bf16 v[134:137], v[134:137], v[10:13], 0
	s_waitcnt lgkmcnt(9)
	v_mfma_f32_16x16x32_bf16 v[138:141], v[130:133], v[2:5], v[138:141]
	v_mfma_f32_16x16x32_bf16 v[134:137], v[130:133], v[14:17], v[134:137]
	s_waitcnt lgkmcnt(8)
	v_mfma_f32_16x16x32_bf16 v[130:133], v[126:129], v[6:9], v[138:141]
	v_mfma_f32_16x16x32_bf16 v[126:129], v[126:129], v[22:25], v[134:137]
	s_waitcnt lgkmcnt(7)
	v_mfma_f32_16x16x32_bf16 v[134:137], v[122:125], v[18:21], 0
	v_mfma_f32_16x16x32_bf16 v[122:125], v[122:125], v[10:13], 0
	s_waitcnt lgkmcnt(6)
	v_mfma_f32_16x16x32_bf16 v[134:137], v[118:121], v[2:5], v[134:137]
	v_mfma_f32_16x16x32_bf16 v[118:121], v[118:121], v[14:17], v[122:125]
	s_waitcnt lgkmcnt(5)
	v_mfma_f32_16x16x32_bf16 v[134:137], v[114:117], v[6:9], v[134:137]
	v_mfma_f32_16x16x32_bf16 v[114:117], v[114:117], v[22:25], v[118:121]
	s_waitcnt lgkmcnt(4)
	v_mfma_f32_16x16x32_bf16 v[118:121], v[106:109], v[18:21], 0
	v_mfma_f32_16x16x32_bf16 v[106:109], v[106:109], v[10:13], 0
	s_waitcnt lgkmcnt(3)
	v_mfma_f32_16x16x32_bf16 v[118:121], v[98:101], v[2:5], v[118:121]
	v_mfma_f32_16x16x32_bf16 v[98:101], v[98:101], v[14:17], v[106:109]
	s_waitcnt lgkmcnt(1)
	v_mfma_f32_16x16x32_bf16 v[106:109], v[102:105], v[18:21], 0
	v_mfma_f32_16x16x32_bf16 v[102:105], v[102:105], v[10:13], 0
	s_waitcnt lgkmcnt(0)
	v_mfma_f32_16x16x32_bf16 v[106:109], v[94:97], v[2:5], v[106:109]
	v_mfma_f32_16x16x32_bf16 v[94:97], v[94:97], v[14:17], v[102:105]
	s_nop 4
	ds_read_b128 v[102:105], v201 offset:128
	v_mfma_f32_16x16x32_bf16 v[118:121], v[110:113], v[6:9], v[118:121]
	v_mfma_f32_16x16x32_bf16 v[98:101], v[110:113], v[22:25], v[98:101]
	s_waitcnt lgkmcnt(0)
	v_mfma_f32_16x16x32_bf16 v[94:97], v[102:105], v[22:25], v[94:97]
	v_mfma_f32_16x16x32_bf16 v[144:147], v[102:105], v[6:9], v[106:109]
	s_setprio 0
	v_add_u32_e32 v103, s69, v241
	v_subrev_u32_e32 v104, 63, v103
	v_subrev_u32_e32 v105, 61, v103
	v_mov_b32_e32 v102, s81
	v_cmp_gt_i32_e64 s[20:21], v104, v194
	v_cmp_lt_i32_e64 s[22:23], v104, v194
	v_cmp_le_i32_e32 vcc, v105, v194
	v_subrev_u32_e32 v106, 60, v103
	v_cndmask_b32_e64 v142, v130, v102, s[20:21]
	v_cndmask_b32_e64 v122, v200, v131, s[22:23]
	v_cndmask_b32_e32 v124, v200, v132, vcc
	v_cmp_le_i32_e32 vcc, v106, v194
	v_max3_f32 v102, v142, s81, v122
	v_subrev_u32_e32 v107, 47, v103
	v_cndmask_b32_e32 v123, v200, v133, vcc
	v_max3_f32 v108, v102, v124, v123
	v_mov_b32_e32 v102, s81
	v_cmp_gt_i32_e32 vcc, v107, v194
	v_subrev_u32_e32 v107, 46, v103
	v_subrev_u32_e32 v110, 44, v103
	v_cndmask_b32_e32 v125, v134, v102, vcc
	v_cmp_le_i32_e32 vcc, v107, v194
	v_subrev_u32_e32 v109, 31, v103
	v_subrev_u32_e32 v111, 30, v103
	v_cndmask_b32_e32 v131, v200, v135, vcc
	v_max3_f32 v102, v108, v125, v131
	v_subrev_u32_e32 v108, 45, v103
	v_cmp_le_i32_e32 vcc, v108, v194
	v_add_u32_e32 v113, -15, v103
	s_nop 0
	v_cndmask_b32_e32 v133, v200, v136, vcc
	v_cmp_le_i32_e32 vcc, v110, v194
	s_nop 1
	v_cndmask_b32_e32 v132, v200, v137, vcc
	v_max3_f32 v112, v102, v133, v132
	v_mov_b32_e32 v102, s81
	v_cmp_gt_i32_e32 vcc, v109, v194
	s_nop 1
	v_cndmask_b32_e32 v134, v118, v102, vcc
	v_cmp_le_i32_e32 vcc, v111, v194
	v_subrev_u32_e32 v118, 28, v103
	s_nop 0
	v_cndmask_b32_e32 v135, v200, v119, vcc
	v_max3_f32 v102, v112, v134, v135
	v_subrev_u32_e32 v112, 29, v103
	v_cmp_le_i32_e32 vcc, v112, v194
	v_add_u32_e32 v119, -14, v103
	s_nop 0
	v_cndmask_b32_e32 v137, v200, v120, vcc
	v_cmp_le_i32_e32 vcc, v118, v194
	s_nop 1
	v_cndmask_b32_e32 v136, v200, v121, vcc
	v_max3_f32 v120, v102, v137, v136
	v_mov_b32_e32 v102, s81
	v_cmp_gt_i32_e32 vcc, v113, v194
	v_add_u32_e32 v121, -12, v103
	s_nop 0
	v_cndmask_b32_e32 v138, v144, v102, vcc
	v_cmp_le_i32_e32 vcc, v119, v194
	s_nop 1
	v_cndmask_b32_e32 v139, v200, v145, vcc
	v_max3_f32 v102, v120, v138, v139
	v_add_u32_e32 v120, -13, v103
	v_cmp_le_i32_e32 vcc, v120, v194
	s_nop 1
	v_cndmask_b32_e32 v141, v200, v146, vcc
	v_cmp_le_i32_e32 vcc, v121, v194
	s_nop 1
	v_cndmask_b32_e32 v140, v200, v147, vcc
	v_max3_f32 v102, v102, v141, v140
	v_mov_b32_e32 v103, v102
	s_nop 1
	v_permlane16_swap_b32_e32 v102, v103
	v_max_f32_e32 v102, v102, v103
	v_mov_b32_e32 v103, v102
	s_nop 1
	v_permlane32_swap_b32_e32 v102, v103
	v_max_f32_e32 v102, v102, v103
	v_cmp_gt_f32_e32 vcc, v102, v1
	s_cbranch_vccz .LBB0_871
	v_max_f32_e32 v1, v102, v102
	v_max_f32_e32 v102, v220, v220
	v_max_f32_e32 v102, v102, v1
	v_cmp_neq_f32_e32 vcc, s81, v102
	v_mov_b32_e32 v103, v221
	s_nop 0
	v_cndmask_b32_e32 v1, 0, v102, vcc
	v_sub_f32_e32 v1, v220, v1
	v_mul_f32_e32 v1, 0x3e16c740, v1
	v_exp_f32_e32 v144, v1
	v_mov_b64_e32 v[220:221], v[102:103]
	v_mul_f32_e32 v218, v218, v144
	v_pk_mul_f32 v[92:93], v[92:93], v[144:145] op_sel_hi:[1,0]
	v_pk_mul_f32 v[90:91], v[90:91], v[144:145] op_sel_hi:[1,0]
	v_pk_mul_f32 v[88:89], v[88:89], v[144:145] op_sel_hi:[1,0]
	v_pk_mul_f32 v[86:87], v[86:87], v[144:145] op_sel_hi:[1,0]
	v_pk_mul_f32 v[76:77], v[76:77], v[144:145] op_sel_hi:[1,0]
	v_pk_mul_f32 v[74:75], v[74:75], v[144:145] op_sel_hi:[1,0]
	v_pk_mul_f32 v[68:69], v[68:69], v[144:145] op_sel_hi:[1,0]
	v_pk_mul_f32 v[66:67], v[66:67], v[144:145] op_sel_hi:[1,0]
	s_branch .LBB0_872

; #define LAS __attribute__((address_space(3)))
; __device__ __forceinline__ float ex2(float x) { return __builtin_amdgcn_exp2f(x); }
; __device__ __forceinline__ f32x4 mfma16(bf16x8 a, bf16x8 b, f32x4 c) { return __builtin_amdgcn_mfma_f32_16x16x32_bf16(a, b, c, 0, 0, 0); }
; template <int NT, int NKK, int NDT, int MODE, bool MASK> ...
;   const int r = lane & 15, lg = lane >> 4, vq = (lane & 15) >> 2, vp = lane & 3;
;   f32x4 s[NT][4];
;   __builtin_amdgcn_s_setprio(1);
; #pragma unroll
;   for (int t = 0; t < 4; ++t)
; #pragma unroll
;     for (int kk = 0; kk < NKK; ++kk) {
;       const bf16x8 kf = *(LAS const bf16x8*)(Kl + (16 * t + r) * KSTR + (32 * kk + 8 * lg) * 2);
; #pragma unroll
;       for (int j = 0; j < NT; ++j) s[j][t] = mfma16(kf, qf[j][kk], kk == 0 ? (f32x4){0.f, 0.f, 0.f, 0.f} : s[j][t]);
;     }
;   __builtin_amdgcn_s_setprio(0);
;   bf16x8 pf[NT][2];
; #pragma unroll
;   for (int j = 0; j < NT; ++j) {
;     float mx = -INFINITY;
; #pragma unroll
;     for (int t = 0; t < 4; ++t)
; #pragma unroll
;       for (int i = 0; i < 4; ++i) {
;         if (MASK) { const int kp = kpos0 + 16 * t + 4 * lg + i; if (!mask_ok<MODE>(tq[j], kp, W)) s[j][t][i] = -INFINITY; }
;         mx = fmaxf(mx, s[j][t][i]);
;       }
;     mx = max_x16_x32(mx);
;     if (__any(mx > m[j] + 8.0f / c)) {
;       const float mnew = fmaxf(m[j], mx);
;       const float ms2 = (mnew == -INFINITY) ? 0.f : mnew;
;       const float alpha = ex2((m[j] - ms2) * c);
;       m[j] = mnew; l[j] *= alpha;
; #pragma unroll
;       for (int dt = 0; dt < NDT; ++dt) o[j][dt] *= alpha;
;     }
; template <int NT, int DQK, int DV, int MODE, int PD, class Src> ...
;     ...
;         const int lo = kbase + 64 * kc, hi = lo + 63;
;         bool rel = true, full = true;
;         if (MODE == MODE_CAUSAL) { rel = lo <= tq_max; full = hi <= tq_min; }
;         if (MODE == MODE_WINDOW) { rel = (lo <= tq_max) && (hi > tq_min - W); full = (hi <= tq_min) && (lo > tq_max - W); }
;         if (MODE == MODE_CMP) { rel = 16 * lo + 31 <= tq_max; full = 16 * hi + 31 <= tq_min; }
;         if (rel) {
;           if (NT <= 2) {
;             if (full) attn_chunk_wide<NT, DQK / 32, DV / 16, MODE, false>(o, m, l, qf, buf, KSTR, buf + KB, VSTR, lo, tq, c, W, lane);
;             else attn_chunk_wide<NT, DQK / 32, DV / 16, MODE, true>(o, m, l, qf, buf, KSTR, buf + KB, VSTR, lo, tq, c, W, lane);
.LBB0_941:
	s_waitcnt lgkmcnt(0)
	s_barrier
	s_add_i32 s8, s43, 0xffffff41
	s_cmp_gt_i32 s8, s40
	s_cbranch_scc1 .LBB0_970
	s_add_i32 s8, s43, 0xffffff80
	s_cmp_gt_i32 s8, s25
	s_setprio 1
	v_add_u32_e32 v1, s45, v236
	s_waitcnt lgkmcnt(0)
	v_add_u32_e32 v94, v1, v237
	ds_read_b128 v[134:137], v94
	ds_read_b128 v[130:133], v94 offset:64
	ds_read_b128 v[126:129], v94 offset:128
	ds_read_b128 v[122:125], v94 offset:3328
	ds_read_b128 v[118:121], v94 offset:3392
	ds_read_b128 v[114:117], v94 offset:3456
	ds_read_b128 v[106:109], v94 offset:6656
	ds_read_b128 v[98:101], v94 offset:6720
	v_add_u32_e32 v201, v1, v238
	ds_read_b128 v[110:113], v94 offset:6784
	ds_read_b128 v[102:105], v201
	ds_read_b128 v[94:97], v201 offset:64
	s_mov_b64 s[20:21], -1
	v_add_f32_e32 v1, 0x4259535f, v220
	s_cbranch_scc1 .LBB0_961
	s_waitcnt lgkmcnt(10)
	v_mfma_f32_16x16x32_bf16 v[138:141], v[134:137], v[18:21], 0
	ds_read_b128 v[146:149], v201 offset:128
	v_mov_b32_e32 v234, 0x260
	v_mfma_f32_16x16x32_bf16 v[142:145], v[134:137], v[10:13], 0
	s_waitcnt lgkmcnt(10)
	v_mfma_f32_16x16x32_bf16 v[138:141], v[130:133], v[2:5], v[138:141]
	v_mfma_f32_16x16x32_bf16 v[142:145], v[130:133], v[14:17], v[142:145]
	s_waitcnt lgkmcnt(9)
	v_mfma_f32_16x16x32_bf16 v[182:185], v[126:129], v[6:9], v[138:141]
	v_mfma_f32_16x16x32_bf16 v[166:169], v[126:129], v[22:25], v[142:145]
	s_waitcnt lgkmcnt(8)
	v_mfma_f32_16x16x32_bf16 v[138:141], v[122:125], v[18:21], 0
	v_mfma_f32_16x16x32_bf16 v[142:145], v[122:125], v[10:13], 0
	s_waitcnt lgkmcnt(7)
	v_mfma_f32_16x16x32_bf16 v[138:141], v[118:121], v[2:5], v[138:141]
	v_mfma_f32_16x16x32_bf16 v[142:145], v[118:121], v[14:17], v[142:145]
	s_waitcnt lgkmcnt(6)
	v_mfma_f32_16x16x32_bf16 v[178:181], v[114:117], v[6:9], v[138:141]
	v_mfma_f32_16x16x32_bf16 v[154:157], v[114:117], v[22:25], v[142:145]
	s_waitcnt lgkmcnt(5)
	v_mfma_f32_16x16x32_bf16 v[138:141], v[106:109], v[18:21], 0
	v_mfma_f32_16x16x32_bf16 v[142:145], v[106:109], v[10:13], 0
	s_waitcnt lgkmcnt(4)
	v_mfma_f32_16x16x32_bf16 v[138:141], v[98:101], v[2:5], v[138:141]
	v_mfma_f32_16x16x32_bf16 v[142:145], v[98:101], v[14:17], v[142:145]
	s_waitcnt lgkmcnt(3)
	v_mfma_f32_16x16x32_bf16 v[174:177], v[110:113], v[6:9], v[138:141]
	v_mfma_f32_16x16x32_bf16 v[150:153], v[110:113], v[22:25], v[142:145]
	s_waitcnt lgkmcnt(2)
	v_mfma_f32_16x16x32_bf16 v[138:141], v[102:105], v[18:21], 0
	v_mfma_f32_16x16x32_bf16 v[142:145], v[102:105], v[10:13], 0
	s_waitcnt lgkmcnt(1)
	v_mfma_f32_16x16x32_bf16 v[138:141], v[94:97], v[2:5], v[138:141]
	v_mfma_f32_16x16x32_bf16 v[142:145], v[94:97], v[14:17], v[142:145]
	s_waitcnt lgkmcnt(0)
	v_mfma_f32_16x16x32_bf16 v[170:173], v[146:149], v[6:9], v[138:141]
	v_mfma_f32_16x16x32_bf16 v[142:145], v[146:149], v[22:25], v[142:145]
	s_setprio 0
	s_nop 2
	v_max3_f32 v138, v182, s81, v183
	v_max3_f32 v138, v138, v184, v185
	v_max3_f32 v138, v138, v178, v179
	v_max3_f32 v138, v138, v180, v181
	v_max3_f32 v138, v138, v174, v175
	v_max3_f32 v138, v138, v176, v177
	v_max3_f32 v138, v138, v170, v171
	v_max3_f32 v138, v138, v172, v173
	v_mov_b32_e32 v139, v138
	s_nop 1
	v_permlane16_swap_b32_e32 v138, v139
	v_max_f32_e32 v138, v138, v139
	v_mov_b32_e32 v139, v138
	s_nop 1
	v_permlane32_swap_b32_e32 v138, v139
	v_max_f32_e32 v186, v138, v139
	v_cmp_gt_f32_e32 vcc, v186, v1
	v_mov_b64_e32 v[222:223], v[220:221]
	v_mov_b64_e32 v[224:225], v[218:219]
	v_mov_b32_e32 v187, v220
	s_cbranch_vccz .LBB0_945
	v_max_f32_e32 v138, v186, v186
	v_max_f32_e32 v139, v220, v220
	v_max_f32_e32 v222, v139, v138
	v_cmp_neq_f32_e32 vcc, s81, v222
	v_mov_b32_e32 v223, v221
	v_mov_b32_e32 v225, v219
	v_cndmask_b32_e32 v138, 0, v222, vcc
	v_sub_f32_e32 v138, v220, v138
	v_mul_f32_e32 v138, 0x3e16c740, v138
	v_exp_f32_e32 v138, v138
	v_mov_b32_e32 v187, v222
	v_mul_f32_e32 v224, v218, v138
	v_pk_mul_f32 v[92:93], v[92:93], v[138:139] op_sel_hi:[1,0]
	v_pk_mul_f32 v[90:91], v[90:91], v[138:139] op_sel_hi:[1,0]
	v_pk_mul_f32 v[88:89], v[88:89], v[138:139] op_sel_hi:[1,0]
	v_pk_mul_f32 v[86:87], v[86:87], v[138:139] op_sel_hi:[1,0]
	v_pk_mul_f32 v[76:77], v[76:77], v[138:139] op_sel_hi:[1,0]
	v_pk_mul_f32 v[74:75], v[74:75], v[138:139] op_sel_hi:[1,0]
	v_pk_mul_f32 v[68:69], v[68:69], v[138:139] op_sel_hi:[1,0]
	v_pk_mul_f32 v[66:67], v[66:67], v[138:139] op_sel_hi:[1,0]

; __device__ __forceinline__ float ex2(float x) { return __builtin_amdgcn_exp2f(x); }
; __device__ __forceinline__ f32x4 mfma16(bf16x8 a, bf16x8 b, f32x4 c) { return __builtin_amdgcn_mfma_f32_16x16x32_bf16(a, b, c, 0, 0, 0); }
; __device__ __forceinline__ s16x4 ds_tr(LAS const unsigned char* p) { return __builtin_bit_cast(s16x4, __builtin_amdgcn_ds_read_tr16_b64_v4i16((LAS v4i16_t*)p)); }
; template <int NT, int NKK, int NDT, int MODE, bool MASK> ...
;     ...
;     const float mc = ((m[j] == -INFINITY) ? 0.f : m[j]) * c;
;     float p[4][4], ps = 0.f;
; #pragma unroll
;     for (int t = 0; t < 4; ++t)
; #pragma unroll
;       for (int i = 0; i < 4; ++i) { p[t][i] = ex2(s[j][t][i] * c - mc); ps += p[t][i]; }
;     l[j] += ps;
;     pf[j][0] = pack8(p[0], p[1]); pf[j][1] = pack8(p[2], p[3]);
;   }
;   __builtin_amdgcn_s_setprio(1);
; #pragma unroll
;   for (int st = 0; st < 2; ++st)
; #pragma unroll
;     for (int dt = 0; dt < NDT; ++dt) {
;       const s16x4 v0 = ds_tr(Vl + (32 * st + 4 * lg + vq) * VSTR + (16 * dt + 4 * vp) * 2);
;       const s16x4 v1 = ds_tr(Vl + (32 * st + 16 + 4 * lg + vq) * VSTR + (16 * dt + 4 * vp) * 2);
;       const bf16x8 vf = (bf16x8){v0[0], v0[1], v0[2], v0[3], v1[0], v1[1], v1[2], v1[3]};
; #pragma unroll
;       for (int j = 0; j < NT; ++j) o[j][dt] = mfma16(vf, pf[j][st], o[j][dt]);
;     }
;   __builtin_amdgcn_s_setprio(0);
.LBB0_960:
	v_cvt_pk_bf16_f32 v173, v196, v173
	v_mul_f32_e32 v196, 0x3e16c740, v197
	v_cmp_neq_f32_e32 vcc, s81, v197
	v_cvt_pk_bf16_f32 v172, v232, v228
	v_cvt_pk_bf16_f32 v228, v205, v207
	v_cndmask_b32_e32 v196, 0, v196, vcc
	v_fma_f32 v166, v166, s88, -v196
	v_exp_f32_e32 v166, v166
	v_fma_f32 v167, v167, s88, -v196
	v_exp_f32_e32 v167, v167
	v_fma_f32 v168, v168, s88, -v196
	v_exp_f32_e32 v168, v168
	v_fma_f32 v169, v169, s88, -v196
	v_exp_f32_e32 v169, v169
	v_fma_f32 v154, v154, s88, -v196
	v_add_f32_e32 v197, 0, v166
	v_exp_f32_e32 v154, v154
	v_fma_f32 v155, v155, s88, -v196
	v_add_f32_e32 v197, v167, v197
	v_exp_f32_e32 v155, v155
	v_fma_f32 v156, v156, s88, -v196
	v_add_f32_e32 v197, v168, v197
	v_exp_f32_e32 v156, v156
	v_fma_f32 v157, v157, s88, -v196
	v_add_f32_e32 v197, v169, v197
	v_exp_f32_e32 v157, v157
	v_fma_f32 v150, v150, s88, -v196
	v_add_f32_e32 v197, v154, v197
	v_exp_f32_e32 v150, v150
	v_fma_f32 v151, v151, s88, -v196
	v_add_f32_e32 v197, v155, v197
	v_exp_f32_e32 v151, v151
	v_fma_f32 v152, v152, s88, -v196
	v_add_f32_e32 v197, v156, v197
	v_exp_f32_e32 v152, v152
	v_fma_f32 v153, v153, s88, -v196
	v_add_f32_e32 v197, v157, v197
	v_exp_f32_e32 v153, v153
	v_fma_f32 v142, v142, s88, -v196
	v_add_f32_e32 v197, v150, v197
	v_exp_f32_e32 v198, v142
	v_fma_f32 v142, v143, s88, -v196
	v_add_f32_e32 v197, v151, v197
	v_exp_f32_e32 v199, v142
	v_fma_f32 v142, v144, s88, -v196
	v_add_f32_e32 v197, v152, v197
	v_exp_f32_e32 v205, v142
	v_fma_f32 v142, v145, s88, -v196
	v_add_f32_e32 v197, v153, v197
	v_exp_f32_e32 v196, v142
	v_add_f32_e32 v142, v198, v197
	v_add_f32_e32 v142, v199, v142
	v_add_f32_e32 v142, v205, v142
	v_add_f32_e32 v142, v196, v142
	v_add_f32_e32 v225, v225, v142
	v_cvt_pk_bf16_f32 v142, v166, v167
	v_cvt_pk_bf16_f32 v143, v168, v169
	v_cvt_pk_bf16_f32 v144, v154, v155
	v_cvt_pk_bf16_f32 v145, v156, v157
	v_cvt_pk_bf16_f32 v170, v252, v231
	v_cvt_pk_bf16_f32 v171, v229, v230
	v_cvt_pk_bf16_f32 v229, v246, v247
	v_cvt_pk_bf16_f32 v230, v248, v249
	v_cvt_pk_bf16_f32 v231, v250, v251
	v_cvt_pk_bf16_f32 v246, v150, v151
	v_cvt_pk_bf16_f32 v247, v152, v153
	v_cvt_pk_bf16_f32 v248, v198, v199
	v_cvt_pk_bf16_f32 v249, v205, v196
	s_setprio 1
	v_add3_u32 v196, s45, v240, v239
	ds_read_b64_tr_b16 v[152:153], v196 offset:15872
	ds_read_b64_tr_b16 v[150:151], v196 offset:13312
	ds_read_b64_tr_b16 v[154:155], v196 offset:13344
	ds_read_b64_tr_b16 v[156:157], v196 offset:15904
	ds_read_b64_tr_b16 v[166:167], v196 offset:13376
	ds_read_b64_tr_b16 v[168:169], v196 offset:15936
	s_mov_b64 s[20:21], 0
	s_waitcnt lgkmcnt(4)
	v_mfma_f32_16x16x32_bf16 v[158:161], v[150:153], v[228:231], v[90:93]
	v_mfma_f32_16x16x32_bf16 v[150:153], v[150:153], v[142:145], v[82:85]
	s_waitcnt lgkmcnt(0)
	v_mfma_f32_16x16x32_bf16 v[182:185], v[166:169], v[228:231], v[74:77]
	s_nop 2
	ds_read_b64_tr_b16 v[146:147], v196 offset:13408
	ds_read_b64_tr_b16 v[148:149], v196 offset:15968
	v_mfma_f32_16x16x32_bf16 v[162:165], v[154:157], v[228:231], v[86:89]
	v_mfma_f32_16x16x32_bf16 v[154:157], v[154:157], v[142:145], v[78:81]
	v_mfma_f32_16x16x32_bf16 v[166:169], v[166:169], v[142:145], v[70:73]
	s_waitcnt lgkmcnt(0)
	v_mfma_f32_16x16x32_bf16 v[174:177], v[146:149], v[142:145], v[62:65]
	ds_read_b64_tr_b16 v[142:143], v196 offset:18432
	ds_read_b64_tr_b16 v[144:145], v196 offset:20992
	v_mfma_f32_16x16x32_bf16 v[178:181], v[146:149], v[228:231], v[66:69]
	s_waitcnt lgkmcnt(0)
	v_mfma_f32_16x16x32_bf16 v[90:93], v[142:145], v[170:173], v[158:161]
	v_mfma_f32_16x16x32_bf16 v[82:85], v[142:145], v[246:249], v[150:153]
	s_nop 2
	ds_read_b64_tr_b16 v[150:151], v196 offset:18464
	ds_read_b64_tr_b16 v[152:153], v196 offset:21024
	ds_read_b64_tr_b16 v[158:159], v196 offset:18496
	ds_read_b64_tr_b16 v[160:161], v196 offset:21056
	s_waitcnt lgkmcnt(2)
	v_mfma_f32_16x16x32_bf16 v[86:89], v[150:153], v[170:173], v[162:165]
	s_nop 2
	ds_read_b64_tr_b16 v[162:163], v196 offset:18528
	ds_read_b64_tr_b16 v[164:165], v196 offset:21088
	v_mfma_f32_16x16x32_bf16 v[78:81], v[150:153], v[246:249], v[154:157]
	s_waitcnt lgkmcnt(2)
	v_mfma_f32_16x16x32_bf16 v[74:77], v[158:161], v[170:173], v[182:185]
	v_mfma_f32_16x16x32_bf16 v[70:73], v[158:161], v[246:249], v[166:169]
	s_waitcnt lgkmcnt(0)
	v_mfma_f32_16x16x32_bf16 v[66:69], v[162:165], v[170:173], v[178:181]
	v_mfma_f32_16x16x32_bf16 v[62:65], v[162:165], v[246:249], v[174:177]
	s_setprio 0
	s_branch .Lmla_post_3
; #define LAS __attribute__((address_space(3)))
; __device__ __forceinline__ float ex2(float x) { return __builtin_amdgcn_exp2f(x); }
; __device__ __forceinline__ f32x4 mfma16(bf16x8 a, bf16x8 b, f32x4 c) { return __builtin_amdgcn_mfma_f32_16x16x32_bf16(a, b, c, 0, 0, 0); }
;   __device__ __forceinline__ bf16_t* W() const { return (bf16_t*)(ws + WS_W); }
; template <int NT, int NKK, int NDT, int MODE, bool MASK> ...
;   const int r = lane & 15, lg = lane >> 4, vq = (lane & 15) >> 2, vp = lane & 3;
;   f32x4 s[NT][4];
;   __builtin_amdgcn_s_setprio(1);
; #pragma unroll
;   for (int t = 0; t < 4; ++t)
; #pragma unroll
;     for (int kk = 0; kk < NKK; ++kk) {
;       const bf16x8 kf = *(LAS const bf16x8*)(Kl + (16 * t + r) * KSTR + (32 * kk + 8 * lg) * 2);
; #pragma unroll
;       for (int j = 0; j < NT; ++j) s[j][t] = mfma16(kf, qf[j][kk], kk == 0 ? (f32x4){0.f, 0.f, 0.f, 0.f} : s[j][t]);
;     }
;   __builtin_amdgcn_s_setprio(0);
;   bf16x8 pf[NT][2];
; #pragma unroll
;   for (int j = 0; j < NT; ++j) {
;     float mx = -INFINITY;
; #pragma unroll
;     for (int t = 0; t < 4; ++t)
; #pragma unroll
;       for (int i = 0; i < 4; ++i) {
;         if (MASK) { const int kp = kpos0 + 16 * t + 4 * lg + i; if (!mask_ok<MODE>(tq[j], kp, W)) s[j][t][i] = -INFINITY; }
;         mx = fmaxf(mx, s[j][t][i]);
;       }
;     mx = max_x16_x32(mx);
;     if (__any(mx > m[j] + 8.0f / c)) {
;       const float mnew = fmaxf(m[j], mx);
;       const float ms2 = (mnew == -INFINITY) ? 0.f : mnew;
;       const float alpha = ex2((m[j] - ms2) * c);
;       m[j] = mnew; l[j] *= alpha;
; #pragma unroll
;       for (int dt = 0; dt < NDT; ++dt) o[j][dt] *= alpha;
;     }
.LBB0_961:
	s_and_b64 vcc, exec, s[20:21]
	s_cbranch_vccz .LBB0_969
	s_waitcnt lgkmcnt(10)
	v_mfma_f32_16x16x32_bf16 v[138:141], v[134:137], v[18:21], 0
	v_mfma_f32_16x16x32_bf16 v[134:137], v[134:137], v[10:13], 0
	s_waitcnt lgkmcnt(9)
	v_mfma_f32_16x16x32_bf16 v[138:141], v[130:133], v[2:5], v[138:141]
	v_mfma_f32_16x16x32_bf16 v[134:137], v[130:133], v[14:17], v[134:137]
	s_waitcnt lgkmcnt(8)
	v_mfma_f32_16x16x32_bf16 v[130:133], v[126:129], v[6:9], v[138:141]
	v_mfma_f32_16x16x32_bf16 v[126:129], v[126:129], v[22:25], v[134:137]
	s_waitcnt lgkmcnt(7)
	v_mfma_f32_16x16x32_bf16 v[134:137], v[122:125], v[18:21], 0
	v_mfma_f32_16x16x32_bf16 v[122:125], v[122:125], v[10:13], 0
	s_waitcnt lgkmcnt(6)
	v_mfma_f32_16x16x32_bf16 v[134:137], v[118:121], v[2:5], v[134:137]
	v_mfma_f32_16x16x32_bf16 v[118:121], v[118:121], v[14:17], v[122:125]
	s_waitcnt lgkmcnt(5)
	v_mfma_f32_16x16x32_bf16 v[134:137], v[114:117], v[6:9], v[134:137]
	v_mfma_f32_16x16x32_bf16 v[114:117], v[114:117], v[22:25], v[118:121]
	s_waitcnt lgkmcnt(4)
	v_mfma_f32_16x16x32_bf16 v[118:121], v[106:109], v[18:21], 0
	v_mfma_f32_16x16x32_bf16 v[106:109], v[106:109], v[10:13], 0
	s_waitcnt lgkmcnt(3)
	v_mfma_f32_16x16x32_bf16 v[118:121], v[98:101], v[2:5], v[118:121]
	v_mfma_f32_16x16x32_bf16 v[98:101], v[98:101], v[14:17], v[106:109]
	s_waitcnt lgkmcnt(1)
	v_mfma_f32_16x16x32_bf16 v[106:109], v[102:105], v[18:21], 0
	v_mfma_f32_16x16x32_bf16 v[102:105], v[102:105], v[10:13], 0
	s_waitcnt lgkmcnt(0)
	v_mfma_f32_16x16x32_bf16 v[106:109], v[94:97], v[2:5], v[106:109]
	v_mfma_f32_16x16x32_bf16 v[94:97], v[94:97], v[14:17], v[102:105]
	s_nop 4
	ds_read_b128 v[102:105], v201 offset:128
	v_mfma_f32_16x16x32_bf16 v[118:121], v[110:113], v[6:9], v[118:121]
	v_mfma_f32_16x16x32_bf16 v[98:101], v[110:113], v[22:25], v[98:101]
	s_waitcnt lgkmcnt(0)
	v_mfma_f32_16x16x32_bf16 v[94:97], v[102:105], v[22:25], v[94:97]
	v_mfma_f32_16x16x32_bf16 v[144:147], v[102:105], v[6:9], v[106:109]
	s_setprio 0
	v_add_u32_e32 v103, s43, v241
	v_add_u32_e32 v104, 0xffffff41, v103
	v_add_u32_e32 v105, 0xffffff43, v103
	v_mov_b32_e32 v102, s81
	v_cmp_gt_i32_e64 s[20:21], v104, v194
	v_cmp_lt_i32_e64 s[22:23], v104, v194
	v_cmp_le_i32_e32 vcc, v105, v194
	v_add_u32_e32 v106, 0xffffff44, v103
	v_cndmask_b32_e64 v142, v130, v102, s[20:21]
	v_cndmask_b32_e64 v122, v200, v131, s[22:23]
	v_cndmask_b32_e32 v124, v200, v132, vcc
	v_cmp_le_i32_e32 vcc, v106, v194
	v_max3_f32 v102, v142, s81, v122
	v_add_u32_e32 v107, 0xffffff51, v103
	v_cndmask_b32_e32 v123, v200, v133, vcc
	v_max3_f32 v108, v102, v124, v123
	v_mov_b32_e32 v102, s81
	v_cmp_gt_i32_e32 vcc, v107, v194
	v_add_u32_e32 v107, 0xffffff52, v103
	v_add_u32_e32 v110, 0xffffff54, v103
	v_cndmask_b32_e32 v125, v134, v102, vcc
	v_cmp_le_i32_e32 vcc, v107, v194
	v_add_u32_e32 v109, 0xffffff61, v103
	v_add_u32_e32 v111, 0xffffff62, v103
	v_cndmask_b32_e32 v131, v200, v135, vcc
	v_max3_f32 v102, v108, v125, v131
	v_add_u32_e32 v108, 0xffffff53, v103
	v_cmp_le_i32_e32 vcc, v108, v194
	v_add_u32_e32 v113, 0xffffff71, v103
	s_nop 0
	v_cndmask_b32_e32 v133, v200, v136, vcc
	v_cmp_le_i32_e32 vcc, v110, v194
	s_nop 1
	v_cndmask_b32_e32 v132, v200, v137, vcc
	v_max3_f32 v112, v102, v133, v132
	v_mov_b32_e32 v102, s81
	v_cmp_gt_i32_e32 vcc, v109, v194
	s_nop 1
	v_cndmask_b32_e32 v134, v118, v102, vcc
	v_cmp_le_i32_e32 vcc, v111, v194
	v_add_u32_e32 v118, 0xffffff64, v103
	s_nop 0
	v_cndmask_b32_e32 v135, v200, v119, vcc
	v_max3_f32 v102, v112, v134, v135
	v_add_u32_e32 v112, 0xffffff63, v103
	v_cmp_le_i32_e32 vcc, v112, v194
	v_add_u32_e32 v119, 0xffffff72, v103
	s_nop 0
	v_cndmask_b32_e32 v137, v200, v120, vcc
	v_cmp_le_i32_e32 vcc, v118, v194
	s_nop 1
	v_cndmask_b32_e32 v136, v200, v121, vcc
	v_max3_f32 v120, v102, v137, v136
	v_mov_b32_e32 v102, s81
	v_cmp_gt_i32_e32 vcc, v113, v194
	v_add_u32_e32 v121, 0xffffff74, v103
	s_nop 0
	v_cndmask_b32_e32 v138, v144, v102, vcc
	v_cmp_le_i32_e32 vcc, v119, v194
	s_nop 1
	v_cndmask_b32_e32 v139, v200, v145, vcc
	v_max3_f32 v102, v120, v138, v139
	v_add_u32_e32 v120, 0xffffff73, v103
	v_cmp_le_i32_e32 vcc, v120, v194
	s_nop 1
	v_cndmask_b32_e32 v141, v200, v146, vcc
	v_cmp_le_i32_e32 vcc, v121, v194
	s_nop 1
	v_cndmask_b32_e32 v140, v200, v147, vcc
	v_max3_f32 v102, v102, v141, v140
	v_mov_b32_e32 v103, v102
	s_nop 1
	v_permlane16_swap_b32_e32 v102, v103
	v_max_f32_e32 v102, v102, v103
	v_mov_b32_e32 v103, v102
	s_nop 1
	v_permlane32_swap_b32_e32 v102, v103
	v_max_f32_e32 v102, v102, v103
	v_cmp_gt_f32_e32 vcc, v102, v1
	s_cbranch_vccz .LBB0_964
	v_max_f32_e32 v1, v102, v102
	v_max_f32_e32 v102, v220, v220
	v_max_f32_e32 v102, v102, v1
	v_cmp_neq_f32_e32 vcc, s81, v102
	v_mov_b32_e32 v103, v221
	s_nop 0
	v_cndmask_b32_e32 v1, 0, v102, vcc
	v_sub_f32_e32 v1, v220, v1
	v_mul_f32_e32 v1, 0x3e16c740, v1
	v_exp_f32_e32 v144, v1
	v_mov_b64_e32 v[220:221], v[102:103]
	v_mul_f32_e32 v218, v218, v144
	v_pk_mul_f32 v[92:93], v[92:93], v[144:145] op_sel_hi:[1,0]
	v_pk_mul_f32 v[90:91], v[90:91], v[144:145] op_sel_hi:[1,0]
	v_pk_mul_f32 v[88:89], v[88:89], v[144:145] op_sel_hi:[1,0]
	v_pk_mul_f32 v[86:87], v[86:87], v[144:145] op_sel_hi:[1,0]
	v_pk_mul_f32 v[76:77], v[76:77], v[144:145] op_sel_hi:[1,0]
	v_pk_mul_f32 v[74:75], v[74:75], v[144:145] op_sel_hi:[1,0]
	v_pk_mul_f32 v[68:69], v[68:69], v[144:145] op_sel_hi:[1,0]
	v_pk_mul_f32 v[66:67], v[66:67], v[144:145] op_sel_hi:[1,0]
	s_branch .LBB0_965

; #define LAS __attribute__((address_space(3)))
; __device__ __forceinline__ float ex2(float x) { return __builtin_amdgcn_exp2f(x); }
; __device__ __forceinline__ f32x4 mfma16(bf16x8 a, bf16x8 b, f32x4 c) { return __builtin_amdgcn_mfma_f32_16x16x32_bf16(a, b, c, 0, 0, 0); }
; template <int NT, int NKK, int NDT, int MODE, bool MASK> ...
;   const int r = lane & 15, lg = lane >> 4, vq = (lane & 15) >> 2, vp = lane & 3;
;   f32x4 s[NT][4];
;   __builtin_amdgcn_s_setprio(1);
; #pragma unroll
;   for (int t = 0; t < 4; ++t)
; #pragma unroll
;     for (int kk = 0; kk < NKK; ++kk) {
;       const bf16x8 kf = *(LAS const bf16x8*)(Kl + (16 * t + r) * KSTR + (32 * kk + 8 * lg) * 2);
; #pragma unroll
;       for (int j = 0; j < NT; ++j) s[j][t] = mfma16(kf, qf[j][kk], kk == 0 ? (f32x4){0.f, 0.f, 0.f, 0.f} : s[j][t]);
;     }
;   __builtin_amdgcn_s_setprio(0);
;   bf16x8 pf[NT][2];
; #pragma unroll
;   for (int j = 0; j < NT; ++j) {
;     float mx = -INFINITY;
; #pragma unroll
;     for (int t = 0; t < 4; ++t)
; #pragma unroll
;       for (int i = 0; i < 4; ++i) {
;         if (MASK) { const int kp = kpos0 + 16 * t + 4 * lg + i; if (!mask_ok<MODE>(tq[j], kp, W)) s[j][t][i] = -INFINITY; }
;         mx = fmaxf(mx, s[j][t][i]);
;       }
;     mx = max_x16_x32(mx);
;     if (__any(mx > m[j] + 8.0f / c)) {
;       const float mnew = fmaxf(m[j], mx);
;       const float ms2 = (mnew == -INFINITY) ? 0.f : mnew;
;       const float alpha = ex2((m[j] - ms2) * c);
;       m[j] = mnew; l[j] *= alpha;
; #pragma unroll
;       for (int dt = 0; dt < NDT; ++dt) o[j][dt] *= alpha;
;     }
; template <int NT, int DQK, int DV, int MODE, int PD, class Src> ...
;     ...
;         const int lo = kbase + 64 * kc, hi = lo + 63;
;         bool rel = true, full = true;
;         if (MODE == MODE_CAUSAL) { rel = lo <= tq_max; full = hi <= tq_min; }
;         if (MODE == MODE_WINDOW) { rel = (lo <= tq_max) && (hi > tq_min - W); full = (hi <= tq_min) && (lo > tq_max - W); }
;         if (MODE == MODE_CMP) { rel = 16 * lo + 31 <= tq_max; full = 16 * hi + 31 <= tq_min; }
;         if (rel) {
;           if (NT <= 2) {
;             if (full) attn_chunk_wide<NT, DQK / 32, DV / 16, MODE, false>(o, m, l, qf, buf, KSTR, buf + KB, VSTR, lo, tq, c, W, lane);
;             else attn_chunk_wide<NT, DQK / 32, DV / 16, MODE, true>(o, m, l, qf, buf, KSTR, buf + KB, VSTR, lo, tq, c, W, lane);
.LBB0_983:
	s_waitcnt lgkmcnt(0)
	s_barrier
	s_add_i32 s8, s43, 0xffffff81
	s_cmp_gt_i32 s8, s40
	s_cbranch_scc1 .LBB0_1010
	s_sub_i32 s8, s43, 64
	s_cmp_gt_i32 s8, s25
	s_setprio 1
	v_add_u32_e32 v1, s59, v236
	s_waitcnt lgkmcnt(0)
	v_add_u32_e32 v94, v1, v237
	ds_read_b128 v[134:137], v94
	ds_read_b128 v[130:133], v94 offset:64
	ds_read_b128 v[126:129], v94 offset:128
	ds_read_b128 v[122:125], v94 offset:3328
	ds_read_b128 v[118:121], v94 offset:3392
	ds_read_b128 v[114:117], v94 offset:3456
	ds_read_b128 v[106:109], v94 offset:6656
	ds_read_b128 v[98:101], v94 offset:6720
	v_add_u32_e32 v201, v1, v238
	ds_read_b128 v[110:113], v94 offset:6784
	ds_read_b128 v[102:105], v201
	ds_read_b128 v[94:97], v201 offset:64
	s_mov_b64 s[20:21], -1
	v_add_f32_e32 v1, 0x4259535f, v220
	s_cbranch_scc1 .LBB0_1001
	s_waitcnt lgkmcnt(10)
	v_mfma_f32_16x16x32_bf16 v[138:141], v[134:137], v[18:21], 0
	ds_read_b128 v[146:149], v201 offset:128
	v_mov_b32_e32 v234, 0x260
	v_mfma_f32_16x16x32_bf16 v[142:145], v[134:137], v[10:13], 0
	s_waitcnt lgkmcnt(10)
	v_mfma_f32_16x16x32_bf16 v[138:141], v[130:133], v[2:5], v[138:141]
	v_mfma_f32_16x16x32_bf16 v[142:145], v[130:133], v[14:17], v[142:145]
	s_waitcnt lgkmcnt(9)
	v_mfma_f32_16x16x32_bf16 v[182:185], v[126:129], v[6:9], v[138:141]
	v_mfma_f32_16x16x32_bf16 v[166:169], v[126:129], v[22:25], v[142:145]
	s_waitcnt lgkmcnt(8)
	v_mfma_f32_16x16x32_bf16 v[138:141], v[122:125], v[18:21], 0
	v_mfma_f32_16x16x32_bf16 v[142:145], v[122:125], v[10:13], 0
	s_waitcnt lgkmcnt(7)
	v_mfma_f32_16x16x32_bf16 v[138:141], v[118:121], v[2:5], v[138:141]
	v_mfma_f32_16x16x32_bf16 v[142:145], v[118:121], v[14:17], v[142:145]
	s_waitcnt lgkmcnt(6)
	v_mfma_f32_16x16x32_bf16 v[178:181], v[114:117], v[6:9], v[138:141]
	v_mfma_f32_16x16x32_bf16 v[154:157], v[114:117], v[22:25], v[142:145]
	s_waitcnt lgkmcnt(5)
	v_mfma_f32_16x16x32_bf16 v[138:141], v[106:109], v[18:21], 0
	v_mfma_f32_16x16x32_bf16 v[142:145], v[106:109], v[10:13], 0
	s_waitcnt lgkmcnt(4)
	v_mfma_f32_16x16x32_bf16 v[138:141], v[98:101], v[2:5], v[138:141]
	v_mfma_f32_16x16x32_bf16 v[142:145], v[98:101], v[14:17], v[142:145]
	s_waitcnt lgkmcnt(3)
	v_mfma_f32_16x16x32_bf16 v[174:177], v[110:113], v[6:9], v[138:141]
	v_mfma_f32_16x16x32_bf16 v[150:153], v[110:113], v[22:25], v[142:145]
	s_waitcnt lgkmcnt(2)
	v_mfma_f32_16x16x32_bf16 v[138:141], v[102:105], v[18:21], 0
	v_mfma_f32_16x16x32_bf16 v[142:145], v[102:105], v[10:13], 0
	s_waitcnt lgkmcnt(1)
	v_mfma_f32_16x16x32_bf16 v[138:141], v[94:97], v[2:5], v[138:141]
	v_mfma_f32_16x16x32_bf16 v[142:145], v[94:97], v[14:17], v[142:145]
	s_waitcnt lgkmcnt(0)
	v_mfma_f32_16x16x32_bf16 v[170:173], v[146:149], v[6:9], v[138:141]
	v_mfma_f32_16x16x32_bf16 v[142:145], v[146:149], v[22:25], v[142:145]
	s_setprio 0
	s_nop 2
	v_max3_f32 v138, v182, s81, v183
	v_max3_f32 v138, v138, v184, v185
	v_max3_f32 v138, v138, v178, v179
	v_max3_f32 v138, v138, v180, v181
	v_max3_f32 v138, v138, v174, v175
	v_max3_f32 v138, v138, v176, v177
	v_max3_f32 v138, v138, v170, v171
	v_max3_f32 v138, v138, v172, v173
	v_mov_b32_e32 v139, v138
	s_nop 1
	v_permlane16_swap_b32_e32 v138, v139
	v_max_f32_e32 v138, v138, v139
	v_mov_b32_e32 v139, v138
	s_nop 1
	v_permlane32_swap_b32_e32 v138, v139
	v_max_f32_e32 v186, v138, v139
	v_cmp_gt_f32_e32 vcc, v186, v1
	v_mov_b64_e32 v[222:223], v[220:221]
	v_mov_b64_e32 v[224:225], v[218:219]
	v_mov_b32_e32 v187, v220
	s_cbranch_vccz .LBB0_987
	v_max_f32_e32 v138, v186, v186
	v_max_f32_e32 v139, v220, v220
	v_max_f32_e32 v222, v139, v138
	v_cmp_neq_f32_e32 vcc, s81, v222
	v_mov_b32_e32 v223, v221
	v_mov_b32_e32 v225, v219
	v_cndmask_b32_e32 v138, 0, v222, vcc
	v_sub_f32_e32 v138, v220, v138
	v_mul_f32_e32 v138, 0x3e16c740, v138
	v_exp_f32_e32 v138, v138
	v_mov_b32_e32 v187, v222
	v_mul_f32_e32 v224, v218, v138
	v_pk_mul_f32 v[92:93], v[92:93], v[138:139] op_sel_hi:[1,0]
	v_pk_mul_f32 v[90:91], v[90:91], v[138:139] op_sel_hi:[1,0]
	v_pk_mul_f32 v[88:89], v[88:89], v[138:139] op_sel_hi:[1,0]
	v_pk_mul_f32 v[86:87], v[86:87], v[138:139] op_sel_hi:[1,0]
	v_pk_mul_f32 v[76:77], v[76:77], v[138:139] op_sel_hi:[1,0]
	v_pk_mul_f32 v[74:75], v[74:75], v[138:139] op_sel_hi:[1,0]
	v_pk_mul_f32 v[68:69], v[68:69], v[138:139] op_sel_hi:[1,0]
	v_pk_mul_f32 v[66:67], v[66:67], v[138:139] op_sel_hi:[1,0]

; __device__ __forceinline__ float ex2(float x) { return __builtin_amdgcn_exp2f(x); }
; __device__ __forceinline__ f32x4 mfma16(bf16x8 a, bf16x8 b, f32x4 c) { return __builtin_amdgcn_mfma_f32_16x16x32_bf16(a, b, c, 0, 0, 0); }
; __device__ __forceinline__ s16x4 ds_tr(LAS const unsigned char* p) { return __builtin_bit_cast(s16x4, __builtin_amdgcn_ds_read_tr16_b64_v4i16((LAS v4i16_t*)p)); }
; template <int NT, int NKK, int NDT, int MODE, bool MASK> ...
;     ...
;     const float mc = ((m[j] == -INFINITY) ? 0.f : m[j]) * c;
;     float p[4][4], ps = 0.f;
; #pragma unroll
;     for (int t = 0; t < 4; ++t)
; #pragma unroll
;       for (int i = 0; i < 4; ++i) { p[t][i] = ex2(s[j][t][i] * c - mc); ps += p[t][i]; }
;     l[j] += ps;
;     pf[j][0] = pack8(p[0], p[1]); pf[j][1] = pack8(p[2], p[3]);
;   }
;   __builtin_amdgcn_s_setprio(1);
; #pragma unroll
;   for (int st = 0; st < 2; ++st)
; #pragma unroll
;     for (int dt = 0; dt < NDT; ++dt) {
;       const s16x4 v0 = ds_tr(Vl + (32 * st + 4 * lg + vq) * VSTR + (16 * dt + 4 * vp) * 2);
;       const s16x4 v1 = ds_tr(Vl + (32 * st + 16 + 4 * lg + vq) * VSTR + (16 * dt + 4 * vp) * 2);
;       const bf16x8 vf = (bf16x8){v0[0], v0[1], v0[2], v0[3], v1[0], v1[1], v1[2], v1[3]};
; #pragma unroll
;       for (int j = 0; j < NT; ++j) o[j][dt] = mfma16(vf, pf[j][st], o[j][dt]);
;     }
;   __builtin_amdgcn_s_setprio(0);
.LBB0_1000:
	v_cvt_pk_bf16_f32 v173, v196, v173
	v_mul_f32_e32 v196, 0x3e16c740, v197
	v_cmp_neq_f32_e32 vcc, s81, v197
	v_cvt_pk_bf16_f32 v172, v232, v228
	v_cvt_pk_bf16_f32 v228, v205, v207
	v_cndmask_b32_e32 v196, 0, v196, vcc
	v_fma_f32 v166, v166, s88, -v196
	v_exp_f32_e32 v166, v166
	v_fma_f32 v167, v167, s88, -v196
	v_exp_f32_e32 v167, v167
	v_fma_f32 v168, v168, s88, -v196
	v_exp_f32_e32 v168, v168
	v_fma_f32 v169, v169, s88, -v196
	v_exp_f32_e32 v169, v169
	v_fma_f32 v154, v154, s88, -v196
	v_add_f32_e32 v197, 0, v166
	v_exp_f32_e32 v154, v154
	v_fma_f32 v155, v155, s88, -v196
	v_add_f32_e32 v197, v167, v197
	v_exp_f32_e32 v155, v155
	v_fma_f32 v156, v156, s88, -v196
	v_add_f32_e32 v197, v168, v197
	v_exp_f32_e32 v156, v156
	v_fma_f32 v157, v157, s88, -v196
	v_add_f32_e32 v197, v169, v197
	v_exp_f32_e32 v157, v157
	v_fma_f32 v150, v150, s88, -v196
	v_add_f32_e32 v197, v154, v197
	v_exp_f32_e32 v150, v150
	v_fma_f32 v151, v151, s88, -v196
	v_add_f32_e32 v197, v155, v197
	v_exp_f32_e32 v151, v151
	v_fma_f32 v152, v152, s88, -v196
	v_add_f32_e32 v197, v156, v197
	v_exp_f32_e32 v152, v152
	v_fma_f32 v153, v153, s88, -v196
	v_add_f32_e32 v197, v157, v197
	v_exp_f32_e32 v153, v153
	v_fma_f32 v142, v142, s88, -v196
	v_add_f32_e32 v197, v150, v197
	v_exp_f32_e32 v198, v142
	v_fma_f32 v142, v143, s88, -v196
	v_add_f32_e32 v197, v151, v197
	v_exp_f32_e32 v199, v142
	v_fma_f32 v142, v144, s88, -v196
	v_add_f32_e32 v197, v152, v197
	v_exp_f32_e32 v205, v142
	v_fma_f32 v142, v145, s88, -v196
	v_add_f32_e32 v197, v153, v197
	v_exp_f32_e32 v196, v142
	v_add_f32_e32 v142, v198, v197
	v_add_f32_e32 v142, v199, v142
	v_add_f32_e32 v142, v205, v142
	v_add_f32_e32 v142, v196, v142
	v_add_f32_e32 v225, v225, v142
	v_cvt_pk_bf16_f32 v142, v166, v167
	v_cvt_pk_bf16_f32 v143, v168, v169
	v_cvt_pk_bf16_f32 v144, v154, v155
	v_cvt_pk_bf16_f32 v145, v156, v157
	v_cvt_pk_bf16_f32 v170, v252, v231
	v_cvt_pk_bf16_f32 v171, v229, v230
	v_cvt_pk_bf16_f32 v229, v246, v247
	v_cvt_pk_bf16_f32 v230, v248, v249
	v_cvt_pk_bf16_f32 v231, v250, v251
	v_cvt_pk_bf16_f32 v246, v150, v151
	v_cvt_pk_bf16_f32 v247, v152, v153
	v_cvt_pk_bf16_f32 v248, v198, v199
	v_cvt_pk_bf16_f32 v249, v205, v196
	s_setprio 1
	v_add3_u32 v196, s59, v240, v239
	ds_read_b64_tr_b16 v[152:153], v196 offset:15872
	ds_read_b64_tr_b16 v[150:151], v196 offset:13312
	ds_read_b64_tr_b16 v[154:155], v196 offset:13344
	ds_read_b64_tr_b16 v[156:157], v196 offset:15904
	ds_read_b64_tr_b16 v[166:167], v196 offset:13376
	ds_read_b64_tr_b16 v[168:169], v196 offset:15936
	s_mov_b64 s[20:21], 0
	s_waitcnt lgkmcnt(4)
	v_mfma_f32_16x16x32_bf16 v[158:161], v[150:153], v[228:231], v[90:93]
	v_mfma_f32_16x16x32_bf16 v[150:153], v[150:153], v[142:145], v[82:85]
	s_waitcnt lgkmcnt(0)
	v_mfma_f32_16x16x32_bf16 v[182:185], v[166:169], v[228:231], v[74:77]
	s_nop 2
	ds_read_b64_tr_b16 v[146:147], v196 offset:13408
	ds_read_b64_tr_b16 v[148:149], v196 offset:15968
	v_mfma_f32_16x16x32_bf16 v[162:165], v[154:157], v[228:231], v[86:89]
	v_mfma_f32_16x16x32_bf16 v[154:157], v[154:157], v[142:145], v[78:81]
	v_mfma_f32_16x16x32_bf16 v[166:169], v[166:169], v[142:145], v[70:73]
	s_waitcnt lgkmcnt(0)
	v_mfma_f32_16x16x32_bf16 v[174:177], v[146:149], v[142:145], v[62:65]
	ds_read_b64_tr_b16 v[142:143], v196 offset:18432
	ds_read_b64_tr_b16 v[144:145], v196 offset:20992
	v_mfma_f32_16x16x32_bf16 v[178:181], v[146:149], v[228:231], v[66:69]
	s_waitcnt lgkmcnt(0)
	v_mfma_f32_16x16x32_bf16 v[90:93], v[142:145], v[170:173], v[158:161]
	v_mfma_f32_16x16x32_bf16 v[82:85], v[142:145], v[246:249], v[150:153]
	s_nop 2
	ds_read_b64_tr_b16 v[150:151], v196 offset:18464
	ds_read_b64_tr_b16 v[152:153], v196 offset:21024
	ds_read_b64_tr_b16 v[158:159], v196 offset:18496
	ds_read_b64_tr_b16 v[160:161], v196 offset:21056
	s_waitcnt lgkmcnt(2)
	v_mfma_f32_16x16x32_bf16 v[86:89], v[150:153], v[170:173], v[162:165]
	s_nop 2
	ds_read_b64_tr_b16 v[162:163], v196 offset:18528
	ds_read_b64_tr_b16 v[164:165], v196 offset:21088
	v_mfma_f32_16x16x32_bf16 v[78:81], v[150:153], v[246:249], v[154:157]
	s_waitcnt lgkmcnt(2)
	v_mfma_f32_16x16x32_bf16 v[74:77], v[158:161], v[170:173], v[182:185]
	v_mfma_f32_16x16x32_bf16 v[70:73], v[158:161], v[246:249], v[166:169]
	s_waitcnt lgkmcnt(0)
	v_mfma_f32_16x16x32_bf16 v[66:69], v[162:165], v[170:173], v[178:181]
	v_mfma_f32_16x16x32_bf16 v[62:65], v[162:165], v[246:249], v[174:177]
	s_setprio 0
	s_branch .Lmla_post_4
; #define LAS __attribute__((address_space(3)))
; __device__ __forceinline__ float ex2(float x) { return __builtin_amdgcn_exp2f(x); }
; __device__ __forceinline__ f32x4 mfma16(bf16x8 a, bf16x8 b, f32x4 c) { return __builtin_amdgcn_mfma_f32_16x16x32_bf16(a, b, c, 0, 0, 0); }
;   __device__ __forceinline__ bf16_t* W() const { return (bf16_t*)(ws + WS_W); }
; template <int NT, int NKK, int NDT, int MODE, bool MASK> ...
;     ...
;   for (int t = 0; t < 4; ++t)
; #pragma unroll
;     for (int kk = 0; kk < NKK; ++kk) {
;       const bf16x8 kf = *(LAS const bf16x8*)(Kl + (16 * t + r) * KSTR + (32 * kk + 8 * lg) * 2);
; #pragma unroll
;       for (int j = 0; j < NT; ++j) s[j][t] = mfma16(kf, qf[j][kk], kk == 0 ? (f32x4){0.f, 0.f, 0.f, 0.f} : s[j][t]);
;     }
;   __builtin_amdgcn_s_setprio(0);
;   bf16x8 pf[NT][2];
; #pragma unroll
;   for (int j = 0; j < NT; ++j) {
;     float mx = -INFINITY;
; #pragma unroll
;     for (int t = 0; t < 4; ++t)
; #pragma unroll
;       for (int i = 0; i < 4; ++i) {
;         if (MASK) { const int kp = kpos0 + 16 * t + 4 * lg + i; if (!mask_ok<MODE>(tq[j], kp, W)) s[j][t][i] = -INFINITY; }
;         mx = fmaxf(mx, s[j][t][i]);
;       }
;     mx = max_x16_x32(mx);
;     if (__any(mx > m[j] + 8.0f / c)) {
;       const float mnew = fmaxf(m[j], mx);
;       const float ms2 = (mnew == -INFINITY) ? 0.f : mnew;
;       const float alpha = ex2((m[j] - ms2) * c);
;       m[j] = mnew; l[j] *= alpha;
; #pragma unroll
;       for (int dt = 0; dt < NDT; ++dt) o[j][dt] *= alpha;
;     }
.LBB0_1001:
	s_and_b64 vcc, exec, s[20:21]
	s_cbranch_vccz .LBB0_1009
	s_waitcnt lgkmcnt(10)
	v_mfma_f32_16x16x32_bf16 v[138:141], v[134:137], v[18:21], 0
	v_mfma_f32_16x16x32_bf16 v[134:137], v[134:137], v[10:13], 0
	s_waitcnt lgkmcnt(9)
	v_mfma_f32_16x16x32_bf16 v[138:141], v[130:133], v[2:5], v[138:141]
	v_mfma_f32_16x16x32_bf16 v[134:137], v[130:133], v[14:17], v[134:137]
	s_waitcnt lgkmcnt(8)
	v_mfma_f32_16x16x32_bf16 v[130:133], v[126:129], v[6:9], v[138:141]
	v_mfma_f32_16x16x32_bf16 v[126:129], v[126:129], v[22:25], v[134:137]
	s_waitcnt lgkmcnt(7)
	v_mfma_f32_16x16x32_bf16 v[134:137], v[122:125], v[18:21], 0
	v_mfma_f32_16x16x32_bf16 v[122:125], v[122:125], v[10:13], 0
	s_waitcnt lgkmcnt(6)
	v_mfma_f32_16x16x32_bf16 v[134:137], v[118:121], v[2:5], v[134:137]
	v_mfma_f32_16x16x32_bf16 v[118:121], v[118:121], v[14:17], v[122:125]
	s_waitcnt lgkmcnt(5)
	v_mfma_f32_16x16x32_bf16 v[134:137], v[114:117], v[6:9], v[134:137]
	v_mfma_f32_16x16x32_bf16 v[114:117], v[114:117], v[22:25], v[118:121]
	s_waitcnt lgkmcnt(4)
	v_mfma_f32_16x16x32_bf16 v[118:121], v[106:109], v[18:21], 0
	v_mfma_f32_16x16x32_bf16 v[106:109], v[106:109], v[10:13], 0
	s_waitcnt lgkmcnt(3)
	v_mfma_f32_16x16x32_bf16 v[118:121], v[98:101], v[2:5], v[118:121]
	v_mfma_f32_16x16x32_bf16 v[98:101], v[98:101], v[14:17], v[106:109]
	s_waitcnt lgkmcnt(1)
	v_mfma_f32_16x16x32_bf16 v[106:109], v[102:105], v[18:21], 0
	v_mfma_f32_16x16x32_bf16 v[102:105], v[102:105], v[10:13], 0
	s_waitcnt lgkmcnt(0)
	v_mfma_f32_16x16x32_bf16 v[106:109], v[94:97], v[2:5], v[106:109]
	v_mfma_f32_16x16x32_bf16 v[94:97], v[94:97], v[14:17], v[102:105]
	s_nop 4
	ds_read_b128 v[102:105], v201 offset:128
	v_mfma_f32_16x16x32_bf16 v[118:121], v[110:113], v[6:9], v[118:121]
	v_mfma_f32_16x16x32_bf16 v[98:101], v[110:113], v[22:25], v[98:101]
	s_waitcnt lgkmcnt(0)
	v_mfma_f32_16x16x32_bf16 v[94:97], v[102:105], v[22:25], v[94:97]
	v_mfma_f32_16x16x32_bf16 v[144:147], v[102:105], v[6:9], v[106:109]
	s_setprio 0
	v_add_u32_e32 v103, s43, v241
	v_add_u32_e32 v104, 0xffffff81, v103
	v_add_u32_e32 v105, 0xffffff83, v103
	v_mov_b32_e32 v102, s81
	v_cmp_gt_i32_e64 s[20:21], v104, v194
	v_cmp_lt_i32_e64 s[22:23], v104, v194
	v_cmp_le_i32_e32 vcc, v105, v194
	v_add_u32_e32 v106, 0xffffff84, v103
	v_cndmask_b32_e64 v142, v130, v102, s[20:21]
	v_cndmask_b32_e64 v122, v200, v131, s[22:23]
	v_cndmask_b32_e32 v124, v200, v132, vcc
	v_cmp_le_i32_e32 vcc, v106, v194
	v_max3_f32 v102, v142, s81, v122
	v_add_u32_e32 v107, 0xffffff91, v103
	v_cndmask_b32_e32 v123, v200, v133, vcc
	v_max3_f32 v108, v102, v124, v123
	v_mov_b32_e32 v102, s81
	v_cmp_gt_i32_e32 vcc, v107, v194
	v_add_u32_e32 v107, 0xffffff92, v103
	v_add_u32_e32 v110, 0xffffff94, v103
	v_cndmask_b32_e32 v125, v134, v102, vcc
	v_cmp_le_i32_e32 vcc, v107, v194
	v_add_u32_e32 v109, 0xffffffa1, v103
	v_add_u32_e32 v111, 0xffffffa2, v103
	v_cndmask_b32_e32 v131, v200, v135, vcc
	v_max3_f32 v102, v108, v125, v131
	v_add_u32_e32 v108, 0xffffff93, v103
	v_cmp_le_i32_e32 vcc, v108, v194
	v_add_u32_e32 v113, 0xffffffb1, v103
	s_nop 0
	v_cndmask_b32_e32 v133, v200, v136, vcc
	v_cmp_le_i32_e32 vcc, v110, v194
	s_nop 1
	v_cndmask_b32_e32 v132, v200, v137, vcc
	v_max3_f32 v112, v102, v133, v132
	v_mov_b32_e32 v102, s81
	v_cmp_gt_i32_e32 vcc, v109, v194
	s_nop 1
	v_cndmask_b32_e32 v134, v118, v102, vcc
	v_cmp_le_i32_e32 vcc, v111, v194
	v_add_u32_e32 v118, 0xffffffa4, v103
	s_nop 0
	v_cndmask_b32_e32 v135, v200, v119, vcc
	v_max3_f32 v102, v112, v134, v135
	v_add_u32_e32 v112, 0xffffffa3, v103
	v_cmp_le_i32_e32 vcc, v112, v194
	v_add_u32_e32 v119, 0xffffffb2, v103
	s_nop 0
	v_cndmask_b32_e32 v137, v200, v120, vcc
	v_cmp_le_i32_e32 vcc, v118, v194
	s_nop 1
	v_cndmask_b32_e32 v136, v200, v121, vcc
	v_max3_f32 v120, v102, v137, v136
	v_mov_b32_e32 v102, s81
	v_cmp_gt_i32_e32 vcc, v113, v194
	v_add_u32_e32 v121, 0xffffffb4, v103
	s_nop 0
	v_cndmask_b32_e32 v138, v144, v102, vcc
	v_cmp_le_i32_e32 vcc, v119, v194
	s_nop 1
	v_cndmask_b32_e32 v139, v200, v145, vcc
	v_max3_f32 v102, v120, v138, v139
	v_add_u32_e32 v120, 0xffffffb3, v103
	v_cmp_le_i32_e32 vcc, v120, v194
	s_nop 1
	v_cndmask_b32_e32 v141, v200, v146, vcc
	v_cmp_le_i32_e32 vcc, v121, v194
	s_nop 1
	v_cndmask_b32_e32 v140, v200, v147, vcc
	v_max3_f32 v102, v102, v141, v140
	v_mov_b32_e32 v103, v102
	s_nop 1
	v_permlane16_swap_b32_e32 v102, v103
	v_max_f32_e32 v102, v102, v103
	v_mov_b32_e32 v103, v102
	s_nop 1
	v_permlane32_swap_b32_e32 v102, v103
	v_max_f32_e32 v102, v102, v103
	v_cmp_gt_f32_e32 vcc, v102, v1
	s_cbranch_vccz .LBB0_1004
	v_max_f32_e32 v1, v102, v102
	v_max_f32_e32 v102, v220, v220
	v_max_f32_e32 v102, v102, v1
	v_cmp_neq_f32_e32 vcc, s81, v102
	v_mov_b32_e32 v103, v221
	s_nop 0
	v_cndmask_b32_e32 v1, 0, v102, vcc
	v_sub_f32_e32 v1, v220, v1
	v_mul_f32_e32 v1, 0x3e16c740, v1
	v_exp_f32_e32 v144, v1
	v_mov_b64_e32 v[220:221], v[102:103]
	v_mul_f32_e32 v218, v218, v144
	v_pk_mul_f32 v[92:93], v[92:93], v[144:145] op_sel_hi:[1,0]
	v_pk_mul_f32 v[90:91], v[90:91], v[144:145] op_sel_hi:[1,0]
	v_pk_mul_f32 v[88:89], v[88:89], v[144:145] op_sel_hi:[1,0]
	v_pk_mul_f32 v[86:87], v[86:87], v[144:145] op_sel_hi:[1,0]
	v_pk_mul_f32 v[76:77], v[76:77], v[144:145] op_sel_hi:[1,0]
	v_pk_mul_f32 v[74:75], v[74:75], v[144:145] op_sel_hi:[1,0]
	v_pk_mul_f32 v[68:69], v[68:69], v[144:145] op_sel_hi:[1,0]
	v_pk_mul_f32 v[66:67], v[66:67], v[144:145] op_sel_hi:[1,0]
	s_branch .LBB0_1005

; #define LAS __attribute__((address_space(3)))
; __device__ __forceinline__ float ex2(float x) { return __builtin_amdgcn_exp2f(x); }
; #define LBAR() asm volatile("s_waitcnt lgkmcnt(0)\n\ts_barrier" ::: "memory")
; __device__ __forceinline__ f32x4 mfma16(bf16x8 a, bf16x8 b, f32x4 c) { return __builtin_amdgcn_mfma_f32_16x16x32_bf16(a, b, c, 0, 0, 0); }
;   __device__ __forceinline__ bf16_t* W() const { return (bf16_t*)(ws + WS_W); }
; template <int NT, int NKK, int NDT, int MODE, bool MASK> ...
;     ...
;   for (int t = 0; t < 4; ++t)
; #pragma unroll
;     for (int kk = 0; kk < NKK; ++kk) {
;       const bf16x8 kf = *(LAS const bf16x8*)(Kl + (16 * t + r) * KSTR + (32 * kk + 8 * lg) * 2);
; #pragma unroll
;       for (int j = 0; j < NT; ++j) s[j][t] = mfma16(kf, qf[j][kk], kk == 0 ? (f32x4){0.f, 0.f, 0.f, 0.f} : s[j][t]);
;     }
;   __builtin_amdgcn_s_setprio(0);
;   bf16x8 pf[NT][2];
; #pragma unroll
;   for (int j = 0; j < NT; ++j) {
;     float mx = -INFINITY;
; #pragma unroll
;     for (int t = 0; t < 4; ++t)
; #pragma unroll
;       for (int i = 0; i < 4; ++i) {
;         if (MASK) { const int kp = kpos0 + 16 * t + 4 * lg + i; if (!mask_ok<MODE>(tq[j], kp, W)) s[j][t][i] = -INFINITY; }
;         mx = fmaxf(mx, s[j][t][i]);
;       }
;     mx = max_x16_x32(mx);
;     if (__any(mx > m[j] + 8.0f / c)) {
;       const float mnew = fmaxf(m[j], mx);
;       const float ms2 = (mnew == -INFINITY) ? 0.f : mnew;
;       const float alpha = ex2((m[j] - ms2) * c);
;       m[j] = mnew; l[j] *= alpha;
; #pragma unroll
;       for (int dt = 0; dt < NDT; ++dt) o[j][dt] *= alpha;
;     }
; template <int NT, int DQK, int DV, int MODE, int PD, class Src> ...
;     ...
;         LBAR();
;         const int lo = kbase + 64 * kc, hi = lo + 63;
;         bool rel = true, full = true;
;         if (MODE == MODE_CAUSAL) { rel = lo <= tq_max; full = hi <= tq_min; }
;         if (MODE == MODE_WINDOW) { rel = (lo <= tq_max) && (hi > tq_min - W); full = (hi <= tq_min) && (lo > tq_max - W); }
;         if (MODE == MODE_CMP) { rel = 16 * lo + 31 <= tq_max; full = 16 * hi + 31 <= tq_min; }
;         if (rel) {
;           if (NT <= 2) {
;             if (full) attn_chunk_wide<NT, DQK / 32, DV / 16, MODE, false>(o, m, l, qf, buf, KSTR, buf + KB, VSTR, lo, tq, c, W, lane);
.LBB0_1023:
	s_waitcnt lgkmcnt(0)
	s_barrier
	s_sub_i32 s8, s43, 63
	s_cmp_gt_i32 s8, s40
	s_cbranch_scc1 .LBB0_1050
	s_cmp_gt_i32 s43, s25
	s_setprio 1
	v_add_u32_e32 v1, s45, v236
	s_waitcnt lgkmcnt(0)
	v_add_u32_e32 v94, v1, v237
	ds_read_b128 v[134:137], v94
	ds_read_b128 v[130:133], v94 offset:64
	ds_read_b128 v[126:129], v94 offset:128
	ds_read_b128 v[122:125], v94 offset:3328
	ds_read_b128 v[118:121], v94 offset:3392
	ds_read_b128 v[114:117], v94 offset:3456
	ds_read_b128 v[106:109], v94 offset:6656
	ds_read_b128 v[98:101], v94 offset:6720
	v_add_u32_e32 v201, v1, v238
	ds_read_b128 v[110:113], v94 offset:6784
	ds_read_b128 v[102:105], v201
	ds_read_b128 v[94:97], v201 offset:64
	s_mov_b64 s[20:21], -1
	v_add_f32_e32 v1, 0x4259535f, v220
	s_cbranch_scc1 .LBB0_1041
	s_waitcnt lgkmcnt(10)
	v_mfma_f32_16x16x32_bf16 v[138:141], v[134:137], v[18:21], 0
	ds_read_b128 v[146:149], v201 offset:128
	v_mov_b32_e32 v234, 0x260
	v_mfma_f32_16x16x32_bf16 v[142:145], v[134:137], v[10:13], 0
	s_waitcnt lgkmcnt(10)
	v_mfma_f32_16x16x32_bf16 v[138:141], v[130:133], v[2:5], v[138:141]
	v_mfma_f32_16x16x32_bf16 v[142:145], v[130:133], v[14:17], v[142:145]
	s_waitcnt lgkmcnt(9)
	v_mfma_f32_16x16x32_bf16 v[182:185], v[126:129], v[6:9], v[138:141]
	v_mfma_f32_16x16x32_bf16 v[166:169], v[126:129], v[22:25], v[142:145]
	s_waitcnt lgkmcnt(8)
	v_mfma_f32_16x16x32_bf16 v[138:141], v[122:125], v[18:21], 0
	v_mfma_f32_16x16x32_bf16 v[142:145], v[122:125], v[10:13], 0
	s_waitcnt lgkmcnt(7)
	v_mfma_f32_16x16x32_bf16 v[138:141], v[118:121], v[2:5], v[138:141]
	v_mfma_f32_16x16x32_bf16 v[142:145], v[118:121], v[14:17], v[142:145]
	s_waitcnt lgkmcnt(6)
	v_mfma_f32_16x16x32_bf16 v[178:181], v[114:117], v[6:9], v[138:141]
	v_mfma_f32_16x16x32_bf16 v[154:157], v[114:117], v[22:25], v[142:145]
	s_waitcnt lgkmcnt(5)
	v_mfma_f32_16x16x32_bf16 v[138:141], v[106:109], v[18:21], 0
	v_mfma_f32_16x16x32_bf16 v[142:145], v[106:109], v[10:13], 0
	s_waitcnt lgkmcnt(4)
	v_mfma_f32_16x16x32_bf16 v[138:141], v[98:101], v[2:5], v[138:141]
	v_mfma_f32_16x16x32_bf16 v[142:145], v[98:101], v[14:17], v[142:145]
	s_waitcnt lgkmcnt(3)
	v_mfma_f32_16x16x32_bf16 v[174:177], v[110:113], v[6:9], v[138:141]
	v_mfma_f32_16x16x32_bf16 v[150:153], v[110:113], v[22:25], v[142:145]
	s_waitcnt lgkmcnt(2)
	v_mfma_f32_16x16x32_bf16 v[138:141], v[102:105], v[18:21], 0
	v_mfma_f32_16x16x32_bf16 v[142:145], v[102:105], v[10:13], 0
	s_waitcnt lgkmcnt(1)
	v_mfma_f32_16x16x32_bf16 v[138:141], v[94:97], v[2:5], v[138:141]
	v_mfma_f32_16x16x32_bf16 v[142:145], v[94:97], v[14:17], v[142:145]
	s_waitcnt lgkmcnt(0)
	v_mfma_f32_16x16x32_bf16 v[170:173], v[146:149], v[6:9], v[138:141]
	v_mfma_f32_16x16x32_bf16 v[142:145], v[146:149], v[22:25], v[142:145]
	s_setprio 0
	s_nop 2
	v_max3_f32 v138, v182, s81, v183
	v_max3_f32 v138, v138, v184, v185
	v_max3_f32 v138, v138, v178, v179
	v_max3_f32 v138, v138, v180, v181
	v_max3_f32 v138, v138, v174, v175
	v_max3_f32 v138, v138, v176, v177
	v_max3_f32 v138, v138, v170, v171
	v_max3_f32 v138, v138, v172, v173
	v_mov_b32_e32 v139, v138
	s_nop 1
	v_permlane16_swap_b32_e32 v138, v139
	v_max_f32_e32 v138, v138, v139
	v_mov_b32_e32 v139, v138
	s_nop 1
	v_permlane32_swap_b32_e32 v138, v139
	v_max_f32_e32 v186, v138, v139
	v_cmp_gt_f32_e32 vcc, v186, v1
	v_mov_b64_e32 v[222:223], v[220:221]
	v_mov_b64_e32 v[224:225], v[218:219]
	v_mov_b32_e32 v187, v220
	s_cbranch_vccz .LBB0_1027
	v_max_f32_e32 v138, v186, v186
	v_max_f32_e32 v139, v220, v220
	v_max_f32_e32 v222, v139, v138
	v_cmp_neq_f32_e32 vcc, s81, v222
	v_mov_b32_e32 v223, v221
	v_mov_b32_e32 v225, v219
	v_cndmask_b32_e32 v138, 0, v222, vcc
	v_sub_f32_e32 v138, v220, v138
	v_mul_f32_e32 v138, 0x3e16c740, v138
	v_exp_f32_e32 v138, v138
	v_mov_b32_e32 v187, v222
	v_mul_f32_e32 v224, v218, v138
	v_pk_mul_f32 v[92:93], v[92:93], v[138:139] op_sel_hi:[1,0]
	v_pk_mul_f32 v[90:91], v[90:91], v[138:139] op_sel_hi:[1,0]
	v_pk_mul_f32 v[88:89], v[88:89], v[138:139] op_sel_hi:[1,0]
	v_pk_mul_f32 v[86:87], v[86:87], v[138:139] op_sel_hi:[1,0]
	v_pk_mul_f32 v[76:77], v[76:77], v[138:139] op_sel_hi:[1,0]
	v_pk_mul_f32 v[74:75], v[74:75], v[138:139] op_sel_hi:[1,0]
	v_pk_mul_f32 v[68:69], v[68:69], v[138:139] op_sel_hi:[1,0]
	v_pk_mul_f32 v[66:67], v[66:67], v[138:139] op_sel_hi:[1,0]

; #define LAS __attribute__((address_space(3)))
; __device__ __forceinline__ float ex2(float x) { return __builtin_amdgcn_exp2f(x); }
; __device__ __forceinline__ f32x4 mfma16(bf16x8 a, bf16x8 b, f32x4 c) { return __builtin_amdgcn_mfma_f32_16x16x32_bf16(a, b, c, 0, 0, 0); }
;   __device__ __forceinline__ bf16_t* W() const { return (bf16_t*)(ws + WS_W); }
; template <int NT, int NKK, int NDT, int MODE, bool MASK> ...
;     ...
;   for (int t = 0; t < 4; ++t)
; #pragma unroll
;     for (int kk = 0; kk < NKK; ++kk) {
;       const bf16x8 kf = *(LAS const bf16x8*)(Kl + (16 * t + r) * KSTR + (32 * kk + 8 * lg) * 2);
; #pragma unroll
;       for (int j = 0; j < NT; ++j) s[j][t] = mfma16(kf, qf[j][kk], kk == 0 ? (f32x4){0.f, 0.f, 0.f, 0.f} : s[j][t]);
;     }
;   __builtin_amdgcn_s_setprio(0);
;   bf16x8 pf[NT][2];
; #pragma unroll
;   for (int j = 0; j < NT; ++j) {
;     float mx = -INFINITY;
; #pragma unroll
;     for (int t = 0; t < 4; ++t)
; #pragma unroll
;       for (int i = 0; i < 4; ++i) {
;         if (MASK) { const int kp = kpos0 + 16 * t + 4 * lg + i; if (!mask_ok<MODE>(tq[j], kp, W)) s[j][t][i] = -INFINITY; }
;         mx = fmaxf(mx, s[j][t][i]);
;       }
;     mx = max_x16_x32(mx);
;     if (__any(mx > m[j] + 8.0f / c)) {
;       const float mnew = fmaxf(m[j], mx);
;       const float ms2 = (mnew == -INFINITY) ? 0.f : mnew;
;       const float alpha = ex2((m[j] - ms2) * c);
;       m[j] = mnew; l[j] *= alpha;
; #pragma unroll
;       for (int dt = 0; dt < NDT; ++dt) o[j][dt] *= alpha;
;     }
.LBB0_1041:
	s_and_b64 vcc, exec, s[20:21]
	s_cbranch_vccz .LBB0_1049
	s_waitcnt lgkmcnt(10)
	v_mfma_f32_16x16x32_bf16 v[138:141], v[134:137], v[18:21], 0
	v_mfma_f32_16x16x32_bf16 v[134:137], v[134:137], v[10:13], 0
	s_waitcnt lgkmcnt(9)
	v_mfma_f32_16x16x32_bf16 v[138:141], v[130:133], v[2:5], v[138:141]
	v_mfma_f32_16x16x32_bf16 v[134:137], v[130:133], v[14:17], v[134:137]
	s_waitcnt lgkmcnt(8)
	v_mfma_f32_16x16x32_bf16 v[130:133], v[126:129], v[6:9], v[138:141]
	v_mfma_f32_16x16x32_bf16 v[126:129], v[126:129], v[22:25], v[134:137]
	s_waitcnt lgkmcnt(7)
	v_mfma_f32_16x16x32_bf16 v[134:137], v[122:125], v[18:21], 0
	v_mfma_f32_16x16x32_bf16 v[122:125], v[122:125], v[10:13], 0
	s_waitcnt lgkmcnt(6)
	v_mfma_f32_16x16x32_bf16 v[134:137], v[118:121], v[2:5], v[134:137]
	v_mfma_f32_16x16x32_bf16 v[118:121], v[118:121], v[14:17], v[122:125]
	s_waitcnt lgkmcnt(5)
	v_mfma_f32_16x16x32_bf16 v[134:137], v[114:117], v[6:9], v[134:137]
	v_mfma_f32_16x16x32_bf16 v[114:117], v[114:117], v[22:25], v[118:121]
	s_waitcnt lgkmcnt(4)
	v_mfma_f32_16x16x32_bf16 v[118:121], v[106:109], v[18:21], 0
	v_mfma_f32_16x16x32_bf16 v[106:109], v[106:109], v[10:13], 0
	s_waitcnt lgkmcnt(3)
	v_mfma_f32_16x16x32_bf16 v[118:121], v[98:101], v[2:5], v[118:121]
	v_mfma_f32_16x16x32_bf16 v[98:101], v[98:101], v[14:17], v[106:109]
	s_waitcnt lgkmcnt(1)
	v_mfma_f32_16x16x32_bf16 v[106:109], v[102:105], v[18:21], 0
	v_mfma_f32_16x16x32_bf16 v[102:105], v[102:105], v[10:13], 0
	s_waitcnt lgkmcnt(0)
	v_mfma_f32_16x16x32_bf16 v[106:109], v[94:97], v[2:5], v[106:109]
	v_mfma_f32_16x16x32_bf16 v[94:97], v[94:97], v[14:17], v[102:105]
	s_nop 4
	ds_read_b128 v[102:105], v201 offset:128
	v_mfma_f32_16x16x32_bf16 v[118:121], v[110:113], v[6:9], v[118:121]
	v_mfma_f32_16x16x32_bf16 v[98:101], v[110:113], v[22:25], v[98:101]
	s_waitcnt lgkmcnt(0)
	v_mfma_f32_16x16x32_bf16 v[94:97], v[102:105], v[22:25], v[94:97]
	v_mfma_f32_16x16x32_bf16 v[144:147], v[102:105], v[6:9], v[106:109]
	s_setprio 0
	v_add_u32_e32 v103, s43, v241
	v_subrev_u32_e32 v104, 63, v103
	v_subrev_u32_e32 v105, 61, v103
	v_mov_b32_e32 v102, s81
	v_cmp_gt_i32_e64 s[20:21], v104, v194
	v_cmp_lt_i32_e64 s[22:23], v104, v194
	v_cmp_le_i32_e32 vcc, v105, v194
	v_subrev_u32_e32 v106, 60, v103
	v_cndmask_b32_e64 v142, v130, v102, s[20:21]
	v_cndmask_b32_e64 v122, v200, v131, s[22:23]
	v_cndmask_b32_e32 v124, v200, v132, vcc
	v_cmp_le_i32_e32 vcc, v106, v194
	v_max3_f32 v102, v142, s81, v122
	v_subrev_u32_e32 v107, 47, v103
	v_cndmask_b32_e32 v123, v200, v133, vcc
	v_max3_f32 v108, v102, v124, v123
	v_mov_b32_e32 v102, s81
	v_cmp_gt_i32_e32 vcc, v107, v194
	v_subrev_u32_e32 v107, 46, v103
	v_subrev_u32_e32 v110, 44, v103
	v_cndmask_b32_e32 v125, v134, v102, vcc
	v_cmp_le_i32_e32 vcc, v107, v194
	v_subrev_u32_e32 v109, 31, v103
	v_subrev_u32_e32 v111, 30, v103
	v_cndmask_b32_e32 v131, v200, v135, vcc
	v_max3_f32 v102, v108, v125, v131
	v_subrev_u32_e32 v108, 45, v103
	v_cmp_le_i32_e32 vcc, v108, v194
	v_add_u32_e32 v113, -15, v103
	s_nop 0
	v_cndmask_b32_e32 v133, v200, v136, vcc
	v_cmp_le_i32_e32 vcc, v110, v194
	s_nop 1
	v_cndmask_b32_e32 v132, v200, v137, vcc
	v_max3_f32 v112, v102, v133, v132
	v_mov_b32_e32 v102, s81
	v_cmp_gt_i32_e32 vcc, v109, v194
	s_nop 1
	v_cndmask_b32_e32 v134, v118, v102, vcc
	v_cmp_le_i32_e32 vcc, v111, v194
	v_subrev_u32_e32 v118, 28, v103
	s_nop 0
	v_cndmask_b32_e32 v135, v200, v119, vcc
	v_max3_f32 v102, v112, v134, v135
	v_subrev_u32_e32 v112, 29, v103
	v_cmp_le_i32_e32 vcc, v112, v194
	v_add_u32_e32 v119, -14, v103
	s_nop 0
	v_cndmask_b32_e32 v137, v200, v120, vcc
	v_cmp_le_i32_e32 vcc, v118, v194
	s_nop 1
	v_cndmask_b32_e32 v136, v200, v121, vcc
	v_max3_f32 v120, v102, v137, v136
	v_mov_b32_e32 v102, s81
	v_cmp_gt_i32_e32 vcc, v113, v194
	v_add_u32_e32 v121, -12, v103
	s_nop 0
	v_cndmask_b32_e32 v138, v144, v102, vcc
	v_cmp_le_i32_e32 vcc, v119, v194
	s_nop 1
	v_cndmask_b32_e32 v139, v200, v145, vcc
	v_max3_f32 v102, v120, v138, v139
	v_add_u32_e32 v120, -13, v103
	v_cmp_le_i32_e32 vcc, v120, v194
	s_nop 1
	v_cndmask_b32_e32 v141, v200, v146, vcc
	v_cmp_le_i32_e32 vcc, v121, v194
	s_nop 1
	v_cndmask_b32_e32 v140, v200, v147, vcc
	v_max3_f32 v102, v102, v141, v140
	v_mov_b32_e32 v103, v102
	s_nop 1
	v_permlane16_swap_b32_e32 v102, v103
	v_max_f32_e32 v102, v102, v103
	v_mov_b32_e32 v103, v102
	s_nop 1
	v_permlane32_swap_b32_e32 v102, v103
	v_max_f32_e32 v102, v102, v103
	v_cmp_gt_f32_e32 vcc, v102, v1
	s_cbranch_vccz .LBB0_1044
	v_max_f32_e32 v1, v102, v102
	v_max_f32_e32 v102, v220, v220
	v_max_f32_e32 v102, v102, v1
	v_cmp_neq_f32_e32 vcc, s81, v102
	v_mov_b32_e32 v103, v221
	s_nop 0
	v_cndmask_b32_e32 v1, 0, v102, vcc
	v_sub_f32_e32 v1, v220, v1
	v_mul_f32_e32 v1, 0x3e16c740, v1
	v_exp_f32_e32 v144, v1
	v_mov_b64_e32 v[220:221], v[102:103]
	v_mul_f32_e32 v218, v218, v144
	v_pk_mul_f32 v[92:93], v[92:93], v[144:145] op_sel_hi:[1,0]
	v_pk_mul_f32 v[90:91], v[90:91], v[144:145] op_sel_hi:[1,0]
	v_pk_mul_f32 v[88:89], v[88:89], v[144:145] op_sel_hi:[1,0]
	v_pk_mul_f32 v[86:87], v[86:87], v[144:145] op_sel_hi:[1,0]
	v_pk_mul_f32 v[76:77], v[76:77], v[144:145] op_sel_hi:[1,0]
	v_pk_mul_f32 v[74:75], v[74:75], v[144:145] op_sel_hi:[1,0]
	v_pk_mul_f32 v[68:69], v[68:69], v[144:145] op_sel_hi:[1,0]
	v_pk_mul_f32 v[66:67], v[66:67], v[144:145] op_sel_hi:[1,0]
	s_branch .LBB0_1045

; template <int NT, int NKK, int NDT, int MODE, bool MASK> ...
;     ...
;     for (int jh = 0; jh < NT / JB; ++jh) {
;       int oz = 0; if (NT > JB) asm volatile("" : "+v"(oz));
;       f32x4 s[JB][2];
;       __builtin_amdgcn_s_setprio(1);
; #pragma unroll
;       for (int t = 0; t < 2; ++t)
; #pragma unroll
;         for (int kk = 0; kk < NKK; ++kk) {
;           const bf16x8 kf = *(LAS const bf16x8*)(Kl + oz + (32 * st + 16 * t + r) * KSTR + (32 * kk + 8 * lg) * 2);
; #pragma unroll
;           for (int jj = 0; jj < JB; ++jj) s[jj][t] = mfma16(kf, qf[jh * JB + jj][kk], kk == 0 ? (f32x4){0.f, 0.f, 0.f, 0.f} : s[jj][t]);
;         }
;       __builtin_amdgcn_s_setprio(0);
;       bf16x8 pf[JB];
;       if (NT > JB) __builtin_amdgcn_sched_barrier(0);
; #pragma unroll
;       for (int jj = 0; jj < JB; ++jj) {
;         const int j = jh * JB + jj;
;         float mx = -INFINITY;
; #pragma unroll
;         for (int t = 0; t < 2; ++t)
; #pragma unroll
;           for (int i = 0; i < 4; ++i) {
;             if (MASK) { const int kp = kpos0 + 32 * st + 16 * t + 4 * lg + i; if (!mask_ok<MODE>(tq[j], kp, W)) s[jj][t][i] = -INFINITY; }
;             mx = fmaxf(mx, s[jj][t][i]);
;           }
;         mx = max_x16_x32(mx);
;         if (NT > 2 || __any(mx > m[j] + 8.0f / c)) {
;           const float mnew = fmaxf(m[j], mx);
;           const float ms2 = (mnew == -INFINITY) ? 0.f : mnew;
;           const float alpha = ex2((m[j] - ms2) * c);
;           m[j] = mnew; l[j] *= alpha;
; #pragma unroll
;           for (int dt = 0; dt < NDT; ++dt) o[j][dt] *= alpha;
;         }
;         const float mc = ((m[j] == -INFINITY) ? 0.f : m[j]) * c;
;         float p0[4], p1[4], ps = 0.f;
; #pragma unroll
;         for (int i = 0; i < 4; ++i) { p0[i] = ex2(s[jj][0][i] * c - mc); p1[i] = ex2(s[jj][1][i] * c - mc); ps += p0[i] + p1[i]; }
;         l[j] += ps;
;         pf[jj] = pack8(p0, p1);
;       }
;       if (NT > JB) __builtin_amdgcn_sched_barrier(0);
;       __builtin_amdgcn_s_setprio(1);
; #pragma unroll
;       for (int dt = 0; dt < NDT; ++dt) {
;         const s16x4 v0 = ds_tr(Vl + oz + (32 * st + 4 * lg + vq) * VSTR + (16 * dt + 4 * vp) * 2);
;         const s16x4 v1 = ds_tr(Vl + oz + (32 * st + 16 + 4 * lg + vq) * VSTR + (16 * dt + 4 * vp) * 2);
;         const bf16x8 vf = (bf16x8){v0[0], v0[1], v0[2], v0[3], v1[0], v1[1], v1[2], v1[3]};
; #pragma unroll
.LBB0_1126:
	v_mov_b32_e32 v196, v206
	v_mov_b32_e32 v232, v209
	v_or_b32_e32 v199, s8, v203
	v_mov_b32_e32 v206, s45
	v_mov_b32_e32 v209, 0
	v_mov_b32_e32 v197, v207
	v_mov_b32_e32 v235, v210
	v_or_b32_e32 v198, s8, v201
	v_mad_u32_u24 v208, v199, s80, v206
	s_setprio 1
	v_mul_u32_u24_e32 v244, 0x90, v198
	v_add3_u32 v198, v1, v209, v244
	ds_read_b128 v[210:213], v198
	ds_read_b128 v[214:217], v198 offset:64
	s_waitcnt lgkmcnt(1)
	v_mfma_f32_16x16x32_bf16 v[218:221], v[210:213], v[2:5], 0
	v_mfma_f32_16x16x32_bf16 v[210:213], v[210:213], v[10:13], 0
	s_waitcnt lgkmcnt(0)
	v_mfma_f32_16x16x32_bf16 v[218:221], v[214:217], v[6:9], v[218:221]
	v_mfma_f32_16x16x32_bf16 v[210:213], v[214:217], v[14:17], v[210:213]
	ds_read_b128 v[214:217], v198 offset:2304
	ds_read_b128 v[222:225], v198 offset:2368
	s_waitcnt lgkmcnt(1)
	v_mfma_f32_16x16x32_bf16 v[228:231], v[214:217], v[2:5], 0
	v_mfma_f32_16x16x32_bf16 v[214:217], v[214:217], v[10:13], 0
	s_waitcnt lgkmcnt(0)
	v_mfma_f32_16x16x32_bf16 v[228:231], v[222:225], v[6:9], v[228:231]
	v_mfma_f32_16x16x32_bf16 v[214:217], v[222:225], v[14:17], v[214:217]
	s_setprio 0
	v_max3_f32 v198, v218, s81, v219
	v_max3_f32 v198, v198, v220, v221
	s_nop 3
	v_max3_f32 v198, v198, v228, v229
	v_max3_f32 v198, v198, v230, v231
	v_mov_b32_e32 v199, v198
	s_nop 1
	v_permlane16_swap_b32_e32 v198, v199
	v_max_f32_e32 v198, v198, v199
	v_mov_b32_e32 v199, v198
	s_nop 1
	v_permlane32_swap_b32_e32 v198, v199
	v_max3_f32 v206, v196, v198, v199
	v_cmp_eq_f32_e32 vcc, s81, v206
	s_nop 1
	v_cndmask_b32_e64 v198, v206, 0, vcc
	v_sub_f32_e32 v196, v196, v198
	v_mul_f32_e32 v198, 0x3e38aa3b, v206
	v_cndmask_b32_e64 v198, v198, 0, vcc
	v_fma_f32 v207, v228, s42, -v198
	v_exp_f32_e32 v223, v207
	v_fma_f32 v207, v219, s42, -v198
	v_exp_f32_e32 v225, v207
	v_fma_f32 v207, v229, s42, -v198
	v_exp_f32_e32 v229, v207
	v_fma_f32 v207, v220, s42, -v198
	v_exp_f32_e32 v237, v207
	v_fma_f32 v207, v230, s42, -v198
	v_fma_f32 v199, v218, s42, -v198
	v_exp_f32_e32 v239, v207
	v_fma_f32 v207, v221, s42, -v198
	v_fma_f32 v198, v231, s42, -v198
	v_exp_f32_e32 v231, v198
	v_max3_f32 v198, v210, s81, v211
	v_max3_f32 v198, v198, v212, v213
	v_max3_f32 v198, v198, v214, v215
	v_max3_f32 v198, v198, v216, v217
	v_exp_f32_e32 v241, v207
	v_mov_b32_e32 v207, v198
	s_nop 1
	v_permlane16_swap_b32_e32 v198, v207
	v_max_f32_e32 v198, v198, v207
	v_mul_f32_e32 v196, 0x3e38aa3b, v196
	v_mov_b32_e32 v207, v198
	v_exp_f32_e32 v196, v196
	s_nop 0
	v_permlane32_swap_b32_e32 v198, v207
	v_max3_f32 v207, v197, v198, v207
	v_cmp_eq_f32_e32 vcc, s81, v207
	v_pk_mul_f32 v[140:141], v[140:141], v[196:197] op_sel_hi:[1,0]
	v_pk_mul_f32 v[138:139], v[138:139], v[196:197] op_sel_hi:[1,0]
	v_cndmask_b32_e64 v198, v207, 0, vcc
	v_pk_mul_f32 v[136:137], v[136:137], v[196:197] op_sel_hi:[1,0]
	v_pk_mul_f32 v[134:135], v[134:135], v[196:197] op_sel_hi:[1,0]
	v_pk_mul_f32 v[156:157], v[156:157], v[196:197] op_sel_hi:[1,0]
	v_pk_mul_f32 v[154:155], v[154:155], v[196:197] op_sel_hi:[1,0]
	v_pk_mul_f32 v[164:165], v[164:165], v[196:197] op_sel_hi:[1,0]
	v_pk_mul_f32 v[162:163], v[162:163], v[196:197] op_sel_hi:[1,0]
	v_sub_f32_e32 v197, v197, v198
	v_mul_f32_e32 v197, 0x3e38aa3b, v197
	v_exp_f32_e32 v242, v197
	v_mul_f32_e32 v197, 0x3e38aa3b, v207
	v_cndmask_b32_e64 v197, v197, 0, vcc
	v_fma_f32 v198, v210, s42, -v197
	v_fma_f32 v210, v214, s42, -v197
	v_exp_f32_e32 v222, v210
	v_fma_f32 v210, v211, s42, -v197
	v_exp_f32_e32 v224, v210
	v_fma_f32 v210, v215, s42, -v197
	v_exp_f32_e32 v199, v199
	v_exp_f32_e32 v198, v198
	v_exp_f32_e32 v228, v210
	v_fma_f32 v210, v212, s42, -v197
	v_exp_f32_e32 v236, v210
	v_fma_f32 v210, v216, s42, -v197
	v_exp_f32_e32 v238, v210
	v_fma_f32 v210, v213, s42, -v197
	v_fma_f32 v197, v217, s42, -v197
	v_exp_f32_e32 v240, v210
	v_exp_f32_e32 v230, v197
	v_pk_mul_f32 v[112:113], v[112:113], v[242:243] op_sel_hi:[1,0]
	v_pk_mul_f32 v[110:111], v[110:111], v[242:243] op_sel_hi:[1,0]
	v_pk_mul_f32 v[108:109], v[108:109], v[242:243] op_sel_hi:[1,0]
	v_pk_mul_f32 v[106:107], v[106:107], v[242:243] op_sel_hi:[1,0]
	v_pk_mul_f32 v[124:125], v[124:125], v[242:243] op_sel_hi:[1,0]
	v_pk_mul_f32 v[122:123], v[122:123], v[242:243] op_sel_hi:[1,0]
	v_pk_mul_f32 v[132:133], v[132:133], v[242:243] op_sel_hi:[1,0]
	v_pk_mul_f32 v[130:131], v[130:131], v[242:243] op_sel_hi:[1,0]
	v_mov_b32_e32 v243, v196
	v_pk_add_f32 v[196:197], v[198:199], v[222:223]
	v_pk_add_f32 v[210:211], v[224:225], v[228:229]
	v_pk_add_f32 v[196:197], v[196:197], 0 op_sel_hi:[1,0]
	v_cvt_pk_bf16_f32 v218, v199, v225
	v_pk_add_f32 v[196:197], v[210:211], v[196:197]
	v_pk_add_f32 v[210:211], v[236:237], v[238:239]
	v_cvt_pk_bf16_f32 v219, v237, v241
	v_pk_add_f32 v[196:197], v[210:211], v[196:197]
	v_pk_add_f32 v[210:211], v[240:241], v[230:231]
	v_cvt_pk_bf16_f32 v220, v223, v229
	v_pk_add_f32 v[196:197], v[210:211], v[196:197]
	v_cvt_pk_bf16_f32 v210, v198, v224
	v_pk_fma_f32 v[180:181], v[180:181], v[242:243], v[196:197]
	v_cvt_pk_bf16_f32 v221, v239, v231
	v_cvt_pk_bf16_f32 v211, v236, v240
	v_cvt_pk_bf16_f32 v212, v222, v228
	v_cvt_pk_bf16_f32 v213, v238, v230
	s_setprio 1
	v_add3_u32 v196, v208, v209, v204
	ds_read_b64_tr_b16 v[216:217], v196 offset:11776
	ds_read_b64_tr_b16 v[214:215], v196 offset:9216
	ds_read_b64_tr_b16 v[222:223], v196 offset:9248
	ds_read_b64_tr_b16 v[224:225], v196 offset:11808
	s_waitcnt lgkmcnt(2)
	v_mfma_f32_16x16x32_bf16 v[138:141], v[214:217], v[218:221], v[138:141]
	v_mfma_f32_16x16x32_bf16 v[110:113], v[214:217], v[210:213], v[110:113]
	ds_read_b64_tr_b16 v[214:215], v196 offset:9280
	ds_read_b64_tr_b16 v[216:217], v196 offset:11840
	s_waitcnt lgkmcnt(0)
; template <int NT, int NKK, int NDT, int MODE, bool MASK> ...
;     ...
;     for (int jh = 0; jh < NT / JB; ++jh) {
;       int oz = 0; if (NT > JB) asm volatile("" : "+v"(oz));
;       f32x4 s[JB][2];
;       __builtin_amdgcn_s_setprio(1);
; #pragma unroll
;       for (int t = 0; t < 2; ++t)
; #pragma unroll
;         for (int kk = 0; kk < NKK; ++kk) {
;           const bf16x8 kf = *(LAS const bf16x8*)(Kl + oz + (32 * st + 16 * t + r) * KSTR + (32 * kk + 8 * lg) * 2);
; #pragma unroll
;           for (int jj = 0; jj < JB; ++jj) s[jj][t] = mfma16(kf, qf[jh * JB + jj][kk], kk == 0 ? (f32x4){0.f, 0.f, 0.f, 0.f} : s[jj][t]);
;         }
;       __builtin_amdgcn_s_setprio(0);
;       bf16x8 pf[JB];
;       if (NT > JB) __builtin_amdgcn_sched_barrier(0);
; #pragma unroll
;       for (int jj = 0; jj < JB; ++jj) {
;         const int j = jh * JB + jj;
;         float mx = -INFINITY;
; #pragma unroll
;         for (int t = 0; t < 2; ++t)
; #pragma unroll
;           for (int i = 0; i < 4; ++i) {
;             if (MASK) { const int kp = kpos0 + 32 * st + 16 * t + 4 * lg + i; if (!mask_ok<MODE>(tq[j], kp, W)) s[jj][t][i] = -INFINITY; }
;             mx = fmaxf(mx, s[jj][t][i]);
;           }
;         mx = max_x16_x32(mx);
;         if (NT > 2 || __any(mx > m[j] + 8.0f / c)) {
;           const float mnew = fmaxf(m[j], mx);
;           const float ms2 = (mnew == -INFINITY) ? 0.f : mnew;
;           const float alpha = ex2((m[j] - ms2) * c);
;           m[j] = mnew; l[j] *= alpha;
; #pragma unroll
;           for (int dt = 0; dt < NDT; ++dt) o[j][dt] *= alpha;
;         }
;         const float mc = ((m[j] == -INFINITY) ? 0.f : m[j]) * c;
;         float p0[4], p1[4], ps = 0.f;
; #pragma unroll
;         for (int i = 0; i < 4; ++i) { p0[i] = ex2(s[jj][0][i] * c - mc); p1[i] = ex2(s[jj][1][i] * c - mc); ps += p0[i] + p1[i]; }
;         l[j] += ps;
;         pf[jj] = pack8(p0, p1);
;       }
;       if (NT > JB) __builtin_amdgcn_sched_barrier(0);
;       __builtin_amdgcn_s_setprio(1);
; #pragma unroll
;       for (int dt = 0; dt < NDT; ++dt) {
;         const s16x4 v0 = ds_tr(Vl + oz + (32 * st + 4 * lg + vq) * VSTR + (16 * dt + 4 * vp) * 2);
;         const s16x4 v1 = ds_tr(Vl + oz + (32 * st + 16 + 4 * lg + vq) * VSTR + (16 * dt + 4 * vp) * 2);
;         const bf16x8 vf = (bf16x8){v0[0], v0[1], v0[2], v0[3], v1[0], v1[1], v1[2], v1[3]};
; #pragma unroll
	v_mfma_f32_16x16x32_bf16 v[154:157], v[214:217], v[218:221], v[154:157]
	v_mfma_f32_16x16x32_bf16 v[122:125], v[214:217], v[210:213], v[122:125]
	ds_read_b64_tr_b16 v[214:215], v196 offset:9312
	ds_read_b64_tr_b16 v[216:217], v196 offset:11872
	v_mfma_f32_16x16x32_bf16 v[134:137], v[222:225], v[218:221], v[134:137]
	v_mfma_f32_16x16x32_bf16 v[106:109], v[222:225], v[210:213], v[106:109]
	s_waitcnt lgkmcnt(0)
	v_mfma_f32_16x16x32_bf16 v[162:165], v[214:217], v[218:221], v[162:165]
	v_mfma_f32_16x16x32_bf16 v[130:133], v[214:217], v[210:213], v[130:133]
	s_setprio 0
	v_mov_b32_e32 v246, 0
	s_setprio 1
	v_add3_u32 v196, v1, v246, v244
	ds_read_b128 v[210:213], v196
	ds_read_b128 v[214:217], v196 offset:64
	ds_read_b128 v[222:225], v196 offset:2304
	ds_read_b128 v[228:231], v196 offset:2368
	s_waitcnt lgkmcnt(3)
	v_mfma_f32_16x16x32_bf16 v[218:221], v[210:213], v[18:21], 0
	v_mfma_f32_16x16x32_bf16 v[210:213], v[210:213], v[26:29], 0
	s_waitcnt lgkmcnt(1)
	v_mfma_f32_16x16x32_bf16 v[236:239], v[222:225], v[18:21], 0
	v_mfma_f32_16x16x32_bf16 v[222:225], v[222:225], v[26:29], 0
	v_mfma_f32_16x16x32_bf16 v[218:221], v[214:217], v[22:25], v[218:221]
	v_mfma_f32_16x16x32_bf16 v[212:215], v[214:217], v[30:33], v[210:213]
	s_waitcnt lgkmcnt(0)
	v_mfma_f32_16x16x32_bf16 v[236:239], v[228:231], v[22:25], v[236:239]
	v_mfma_f32_16x16x32_bf16 v[222:225], v[228:231], v[30:33], v[222:225]
	s_setprio 0
	s_nop 1
	v_max3_f32 v196, v218, s81, v219
	v_max3_f32 v196, v196, v220, v221
	s_nop 1
	v_max3_f32 v196, v196, v236, v237
	v_max3_f32 v196, v196, v238, v239
	v_mov_b32_e32 v197, v196
	s_nop 1
	v_permlane16_swap_b32_e32 v196, v197
	v_max_f32_e32 v196, v196, v197
	v_mov_b32_e32 v197, v196
	s_nop 1
	v_permlane32_swap_b32_e32 v196, v197
	v_max3_f32 v209, v232, v196, v197
	v_cmp_eq_f32_e32 vcc, s81, v209
	s_nop 1
	v_cndmask_b32_e64 v196, v209, 0, vcc
	v_sub_f32_e32 v196, v232, v196
	v_mul_f32_e32 v196, 0x3e38aa3b, v196
	v_exp_f32_e32 v196, v196
	s_nop 0
	v_pk_mul_f32 v[152:153], v[152:153], v[196:197] op_sel_hi:[1,0]
	v_pk_mul_f32 v[150:151], v[150:151], v[196:197] op_sel_hi:[1,0]
	v_pk_mul_f32 v[148:149], v[148:149], v[196:197] op_sel_hi:[1,0]
	v_pk_mul_f32 v[146:147], v[146:147], v[196:197] op_sel_hi:[1,0]
	v_pk_mul_f32 v[160:161], v[160:161], v[196:197] op_sel_hi:[1,0]
	v_pk_mul_f32 v[158:159], v[158:159], v[196:197] op_sel_hi:[1,0]
	v_pk_mul_f32 v[168:169], v[168:169], v[196:197] op_sel_hi:[1,0]
	v_pk_mul_f32 v[166:167], v[166:167], v[196:197] op_sel_hi:[1,0]
	v_mul_f32_e32 v197, 0x3e38aa3b, v209
	v_cndmask_b32_e64 v197, v197, 0, vcc
	v_fma_f32 v198, v218, s42, -v197
	v_exp_f32_e32 v199, v198
	v_fma_f32 v198, v236, s42, -v197
	v_exp_f32_e32 v229, v198
	v_fma_f32 v198, v219, s42, -v197
	v_exp_f32_e32 v231, v198
	v_fma_f32 v198, v237, s42, -v197
	v_exp_f32_e32 v237, v198
	v_fma_f32 v198, v220, s42, -v197
	v_exp_f32_e32 v241, v198
	v_fma_f32 v198, v238, s42, -v197
	v_exp_f32_e32 v243, v198
	v_fma_f32 v198, v221, s42, -v197
	v_fma_f32 v197, v239, s42, -v197
	v_exp_f32_e32 v239, v197
	v_max3_f32 v197, v212, s81, v213
	v_max3_f32 v197, v197, v214, v215
	v_max3_f32 v197, v197, v222, v223
	v_max3_f32 v197, v197, v224, v225
	v_exp_f32_e32 v221, v198
	v_mov_b32_e32 v198, v197
	s_nop 1
	v_permlane16_swap_b32_e32 v197, v198
	v_max_f32_e32 v197, v197, v198
	v_mov_b32_e32 v198, v197
	s_nop 1
	v_permlane32_swap_b32_e32 v197, v198
	v_max3_f32 v210, v235, v197, v198
	v_cmp_eq_f32_e32 vcc, s81, v210
	v_cvt_pk_bf16_f32 v216, v199, v231
	v_cvt_pk_bf16_f32 v217, v241, v221
	v_cndmask_b32_e64 v197, v210, 0, vcc
	v_sub_f32_e32 v197, v235, v197
	v_mul_f32_e32 v197, 0x3e38aa3b, v197
	v_exp_f32_e32 v244, v197
	v_mul_f32_e32 v197, 0x3e38aa3b, v210
	v_cndmask_b32_e64 v197, v197, 0, vcc
	v_fma_f32 v211, v222, s42, -v197
	v_exp_f32_e32 v228, v211
	v_fma_f32 v211, v213, s42, -v197
	v_fma_f32 v198, v212, s42, -v197
	v_exp_f32_e32 v230, v211
	v_fma_f32 v211, v223, s42, -v197
	v_exp_f32_e32 v198, v198
	v_exp_f32_e32 v236, v211
	v_fma_f32 v211, v214, s42, -v197
	v_exp_f32_e32 v240, v211
	v_fma_f32 v211, v224, s42, -v197
	v_exp_f32_e32 v242, v211
	v_fma_f32 v211, v215, s42, -v197
	v_fma_f32 v197, v225, s42, -v197
	v_exp_f32_e32 v220, v211
	v_exp_f32_e32 v238, v197
	v_pk_mul_f32 v[120:121], v[120:121], v[244:245] op_sel_hi:[1,0]
	v_pk_mul_f32 v[118:119], v[118:119], v[244:245] op_sel_hi:[1,0]
	v_pk_mul_f32 v[116:117], v[116:117], v[244:245] op_sel_hi:[1,0]
	v_pk_mul_f32 v[114:115], v[114:115], v[244:245] op_sel_hi:[1,0]
	v_pk_mul_f32 v[128:129], v[128:129], v[244:245] op_sel_hi:[1,0]
	v_pk_mul_f32 v[126:127], v[126:127], v[244:245] op_sel_hi:[1,0]
	v_pk_mul_f32 v[144:145], v[144:145], v[244:245] op_sel_hi:[1,0]
	v_pk_mul_f32 v[142:143], v[142:143], v[244:245] op_sel_hi:[1,0]
	v_mov_b32_e32 v245, v196
	v_pk_add_f32 v[196:197], v[198:199], v[228:229]
	v_pk_add_f32 v[212:213], v[230:231], v[236:237]
	v_pk_add_f32 v[196:197], v[196:197], 0 op_sel_hi:[1,0]
	v_cvt_pk_bf16_f32 v218, v229, v237
	v_pk_add_f32 v[196:197], v[212:213], v[196:197]
	v_pk_add_f32 v[212:213], v[240:241], v[242:243]
	v_cvt_pk_bf16_f32 v219, v243, v239
	v_pk_add_f32 v[196:197], v[212:213], v[196:197]
	v_pk_add_f32 v[212:213], v[220:221], v[238:239]
	v_cvt_pk_bf16_f32 v214, v228, v236
	v_pk_add_f32 v[196:197], v[212:213], v[196:197]
	v_cvt_pk_bf16_f32 v212, v198, v230
	v_pk_fma_f32 v[182:183], v[182:183], v[244:245], v[196:197]
	v_cvt_pk_bf16_f32 v213, v240, v220
	v_cvt_pk_bf16_f32 v215, v242, v238
	s_setprio 1
	v_add3_u32 v196, v208, v246, v204
	ds_read_b64_tr_b16 v[222:223], v196 offset:11776
	ds_read_b64_tr_b16 v[220:221], v196 offset:9216
	ds_read_b64_tr_b16 v[228:229], v196 offset:9248
	ds_read_b64_tr_b16 v[230:231], v196 offset:11808
	s_waitcnt lgkmcnt(2)
	v_mfma_f32_16x16x32_bf16 v[150:153], v[220:223], v[216:219], v[150:153]
	v_mfma_f32_16x16x32_bf16 v[118:121], v[220:223], v[212:215], v[118:121]
	ds_read_b64_tr_b16 v[220:221], v196 offset:9280
	ds_read_b64_tr_b16 v[222:223], v196 offset:11840
	s_waitcnt lgkmcnt(0)
	v_mfma_f32_16x16x32_bf16 v[158:161], v[220:223], v[216:219], v[158:161]
	v_mfma_f32_16x16x32_bf16 v[126:129], v[220:223], v[212:215], v[126:129]
	ds_read_b64_tr_b16 v[220:221], v196 offset:9312
	ds_read_b64_tr_b16 v[222:223], v196 offset:11872
	v_mfma_f32_16x16x32_bf16 v[146:149], v[228:231], v[216:219], v[146:149]
	v_mfma_f32_16x16x32_bf16 v[114:117], v[228:231], v[212:215], v[114:117]
	s_waitcnt lgkmcnt(0)
	v_mfma_f32_16x16x32_bf16 v[166:169], v[220:223], v[216:219], v[166:169]
	v_mfma_f32_16x16x32_bf16 v[142:145], v[220:223], v[212:215], v[142:145]
	s_setprio 0
	s_mov_b32 s8, 32
	s_andn2_b64 vcc, exec, s[26:27]
	s_mov_b64 s[26:27], 0
	s_cbranch_vccz .LBB0_1126

; #define LAS __attribute__((address_space(3)))
; __device__ __forceinline__ float ex2(float x) { return __builtin_amdgcn_exp2f(x); }
; __device__ __forceinline__ f32x4 mfma16(bf16x8 a, bf16x8 b, f32x4 c) { return __builtin_amdgcn_mfma_f32_16x16x32_bf16(a, b, c, 0, 0, 0); }
;   __device__ __forceinline__ bf16_t* W() const { return (bf16_t*)(ws + WS_W); }
; template <int MODE> __device__ __forceinline__ bool mask_ok(int tq, int kp, int W) {
;     ...
;   if (MODE == MODE_CMP) return 16 * kp + 31 <= tq;
; template <int NT, int NKK, int NDT, int MODE, bool MASK> ...
;     ...
;     for (int jh = 0; jh < NT / JB; ++jh) {
;       int oz = 0; if (NT > JB) asm volatile("" : "+v"(oz));
;       f32x4 s[JB][2];
;       __builtin_amdgcn_s_setprio(1);
; #pragma unroll
;       for (int t = 0; t < 2; ++t)
; #pragma unroll
;         for (int kk = 0; kk < NKK; ++kk) {
;           const bf16x8 kf = *(LAS const bf16x8*)(Kl + oz + (32 * st + 16 * t + r) * KSTR + (32 * kk + 8 * lg) * 2);
; #pragma unroll
;           for (int jj = 0; jj < JB; ++jj) s[jj][t] = mfma16(kf, qf[jh * JB + jj][kk], kk == 0 ? (f32x4){0.f, 0.f, 0.f, 0.f} : s[jj][t]);
;         }
;       __builtin_amdgcn_s_setprio(0);
;       bf16x8 pf[JB];
;       if (NT > JB) __builtin_amdgcn_sched_barrier(0);
; #pragma unroll
;       for (int jj = 0; jj < JB; ++jj) {
;         const int j = jh * JB + jj;
;         float mx = -INFINITY;
; #pragma unroll
;         for (int t = 0; t < 2; ++t)
; #pragma unroll
;           for (int i = 0; i < 4; ++i) {
;             if (MASK) { const int kp = kpos0 + 32 * st + 16 * t + 4 * lg + i; if (!mask_ok<MODE>(tq[j], kp, W)) s[jj][t][i] = -INFINITY; }
;             mx = fmaxf(mx, s[jj][t][i]);
;           }
;         mx = max_x16_x32(mx);
;         if (NT > 2 || __any(mx > m[j] + 8.0f / c)) {
;           const float mnew = fmaxf(m[j], mx);
;           const float ms2 = (mnew == -INFINITY) ? 0.f : mnew;
;           const float alpha = ex2((m[j] - ms2) * c);
;           m[j] = mnew; l[j] *= alpha;
; #pragma unroll
;           for (int dt = 0; dt < NDT; ++dt) o[j][dt] *= alpha;
;         }
;         const float mc = ((m[j] == -INFINITY) ? 0.f : m[j]) * c;
;         float p0[4], p1[4], ps = 0.f;
; #pragma unroll
;         for (int i = 0; i < 4; ++i) { p0[i] = ex2(s[jj][0][i] * c - mc); p1[i] = ex2(s[jj][1][i] * c - mc); ps += p0[i] + p1[i]; }
;         l[j] += ps;
;         pf[jj] = pack8(p0, p1);
;       }
.LBB0_1129:
	v_or_b32_e32 v107, s8, v203
	v_mov_b32_e32 v111, s45
	v_mov_b32_e32 v141, 0
	v_mov_b32_e32 v109, v175
	v_mov_b32_e32 v130, v190
	v_mov_b32_e32 v140, v191
	v_mov_b32_e32 v108, v192
	v_or_b32_e32 v110, s8, v201
	v_or_b32_e32 v131, s8, v106
	v_mad_u32_u24 v107, v107, s80, v111
	s_setprio 1
	v_mul_u32_u24_e32 v142, 0x90, v110
	v_add3_u32 v122, v1, v141, v142
	ds_read_b128 v[110:113], v122
	ds_read_b128 v[114:117], v122 offset:64
	s_waitcnt lgkmcnt(1)
	v_mfma_f32_16x16x32_bf16 v[118:121], v[110:113], v[2:5], 0
	v_mfma_f32_16x16x32_bf16 v[110:113], v[110:113], v[10:13], 0
	s_waitcnt lgkmcnt(0)
	v_mfma_f32_16x16x32_bf16 v[118:121], v[114:117], v[6:9], v[118:121]
	v_mfma_f32_16x16x32_bf16 v[110:113], v[114:117], v[14:17], v[110:113]
	ds_read_b128 v[114:117], v122 offset:2304
	ds_read_b128 v[122:125], v122 offset:2368
	s_waitcnt lgkmcnt(1)
	v_mfma_f32_16x16x32_bf16 v[126:129], v[114:117], v[2:5], 0
	v_mfma_f32_16x16x32_bf16 v[114:117], v[114:117], v[10:13], 0
	s_waitcnt lgkmcnt(0)
	v_mfma_f32_16x16x32_bf16 v[126:129], v[122:125], v[6:9], v[126:129]
	v_mfma_f32_16x16x32_bf16 v[114:117], v[122:125], v[14:17], v[114:117]
	s_setprio 0
	v_lshlrev_b32_e32 v123, 4, v131
	v_or_b32_e32 v143, 31, v123
	v_mov_b32_e32 v122, s81
	v_cmp_gt_i32_e32 vcc, v143, v184
	v_or_b32_e32 v144, 47, v123
	v_or_b32_e32 v145, 63, v123
	v_cndmask_b32_e32 v124, v118, v122, vcc
	v_cmp_le_i32_e32 vcc, v144, v184
	v_add_u32_e32 v146, 0x4f, v123
	v_or_b32_e32 v147, 0x11f, v123
	v_cndmask_b32_e32 v119, v200, v119, vcc
	v_cmp_le_i32_e32 vcc, v145, v184
	v_max3_f32 v118, v124, s81, v119
	v_or_b32_e32 v148, 0x12f, v123
	v_cndmask_b32_e32 v120, v200, v120, vcc
	v_cmp_le_i32_e32 vcc, v146, v184
	v_or_b32_e32 v149, 0x13f, v123
	v_add_u32_e32 v150, 0x14f, v123
	v_cndmask_b32_e32 v121, v200, v121, vcc
	v_max3_f32 v122, v118, v120, v121
	v_mov_b32_e32 v118, s81
	v_cmp_gt_i32_e32 vcc, v147, v184
	s_nop 1
	v_cndmask_b32_e32 v118, v126, v118, vcc
	v_cmp_le_i32_e32 vcc, v148, v184
	s_nop 1
	v_cndmask_b32_e32 v126, v200, v127, vcc
	v_cmp_le_i32_e32 vcc, v149, v184
	v_max3_f32 v122, v122, v118, v126
	s_nop 0
	v_cndmask_b32_e32 v128, v200, v128, vcc
	v_cmp_le_i32_e32 vcc, v150, v184
	s_nop 1
	v_cndmask_b32_e32 v123, v200, v129, vcc
	v_max3_f32 v122, v122, v128, v123
	v_mov_b32_e32 v125, v122
	s_nop 1
	v_permlane16_swap_b32_e32 v122, v125
	v_max_f32_e32 v122, v122, v125
	v_mov_b32_e32 v125, v122
	s_nop 1
	v_permlane32_swap_b32_e32 v122, v125
	v_max3_f32 v175, v109, v122, v125
	v_cmp_eq_f32_e32 vcc, s81, v175
	s_nop 1
	v_cndmask_b32_e64 v122, v175, 0, vcc
	v_sub_f32_e32 v109, v109, v122
	v_mul_f32_e32 v109, 0x3e38aa3b, v109
	v_exp_f32_e32 v122, v109
	v_mul_f32_e32 v109, 0x3e38aa3b, v175
	v_cndmask_b32_e64 v109, v109, 0, vcc
	v_fma_f32 v118, v118, s42, -v109
	v_exp_f32_e32 v127, v118
	v_fma_f32 v118, v119, s42, -v109
	v_exp_f32_e32 v129, v118
	v_fma_f32 v118, v126, s42, -v109
	v_exp_f32_e32 v131, v118
	v_fma_f32 v118, v120, s42, -v109
	v_exp_f32_e32 v133, v118
	v_fma_f32 v118, v128, s42, -v109
	v_fma_f32 v124, v124, s42, -v109
	v_exp_f32_e32 v135, v118
	v_fma_f32 v118, v121, s42, -v109
	v_fma_f32 v109, v123, s42, -v109
	v_mov_b32_e32 v120, s81
	v_cmp_gt_i32_e32 vcc, v143, v185
	v_exp_f32_e32 v139, v109
	v_pk_mul_f32 v[92:93], v[92:93], v[122:123] op_sel_hi:[1,0]
	v_cndmask_b32_e32 v109, v110, v120, vcc
	v_cmp_le_i32_e32 vcc, v144, v185
	v_pk_mul_f32 v[90:91], v[90:91], v[122:123] op_sel_hi:[1,0]
	v_pk_mul_f32 v[88:89], v[88:89], v[122:123] op_sel_hi:[1,0]
	v_cndmask_b32_e32 v111, v200, v111, vcc
	v_cmp_le_i32_e32 vcc, v145, v185
	v_max3_f32 v110, v109, s81, v111
	v_pk_mul_f32 v[86:87], v[86:87], v[122:123] op_sel_hi:[1,0]
	v_cndmask_b32_e32 v112, v200, v112, vcc
	v_cmp_le_i32_e32 vcc, v146, v185
	v_pk_mul_f32 v[96:97], v[96:97], v[122:123] op_sel_hi:[1,0]
	v_pk_mul_f32 v[94:95], v[94:95], v[122:123] op_sel_hi:[1,0]
	v_cndmask_b32_e32 v113, v200, v113, vcc
	v_max3_f32 v119, v110, v112, v113
	v_mov_b32_e32 v110, s81
	v_cmp_gt_i32_e32 vcc, v147, v185
	v_pk_mul_f32 v[84:85], v[84:85], v[122:123] op_sel_hi:[1,0]
	v_pk_mul_f32 v[82:83], v[82:83], v[122:123] op_sel_hi:[1,0]
	v_cndmask_b32_e32 v114, v114, v110, vcc
	v_cmp_le_i32_e32 vcc, v148, v185
	v_exp_f32_e32 v125, v124
	v_exp_f32_e32 v137, v118
	v_cndmask_b32_e32 v115, v200, v115, vcc
	v_cmp_le_i32_e32 vcc, v149, v185
	v_max3_f32 v110, v119, v114, v115
	v_cvt_pk_bf16_f32 v118, v125, v129
	v_cndmask_b32_e32 v116, v200, v116, vcc
	v_cmp_le_i32_e32 vcc, v150, v185
	v_cvt_pk_bf16_f32 v120, v127, v131
	v_cvt_pk_bf16_f32 v121, v135, v139
	v_cndmask_b32_e32 v117, v200, v117, vcc
	v_max3_f32 v110, v110, v116, v117
	v_mov_b32_e32 v119, v110
	s_nop 1
	v_permlane16_swap_b32_e32 v110, v119
	v_max_f32_e32 v110, v110, v119
	v_mov_b32_e32 v119, v110
	s_nop 1
	v_permlane32_swap_b32_e32 v110, v119
	v_max3_f32 v190, v130, v110, v119
	v_cmp_eq_f32_e32 vcc, s81, v190
	v_mul_f32_e32 v123, 0x3e38aa3b, v190
	v_cvt_pk_bf16_f32 v119, v133, v137
	v_cndmask_b32_e64 v123, v123, 0, vcc
	v_fma_f32 v109, v109, s42, -v123
	v_exp_f32_e32 v124, v109
	v_fma_f32 v109, v114, s42, -v123
	v_exp_f32_e32 v126, v109
	v_fma_f32 v109, v111, s42, -v123
	v_cndmask_b32_e64 v110, v190, 0, vcc
	v_exp_f32_e32 v128, v109
	v_fma_f32 v109, v115, s42, -v123
	v_sub_f32_e32 v110, v130, v110
	v_exp_f32_e32 v130, v109
	v_fma_f32 v109, v112, s42, -v123
	v_exp_f32_e32 v132, v109
	v_fma_f32 v109, v116, s42, -v123
	v_exp_f32_e32 v134, v109
	v_fma_f32 v109, v113, s42, -v123
	v_exp_f32_e32 v136, v109
	v_fma_f32 v109, v117, s42, -v123
	v_mul_f32_e32 v110, 0x3e38aa3b, v110
	v_exp_f32_e32 v138, v109
	v_exp_f32_e32 v110, v110
	v_pk_add_f32 v[112:113], v[124:125], v[126:127]
	v_pk_add_f32 v[114:115], v[128:129], v[130:131]
	v_pk_add_f32 v[112:113], v[112:113], 0 op_sel_hi:[1,0]
	v_pk_mul_f32 v[80:81], v[80:81], v[110:111] op_sel_hi:[1,0]
	v_pk_add_f32 v[112:113], v[114:115], v[112:113]
	v_pk_add_f32 v[114:115], v[132:133], v[134:135]
	v_pk_mul_f32 v[78:79], v[78:79], v[110:111] op_sel_hi:[1,0]
	v_pk_add_f32 v[112:113], v[114:115], v[112:113]
	v_pk_add_f32 v[114:115], v[136:137], v[138:139]
	v_pk_mul_f32 v[76:77], v[76:77], v[110:111] op_sel_hi:[1,0]
	v_pk_mul_f32 v[74:75], v[74:75], v[110:111] op_sel_hi:[1,0]
	v_pk_mul_f32 v[72:73], v[72:73], v[110:111] op_sel_hi:[1,0]
	v_pk_mul_f32 v[70:71], v[70:71], v[110:111] op_sel_hi:[1,0]
	v_pk_mul_f32 v[68:69], v[68:69], v[110:111] op_sel_hi:[1,0]
	v_pk_mul_f32 v[66:67], v[66:67], v[110:111] op_sel_hi:[1,0]
	v_mov_b32_e32 v111, v122
	v_pk_add_f32 v[112:113], v[114:115], v[112:113]
	s_nop 0
	v_pk_fma_f32 v[172:173], v[172:173], v[110:111], v[112:113]
	v_cvt_pk_bf16_f32 v110, v124, v128
	v_cvt_pk_bf16_f32 v111, v132, v136
	v_cvt_pk_bf16_f32 v112, v126, v130
	v_cvt_pk_bf16_f32 v113, v134, v138
	s_setprio 1
	v_add3_u32 v109, v107, v141, v204
	ds_read_b64_tr_b16 v[116:117], v109 offset:11776
	ds_read_b64_tr_b16 v[114:115], v109 offset:9216
	ds_read_b64_tr_b16 v[122:123], v109 offset:9248
	ds_read_b64_tr_b16 v[124:125], v109 offset:11808
	s_waitcnt lgkmcnt(2)
; #define LAS __attribute__((address_space(3)))
; __device__ __forceinline__ float ex2(float x) { return __builtin_amdgcn_exp2f(x); }
; __device__ __forceinline__ f32x4 mfma16(bf16x8 a, bf16x8 b, f32x4 c) { return __builtin_amdgcn_mfma_f32_16x16x32_bf16(a, b, c, 0, 0, 0); }
;   __device__ __forceinline__ bf16_t* W() const { return (bf16_t*)(ws + WS_W); }
; template <int NT, int NKK, int NDT, int MODE, bool MASK> ...
;     ...
; #pragma unroll
;       for (int t = 0; t < 2; ++t)
; #pragma unroll
;         for (int kk = 0; kk < NKK; ++kk) {
;           const bf16x8 kf = *(LAS const bf16x8*)(Kl + oz + (32 * st + 16 * t + r) * KSTR + (32 * kk + 8 * lg) * 2);
; #pragma unroll
;           for (int jj = 0; jj < JB; ++jj) s[jj][t] = mfma16(kf, qf[jh * JB + jj][kk], kk == 0 ? (f32x4){0.f, 0.f, 0.f, 0.f} : s[jj][t]);
;         }
;       __builtin_amdgcn_s_setprio(0);
;       bf16x8 pf[JB];
;       if (NT > JB) __builtin_amdgcn_sched_barrier(0);
; #pragma unroll
;       for (int jj = 0; jj < JB; ++jj) {
;         const int j = jh * JB + jj;
;         float mx = -INFINITY;
; #pragma unroll
;         for (int t = 0; t < 2; ++t)
; #pragma unroll
;           for (int i = 0; i < 4; ++i) {
;             if (MASK) { const int kp = kpos0 + 32 * st + 16 * t + 4 * lg + i; if (!mask_ok<MODE>(tq[j], kp, W)) s[jj][t][i] = -INFINITY; }
;             mx = fmaxf(mx, s[jj][t][i]);
;           }
;         mx = max_x16_x32(mx);
;         if (NT > 2 || __any(mx > m[j] + 8.0f / c)) {
;           const float mnew = fmaxf(m[j], mx);
;           const float ms2 = (mnew == -INFINITY) ? 0.f : mnew;
;           const float alpha = ex2((m[j] - ms2) * c);
;           m[j] = mnew; l[j] *= alpha;
; #pragma unroll
;           for (int dt = 0; dt < NDT; ++dt) o[j][dt] *= alpha;
;         }
;         const float mc = ((m[j] == -INFINITY) ? 0.f : m[j]) * c;
;         float p0[4], p1[4], ps = 0.f;
; #pragma unroll
;         for (int i = 0; i < 4; ++i) { p0[i] = ex2(s[jj][0][i] * c - mc); p1[i] = ex2(s[jj][1][i] * c - mc); ps += p0[i] + p1[i]; }
;         l[j] += ps;
;         pf[jj] = pack8(p0, p1);
;       }
	v_mfma_f32_16x16x32_bf16 v[90:93], v[114:117], v[118:121], v[90:93]
	v_mfma_f32_16x16x32_bf16 v[78:81], v[114:117], v[110:113], v[78:81]
	ds_read_b64_tr_b16 v[114:115], v109 offset:9280
	ds_read_b64_tr_b16 v[116:117], v109 offset:11840
	s_waitcnt lgkmcnt(0)
	v_mfma_f32_16x16x32_bf16 v[94:97], v[114:117], v[118:121], v[94:97]
	v_mfma_f32_16x16x32_bf16 v[70:73], v[114:117], v[110:113], v[70:73]
	ds_read_b64_tr_b16 v[114:115], v109 offset:9312
	ds_read_b64_tr_b16 v[116:117], v109 offset:11872
	v_mfma_f32_16x16x32_bf16 v[86:89], v[122:125], v[118:121], v[86:89]
	v_mfma_f32_16x16x32_bf16 v[74:77], v[122:125], v[110:113], v[74:77]
	s_waitcnt lgkmcnt(0)
	v_mfma_f32_16x16x32_bf16 v[82:85], v[114:117], v[118:121], v[82:85]
	v_mfma_f32_16x16x32_bf16 v[66:69], v[114:117], v[110:113], v[66:69]
	s_setprio 0
	v_mov_b32_e32 v138, 0
	s_setprio 1
	v_add3_u32 v109, v1, v138, v142
	ds_read_b128 v[110:113], v109
	ds_read_b128 v[114:117], v109 offset:64
	s_waitcnt lgkmcnt(1)
	v_mfma_f32_16x16x32_bf16 v[118:121], v[110:113], v[18:21], 0
	v_mfma_f32_16x16x32_bf16 v[110:113], v[110:113], v[26:29], 0
	s_waitcnt lgkmcnt(0)
	v_mfma_f32_16x16x32_bf16 v[118:121], v[114:117], v[22:25], v[118:121]
	v_mfma_f32_16x16x32_bf16 v[110:113], v[114:117], v[30:33], v[110:113]
	ds_read_b128 v[114:117], v109 offset:2304
	ds_read_b128 v[122:125], v109 offset:2368
	s_waitcnt lgkmcnt(1)
	v_mfma_f32_16x16x32_bf16 v[126:129], v[114:117], v[18:21], 0
	v_mfma_f32_16x16x32_bf16 v[114:117], v[114:117], v[26:29], 0
	s_waitcnt lgkmcnt(0)
	v_mfma_f32_16x16x32_bf16 v[126:129], v[122:125], v[22:25], v[126:129]
	v_mfma_f32_16x16x32_bf16 v[114:117], v[122:125], v[30:33], v[114:117]
	s_setprio 0
	v_mov_b32_e32 v122, s81
	v_cmp_gt_i32_e32 vcc, v143, v186
	s_nop 1
	v_cndmask_b32_e32 v109, v118, v122, vcc
	v_cmp_le_i32_e32 vcc, v144, v186
	s_nop 1
	v_cndmask_b32_e32 v119, v200, v119, vcc
	v_cmp_le_i32_e32 vcc, v145, v186
	v_max3_f32 v118, v109, s81, v119
	s_nop 0
	v_cndmask_b32_e32 v120, v200, v120, vcc
	v_cmp_le_i32_e32 vcc, v146, v186
	s_nop 1
	v_cndmask_b32_e32 v121, v200, v121, vcc
	v_max3_f32 v122, v118, v120, v121
	v_mov_b32_e32 v118, s81
	v_cmp_gt_i32_e32 vcc, v147, v186
	s_nop 1
	v_cndmask_b32_e32 v118, v126, v118, vcc
	v_cmp_le_i32_e32 vcc, v148, v186
	s_nop 1
	v_cndmask_b32_e32 v123, v200, v127, vcc
	v_cmp_le_i32_e32 vcc, v149, v186
	v_max3_f32 v122, v122, v118, v123
	s_nop 0
	v_cndmask_b32_e32 v124, v200, v128, vcc
	v_cmp_le_i32_e32 vcc, v150, v186
	s_nop 1
	v_cndmask_b32_e32 v126, v200, v129, vcc
	v_max3_f32 v122, v122, v124, v126
	v_mov_b32_e32 v125, v122
	s_nop 1
	v_permlane16_swap_b32_e32 v122, v125
	v_max_f32_e32 v122, v122, v125
	v_mov_b32_e32 v125, v122
	s_nop 1
	v_permlane32_swap_b32_e32 v122, v125
	v_max3_f32 v191, v140, v122, v125
	v_cmp_eq_f32_e32 vcc, s81, v191
	v_mul_f32_e32 v125, 0x3e38aa3b, v191
	s_nop 0
	v_cndmask_b32_e64 v122, v191, 0, vcc
	v_sub_f32_e32 v122, v140, v122
	v_mul_f32_e32 v122, 0x3e38aa3b, v122
	v_cndmask_b32_e64 v128, v125, 0, vcc
	v_exp_f32_e32 v122, v122
	v_fma_f32 v118, v118, s42, -v128
	v_exp_f32_e32 v125, v118
	v_fma_f32 v118, v119, s42, -v128
	v_exp_f32_e32 v127, v118
	v_fma_f32 v118, v123, s42, -v128
	v_exp_f32_e32 v129, v118
	v_fma_f32 v118, v120, s42, -v128
	v_mov_b32_e32 v120, s81
	v_cmp_gt_i32_e32 vcc, v143, v187
	v_pk_mul_f32 v[64:65], v[64:65], v[122:123] op_sel_hi:[1,0]
	v_pk_mul_f32 v[62:63], v[62:63], v[122:123] op_sel_hi:[1,0]
	v_pk_mul_f32 v[60:61], v[60:61], v[122:123] op_sel_hi:[1,0]
	v_pk_mul_f32 v[58:59], v[58:59], v[122:123] op_sel_hi:[1,0]
	v_pk_mul_f32 v[52:53], v[52:53], v[122:123] op_sel_hi:[1,0]
	v_pk_mul_f32 v[50:51], v[50:51], v[122:123] op_sel_hi:[1,0]
	v_pk_mul_f32 v[56:57], v[56:57], v[122:123] op_sel_hi:[1,0]
	v_pk_mul_f32 v[54:55], v[54:55], v[122:123] op_sel_hi:[1,0]
	v_cndmask_b32_e32 v123, v110, v120, vcc
	v_cmp_le_i32_e32 vcc, v144, v187
	v_exp_f32_e32 v131, v118
	v_fma_f32 v118, v124, s42, -v128
	v_cndmask_b32_e32 v111, v200, v111, vcc
	v_cmp_le_i32_e32 vcc, v145, v187
	v_max3_f32 v110, v123, s81, v111
	v_exp_f32_e32 v133, v118
	v_cndmask_b32_e32 v112, v200, v112, vcc
	v_cmp_le_i32_e32 vcc, v146, v187
	v_fma_f32 v118, v121, s42, -v128
	v_exp_f32_e32 v135, v118
	v_cndmask_b32_e32 v113, v200, v113, vcc
	v_max3_f32 v119, v110, v112, v113
	v_mov_b32_e32 v110, s81
	v_cmp_gt_i32_e32 vcc, v147, v187
	v_fma_f32 v118, v126, s42, -v128
	v_fma_f32 v109, v109, s42, -v128
	v_cndmask_b32_e32 v114, v114, v110, vcc
	v_cmp_le_i32_e32 vcc, v148, v187
	v_exp_f32_e32 v109, v109
	v_exp_f32_e32 v137, v118
	v_cndmask_b32_e32 v115, v200, v115, vcc
	v_cmp_le_i32_e32 vcc, v149, v187
	v_max3_f32 v110, v119, v114, v115
	v_cvt_pk_bf16_f32 v118, v109, v127
	v_cndmask_b32_e32 v116, v200, v116, vcc
	v_cmp_le_i32_e32 vcc, v150, v187
	v_cvt_pk_bf16_f32 v120, v125, v129
; __device__ __forceinline__ float ex2(float x) { return __builtin_amdgcn_exp2f(x); }
; __device__ __forceinline__ f32x4 mfma16(bf16x8 a, bf16x8 b, f32x4 c) { return __builtin_amdgcn_mfma_f32_16x16x32_bf16(a, b, c, 0, 0, 0); }
; __device__ __forceinline__ s16x4 ds_tr(LAS const unsigned char* p) { return __builtin_bit_cast(s16x4, __builtin_amdgcn_ds_read_tr16_b64_v4i16((LAS v4i16_t*)p)); }
; template <int NT, int NKK, int NDT, int MODE, bool MASK> ...
;     ...
;             mx = fmaxf(mx, s[jj][t][i]);
;           }
;         mx = max_x16_x32(mx);
;         if (NT > 2 || __any(mx > m[j] + 8.0f / c)) {
;           const float mnew = fmaxf(m[j], mx);
;           const float ms2 = (mnew == -INFINITY) ? 0.f : mnew;
;           const float alpha = ex2((m[j] - ms2) * c);
;           m[j] = mnew; l[j] *= alpha;
; #pragma unroll
;           for (int dt = 0; dt < NDT; ++dt) o[j][dt] *= alpha;
;         }
;         const float mc = ((m[j] == -INFINITY) ? 0.f : m[j]) * c;
;         float p0[4], p1[4], ps = 0.f;
; #pragma unroll
;         for (int i = 0; i < 4; ++i) { p0[i] = ex2(s[jj][0][i] * c - mc); p1[i] = ex2(s[jj][1][i] * c - mc); ps += p0[i] + p1[i]; }
;         l[j] += ps;
;         pf[jj] = pack8(p0, p1);
;       }
;       if (NT > JB) __builtin_amdgcn_sched_barrier(0);
;       __builtin_amdgcn_s_setprio(1);
; #pragma unroll
;       for (int dt = 0; dt < NDT; ++dt) {
;         const s16x4 v0 = ds_tr(Vl + oz + (32 * st + 4 * lg + vq) * VSTR + (16 * dt + 4 * vp) * 2);
;         const s16x4 v1 = ds_tr(Vl + oz + (32 * st + 16 + 4 * lg + vq) * VSTR + (16 * dt + 4 * vp) * 2);
;         const bf16x8 vf = (bf16x8){v0[0], v0[1], v0[2], v0[3], v1[0], v1[1], v1[2], v1[3]};
; #pragma unroll
;         for (int jj = 0; jj < JB; ++jj) o[jh * JB + jj][dt] = mfma16(vf, pf[jj], o[jh * JB + jj][dt]);
;       }
;       __builtin_amdgcn_s_setprio(0);
;       if (NT > JB) __builtin_amdgcn_sched_barrier(0);
	v_cvt_pk_bf16_f32 v121, v133, v137
	v_cndmask_b32_e32 v117, v200, v117, vcc
	v_max3_f32 v110, v110, v116, v117
	v_mov_b32_e32 v119, v110
	s_nop 1
	v_permlane16_swap_b32_e32 v110, v119
	v_max_f32_e32 v110, v110, v119
	v_mov_b32_e32 v119, v110
	s_nop 1
	v_permlane32_swap_b32_e32 v110, v119
	v_max3_f32 v192, v108, v110, v119
	v_cmp_eq_f32_e32 vcc, s81, v192
	v_cvt_pk_bf16_f32 v119, v131, v135
	s_nop 0
	v_cndmask_b32_e64 v110, v192, 0, vcc
	v_sub_f32_e32 v108, v108, v110
	v_mul_f32_e32 v108, 0x3e38aa3b, v108
	v_exp_f32_e32 v110, v108
	v_mul_f32_e32 v108, 0x3e38aa3b, v192
	v_cndmask_b32_e64 v136, v108, 0, vcc
	v_fma_f32 v108, v123, s42, -v136
	v_pk_mul_f32 v[48:49], v[48:49], v[110:111] op_sel_hi:[1,0]
	v_pk_mul_f32 v[46:47], v[46:47], v[110:111] op_sel_hi:[1,0]
	v_pk_mul_f32 v[44:45], v[44:45], v[110:111] op_sel_hi:[1,0]
	v_pk_mul_f32 v[42:43], v[42:43], v[110:111] op_sel_hi:[1,0]
	v_pk_mul_f32 v[36:37], v[36:37], v[110:111] op_sel_hi:[1,0]
	v_pk_mul_f32 v[34:35], v[34:35], v[110:111] op_sel_hi:[1,0]
	v_pk_mul_f32 v[40:41], v[40:41], v[110:111] op_sel_hi:[1,0]
	v_pk_mul_f32 v[38:39], v[38:39], v[110:111] op_sel_hi:[1,0]
	v_fma_f32 v111, v111, s42, -v136
	v_exp_f32_e32 v126, v111
	v_fma_f32 v111, v115, s42, -v136
	v_fma_f32 v114, v114, s42, -v136
	v_exp_f32_e32 v128, v111
	v_fma_f32 v111, v112, s42, -v136
	v_exp_f32_e32 v108, v108
	v_exp_f32_e32 v124, v114
	v_exp_f32_e32 v130, v111
	v_fma_f32 v111, v116, s42, -v136
	v_exp_f32_e32 v132, v111
	v_fma_f32 v111, v113, s42, -v136
	v_exp_f32_e32 v134, v111
	v_fma_f32 v111, v117, s42, -v136
	v_exp_f32_e32 v136, v111
	v_pk_add_f32 v[112:113], v[108:109], v[124:125]
	v_pk_add_f32 v[114:115], v[126:127], v[128:129]
	v_pk_add_f32 v[112:113], v[112:113], 0 op_sel_hi:[1,0]
	v_mov_b32_e32 v111, v122
	v_pk_add_f32 v[112:113], v[114:115], v[112:113]
	v_pk_add_f32 v[114:115], v[130:131], v[132:133]
	v_cvt_pk_bf16_f32 v108, v108, v126
	v_pk_add_f32 v[112:113], v[114:115], v[112:113]
	v_pk_add_f32 v[114:115], v[134:135], v[136:137]
	v_cvt_pk_bf16_f32 v109, v130, v134
	v_pk_add_f32 v[112:113], v[114:115], v[112:113]
	s_nop 0
	v_pk_fma_f32 v[170:171], v[170:171], v[110:111], v[112:113]
	v_cvt_pk_bf16_f32 v110, v124, v128
	v_cvt_pk_bf16_f32 v111, v132, v136
	s_setprio 1
	v_add3_u32 v107, v107, v138, v204
	ds_read_b64_tr_b16 v[114:115], v107 offset:11776
	ds_read_b64_tr_b16 v[112:113], v107 offset:9216
	ds_read_b64_tr_b16 v[122:123], v107 offset:9248
	ds_read_b64_tr_b16 v[124:125], v107 offset:11808
	s_waitcnt lgkmcnt(2)
	v_mfma_f32_16x16x32_bf16 v[62:65], v[112:115], v[118:121], v[62:65]
	v_mfma_f32_16x16x32_bf16 v[46:49], v[112:115], v[108:111], v[46:49]
	ds_read_b64_tr_b16 v[112:113], v107 offset:9280
	ds_read_b64_tr_b16 v[114:115], v107 offset:11840
	s_waitcnt lgkmcnt(0)
	v_mfma_f32_16x16x32_bf16 v[50:53], v[112:115], v[118:121], v[50:53]
	v_mfma_f32_16x16x32_bf16 v[34:37], v[112:115], v[108:111], v[34:37]
	ds_read_b64_tr_b16 v[112:113], v107 offset:9312
	ds_read_b64_tr_b16 v[114:115], v107 offset:11872
	v_mfma_f32_16x16x32_bf16 v[58:61], v[122:125], v[118:121], v[58:61]
	v_mfma_f32_16x16x32_bf16 v[42:45], v[122:125], v[108:111], v[42:45]
	s_waitcnt lgkmcnt(0)
	v_mfma_f32_16x16x32_bf16 v[54:57], v[112:115], v[118:121], v[54:57]
	v_mfma_f32_16x16x32_bf16 v[38:41], v[112:115], v[108:111], v[38:41]
	s_setprio 0
	s_mov_b32 s8, 32
	s_andn2_b64 vcc, exec, s[26:27]
	s_mov_b64 s[26:27], 0
	s_cbranch_vccz .LBB0_1129
	s_branch .Lrt_skip_0
	v_mov_b64_e32 v[140:141], v[92:93]
	v_mov_b64_e32 v[136:137], v[88:89]
	v_mov_b64_e32 v[156:157], v[96:97]
	v_mov_b64_e32 v[164:165], v[84:85]
	v_mov_b64_e32 v[112:113], v[80:81]
	v_mov_b64_e32 v[108:109], v[76:77]
	v_mov_b64_e32 v[124:125], v[72:73]
	v_mov_b64_e32 v[132:133], v[68:69]
	v_mov_b64_e32 v[152:153], v[64:65]
	v_mov_b64_e32 v[148:149], v[60:61]
	v_mov_b64_e32 v[160:161], v[52:53]
	v_mov_b64_e32 v[168:169], v[56:57]
	v_mov_b64_e32 v[120:121], v[48:49]
	v_mov_b64_e32 v[116:117], v[44:45]
	v_mov_b64_e32 v[128:129], v[36:37]
	v_mov_b64_e32 v[144:145], v[40:41]
	v_mov_b64_e32 v[180:181], v[172:173]
	v_mov_b64_e32 v[182:183], v[170:171]
	v_mov_b32_e32 v206, v175
	v_mov_b64_e32 v[138:139], v[90:91]
	v_mov_b64_e32 v[134:135], v[86:87]
	v_mov_b64_e32 v[154:155], v[94:95]
	v_mov_b64_e32 v[162:163], v[82:83]
	v_mov_b32_e32 v207, v190
	v_mov_b64_e32 v[110:111], v[78:79]
	v_mov_b64_e32 v[106:107], v[74:75]
	v_mov_b64_e32 v[122:123], v[70:71]
	v_mov_b64_e32 v[130:131], v[66:67]
	v_mov_b32_e32 v209, v191
	v_mov_b64_e32 v[150:151], v[62:63]
	v_mov_b64_e32 v[146:147], v[58:59]
	v_mov_b64_e32 v[158:159], v[50:51]
	v_mov_b64_e32 v[166:167], v[54:55]
	v_mov_b32_e32 v210, v192
	v_mov_b64_e32 v[118:119], v[46:47]
	v_mov_b64_e32 v[114:115], v[42:43]
	v_mov_b64_e32 v[126:127], v[34:35]
	v_mov_b64_e32 v[142:143], v[38:39]

; template <int NT, int DQK, int DV, int MODE, int PD, class Src> ...
;     ...
;   for (int kcb = kc0; kcb < kc1; kcb += PD) {
; #pragma unroll
;     for (int u = 0; u < PD; ++u) {
;       const int kc = kcb + u;
;       if (kc < kc1) {
.Lrt_skip_0:
.LBB0_1132:
	s_cmp_lg_u32 s44, s47
	s_cbranch_scc0 .LBB0_1134
	s_mov_b32 s53, s44
	s_branch .LBB0_1115

; #define LAS __attribute__((address_space(3)))
; __device__ __forceinline__ float ex2(float x) { return __builtin_amdgcn_exp2f(x); }
; __device__ __forceinline__ f32x4 mfma16(bf16x8 a, bf16x8 b, f32x4 c) { return __builtin_amdgcn_mfma_f32_16x16x32_bf16(a, b, c, 0, 0, 0); }
;   __device__ __forceinline__ bf16_t* W() const { return (bf16_t*)(ws + WS_W); }
; template <int MODE> __device__ __forceinline__ bool mask_ok(int tq, int kp, int W) {
;     ...
;   if (MODE == MODE_WINDOW) return kp <= tq && kp > tq - W;
; template <int NT, int NKK, int NDT, int MODE, bool MASK> ...
;     ...
; #pragma unroll
;       for (int t = 0; t < 2; ++t)
; #pragma unroll
;         for (int kk = 0; kk < NKK; ++kk) {
;           const bf16x8 kf = *(LAS const bf16x8*)(Kl + oz + (32 * st + 16 * t + r) * KSTR + (32 * kk + 8 * lg) * 2);
; #pragma unroll
;           for (int jj = 0; jj < JB; ++jj) s[jj][t] = mfma16(kf, qf[jh * JB + jj][kk], kk == 0 ? (f32x4){0.f, 0.f, 0.f, 0.f} : s[jj][t]);
;         }
;       __builtin_amdgcn_s_setprio(0);
;       bf16x8 pf[JB];
;       if (NT > JB) __builtin_amdgcn_sched_barrier(0);
; #pragma unroll
;       for (int jj = 0; jj < JB; ++jj) {
;         const int j = jh * JB + jj;
;         float mx = -INFINITY;
; #pragma unroll
;         for (int t = 0; t < 2; ++t)
; #pragma unroll
;           for (int i = 0; i < 4; ++i) {
;             if (MASK) { const int kp = kpos0 + 32 * st + 16 * t + 4 * lg + i; if (!mask_ok<MODE>(tq[j], kp, W)) s[jj][t][i] = -INFINITY; }
;             mx = fmaxf(mx, s[jj][t][i]);
;           }
;         mx = max_x16_x32(mx);
;         if (NT > 2 || __any(mx > m[j] + 8.0f / c)) {
;           const float mnew = fmaxf(m[j], mx);
;           const float ms2 = (mnew == -INFINITY) ? 0.f : mnew;
;           const float alpha = ex2((m[j] - ms2) * c);
;           m[j] = mnew; l[j] *= alpha;
; #pragma unroll
;           for (int dt = 0; dt < NDT; ++dt) o[j][dt] *= alpha;
;         }
;         const float mc = ((m[j] == -INFINITY) ? 0.f : m[j]) * c;
;         float p0[4], p1[4], ps = 0.f;
; #pragma unroll
;         for (int i = 0; i < 4; ++i) { p0[i] = ex2(s[jj][0][i] * c - mc); p1[i] = ex2(s[jj][1][i] * c - mc); ps += p0[i] + p1[i]; }
;         l[j] += ps;
;         pf[jj] = pack8(p0, p1);
;       }
.LBB0_1199:
	v_mov_b32_e32 v197, v207
	v_mov_b32_e32 v232, v213
	v_mov_b32_e32 v211, v212
	v_or_b32_e32 v212, s8, v208
	v_or_b32_e32 v198, s8, v191
	v_mov_b32_e32 v207, s75
	v_mov_b32_e32 v213, 0
	v_mov_b32_e32 v199, v209
	v_or_b32_e32 v196, s8, v189
	v_mad_u32_u24 v210, v198, s80, v207
	s_setprio 1
	v_mul_u32_u24_e32 v235, 0x90, v196
	v_add3_u32 v196, v1, v213, v235
	ds_read_b128 v[214:217], v196
	ds_read_b128 v[218:221], v196 offset:64
	s_waitcnt lgkmcnt(1)
	v_mfma_f32_16x16x32_bf16 v[222:225], v[214:217], v[54:57], 0
	v_mfma_f32_16x16x32_bf16 v[214:217], v[214:217], v[62:65], 0
	s_waitcnt lgkmcnt(0)
	v_mfma_f32_16x16x32_bf16 v[222:225], v[218:221], v[58:61], v[222:225]
	v_mfma_f32_16x16x32_bf16 v[214:217], v[218:221], v[66:69], v[214:217]
	ds_read_b128 v[218:221], v196 offset:2304
	ds_read_b128 v[228:231], v196 offset:2368
	s_waitcnt lgkmcnt(1)
	v_mfma_f32_16x16x32_bf16 v[236:239], v[218:221], v[54:57], 0
	v_mfma_f32_16x16x32_bf16 v[218:221], v[218:221], v[62:65], 0
	s_waitcnt lgkmcnt(0)
	v_mfma_f32_16x16x32_bf16 v[236:239], v[228:231], v[58:61], v[236:239]
	v_mfma_f32_16x16x32_bf16 v[218:221], v[228:231], v[66:69], v[218:221]
	s_setprio 0
	v_cmp_le_i32_e32 vcc, v212, v184
	v_cmp_gt_i32_e64 s[12:13], v212, v194
	v_mov_b32_e32 v196, s81
	s_and_b64 vcc, vcc, s[12:13]
	v_cndmask_b32_e32 v209, v196, v222, vcc
	v_cmp_lt_i32_e32 vcc, v212, v184
	v_cmp_ge_i32_e64 s[12:13], v212, v194
	s_and_b64 vcc, vcc, s[12:13]
	v_or_b32_e32 v246, 2, v212
	v_cndmask_b32_e32 v222, v200, v223, vcc
	v_cmp_le_i32_e32 vcc, v246, v184
	v_cmp_gt_i32_e64 s[12:13], v246, v194
	s_and_b64 vcc, vcc, s[12:13]
	v_or_b32_e32 v247, 3, v212
	v_cndmask_b32_e32 v223, v200, v224, vcc
	v_cmp_le_i32_e32 vcc, v247, v184
	v_cmp_gt_i32_e64 s[12:13], v247, v194
	s_and_b64 vcc, vcc, s[12:13]
	v_or_b32_e32 v248, 16, v212
	v_max3_f32 v196, v209, s81, v222
	v_cndmask_b32_e32 v224, v200, v225, vcc
	v_cmp_le_i32_e32 vcc, v248, v184
	v_cmp_gt_i32_e64 s[12:13], v248, v194
	v_max3_f32 v198, v196, v223, v224
	v_mov_b32_e32 v196, s81
	s_and_b64 vcc, vcc, s[12:13]
	v_or_b32_e32 v249, 17, v212
	v_cndmask_b32_e32 v196, v196, v236, vcc
	v_cmp_le_i32_e32 vcc, v249, v184
	v_cmp_gt_i32_e64 s[12:13], v249, v194
	s_and_b64 vcc, vcc, s[12:13]
	v_or_b32_e32 v250, 18, v212
	v_cndmask_b32_e32 v225, v200, v237, vcc
	v_cmp_le_i32_e32 vcc, v250, v184
	v_cmp_gt_i32_e64 s[12:13], v250, v194
	s_and_b64 vcc, vcc, s[12:13]
	v_or_b32_e32 v251, 19, v212
	v_cndmask_b32_e32 v228, v200, v238, vcc
	v_cmp_le_i32_e32 vcc, v251, v184
	v_cmp_gt_i32_e64 s[12:13], v251, v194
	s_and_b64 vcc, vcc, s[12:13]
	v_max3_f32 v198, v198, v196, v225
	v_cndmask_b32_e32 v230, v200, v239, vcc
	v_max3_f32 v198, v198, v228, v230
	v_mov_b32_e32 v207, v198
	s_nop 1
	v_permlane16_swap_b32_e32 v198, v207
	v_max_f32_e32 v198, v198, v207
	v_mov_b32_e32 v207, v198
	s_nop 1
	v_permlane32_swap_b32_e32 v198, v207
	v_max3_f32 v207, v197, v198, v207
	v_cmp_eq_f32_e32 vcc, s81, v207
	v_cmp_gt_i32_e64 s[12:13], v212, v195
	s_nop 0
	v_cndmask_b32_e64 v198, v207, 0, vcc
	v_sub_f32_e32 v197, v197, v198
	v_mul_f32_e32 v197, 0x3e38aa3b, v197
	v_exp_f32_e32 v198, v197
	v_mul_f32_e32 v197, 0x3e38aa3b, v207
	v_cndmask_b32_e64 v236, v197, 0, vcc
	v_fma_f32 v196, v196, s42, -v236
	v_exp_f32_e32 v229, v196
	v_fma_f32 v196, v222, s42, -v236
	v_exp_f32_e32 v231, v196
	v_fma_f32 v196, v225, s42, -v236
	v_exp_f32_e32 v237, v196
	v_fma_f32 v196, v223, s42, -v236
	v_exp_f32_e32 v239, v196
	v_fma_f32 v196, v228, s42, -v236
	v_exp_f32_e32 v241, v196
	v_fma_f32 v196, v224, s42, -v236
	v_exp_f32_e32 v243, v196
	v_fma_f32 v196, v230, s42, -v236
	v_cmp_le_i32_e32 vcc, v212, v185
	v_exp_f32_e32 v245, v196
	v_mov_b32_e32 v196, s81
	s_and_b64 vcc, vcc, s[12:13]
	v_cndmask_b32_e32 v228, v196, v214, vcc
	v_cmp_lt_i32_e32 vcc, v212, v185
	v_cmp_ge_i32_e64 s[12:13], v212, v195
	s_and_b64 vcc, vcc, s[12:13]
	v_cndmask_b32_e32 v215, v200, v215, vcc
	v_cmp_le_i32_e32 vcc, v246, v185
	v_cmp_gt_i32_e64 s[12:13], v246, v195
	s_and_b64 vcc, vcc, s[12:13]
	v_cndmask_b32_e32 v216, v200, v216, vcc
	v_cmp_le_i32_e32 vcc, v247, v185
	v_cmp_gt_i32_e64 s[12:13], v247, v195
	s_and_b64 vcc, vcc, s[12:13]
	v_max3_f32 v196, v228, s81, v215
	v_cndmask_b32_e32 v217, v200, v217, vcc
	v_cmp_le_i32_e32 vcc, v248, v185
	v_cmp_gt_i32_e64 s[12:13], v248, v195
	v_fma_f32 v197, v209, s42, -v236
	v_max3_f32 v209, v196, v216, v217
	v_mov_b32_e32 v196, s81
	s_and_b64 vcc, vcc, s[12:13]
	v_cndmask_b32_e32 v218, v196, v218, vcc
	v_cmp_le_i32_e32 vcc, v249, v185
	v_cmp_gt_i32_e64 s[12:13], v249, v195
	s_and_b64 vcc, vcc, s[12:13]
	v_cndmask_b32_e32 v219, v200, v219, vcc
	v_cmp_le_i32_e32 vcc, v250, v185
	v_cmp_gt_i32_e64 s[12:13], v250, v195
	s_and_b64 vcc, vcc, s[12:13]
	v_cndmask_b32_e32 v220, v200, v220, vcc
	v_cmp_le_i32_e32 vcc, v251, v185
	v_cmp_gt_i32_e64 s[12:13], v251, v195
	s_and_b64 vcc, vcc, s[12:13]
	v_max3_f32 v196, v209, v218, v219
	v_cndmask_b32_e32 v221, v200, v221, vcc
	v_max3_f32 v196, v196, v220, v221
	v_mov_b32_e32 v209, v196
	s_nop 1
	v_permlane16_swap_b32_e32 v196, v209
	v_max_f32_e32 v196, v196, v209
	v_mov_b32_e32 v209, v196
	s_nop 1
	v_permlane32_swap_b32_e32 v196, v209
	v_max3_f32 v209, v199, v196, v209
	v_cmp_eq_f32_e32 vcc, s81, v209
	v_pk_mul_f32 v[144:145], v[144:145], v[198:199] op_sel_hi:[1,0]
	v_pk_mul_f32 v[142:143], v[142:143], v[198:199] op_sel_hi:[1,0]
	v_cndmask_b32_e64 v196, v209, 0, vcc
	v_sub_f32_e32 v196, v199, v196
	v_mul_f32_e32 v196, 0x3e38aa3b, v196
	v_exp_f32_e32 v214, v196
	v_mul_f32_e32 v196, 0x3e38aa3b, v209
	v_pk_mul_f32 v[140:141], v[140:141], v[198:199] op_sel_hi:[1,0]
	v_pk_mul_f32 v[138:139], v[138:139], v[198:199] op_sel_hi:[1,0]
; #define LAS __attribute__((address_space(3)))
; template <int NT, int NKK, int NDT, int MODE, bool MASK> ...
;     ...
; #pragma unroll
;       for (int t = 0; t < 2; ++t)
; #pragma unroll
;         for (int kk = 0; kk < NKK; ++kk) {
;           const bf16x8 kf = *(LAS const bf16x8*)(Kl + oz + (32 * st + 16 * t + r) * KSTR + (32 * kk + 8 * lg) * 2);
; #pragma unroll
;           for (int jj = 0; jj < JB; ++jj) s[jj][t] = mfma16(kf, qf[jh * JB + jj][kk], kk == 0 ? (f32x4){0.f, 0.f, 0.f, 0.f} : s[jj][t]);
;         }
;       __builtin_amdgcn_s_setprio(0);
;       bf16x8 pf[JB];
;       if (NT > JB) __builtin_amdgcn_sched_barrier(0);
; #pragma unroll
;       for (int jj = 0; jj < JB; ++jj) {
;         const int j = jh * JB + jj;
;         float mx = -INFINITY;
; #pragma unroll
;         for (int t = 0; t < 2; ++t)
; #pragma unroll
;           for (int i = 0; i < 4; ++i) {
;             if (MASK) { const int kp = kpos0 + 32 * st + 16 * t + 4 * lg + i; if (!mask_ok<MODE>(tq[j], kp, W)) s[jj][t][i] = -INFINITY; }
;             mx = fmaxf(mx, s[jj][t][i]);
;           }
;         mx = max_x16_x32(mx);
;         if (NT > 2 || __any(mx > m[j] + 8.0f / c)) {
;           const float mnew = fmaxf(m[j], mx);
;           const float ms2 = (mnew == -INFINITY) ? 0.f : mnew;
;           const float alpha = ex2((m[j] - ms2) * c);
;           m[j] = mnew; l[j] *= alpha;
; #pragma unroll
;           for (int dt = 0; dt < NDT; ++dt) o[j][dt] *= alpha;
;         }
;         const float mc = ((m[j] == -INFINITY) ? 0.f : m[j]) * c;
;         float p0[4], p1[4], ps = 0.f;
; #pragma unroll
;         for (int i = 0; i < 4; ++i) { p0[i] = ex2(s[jj][0][i] * c - mc); p1[i] = ex2(s[jj][1][i] * c - mc); ps += p0[i] + p1[i]; }
;         l[j] += ps;
;         pf[jj] = pack8(p0, p1);
;       }
;       if (NT > JB) __builtin_amdgcn_sched_barrier(0);
;       __builtin_amdgcn_s_setprio(1);
; #pragma unroll
;       for (int dt = 0; dt < NDT; ++dt) {
;         const s16x4 v0 = ds_tr(Vl + oz + (32 * st + 4 * lg + vq) * VSTR + (16 * dt + 4 * vp) * 2);
;         const s16x4 v1 = ds_tr(Vl + oz + (32 * st + 16 + 4 * lg + vq) * VSTR + (16 * dt + 4 * vp) * 2);
;         const bf16x8 vf = (bf16x8){v0[0], v0[1], v0[2], v0[3], v1[0], v1[1], v1[2], v1[3]};
; #pragma unroll
;         for (int jj = 0; jj < JB; ++jj) o[jh * JB + jj][dt] = mfma16(vf, pf[jj], o[jh * JB + jj][dt]);
	v_pk_mul_f32 v[156:157], v[156:157], v[198:199] op_sel_hi:[1,0]
	v_pk_mul_f32 v[154:155], v[154:155], v[198:199] op_sel_hi:[1,0]
	v_pk_mul_f32 v[164:165], v[164:165], v[198:199] op_sel_hi:[1,0]
	v_pk_mul_f32 v[162:163], v[162:163], v[198:199] op_sel_hi:[1,0]
	v_cndmask_b32_e64 v199, v196, 0, vcc
	v_pk_mul_f32 v[112:113], v[112:113], v[214:215] op_sel_hi:[1,0]
	v_pk_mul_f32 v[110:111], v[110:111], v[214:215] op_sel_hi:[1,0]
	v_pk_mul_f32 v[108:109], v[108:109], v[214:215] op_sel_hi:[1,0]
	v_pk_mul_f32 v[106:107], v[106:107], v[214:215] op_sel_hi:[1,0]
	v_pk_mul_f32 v[124:125], v[124:125], v[214:215] op_sel_hi:[1,0]
	v_pk_mul_f32 v[122:123], v[122:123], v[214:215] op_sel_hi:[1,0]
	v_pk_mul_f32 v[132:133], v[132:133], v[214:215] op_sel_hi:[1,0]
	v_pk_mul_f32 v[130:131], v[130:131], v[214:215] op_sel_hi:[1,0]
	v_fma_f32 v215, v215, s42, -v199
	v_fma_f32 v196, v228, s42, -v199
	v_fma_f32 v218, v218, s42, -v199
	v_exp_f32_e32 v230, v215
	v_fma_f32 v215, v219, s42, -v199
	v_exp_f32_e32 v197, v197
	v_exp_f32_e32 v196, v196
	v_exp_f32_e32 v228, v218
	v_exp_f32_e32 v236, v215
	v_fma_f32 v215, v216, s42, -v199
	v_exp_f32_e32 v238, v215
	v_fma_f32 v215, v220, s42, -v199
	v_exp_f32_e32 v240, v215
	v_fma_f32 v215, v217, s42, -v199
	v_fma_f32 v199, v221, s42, -v199
	v_exp_f32_e32 v242, v215
	v_exp_f32_e32 v244, v199
	v_mov_b32_e32 v215, v198
	v_pk_add_f32 v[198:199], v[196:197], v[228:229]
	v_pk_add_f32 v[216:217], v[230:231], v[236:237]
	v_pk_add_f32 v[198:199], v[198:199], 0 op_sel_hi:[1,0]
	v_cvt_pk_bf16_f32 v222, v197, v231
	v_pk_add_f32 v[198:199], v[216:217], v[198:199]
	v_pk_add_f32 v[216:217], v[238:239], v[240:241]
	v_cvt_pk_bf16_f32 v223, v239, v243
	v_pk_add_f32 v[198:199], v[216:217], v[198:199]
	v_pk_add_f32 v[216:217], v[242:243], v[244:245]
	v_cvt_pk_bf16_f32 v224, v229, v237
	v_pk_add_f32 v[198:199], v[216:217], v[198:199]
	v_cvt_pk_bf16_f32 v225, v241, v245
	v_pk_fma_f32 v[178:179], v[178:179], v[214:215], v[198:199]
	v_cvt_pk_bf16_f32 v214, v196, v230
	v_cvt_pk_bf16_f32 v215, v238, v242
	v_cvt_pk_bf16_f32 v216, v228, v236
	v_cvt_pk_bf16_f32 v217, v240, v244
	s_setprio 1
	v_add3_u32 v196, v210, v213, v193
	ds_read_b64_tr_b16 v[220:221], v196 offset:11776
	ds_read_b64_tr_b16 v[218:219], v196 offset:9216
	ds_read_b64_tr_b16 v[228:229], v196 offset:9248
	ds_read_b64_tr_b16 v[230:231], v196 offset:11808
	s_waitcnt lgkmcnt(2)
	v_mfma_f32_16x16x32_bf16 v[142:145], v[218:221], v[222:225], v[142:145]
	v_mfma_f32_16x16x32_bf16 v[110:113], v[218:221], v[214:217], v[110:113]
	ds_read_b64_tr_b16 v[218:219], v196 offset:9280
	ds_read_b64_tr_b16 v[220:221], v196 offset:11840
	s_waitcnt lgkmcnt(0)
	v_mfma_f32_16x16x32_bf16 v[154:157], v[218:221], v[222:225], v[154:157]
	v_mfma_f32_16x16x32_bf16 v[122:125], v[218:221], v[214:217], v[122:125]
	ds_read_b64_tr_b16 v[218:219], v196 offset:9312
	ds_read_b64_tr_b16 v[220:221], v196 offset:11872
	v_mfma_f32_16x16x32_bf16 v[138:141], v[228:231], v[222:225], v[138:141]
	v_mfma_f32_16x16x32_bf16 v[106:109], v[228:231], v[214:217], v[106:109]
	s_waitcnt lgkmcnt(0)
	v_mfma_f32_16x16x32_bf16 v[162:165], v[218:221], v[222:225], v[162:165]
	v_mfma_f32_16x16x32_bf16 v[130:133], v[218:221], v[214:217], v[130:133]
	s_setprio 0
	v_mov_b32_e32 v252, 0
	s_setprio 1
	v_add3_u32 v196, v1, v252, v235
	ds_read_b128 v[214:217], v196
	ds_read_b128 v[218:221], v196 offset:64
	s_waitcnt lgkmcnt(1)
	v_mfma_f32_16x16x32_bf16 v[222:225], v[214:217], v[74:77], 0
	v_mfma_f32_16x16x32_bf16 v[214:217], v[214:217], v[82:85], 0
	s_waitcnt lgkmcnt(0)
	v_mfma_f32_16x16x32_bf16 v[222:225], v[218:221], v[78:81], v[222:225]
	v_mfma_f32_16x16x32_bf16 v[214:217], v[218:221], v[86:89], v[214:217]
	ds_read_b128 v[218:221], v196 offset:2304
	ds_read_b128 v[228:231], v196 offset:2368
	s_waitcnt lgkmcnt(1)
	v_mfma_f32_16x16x32_bf16 v[236:239], v[218:221], v[74:77], 0
	v_mfma_f32_16x16x32_bf16 v[218:221], v[218:221], v[82:85], 0
	s_waitcnt lgkmcnt(0)
	v_mfma_f32_16x16x32_bf16 v[236:239], v[228:231], v[78:81], v[236:239]
	v_mfma_f32_16x16x32_bf16 v[218:221], v[228:231], v[86:89], v[218:221]
	s_setprio 0
	v_cmp_le_i32_e32 vcc, v212, v186
	v_cmp_gt_i32_e64 s[12:13], v212, v201
	v_mov_b32_e32 v196, s81
	s_and_b64 vcc, vcc, s[12:13]
	v_cndmask_b32_e32 v197, v196, v222, vcc
	v_cmp_lt_i32_e32 vcc, v212, v186
	v_cmp_ge_i32_e64 s[12:13], v212, v201
	s_and_b64 vcc, vcc, s[12:13]
	v_cndmask_b32_e32 v199, v200, v223, vcc
	v_cmp_le_i32_e32 vcc, v246, v186
	v_cmp_gt_i32_e64 s[12:13], v246, v201
	s_and_b64 vcc, vcc, s[12:13]
	v_cndmask_b32_e32 v222, v200, v224, vcc
	v_cmp_le_i32_e32 vcc, v247, v186
	v_cmp_gt_i32_e64 s[12:13], v247, v201
	s_and_b64 vcc, vcc, s[12:13]
	v_max3_f32 v196, v197, s81, v199
	v_cndmask_b32_e32 v223, v200, v225, vcc
	v_cmp_le_i32_e32 vcc, v248, v186
	v_cmp_gt_i32_e64 s[12:13], v248, v201
	v_max3_f32 v198, v196, v222, v223
	v_mov_b32_e32 v196, s81
	s_and_b64 vcc, vcc, s[12:13]
	v_cndmask_b32_e32 v196, v196, v236, vcc
	v_cmp_le_i32_e32 vcc, v249, v186
	v_cmp_gt_i32_e64 s[12:13], v249, v201
	s_and_b64 vcc, vcc, s[12:13]
	v_cndmask_b32_e32 v224, v200, v237, vcc
	v_cmp_le_i32_e32 vcc, v250, v186
	v_cmp_gt_i32_e64 s[12:13], v250, v201
	s_and_b64 vcc, vcc, s[12:13]
	v_cndmask_b32_e32 v225, v200, v238, vcc
	v_cmp_le_i32_e32 vcc, v251, v186
	v_cmp_gt_i32_e64 s[12:13], v251, v201
	s_and_b64 vcc, vcc, s[12:13]
	v_max3_f32 v198, v198, v196, v224
	v_cndmask_b32_e32 v228, v200, v239, vcc
	v_max3_f32 v198, v198, v225, v228
	v_mov_b32_e32 v213, v198
	s_nop 1
	v_permlane16_swap_b32_e32 v198, v213
	v_max_f32_e32 v198, v198, v213
	v_mov_b32_e32 v213, v198
	s_nop 1
	v_permlane32_swap_b32_e32 v198, v213
	v_max3_f32 v213, v232, v198, v213
	v_cmp_eq_f32_e32 vcc, s81, v213
; __device__ __forceinline__ float ex2(float x) { return __builtin_amdgcn_exp2f(x); }
; __device__ __forceinline__ f32x4 mfma16(bf16x8 a, bf16x8 b, f32x4 c) { return __builtin_amdgcn_mfma_f32_16x16x32_bf16(a, b, c, 0, 0, 0); }
; __device__ __forceinline__ s16x4 ds_tr(LAS const unsigned char* p) { return __builtin_bit_cast(s16x4, __builtin_amdgcn_ds_read_tr16_b64_v4i16((LAS v4i16_t*)p)); }
;   __device__ __forceinline__ bf16_t* W() const { return (bf16_t*)(ws + WS_W); }
; template <int NT, int NKK, int NDT, int MODE, bool MASK> ...
;     ...
;       for (int jj = 0; jj < JB; ++jj) {
;         const int j = jh * JB + jj;
;         float mx = -INFINITY;
; #pragma unroll
;         for (int t = 0; t < 2; ++t)
; #pragma unroll
;           for (int i = 0; i < 4; ++i) {
;             if (MASK) { const int kp = kpos0 + 32 * st + 16 * t + 4 * lg + i; if (!mask_ok<MODE>(tq[j], kp, W)) s[jj][t][i] = -INFINITY; }
;             mx = fmaxf(mx, s[jj][t][i]);
;           }
;         mx = max_x16_x32(mx);
;         if (NT > 2 || __any(mx > m[j] + 8.0f / c)) {
;           const float mnew = fmaxf(m[j], mx);
;           const float ms2 = (mnew == -INFINITY) ? 0.f : mnew;
;           const float alpha = ex2((m[j] - ms2) * c);
;           m[j] = mnew; l[j] *= alpha;
; #pragma unroll
;           for (int dt = 0; dt < NDT; ++dt) o[j][dt] *= alpha;
;         }
;         const float mc = ((m[j] == -INFINITY) ? 0.f : m[j]) * c;
;         float p0[4], p1[4], ps = 0.f;
; #pragma unroll
;         for (int i = 0; i < 4; ++i) { p0[i] = ex2(s[jj][0][i] * c - mc); p1[i] = ex2(s[jj][1][i] * c - mc); ps += p0[i] + p1[i]; }
;         l[j] += ps;
;         pf[jj] = pack8(p0, p1);
;       }
;       if (NT > JB) __builtin_amdgcn_sched_barrier(0);
;       __builtin_amdgcn_s_setprio(1);
; #pragma unroll
;       for (int dt = 0; dt < NDT; ++dt) {
;         const s16x4 v0 = ds_tr(Vl + oz + (32 * st + 4 * lg + vq) * VSTR + (16 * dt + 4 * vp) * 2);
;         const s16x4 v1 = ds_tr(Vl + oz + (32 * st + 16 + 4 * lg + vq) * VSTR + (16 * dt + 4 * vp) * 2);
;         const bf16x8 vf = (bf16x8){v0[0], v0[1], v0[2], v0[3], v1[0], v1[1], v1[2], v1[3]};
; #pragma unroll
;         for (int jj = 0; jj < JB; ++jj) o[jh * JB + jj][dt] = mfma16(vf, pf[jj], o[jh * JB + jj][dt]);
	v_mul_f32_e32 v229, 0x3e38aa3b, v213
	v_cmp_gt_i32_e64 s[12:13], v212, v202
	v_cndmask_b32_e64 v230, v229, 0, vcc
	v_fma_f32 v196, v196, s42, -v230
	v_cndmask_b32_e64 v198, v213, 0, vcc
	v_exp_f32_e32 v229, v196
	v_fma_f32 v196, v199, s42, -v230
	v_sub_f32_e32 v198, v232, v198
	v_exp_f32_e32 v231, v196
	v_fma_f32 v196, v224, s42, -v230
	v_mul_f32_e32 v198, 0x3e38aa3b, v198
	v_exp_f32_e32 v237, v196
	v_fma_f32 v196, v222, s42, -v230
	v_exp_f32_e32 v198, v198
	v_exp_f32_e32 v239, v196
	v_fma_f32 v196, v225, s42, -v230
	v_exp_f32_e32 v241, v196
	v_fma_f32 v196, v223, s42, -v230
	v_exp_f32_e32 v243, v196
	v_fma_f32 v196, v228, s42, -v230
	v_cmp_le_i32_e32 vcc, v212, v187
	v_exp_f32_e32 v245, v196
	v_mov_b32_e32 v196, s81
	s_and_b64 vcc, vcc, s[12:13]
	v_pk_mul_f32 v[152:153], v[152:153], v[198:199] op_sel_hi:[1,0]
	v_pk_mul_f32 v[150:151], v[150:151], v[198:199] op_sel_hi:[1,0]
	v_pk_mul_f32 v[148:149], v[148:149], v[198:199] op_sel_hi:[1,0]
	v_pk_mul_f32 v[146:147], v[146:147], v[198:199] op_sel_hi:[1,0]
	v_pk_mul_f32 v[160:161], v[160:161], v[198:199] op_sel_hi:[1,0]
	v_pk_mul_f32 v[158:159], v[158:159], v[198:199] op_sel_hi:[1,0]
	v_pk_mul_f32 v[168:169], v[168:169], v[198:199] op_sel_hi:[1,0]
	v_pk_mul_f32 v[166:167], v[166:167], v[198:199] op_sel_hi:[1,0]
	v_cndmask_b32_e32 v199, v196, v214, vcc
	v_cmp_lt_i32_e32 vcc, v212, v187
	v_cmp_ge_i32_e64 s[12:13], v212, v202
	s_and_b64 vcc, vcc, s[12:13]
	v_cndmask_b32_e32 v215, v200, v215, vcc
	v_cmp_le_i32_e32 vcc, v246, v187
	v_cmp_gt_i32_e64 s[12:13], v246, v202
	s_and_b64 vcc, vcc, s[12:13]
	v_cndmask_b32_e32 v216, v200, v216, vcc
	v_cmp_le_i32_e32 vcc, v247, v187
	v_cmp_gt_i32_e64 s[12:13], v247, v202
	s_and_b64 vcc, vcc, s[12:13]
	v_max3_f32 v196, v199, s81, v215
	v_cndmask_b32_e32 v217, v200, v217, vcc
	v_cmp_le_i32_e32 vcc, v248, v187
	v_cmp_gt_i32_e64 s[12:13], v248, v202
	v_max3_f32 v212, v196, v216, v217
	v_mov_b32_e32 v196, s81
	s_and_b64 vcc, vcc, s[12:13]
	v_cndmask_b32_e32 v218, v196, v218, vcc
	v_cmp_le_i32_e32 vcc, v249, v187
	v_cmp_gt_i32_e64 s[12:13], v249, v202
	s_and_b64 vcc, vcc, s[12:13]
	v_cndmask_b32_e32 v219, v200, v219, vcc
	v_cmp_le_i32_e32 vcc, v250, v187
	v_cmp_gt_i32_e64 s[12:13], v250, v202
	s_and_b64 vcc, vcc, s[12:13]
	v_cndmask_b32_e32 v220, v200, v220, vcc
	v_cmp_le_i32_e32 vcc, v251, v187
	v_cmp_gt_i32_e64 s[12:13], v251, v202
	s_and_b64 vcc, vcc, s[12:13]
	v_max3_f32 v196, v212, v218, v219
	v_cndmask_b32_e32 v221, v200, v221, vcc
	v_max3_f32 v196, v196, v220, v221
	v_mov_b32_e32 v212, v196
	s_nop 1
	v_permlane16_swap_b32_e32 v196, v212
	v_max_f32_e32 v196, v196, v212
	v_mov_b32_e32 v212, v196
	s_nop 1
	v_permlane32_swap_b32_e32 v196, v212
	v_max3_f32 v212, v211, v196, v212
	v_cmp_eq_f32_e32 vcc, s81, v212
	v_fma_f32 v197, v197, s42, -v230
	v_exp_f32_e32 v197, v197
	v_cndmask_b32_e64 v196, v212, 0, vcc
	v_sub_f32_e32 v196, v211, v196
	v_mul_f32_e32 v196, 0x3e38aa3b, v196
	v_exp_f32_e32 v214, v196
	v_mul_f32_e32 v196, 0x3e38aa3b, v212
	v_cndmask_b32_e64 v211, v196, 0, vcc
	v_fma_f32 v196, v199, s42, -v211
	v_fma_f32 v199, v218, s42, -v211
	v_exp_f32_e32 v228, v199
	v_fma_f32 v199, v215, s42, -v211
	v_exp_f32_e32 v230, v199
	v_fma_f32 v199, v219, s42, -v211
	v_exp_f32_e32 v236, v199
	v_fma_f32 v199, v216, s42, -v211
	v_exp_f32_e32 v196, v196
	v_exp_f32_e32 v238, v199
	v_fma_f32 v199, v220, s42, -v211
	v_exp_f32_e32 v240, v199
	v_fma_f32 v199, v217, s42, -v211
	v_exp_f32_e32 v242, v199
	v_fma_f32 v199, v221, s42, -v211
	v_exp_f32_e32 v244, v199
	v_pk_mul_f32 v[120:121], v[120:121], v[214:215] op_sel_hi:[1,0]
	v_pk_mul_f32 v[118:119], v[118:119], v[214:215] op_sel_hi:[1,0]
	v_pk_mul_f32 v[116:117], v[116:117], v[214:215] op_sel_hi:[1,0]
	v_pk_mul_f32 v[114:115], v[114:115], v[214:215] op_sel_hi:[1,0]
	v_pk_mul_f32 v[128:129], v[128:129], v[214:215] op_sel_hi:[1,0]
	v_pk_mul_f32 v[126:127], v[126:127], v[214:215] op_sel_hi:[1,0]
	v_pk_mul_f32 v[136:137], v[136:137], v[214:215] op_sel_hi:[1,0]
	v_pk_mul_f32 v[134:135], v[134:135], v[214:215] op_sel_hi:[1,0]
	v_mov_b32_e32 v215, v198
	v_pk_add_f32 v[198:199], v[196:197], v[228:229]
	v_pk_add_f32 v[216:217], v[230:231], v[236:237]
	v_pk_add_f32 v[198:199], v[198:199], 0 op_sel_hi:[1,0]
	v_cvt_pk_bf16_f32 v222, v197, v231
	v_pk_add_f32 v[198:199], v[216:217], v[198:199]
	v_pk_add_f32 v[216:217], v[238:239], v[240:241]
	v_cvt_pk_bf16_f32 v223, v239, v243
	v_pk_add_f32 v[198:199], v[216:217], v[198:199]
	v_pk_add_f32 v[216:217], v[242:243], v[244:245]
	v_cvt_pk_bf16_f32 v224, v229, v237
	v_pk_add_f32 v[198:199], v[216:217], v[198:199]
	v_cvt_pk_bf16_f32 v225, v241, v245
	v_pk_fma_f32 v[180:181], v[180:181], v[214:215], v[198:199]
	v_cvt_pk_bf16_f32 v214, v196, v230
	v_cvt_pk_bf16_f32 v215, v238, v242
	v_cvt_pk_bf16_f32 v216, v228, v236
	v_cvt_pk_bf16_f32 v217, v240, v244
	s_setprio 1
	v_add3_u32 v196, v210, v252, v193
	ds_read_b64_tr_b16 v[220:221], v196 offset:11776
	ds_read_b64_tr_b16 v[218:219], v196 offset:9216
	ds_read_b64_tr_b16 v[228:229], v196 offset:9248
	ds_read_b64_tr_b16 v[230:231], v196 offset:11808
	s_waitcnt lgkmcnt(2)
	v_mfma_f32_16x16x32_bf16 v[150:153], v[218:221], v[222:225], v[150:153]
	v_mfma_f32_16x16x32_bf16 v[118:121], v[218:221], v[214:217], v[118:121]
	ds_read_b64_tr_b16 v[218:219], v196 offset:9280
	ds_read_b64_tr_b16 v[220:221], v196 offset:11840
	s_waitcnt lgkmcnt(0)
	v_mfma_f32_16x16x32_bf16 v[158:161], v[218:221], v[222:225], v[158:161]
	v_mfma_f32_16x16x32_bf16 v[126:129], v[218:221], v[214:217], v[126:129]
	ds_read_b64_tr_b16 v[218:219], v196 offset:9312
	ds_read_b64_tr_b16 v[220:221], v196 offset:11872
	v_mfma_f32_16x16x32_bf16 v[146:149], v[228:231], v[222:225], v[146:149]
	v_mfma_f32_16x16x32_bf16 v[114:117], v[228:231], v[214:217], v[114:117]
	s_waitcnt lgkmcnt(0)
	v_mfma_f32_16x16x32_bf16 v[166:169], v[218:221], v[222:225], v[166:169]
	v_mfma_f32_16x16x32_bf16 v[134:137], v[218:221], v[214:217], v[134:137]
	s_setprio 0
	s_mov_b32 s8, 32
	s_and_b64 vcc, exec, s[52:53]
	s_mov_b64 s[52:53], 0
	s_cbranch_vccnz .LBB0_1199
	s_mov_b64 s[12:13], 0

; template <int NT, int NKK, int NDT, int MODE, bool MASK> ...
;     ...
;     for (int jh = 0; jh < NT / JB; ++jh) {
;       int oz = 0; if (NT > JB) asm volatile("" : "+v"(oz));
;       f32x4 s[JB][2];
;       __builtin_amdgcn_s_setprio(1);
; #pragma unroll
;       for (int t = 0; t < 2; ++t)
; #pragma unroll
;         for (int kk = 0; kk < NKK; ++kk) {
;           const bf16x8 kf = *(LAS const bf16x8*)(Kl + oz + (32 * st + 16 * t + r) * KSTR + (32 * kk + 8 * lg) * 2);
; #pragma unroll
;           for (int jj = 0; jj < JB; ++jj) s[jj][t] = mfma16(kf, qf[jh * JB + jj][kk], kk == 0 ? (f32x4){0.f, 0.f, 0.f, 0.f} : s[jj][t]);
;         }
;       __builtin_amdgcn_s_setprio(0);
;       bf16x8 pf[JB];
;       if (NT > JB) __builtin_amdgcn_sched_barrier(0);
; #pragma unroll
;       for (int jj = 0; jj < JB; ++jj) {
;         const int j = jh * JB + jj;
;         float mx = -INFINITY;
; #pragma unroll
;         for (int t = 0; t < 2; ++t)
; #pragma unroll
;           for (int i = 0; i < 4; ++i) {
;             if (MASK) { const int kp = kpos0 + 32 * st + 16 * t + 4 * lg + i; if (!mask_ok<MODE>(tq[j], kp, W)) s[jj][t][i] = -INFINITY; }
;             mx = fmaxf(mx, s[jj][t][i]);
;           }
;         mx = max_x16_x32(mx);
;         if (NT > 2 || __any(mx > m[j] + 8.0f / c)) {
;           const float mnew = fmaxf(m[j], mx);
;           const float ms2 = (mnew == -INFINITY) ? 0.f : mnew;
;           const float alpha = ex2((m[j] - ms2) * c);
;           m[j] = mnew; l[j] *= alpha;
; #pragma unroll
;           for (int dt = 0; dt < NDT; ++dt) o[j][dt] *= alpha;
;         }
;         const float mc = ((m[j] == -INFINITY) ? 0.f : m[j]) * c;
;         float p0[4], p1[4], ps = 0.f;
; #pragma unroll
;         for (int i = 0; i < 4; ++i) { p0[i] = ex2(s[jj][0][i] * c - mc); p1[i] = ex2(s[jj][1][i] * c - mc); ps += p0[i] + p1[i]; }
;         l[j] += ps;
;         pf[jj] = pack8(p0, p1);
;       }
;       if (NT > JB) __builtin_amdgcn_sched_barrier(0);
;       __builtin_amdgcn_s_setprio(1);
; #pragma unroll
;       for (int dt = 0; dt < NDT; ++dt) {
;         const s16x4 v0 = ds_tr(Vl + oz + (32 * st + 4 * lg + vq) * VSTR + (16 * dt + 4 * vp) * 2);
;         const s16x4 v1 = ds_tr(Vl + oz + (32 * st + 16 + 4 * lg + vq) * VSTR + (16 * dt + 4 * vp) * 2);
;         const bf16x8 vf = (bf16x8){v0[0], v0[1], v0[2], v0[3], v1[0], v1[1], v1[2], v1[3]};
; #pragma unroll
.LBB0_1203:
	v_or_b32_e32 v106, s8, v191
	v_mov_b32_e32 v109, s75
	v_mov_b32_e32 v142, 0
	v_mov_b32_e32 v107, v203
	v_mov_b32_e32 v128, v204
	v_mov_b32_e32 v140, v205
	v_mov_b32_e32 v141, v206
	v_or_b32_e32 v108, s8, v189
	v_mad_u32_u24 v106, v106, s80, v109
	s_setprio 1
	v_mul_u32_u24_e32 v143, 0x90, v108
	v_add3_u32 v120, v1, v142, v143
	ds_read_b128 v[108:111], v120
	ds_read_b128 v[112:115], v120 offset:64
	s_waitcnt lgkmcnt(1)
	v_mfma_f32_16x16x32_bf16 v[116:119], v[108:111], v[54:57], 0
	v_mfma_f32_16x16x32_bf16 v[108:111], v[108:111], v[62:65], 0
	s_waitcnt lgkmcnt(0)
	v_mfma_f32_16x16x32_bf16 v[116:119], v[112:115], v[58:61], v[116:119]
	v_mfma_f32_16x16x32_bf16 v[108:111], v[112:115], v[66:69], v[108:111]
	ds_read_b128 v[112:115], v120 offset:2304
	ds_read_b128 v[120:123], v120 offset:2368
	s_waitcnt lgkmcnt(1)
	v_mfma_f32_16x16x32_bf16 v[124:127], v[112:115], v[54:57], 0
	v_mfma_f32_16x16x32_bf16 v[112:115], v[112:115], v[62:65], 0
	s_waitcnt lgkmcnt(0)
	v_mfma_f32_16x16x32_bf16 v[124:127], v[120:123], v[58:61], v[124:127]
	v_mfma_f32_16x16x32_bf16 v[112:115], v[120:123], v[66:69], v[112:115]
	s_setprio 0
	v_max3_f32 v120, v116, s81, v117
	v_max3_f32 v120, v120, v118, v119
	s_nop 3
	v_max3_f32 v120, v120, v124, v125
	v_max3_f32 v120, v120, v126, v127
	v_mov_b32_e32 v121, v120
	s_nop 1
	v_permlane16_swap_b32_e32 v120, v121
	v_max_f32_e32 v120, v120, v121
	v_mov_b32_e32 v121, v120
	s_nop 1
	v_permlane32_swap_b32_e32 v120, v121
	v_max3_f32 v203, v107, v120, v121
	v_cmp_eq_f32_e32 vcc, s81, v203
	s_nop 1
	v_cndmask_b32_e64 v120, v203, 0, vcc
	v_sub_f32_e32 v107, v107, v120
	v_mul_f32_e32 v107, 0x3e38aa3b, v107
	v_exp_f32_e32 v120, v107
	v_mul_f32_e32 v107, 0x3e38aa3b, v203
	v_cndmask_b32_e64 v107, v107, 0, vcc
	v_fma_f32 v116, v116, s42, -v107
	v_exp_f32_e32 v123, v116
	v_fma_f32 v116, v124, s42, -v107
	v_exp_f32_e32 v129, v116
	v_fma_f32 v116, v117, s42, -v107
	v_exp_f32_e32 v131, v116
	v_fma_f32 v116, v125, s42, -v107
	v_exp_f32_e32 v125, v116
	v_fma_f32 v116, v118, s42, -v107
	v_exp_f32_e32 v133, v116
	v_fma_f32 v116, v126, s42, -v107
	v_exp_f32_e32 v135, v116
	v_fma_f32 v116, v119, s42, -v107
	v_fma_f32 v107, v127, s42, -v107
	v_exp_f32_e32 v127, v107
	v_max3_f32 v107, v108, s81, v109
	v_max3_f32 v107, v107, v110, v111
	v_max3_f32 v107, v107, v112, v113
	v_max3_f32 v107, v107, v114, v115
	v_mov_b32_e32 v117, v107
	s_nop 1
	v_permlane16_swap_b32_e32 v107, v117
	v_max_f32_e32 v107, v107, v117
	v_mov_b32_e32 v117, v107
	s_nop 1
	v_permlane32_swap_b32_e32 v107, v117
	v_max3_f32 v204, v128, v107, v117
	v_cmp_eq_f32_e32 vcc, s81, v204
	v_exp_f32_e32 v137, v116
	v_pk_mul_f32 v[104:105], v[104:105], v[120:121] op_sel_hi:[1,0]
	v_cndmask_b32_e64 v107, v204, 0, vcc
	v_sub_f32_e32 v107, v128, v107
	v_mul_f32_e32 v107, 0x3e38aa3b, v107
	v_exp_f32_e32 v138, v107
	v_mul_f32_e32 v107, 0x3e38aa3b, v204
	v_cndmask_b32_e64 v107, v107, 0, vcc
	v_fma_f32 v108, v108, s42, -v107
	v_exp_f32_e32 v122, v108
	v_fma_f32 v108, v112, s42, -v107
	v_exp_f32_e32 v128, v108
	v_fma_f32 v108, v109, s42, -v107
	v_exp_f32_e32 v130, v108
	v_fma_f32 v108, v113, s42, -v107
	v_exp_f32_e32 v124, v108
	v_fma_f32 v108, v110, s42, -v107
	v_exp_f32_e32 v132, v108
	v_fma_f32 v108, v114, s42, -v107
	v_exp_f32_e32 v134, v108
	v_fma_f32 v108, v111, s42, -v107
	v_fma_f32 v107, v115, s42, -v107
	v_exp_f32_e32 v136, v108
	v_exp_f32_e32 v126, v107
	v_pk_add_f32 v[108:109], v[122:123], v[128:129]
	v_pk_add_f32 v[110:111], v[130:131], v[124:125]
	v_pk_add_f32 v[108:109], v[108:109], 0 op_sel_hi:[1,0]
	v_pk_mul_f32 v[48:49], v[48:49], v[138:139] op_sel_hi:[1,0]
	v_pk_add_f32 v[108:109], v[110:111], v[108:109]
	v_pk_add_f32 v[110:111], v[132:133], v[134:135]
	v_pk_mul_f32 v[46:47], v[46:47], v[138:139] op_sel_hi:[1,0]
	v_pk_add_f32 v[108:109], v[110:111], v[108:109]
	v_pk_add_f32 v[110:111], v[136:137], v[126:127]
	v_pk_mul_f32 v[44:45], v[44:45], v[138:139] op_sel_hi:[1,0]
	v_pk_mul_f32 v[42:43], v[42:43], v[138:139] op_sel_hi:[1,0]
	v_pk_mul_f32 v[40:41], v[40:41], v[138:139] op_sel_hi:[1,0]
	v_pk_mul_f32 v[38:39], v[38:39], v[138:139] op_sel_hi:[1,0]
	v_pk_mul_f32 v[36:37], v[36:37], v[138:139] op_sel_hi:[1,0]
	v_pk_mul_f32 v[34:35], v[34:35], v[138:139] op_sel_hi:[1,0]
	v_mov_b32_e32 v139, v120
	v_pk_add_f32 v[108:109], v[110:111], v[108:109]
	v_pk_mul_f32 v[102:103], v[102:103], v[120:121] op_sel_hi:[1,0]
	v_pk_mul_f32 v[92:93], v[92:93], v[120:121] op_sel_hi:[1,0]
	v_pk_mul_f32 v[90:91], v[90:91], v[120:121] op_sel_hi:[1,0]
	v_pk_mul_f32 v[72:73], v[72:73], v[120:121] op_sel_hi:[1,0]
	v_pk_mul_f32 v[70:71], v[70:71], v[120:121] op_sel_hi:[1,0]
	v_pk_mul_f32 v[52:53], v[52:53], v[120:121] op_sel_hi:[1,0]
	v_pk_mul_f32 v[50:51], v[50:51], v[120:121] op_sel_hi:[1,0]
	v_pk_fma_f32 v[172:173], v[172:173], v[138:139], v[108:109]
	v_cvt_pk_bf16_f32 v116, v123, v131
	v_cvt_pk_bf16_f32 v117, v133, v137
	v_cvt_pk_bf16_f32 v118, v129, v125
	v_cvt_pk_bf16_f32 v119, v135, v127
	v_cvt_pk_bf16_f32 v108, v122, v130
	v_cvt_pk_bf16_f32 v109, v132, v136
	v_cvt_pk_bf16_f32 v110, v128, v124
	v_cvt_pk_bf16_f32 v111, v134, v126
	s_setprio 1
	v_add3_u32 v107, v106, v142, v193
	ds_read_b64_tr_b16 v[114:115], v107 offset:11776
	ds_read_b64_tr_b16 v[112:113], v107 offset:9216
	ds_read_b64_tr_b16 v[120:121], v107 offset:9248
	ds_read_b64_tr_b16 v[122:123], v107 offset:11808
	s_waitcnt lgkmcnt(2)
	v_mfma_f32_16x16x32_bf16 v[102:105], v[112:115], v[116:119], v[102:105]
	v_mfma_f32_16x16x32_bf16 v[46:49], v[112:115], v[108:111], v[46:49]
	ds_read_b64_tr_b16 v[112:113], v107 offset:9280
	ds_read_b64_tr_b16 v[114:115], v107 offset:11840
	s_waitcnt lgkmcnt(0)
; template <int NT, int NKK, int NDT, int MODE, bool MASK> ...
;     ...
;     for (int jh = 0; jh < NT / JB; ++jh) {
;       int oz = 0; if (NT > JB) asm volatile("" : "+v"(oz));
;       f32x4 s[JB][2];
;       __builtin_amdgcn_s_setprio(1);
; #pragma unroll
;       for (int t = 0; t < 2; ++t)
; #pragma unroll
;         for (int kk = 0; kk < NKK; ++kk) {
;           const bf16x8 kf = *(LAS const bf16x8*)(Kl + oz + (32 * st + 16 * t + r) * KSTR + (32 * kk + 8 * lg) * 2);
; #pragma unroll
;           for (int jj = 0; jj < JB; ++jj) s[jj][t] = mfma16(kf, qf[jh * JB + jj][kk], kk == 0 ? (f32x4){0.f, 0.f, 0.f, 0.f} : s[jj][t]);
;         }
;       __builtin_amdgcn_s_setprio(0);
;       bf16x8 pf[JB];
;       if (NT > JB) __builtin_amdgcn_sched_barrier(0);
; #pragma unroll
;       for (int jj = 0; jj < JB; ++jj) {
;         const int j = jh * JB + jj;
;         float mx = -INFINITY;
; #pragma unroll
;         for (int t = 0; t < 2; ++t)
; #pragma unroll
;           for (int i = 0; i < 4; ++i) {
;             if (MASK) { const int kp = kpos0 + 32 * st + 16 * t + 4 * lg + i; if (!mask_ok<MODE>(tq[j], kp, W)) s[jj][t][i] = -INFINITY; }
;             mx = fmaxf(mx, s[jj][t][i]);
;           }
;         mx = max_x16_x32(mx);
;         if (NT > 2 || __any(mx > m[j] + 8.0f / c)) {
;           const float mnew = fmaxf(m[j], mx);
;           const float ms2 = (mnew == -INFINITY) ? 0.f : mnew;
;           const float alpha = ex2((m[j] - ms2) * c);
;           m[j] = mnew; l[j] *= alpha;
; #pragma unroll
;           for (int dt = 0; dt < NDT; ++dt) o[j][dt] *= alpha;
;         }
;         const float mc = ((m[j] == -INFINITY) ? 0.f : m[j]) * c;
;         float p0[4], p1[4], ps = 0.f;
; #pragma unroll
;         for (int i = 0; i < 4; ++i) { p0[i] = ex2(s[jj][0][i] * c - mc); p1[i] = ex2(s[jj][1][i] * c - mc); ps += p0[i] + p1[i]; }
;         l[j] += ps;
;         pf[jj] = pack8(p0, p1);
;       }
;       if (NT > JB) __builtin_amdgcn_sched_barrier(0);
;       __builtin_amdgcn_s_setprio(1);
; #pragma unroll
;       for (int dt = 0; dt < NDT; ++dt) {
;         const s16x4 v0 = ds_tr(Vl + oz + (32 * st + 4 * lg + vq) * VSTR + (16 * dt + 4 * vp) * 2);
;         const s16x4 v1 = ds_tr(Vl + oz + (32 * st + 16 + 4 * lg + vq) * VSTR + (16 * dt + 4 * vp) * 2);
;         const bf16x8 vf = (bf16x8){v0[0], v0[1], v0[2], v0[3], v1[0], v1[1], v1[2], v1[3]};
; #pragma unroll
	v_mfma_f32_16x16x32_bf16 v[70:73], v[112:115], v[116:119], v[70:73]
	v_mfma_f32_16x16x32_bf16 v[38:41], v[112:115], v[108:111], v[38:41]
	ds_read_b64_tr_b16 v[112:113], v107 offset:9312
	ds_read_b64_tr_b16 v[114:115], v107 offset:11872
	v_mfma_f32_16x16x32_bf16 v[90:93], v[120:123], v[116:119], v[90:93]
	v_mfma_f32_16x16x32_bf16 v[42:45], v[120:123], v[108:111], v[42:45]
	s_waitcnt lgkmcnt(0)
	v_mfma_f32_16x16x32_bf16 v[50:53], v[112:115], v[116:119], v[50:53]
	v_mfma_f32_16x16x32_bf16 v[34:37], v[112:115], v[108:111], v[34:37]
	s_setprio 0
	v_mov_b32_e32 v107, 0
	s_setprio 1
	v_add3_u32 v120, v1, v107, v143
	ds_read_b128 v[108:111], v120
	ds_read_b128 v[112:115], v120 offset:64
	s_waitcnt lgkmcnt(1)
	v_mfma_f32_16x16x32_bf16 v[116:119], v[108:111], v[74:77], 0
	v_mfma_f32_16x16x32_bf16 v[108:111], v[108:111], v[82:85], 0
	s_waitcnt lgkmcnt(0)
	v_mfma_f32_16x16x32_bf16 v[116:119], v[112:115], v[78:81], v[116:119]
	v_mfma_f32_16x16x32_bf16 v[108:111], v[112:115], v[86:89], v[108:111]
	ds_read_b128 v[112:115], v120 offset:2304
	ds_read_b128 v[120:123], v120 offset:2368
	s_waitcnt lgkmcnt(1)
	v_mfma_f32_16x16x32_bf16 v[124:127], v[112:115], v[74:77], 0
	v_mfma_f32_16x16x32_bf16 v[112:115], v[112:115], v[82:85], 0
	s_waitcnt lgkmcnt(0)
	v_mfma_f32_16x16x32_bf16 v[124:127], v[120:123], v[78:81], v[124:127]
	v_mfma_f32_16x16x32_bf16 v[112:115], v[120:123], v[86:89], v[112:115]
	s_setprio 0
	v_max3_f32 v120, v116, s81, v117
	v_max3_f32 v120, v120, v118, v119
	s_nop 3
	v_max3_f32 v120, v120, v124, v125
	v_max3_f32 v120, v120, v126, v127
	v_mov_b32_e32 v121, v120
	s_nop 1
	v_permlane16_swap_b32_e32 v120, v121
	v_max_f32_e32 v120, v120, v121
	v_mov_b32_e32 v121, v120
	s_nop 1
	v_permlane32_swap_b32_e32 v120, v121
	v_max3_f32 v205, v140, v120, v121
	v_cmp_eq_f32_e32 vcc, s81, v205
	s_nop 1
	v_cndmask_b32_e64 v120, v205, 0, vcc
	v_sub_f32_e32 v120, v140, v120
	v_mul_f32_e32 v120, 0x3e38aa3b, v120
	v_exp_f32_e32 v120, v120
	s_nop 0
	v_pk_mul_f32 v[32:33], v[32:33], v[120:121] op_sel_hi:[1,0]
	v_pk_mul_f32 v[30:31], v[30:31], v[120:121] op_sel_hi:[1,0]
	v_pk_mul_f32 v[28:29], v[28:29], v[120:121] op_sel_hi:[1,0]
	v_pk_mul_f32 v[26:27], v[26:27], v[120:121] op_sel_hi:[1,0]
	v_pk_mul_f32 v[20:21], v[20:21], v[120:121] op_sel_hi:[1,0]
	v_pk_mul_f32 v[18:19], v[18:19], v[120:121] op_sel_hi:[1,0]
	v_pk_mul_f32 v[24:25], v[24:25], v[120:121] op_sel_hi:[1,0]
	v_pk_mul_f32 v[22:23], v[22:23], v[120:121] op_sel_hi:[1,0]
	v_mul_f32_e32 v121, 0x3e38aa3b, v205
	v_cndmask_b32_e64 v121, v121, 0, vcc
	v_fma_f32 v116, v116, s42, -v121
	v_exp_f32_e32 v123, v116
	v_fma_f32 v116, v124, s42, -v121
	v_exp_f32_e32 v129, v116
	v_fma_f32 v116, v117, s42, -v121
	v_max3_f32 v117, v108, s81, v109
	v_max3_f32 v117, v117, v110, v111
	v_max3_f32 v117, v117, v112, v113
	v_exp_f32_e32 v131, v116
	v_fma_f32 v116, v125, s42, -v121
	v_max3_f32 v117, v117, v114, v115
	v_exp_f32_e32 v125, v116
	v_fma_f32 v116, v118, s42, -v121
	v_mov_b32_e32 v118, v117
	s_nop 1
	v_permlane16_swap_b32_e32 v117, v118
	v_max_f32_e32 v117, v117, v118
	v_mov_b32_e32 v118, v117
	v_exp_f32_e32 v133, v116
	v_fma_f32 v116, v126, s42, -v121
	v_permlane32_swap_b32_e32 v117, v118
	v_exp_f32_e32 v135, v116
	v_fma_f32 v116, v119, s42, -v121
	v_max3_f32 v206, v141, v117, v118
	v_exp_f32_e32 v137, v116
	v_fma_f32 v116, v127, s42, -v121
	v_cmp_eq_f32_e32 vcc, s81, v206
	v_mul_f32_e32 v121, 0x3e38aa3b, v206
	v_exp_f32_e32 v127, v116
	v_cndmask_b32_e64 v121, v121, 0, vcc
	v_fma_f32 v108, v108, s42, -v121
	v_exp_f32_e32 v122, v108
	v_fma_f32 v108, v112, s42, -v121
	v_exp_f32_e32 v128, v108
	v_fma_f32 v108, v109, s42, -v121
	v_exp_f32_e32 v130, v108
	v_fma_f32 v108, v113, s42, -v121
	v_exp_f32_e32 v124, v108
	v_fma_f32 v108, v110, s42, -v121
	v_exp_f32_e32 v132, v108
	v_fma_f32 v108, v114, s42, -v121
	v_cndmask_b32_e64 v117, v206, 0, vcc
	v_exp_f32_e32 v134, v108
	v_fma_f32 v108, v111, s42, -v121
	v_sub_f32_e32 v117, v141, v117
	v_exp_f32_e32 v136, v108
	v_fma_f32 v108, v115, s42, -v121
	v_mul_f32_e32 v117, 0x3e38aa3b, v117
	v_exp_f32_e32 v126, v108
	v_exp_f32_e32 v138, v117
	v_pk_add_f32 v[108:109], v[122:123], v[128:129]
	v_pk_add_f32 v[110:111], v[130:131], v[124:125]
	v_pk_add_f32 v[108:109], v[108:109], 0 op_sel_hi:[1,0]
	v_pk_mul_f32 v[16:17], v[16:17], v[138:139] op_sel_hi:[1,0]
	v_pk_add_f32 v[108:109], v[110:111], v[108:109]
	v_pk_add_f32 v[110:111], v[132:133], v[134:135]
	v_pk_mul_f32 v[14:15], v[14:15], v[138:139] op_sel_hi:[1,0]
	v_pk_add_f32 v[108:109], v[110:111], v[108:109]
	v_pk_add_f32 v[110:111], v[136:137], v[126:127]
	v_pk_mul_f32 v[12:13], v[12:13], v[138:139] op_sel_hi:[1,0]
	v_pk_mul_f32 v[10:11], v[10:11], v[138:139] op_sel_hi:[1,0]
	v_pk_mul_f32 v[8:9], v[8:9], v[138:139] op_sel_hi:[1,0]
	v_pk_mul_f32 v[6:7], v[6:7], v[138:139] op_sel_hi:[1,0]
	v_pk_mul_f32 v[4:5], v[4:5], v[138:139] op_sel_hi:[1,0]
	v_pk_mul_f32 v[2:3], v[2:3], v[138:139] op_sel_hi:[1,0]
	v_mov_b32_e32 v139, v120
	v_pk_add_f32 v[108:109], v[110:111], v[108:109]
	v_cvt_pk_bf16_f32 v116, v123, v131
	v_pk_fma_f32 v[170:171], v[170:171], v[138:139], v[108:109]
	v_cvt_pk_bf16_f32 v117, v133, v137
	v_cvt_pk_bf16_f32 v118, v129, v125
	v_cvt_pk_bf16_f32 v119, v135, v127
	v_cvt_pk_bf16_f32 v108, v122, v130
	v_cvt_pk_bf16_f32 v109, v132, v136
	v_cvt_pk_bf16_f32 v110, v128, v124
	v_cvt_pk_bf16_f32 v111, v134, v126
	s_setprio 1
	v_add3_u32 v106, v106, v107, v193
	ds_read_b64_tr_b16 v[114:115], v106 offset:11776
	ds_read_b64_tr_b16 v[112:113], v106 offset:9216
	ds_read_b64_tr_b16 v[120:121], v106 offset:9248
	ds_read_b64_tr_b16 v[122:123], v106 offset:11808
	s_waitcnt lgkmcnt(2)
	v_mfma_f32_16x16x32_bf16 v[30:33], v[112:115], v[116:119], v[30:33]
	v_mfma_f32_16x16x32_bf16 v[14:17], v[112:115], v[108:111], v[14:17]
	ds_read_b64_tr_b16 v[112:113], v106 offset:9280
	ds_read_b64_tr_b16 v[114:115], v106 offset:11840
	s_waitcnt lgkmcnt(0)
	v_mfma_f32_16x16x32_bf16 v[18:21], v[112:115], v[116:119], v[18:21]
	v_mfma_f32_16x16x32_bf16 v[6:9], v[112:115], v[108:111], v[6:9]
	ds_read_b64_tr_b16 v[112:113], v106 offset:9312
	ds_read_b64_tr_b16 v[114:115], v106 offset:11872
	v_mfma_f32_16x16x32_bf16 v[26:29], v[120:123], v[116:119], v[26:29]
	v_mfma_f32_16x16x32_bf16 v[10:13], v[120:123], v[108:111], v[10:13]
	s_waitcnt lgkmcnt(0)
	v_mfma_f32_16x16x32_bf16 v[22:25], v[112:115], v[116:119], v[22:25]
	v_mfma_f32_16x16x32_bf16 v[2:5], v[112:115], v[108:111], v[2:5]
	s_setprio 0
	s_mov_b32 s8, 32
	s_andn2_b64 vcc, exec, s[12:13]
	s_mov_b64 s[12:13], 0
	s_cbranch_vccz .LBB0_1203
;   __device__ __forceinline__ bf16_t* W() const { return (bf16_t*)(ws + WS_W); }
; template <int NT, int DQK, int DV, int MODE, int PD, class Src> ...
;     ...
;         if (rel) {
;           if (NT <= 2) {
;             if (full) attn_chunk_wide<NT, DQK / 32, DV / 16, MODE, false>(o, m, l, qf, buf, KSTR, buf + KB, VSTR, lo, tq, c, W, lane);
;             else attn_chunk_wide<NT, DQK / 32, DV / 16, MODE, true>(o, m, l, qf, buf, KSTR, buf + KB, VSTR, lo, tq, c, W, lane);
;           } else {
;             if (full) attn_chunk<NT, DQK / 32, DV / 16, MODE, false>(o, m, l, qf, buf, KSTR, buf + KB, VSTR, lo, tq, c, W, lane);
;             else attn_chunk<NT, DQK / 32, DV / 16, MODE, true>(o, m, l, qf, buf, KSTR, buf + KB, VSTR, lo, tq, c, W, lane);
;           }
;         }
	s_branch .Lrt_skip_1
	v_mov_b64_e32 v[144:145], v[104:105]
	v_mov_b64_e32 v[140:141], v[92:93]
	v_mov_b64_e32 v[156:157], v[72:73]
	v_mov_b64_e32 v[164:165], v[52:53]
	v_mov_b64_e32 v[112:113], v[48:49]
	v_mov_b64_e32 v[108:109], v[44:45]
	v_mov_b64_e32 v[124:125], v[40:41]
	v_mov_b64_e32 v[132:133], v[36:37]
	v_mov_b64_e32 v[152:153], v[32:33]
	v_mov_b64_e32 v[148:149], v[28:29]
	v_mov_b64_e32 v[160:161], v[20:21]
	v_mov_b64_e32 v[168:169], v[24:25]
	v_mov_b64_e32 v[120:121], v[16:17]
	v_mov_b64_e32 v[116:117], v[12:13]
	v_mov_b64_e32 v[128:129], v[8:9]
	v_mov_b64_e32 v[136:137], v[4:5]
	v_mov_b64_e32 v[178:179], v[172:173]
	v_mov_b64_e32 v[180:181], v[170:171]
	v_mov_b32_e32 v207, v203
	v_mov_b64_e32 v[142:143], v[102:103]
	v_mov_b64_e32 v[138:139], v[90:91]
	v_mov_b64_e32 v[154:155], v[70:71]
	v_mov_b64_e32 v[162:163], v[50:51]
	v_mov_b32_e32 v209, v204
	v_mov_b64_e32 v[110:111], v[46:47]
	v_mov_b64_e32 v[106:107], v[42:43]
	v_mov_b64_e32 v[122:123], v[38:39]
	v_mov_b64_e32 v[130:131], v[34:35]
	v_mov_b32_e32 v213, v205
	v_mov_b64_e32 v[150:151], v[30:31]
	v_mov_b64_e32 v[146:147], v[26:27]
	v_mov_b64_e32 v[158:159], v[18:19]
	v_mov_b64_e32 v[166:167], v[22:23]
	v_mov_b32_e32 v212, v206
	v_mov_b64_e32 v[118:119], v[14:15]
	v_mov_b64_e32 v[114:115], v[10:11]
	v_mov_b64_e32 v[126:127], v[6:7]
	v_mov_b64_e32 v[134:135], v[2:3]

; template <int NT, int DQK, int DV, int MODE, int PD, class Src> ...
;     ...
;   for (int kcb = kc0; kcb < kc1; kcb += PD) {
; #pragma unroll
;     for (int u = 0; u < PD; ++u) {
;       const int kc = kcb + u;
;       if (kc < kc1) {
.Lrt_skip_1:
.LBB0_1206:
	s_cmp_lt_i32 s35, 9
	s_cbranch_scc0 .LBB0_1107
	s_mov_b32 s35, s74
	s_branch .LBB0_1188

; #define LAS __attribute__((address_space(3)))
; __device__ __forceinline__ float ex2(float x) { return __builtin_amdgcn_exp2f(x); }
; __device__ __forceinline__ f32x4 mfma16(bf16x8 a, bf16x8 b, f32x4 c) { return __builtin_amdgcn_mfma_f32_16x16x32_bf16(a, b, c, 0, 0, 0); }
;   __device__ __forceinline__ bf16_t* W() const { return (bf16_t*)(ws + WS_W); }
; template <int NT, int NKK, int NDT, int MODE, bool MASK> ...
;     ...
; #pragma unroll
;       for (int t = 0; t < 2; ++t)
; #pragma unroll
;         for (int kk = 0; kk < NKK; ++kk) {
;           const bf16x8 kf = *(LAS const bf16x8*)(Kl + oz + (32 * st + 16 * t + r) * KSTR + (32 * kk + 8 * lg) * 2);
; #pragma unroll
;           for (int jj = 0; jj < JB; ++jj) s[jj][t] = mfma16(kf, qf[jh * JB + jj][kk], kk == 0 ? (f32x4){0.f, 0.f, 0.f, 0.f} : s[jj][t]);
;         }
;       __builtin_amdgcn_s_setprio(0);
;       bf16x8 pf[JB];
;       if (NT > JB) __builtin_amdgcn_sched_barrier(0);
; #pragma unroll
;       for (int jj = 0; jj < JB; ++jj) {
;         const int j = jh * JB + jj;
;         float mx = -INFINITY;
; #pragma unroll
;         for (int t = 0; t < 2; ++t)
; #pragma unroll
;           for (int i = 0; i < 4; ++i) {
;             if (MASK) { const int kp = kpos0 + 32 * st + 16 * t + 4 * lg + i; if (!mask_ok<MODE>(tq[j], kp, W)) s[jj][t][i] = -INFINITY; }
;             mx = fmaxf(mx, s[jj][t][i]);
;           }
;         mx = max_x16_x32(mx);
;         if (NT > 2 || __any(mx > m[j] + 8.0f / c)) {
;           const float mnew = fmaxf(m[j], mx);
;           const float ms2 = (mnew == -INFINITY) ? 0.f : mnew;
;           const float alpha = ex2((m[j] - ms2) * c);
;           m[j] = mnew; l[j] *= alpha;
; #pragma unroll
;           for (int dt = 0; dt < NDT; ++dt) o[j][dt] *= alpha;
;         }
;         const float mc = ((m[j] == -INFINITY) ? 0.f : m[j]) * c;
;         float p0[4], p1[4], ps = 0.f;
; #pragma unroll
;         for (int i = 0; i < 4; ++i) { p0[i] = ex2(s[jj][0][i] * c - mc); p1[i] = ex2(s[jj][1][i] * c - mc); ps += p0[i] + p1[i]; }
;         l[j] += ps;
;         pf[jj] = pack8(p0, p1);
.LBB0_1265:
	v_mov_b32_e32 v197, v1
	v_or_b32_e32 v1, s8, v183
	v_or_b32_e32 v196, s8, v204
	v_mov_b32_e32 v246, 0
	v_mov_b32_e32 v199, v212
	v_mov_b32_e32 v232, v214
	v_mov_b32_e32 v235, v215
	v_or_b32_e32 v198, s8, v211
	v_mad_u32_u24 v213, v196, s80, 0
	s_setprio 1
	v_mul_u32_u24_e32 v247, 0x90, v1
	v_add3_u32 v1, v207, v246, v247
	ds_read_b128 v[214:217], v1
	ds_read_b128 v[218:221], v1 offset:64
	s_waitcnt lgkmcnt(1)
	v_mfma_f32_16x16x32_bf16 v[222:225], v[214:217], v[12:15], 0
	v_mfma_f32_16x16x32_bf16 v[214:217], v[214:217], v[20:23], 0
	s_waitcnt lgkmcnt(0)
	v_mfma_f32_16x16x32_bf16 v[222:225], v[218:221], v[16:19], v[222:225]
	v_mfma_f32_16x16x32_bf16 v[214:217], v[218:221], v[24:27], v[214:217]
	ds_read_b128 v[218:221], v1 offset:2304
	ds_read_b128 v[228:231], v1 offset:2368
	s_waitcnt lgkmcnt(1)
	v_mfma_f32_16x16x32_bf16 v[236:239], v[218:221], v[12:15], 0
	v_mfma_f32_16x16x32_bf16 v[218:221], v[218:221], v[20:23], 0
	s_waitcnt lgkmcnt(0)
	v_mfma_f32_16x16x32_bf16 v[236:239], v[228:231], v[16:19], v[236:239]
	v_mfma_f32_16x16x32_bf16 v[218:221], v[228:231], v[24:27], v[218:221]
	s_setprio 0
	v_cmp_le_i32_e32 vcc, v198, v182
	v_cmp_gt_i32_e64 s[12:13], v198, v208
	v_mov_b32_e32 v196, s81
	s_and_b64 vcc, vcc, s[12:13]
	v_cndmask_b32_e32 v212, v196, v222, vcc
	v_cmp_lt_i32_e64 s[12:13], v198, v182
	v_cmp_ge_i32_e64 s[14:15], v198, v208
	v_or_b32_e32 v196, 2, v198
	s_and_b64 s[12:13], s[12:13], s[14:15]
	v_cmp_le_i32_e64 s[14:15], v196, v182
	v_cmp_gt_i32_e64 s[16:17], v196, v208
	v_or_b32_e32 v196, 3, v198
	s_and_b64 s[14:15], s[14:15], s[16:17]
	v_cmp_le_i32_e64 s[16:17], v196, v182
	v_cmp_gt_i32_e64 s[18:19], v196, v208
	s_and_b64 s[16:17], s[16:17], s[18:19]
	v_or_b32_e32 v196, 16, v198
	v_cndmask_b32_e64 v222, v200, v223, s[12:13]
	v_cndmask_b32_e64 v223, v200, v224, s[14:15]
	v_cndmask_b32_e64 v224, v200, v225, s[16:17]
	v_cmp_le_i32_e64 s[18:19], v196, v182
	v_cmp_gt_i32_e64 s[20:21], v196, v208
	v_or_b32_e32 v225, 17, v198
	s_and_b64 s[18:19], s[18:19], s[20:21]
	v_cmp_le_i32_e64 s[20:21], v225, v182
	v_cmp_gt_i32_e64 s[22:23], v225, v208
	v_or_b32_e32 v228, 18, v198
	s_and_b64 s[20:21], s[20:21], s[22:23]
	v_cmp_le_i32_e64 s[22:23], v228, v182
	v_cmp_gt_i32_e64 s[24:25], v228, v208
	v_or_b32_e32 v198, 19, v198
	v_max3_f32 v1, v212, s81, v222
	v_mov_b32_e32 v196, s81
	s_and_b64 s[22:23], s[22:23], s[24:25]
	v_cmp_le_i32_e64 s[24:25], v198, v182
	v_cmp_gt_i32_e64 s[28:29], v198, v208
	v_max3_f32 v1, v1, v223, v224
	v_cndmask_b32_e64 v196, v196, v236, s[18:19]
	v_cndmask_b32_e64 v225, v200, v237, s[20:21]
	s_and_b64 s[24:25], s[24:25], s[28:29]
	v_max3_f32 v1, v1, v196, v225
	v_cndmask_b32_e64 v228, v200, v238, s[22:23]
	v_cndmask_b32_e64 v230, v200, v239, s[24:25]
	v_max3_f32 v1, v1, v228, v230
	v_mov_b32_e32 v198, v1
	s_nop 1
	v_permlane16_swap_b32_e32 v1, v198
	v_max_f32_e32 v1, v1, v198
	v_mov_b32_e32 v198, v1
	s_nop 1
	v_permlane32_swap_b32_e32 v1, v198
	v_max3_f32 v1, v197, v1, v198
	v_cmp_eq_f32_e64 s[28:29], s81, v1
	v_cndmask_b32_e64 v215, v200, v215, s[12:13]
	v_cndmask_b32_e64 v238, v200, v216, s[14:15]
	v_cndmask_b32_e64 v198, v1, 0, s[28:29]
	v_sub_f32_e32 v197, v197, v198
	v_mul_f32_e32 v197, 0x3e38aa3b, v197
	v_exp_f32_e32 v198, v197
	v_mul_f32_e32 v197, 0x3e38aa3b, v1
	v_cndmask_b32_e64 v236, v197, 0, s[28:29]
	v_fma_f32 v196, v196, s42, -v236
	v_exp_f32_e32 v229, v196
	v_fma_f32 v196, v222, s42, -v236
	v_exp_f32_e32 v231, v196
	v_fma_f32 v196, v225, s42, -v236
	v_exp_f32_e32 v237, v196
	v_fma_f32 v196, v223, s42, -v236
	v_exp_f32_e32 v239, v196
	v_fma_f32 v196, v228, s42, -v236
	v_exp_f32_e32 v241, v196
	v_fma_f32 v196, v224, s42, -v236
	v_exp_f32_e32 v243, v196
	v_fma_f32 v196, v230, s42, -v236
	v_exp_f32_e32 v245, v196
	v_mov_b32_e32 v196, s81
	v_cndmask_b32_e32 v228, v196, v214, vcc
	v_max3_f32 v196, v228, s81, v215
	v_cndmask_b32_e64 v242, v200, v217, s[16:17]
	v_fma_f32 v197, v212, s42, -v236
	v_max3_f32 v212, v196, v238, v242
	v_mov_b32_e32 v196, s81
	v_cndmask_b32_e64 v216, v196, v218, s[18:19]
	v_cndmask_b32_e64 v217, v200, v219, s[20:21]
	v_max3_f32 v196, v212, v216, v217
	v_cndmask_b32_e64 v220, v200, v220, s[22:23]
	v_cndmask_b32_e64 v221, v200, v221, s[24:25]
	v_max3_f32 v196, v196, v220, v221
	v_mov_b32_e32 v212, v196
	s_nop 1
	v_permlane16_swap_b32_e32 v196, v212
	v_max_f32_e32 v196, v196, v212
	v_mov_b32_e32 v212, v196
	s_nop 1
	v_permlane32_swap_b32_e32 v196, v212
	v_max3_f32 v212, v199, v196, v212
	v_cmp_eq_f32_e64 s[28:29], s81, v212
	v_pk_mul_f32 v[154:155], v[154:155], v[198:199] op_sel_hi:[1,0]
	v_pk_mul_f32 v[152:153], v[152:153], v[198:199] op_sel_hi:[1,0]
	v_cndmask_b32_e64 v196, v212, 0, s[28:29]
	v_sub_f32_e32 v196, v199, v196
	v_mul_f32_e32 v196, 0x3e38aa3b, v196
	v_exp_f32_e32 v214, v196
	v_mul_f32_e32 v196, 0x3e38aa3b, v212
	v_pk_mul_f32 v[150:151], v[150:151], v[198:199] op_sel_hi:[1,0]
	v_pk_mul_f32 v[148:149], v[148:149], v[198:199] op_sel_hi:[1,0]
	v_pk_mul_f32 v[166:167], v[166:167], v[198:199] op_sel_hi:[1,0]
	v_pk_mul_f32 v[164:165], v[164:165], v[198:199] op_sel_hi:[1,0]
	v_pk_mul_f32 v[174:175], v[174:175], v[198:199] op_sel_hi:[1,0]
	v_pk_mul_f32 v[172:173], v[172:173], v[198:199] op_sel_hi:[1,0]
	v_cndmask_b32_e64 v199, v196, 0, s[28:29]
	v_fma_f32 v196, v228, s42, -v199
	v_fma_f32 v216, v216, s42, -v199
	v_exp_f32_e32 v197, v197
	v_exp_f32_e32 v196, v196
	v_exp_f32_e32 v228, v216
	v_pk_mul_f32 v[122:123], v[122:123], v[214:215] op_sel_hi:[1,0]
	v_pk_mul_f32 v[120:121], v[120:121], v[214:215] op_sel_hi:[1,0]
	v_pk_mul_f32 v[118:119], v[118:119], v[214:215] op_sel_hi:[1,0]
	v_pk_mul_f32 v[116:117], v[116:117], v[214:215] op_sel_hi:[1,0]
; __device__ __forceinline__ float ex2(float x) { return __builtin_amdgcn_exp2f(x); }
; __device__ __forceinline__ f32x4 mfma16(bf16x8 a, bf16x8 b, f32x4 c) { return __builtin_amdgcn_mfma_f32_16x16x32_bf16(a, b, c, 0, 0, 0); }
; __device__ __forceinline__ s16x4 ds_tr(LAS const unsigned char* p) { return __builtin_bit_cast(s16x4, __builtin_amdgcn_ds_read_tr16_b64_v4i16((LAS v4i16_t*)p)); }
; template <int NT, int NKK, int NDT, int MODE, bool MASK> ...
;     ...
;           m[j] = mnew; l[j] *= alpha;
; #pragma unroll
;           for (int dt = 0; dt < NDT; ++dt) o[j][dt] *= alpha;
;         }
;         const float mc = ((m[j] == -INFINITY) ? 0.f : m[j]) * c;
;         float p0[4], p1[4], ps = 0.f;
; #pragma unroll
;         for (int i = 0; i < 4; ++i) { p0[i] = ex2(s[jj][0][i] * c - mc); p1[i] = ex2(s[jj][1][i] * c - mc); ps += p0[i] + p1[i]; }
;         l[j] += ps;
;         pf[jj] = pack8(p0, p1);
;       }
;       if (NT > JB) __builtin_amdgcn_sched_barrier(0);
;       __builtin_amdgcn_s_setprio(1);
; #pragma unroll
;       for (int dt = 0; dt < NDT; ++dt) {
;         const s16x4 v0 = ds_tr(Vl + oz + (32 * st + 4 * lg + vq) * VSTR + (16 * dt + 4 * vp) * 2);
;         const s16x4 v1 = ds_tr(Vl + oz + (32 * st + 16 + 4 * lg + vq) * VSTR + (16 * dt + 4 * vp) * 2);
;         const bf16x8 vf = (bf16x8){v0[0], v0[1], v0[2], v0[3], v1[0], v1[1], v1[2], v1[3]};
; #pragma unroll
;         for (int jj = 0; jj < JB; ++jj) o[jh * JB + jj][dt] = mfma16(vf, pf[jj], o[jh * JB + jj][dt]);
	v_pk_mul_f32 v[134:135], v[134:135], v[214:215] op_sel_hi:[1,0]
	v_pk_mul_f32 v[132:133], v[132:133], v[214:215] op_sel_hi:[1,0]
	v_pk_mul_f32 v[142:143], v[142:143], v[214:215] op_sel_hi:[1,0]
	v_fma_f32 v215, v215, s42, -v199
	v_cvt_pk_bf16_f32 v222, v197, v231
	v_exp_f32_e32 v230, v215
	v_fma_f32 v215, v217, s42, -v199
	v_pk_add_f32 v[216:217], v[196:197], v[228:229]
	v_fma_f32 v197, v238, s42, -v199
	v_exp_f32_e32 v238, v197
	v_fma_f32 v197, v220, s42, -v199
	v_exp_f32_e32 v236, v215
	v_exp_f32_e32 v240, v197
	v_fma_f32 v197, v242, s42, -v199
	v_exp_f32_e32 v242, v197
	v_fma_f32 v197, v221, s42, -v199
	v_exp_f32_e32 v244, v197
	v_pk_add_f32 v[216:217], v[216:217], 0 op_sel_hi:[1,0]
	v_pk_add_f32 v[218:219], v[230:231], v[236:237]
	v_pk_mul_f32 v[140:141], v[140:141], v[214:215] op_sel_hi:[1,0]
	v_mov_b32_e32 v215, v198
	v_pk_add_f32 v[198:199], v[218:219], v[216:217]
	v_pk_add_f32 v[216:217], v[238:239], v[240:241]
	v_cvt_pk_bf16_f32 v223, v239, v243
	v_pk_add_f32 v[198:199], v[216:217], v[198:199]
	v_pk_add_f32 v[216:217], v[242:243], v[244:245]
	v_cvt_pk_bf16_f32 v224, v229, v237
	v_pk_add_f32 v[198:199], v[216:217], v[198:199]
	v_cvt_pk_bf16_f32 v225, v241, v245
	v_pk_fma_f32 v[194:195], v[194:195], v[214:215], v[198:199]
	v_cvt_pk_bf16_f32 v214, v196, v230
	v_cvt_pk_bf16_f32 v215, v238, v242
	v_cvt_pk_bf16_f32 v216, v228, v236
	v_cvt_pk_bf16_f32 v217, v240, v244
	s_setprio 1
	v_add3_u32 v196, v213, v246, v206
	ds_read_b64_tr_b16 v[220:221], v196 offset:11776
	ds_read_b64_tr_b16 v[218:219], v196 offset:9216
	ds_read_b64_tr_b16 v[228:229], v196 offset:9248
	ds_read_b64_tr_b16 v[230:231], v196 offset:11808
	s_waitcnt lgkmcnt(2)
	v_mfma_f32_16x16x32_bf16 v[152:155], v[218:221], v[222:225], v[152:155]
	v_mfma_f32_16x16x32_bf16 v[120:123], v[218:221], v[214:217], v[120:123]
	ds_read_b64_tr_b16 v[218:219], v196 offset:9280
	ds_read_b64_tr_b16 v[220:221], v196 offset:11840
	s_waitcnt lgkmcnt(0)
	v_mfma_f32_16x16x32_bf16 v[164:167], v[218:221], v[222:225], v[164:167]
	v_mfma_f32_16x16x32_bf16 v[132:135], v[218:221], v[214:217], v[132:135]
	ds_read_b64_tr_b16 v[218:219], v196 offset:9312
	ds_read_b64_tr_b16 v[220:221], v196 offset:11872
	v_mfma_f32_16x16x32_bf16 v[148:151], v[228:231], v[222:225], v[148:151]
	v_mfma_f32_16x16x32_bf16 v[116:119], v[228:231], v[214:217], v[116:119]
	s_waitcnt lgkmcnt(0)
	v_mfma_f32_16x16x32_bf16 v[172:175], v[218:221], v[222:225], v[172:175]
	v_mfma_f32_16x16x32_bf16 v[140:143], v[218:221], v[214:217], v[140:143]
	s_setprio 0
	v_mov_b32_e32 v248, 0
	s_setprio 1
	v_add3_u32 v196, v207, v248, v247
	ds_read_b128 v[214:217], v196
	ds_read_b128 v[218:221], v196 offset:64
	ds_read_b128 v[228:231], v196 offset:2304
	ds_read_b128 v[236:239], v196 offset:2368
	s_waitcnt lgkmcnt(3)
	v_mfma_f32_16x16x32_bf16 v[222:225], v[214:217], v[28:31], 0
	v_mfma_f32_16x16x32_bf16 v[214:217], v[214:217], v[36:39], 0
	s_waitcnt lgkmcnt(1)
	v_mfma_f32_16x16x32_bf16 v[240:243], v[228:231], v[28:31], 0
	v_mfma_f32_16x16x32_bf16 v[228:231], v[228:231], v[36:39], 0
	v_mfma_f32_16x16x32_bf16 v[222:225], v[218:221], v[32:35], v[222:225]
	v_mfma_f32_16x16x32_bf16 v[216:219], v[218:221], v[40:43], v[214:217]
	s_waitcnt lgkmcnt(0)
; __device__ __forceinline__ float ex2(float x) { return __builtin_amdgcn_exp2f(x); }
; __device__ __forceinline__ f32x4 mfma16(bf16x8 a, bf16x8 b, f32x4 c) { return __builtin_amdgcn_mfma_f32_16x16x32_bf16(a, b, c, 0, 0, 0); }
; __device__ __forceinline__ s16x4 ds_tr(LAS const unsigned char* p) { return __builtin_bit_cast(s16x4, __builtin_amdgcn_ds_read_tr16_b64_v4i16((LAS v4i16_t*)p)); }
;   __device__ __forceinline__ bf16_t* W() const { return (bf16_t*)(ws + WS_W); }
; template <int NT, int NKK, int NDT, int MODE, bool MASK> ...
;     ...
;       for (int jj = 0; jj < JB; ++jj) {
;         const int j = jh * JB + jj;
;         float mx = -INFINITY;
; #pragma unroll
;         for (int t = 0; t < 2; ++t)
; #pragma unroll
;           for (int i = 0; i < 4; ++i) {
;             if (MASK) { const int kp = kpos0 + 32 * st + 16 * t + 4 * lg + i; if (!mask_ok<MODE>(tq[j], kp, W)) s[jj][t][i] = -INFINITY; }
;             mx = fmaxf(mx, s[jj][t][i]);
;           }
;         mx = max_x16_x32(mx);
;         if (NT > 2 || __any(mx > m[j] + 8.0f / c)) {
;           const float mnew = fmaxf(m[j], mx);
;           const float ms2 = (mnew == -INFINITY) ? 0.f : mnew;
;           const float alpha = ex2((m[j] - ms2) * c);
;           m[j] = mnew; l[j] *= alpha;
; #pragma unroll
;           for (int dt = 0; dt < NDT; ++dt) o[j][dt] *= alpha;
;         }
;         const float mc = ((m[j] == -INFINITY) ? 0.f : m[j]) * c;
;         float p0[4], p1[4], ps = 0.f;
; #pragma unroll
;         for (int i = 0; i < 4; ++i) { p0[i] = ex2(s[jj][0][i] * c - mc); p1[i] = ex2(s[jj][1][i] * c - mc); ps += p0[i] + p1[i]; }
;         l[j] += ps;
;         pf[jj] = pack8(p0, p1);
;       }
;       if (NT > JB) __builtin_amdgcn_sched_barrier(0);
;       __builtin_amdgcn_s_setprio(1);
; #pragma unroll
;       for (int dt = 0; dt < NDT; ++dt) {
;         const s16x4 v0 = ds_tr(Vl + oz + (32 * st + 4 * lg + vq) * VSTR + (16 * dt + 4 * vp) * 2);
;         const s16x4 v1 = ds_tr(Vl + oz + (32 * st + 16 + 4 * lg + vq) * VSTR + (16 * dt + 4 * vp) * 2);
;         const bf16x8 vf = (bf16x8){v0[0], v0[1], v0[2], v0[3], v1[0], v1[1], v1[2], v1[3]};
; #pragma unroll
;         for (int jj = 0; jj < JB; ++jj) o[jh * JB + jj][dt] = mfma16(vf, pf[jj], o[jh * JB + jj][dt]);
;       }
;       __builtin_amdgcn_s_setprio(0);
;       if (NT > JB) __builtin_amdgcn_sched_barrier(0);
	v_mfma_f32_16x16x32_bf16 v[240:243], v[236:239], v[32:35], v[240:243]
	v_mfma_f32_16x16x32_bf16 v[228:231], v[236:239], v[40:43], v[228:231]
	s_setprio 0
	v_mov_b32_e32 v196, s81
	s_nop 0
	v_cndmask_b32_e32 v197, v196, v222, vcc
	v_cndmask_b32_e64 v199, v200, v223, s[12:13]
	v_max3_f32 v196, v197, s81, v199
	v_cndmask_b32_e64 v215, v200, v224, s[14:15]
	v_cndmask_b32_e64 v220, v200, v225, s[16:17]
	v_max3_f32 v198, v196, v215, v220
	v_mov_b32_e32 v196, s81
	v_cndmask_b32_e64 v196, v196, v240, s[18:19]
	v_cndmask_b32_e64 v221, v200, v241, s[20:21]
	v_max3_f32 v198, v198, v196, v221
	v_cndmask_b32_e64 v222, v200, v242, s[22:23]
	v_cndmask_b32_e64 v223, v200, v243, s[24:25]
	v_max3_f32 v198, v198, v222, v223
	v_mov_b32_e32 v214, v198
	s_nop 1
	v_permlane16_swap_b32_e32 v198, v214
	v_max_f32_e32 v198, v198, v214
	v_mov_b32_e32 v214, v198
	s_nop 1
	v_permlane32_swap_b32_e32 v198, v214
	v_max3_f32 v214, v232, v198, v214
	v_cmp_eq_f32_e64 s[28:29], s81, v214
	v_mul_f32_e32 v224, 0x3e38aa3b, v214
	v_cndmask_b32_e64 v217, v200, v217, s[12:13]
	v_cndmask_b32_e64 v224, v224, 0, s[28:29]
	v_fma_f32 v196, v196, s42, -v224
	v_cndmask_b32_e64 v198, v214, 0, s[28:29]
	v_exp_f32_e32 v225, v196
	v_fma_f32 v196, v199, s42, -v224
	v_sub_f32_e32 v198, v232, v198
	v_exp_f32_e32 v237, v196
	v_fma_f32 v196, v221, s42, -v224
	v_mul_f32_e32 v198, 0x3e38aa3b, v198
	v_exp_f32_e32 v239, v196
	v_fma_f32 v196, v215, s42, -v224
	v_exp_f32_e32 v198, v198
	v_exp_f32_e32 v241, v196
	v_fma_f32 v196, v222, s42, -v224
	v_exp_f32_e32 v243, v196
	v_fma_f32 v196, v220, s42, -v224
	v_exp_f32_e32 v245, v196
	v_fma_f32 v196, v223, s42, -v224
	v_exp_f32_e32 v247, v196
	v_mov_b32_e32 v196, s81
	v_pk_mul_f32 v[162:163], v[162:163], v[198:199] op_sel_hi:[1,0]
	v_pk_mul_f32 v[160:161], v[160:161], v[198:199] op_sel_hi:[1,0]
	v_pk_mul_f32 v[158:159], v[158:159], v[198:199] op_sel_hi:[1,0]
	v_pk_mul_f32 v[156:157], v[156:157], v[198:199] op_sel_hi:[1,0]
	v_pk_mul_f32 v[170:171], v[170:171], v[198:199] op_sel_hi:[1,0]
	v_pk_mul_f32 v[168:169], v[168:169], v[198:199] op_sel_hi:[1,0]
	v_pk_mul_f32 v[178:179], v[178:179], v[198:199] op_sel_hi:[1,0]
	v_pk_mul_f32 v[176:177], v[176:177], v[198:199] op_sel_hi:[1,0]
	v_cndmask_b32_e32 v199, v196, v216, vcc
	v_max3_f32 v196, v199, s81, v217
	v_cndmask_b32_e64 v232, v200, v218, s[14:15]
	v_cndmask_b32_e64 v244, v200, v219, s[16:17]
	v_max3_f32 v215, v196, v232, v244
	v_mov_b32_e32 v196, s81
	v_cndmask_b32_e64 v218, v196, v228, s[18:19]
	v_cndmask_b32_e64 v219, v200, v229, s[20:21]
	v_max3_f32 v196, v215, v218, v219
	v_cndmask_b32_e64 v230, v200, v230, s[22:23]
	v_cndmask_b32_e64 v231, v200, v231, s[24:25]
	v_max3_f32 v196, v196, v230, v231
	v_mov_b32_e32 v215, v196
	s_nop 1
	v_permlane16_swap_b32_e32 v196, v215
	v_max_f32_e32 v196, v196, v215
	v_mov_b32_e32 v215, v196
	s_nop 1
	v_permlane32_swap_b32_e32 v196, v215
	v_max3_f32 v215, v235, v196, v215
	v_cmp_eq_f32_e32 vcc, s81, v215
	v_fma_f32 v197, v197, s42, -v224
	v_exp_f32_e32 v197, v197
	v_cndmask_b32_e64 v196, v215, 0, vcc
	v_sub_f32_e32 v196, v235, v196
	v_mul_f32_e32 v196, 0x3e38aa3b, v196
	v_exp_f32_e32 v216, v196
	v_mul_f32_e32 v196, 0x3e38aa3b, v215
	v_cndmask_b32_e64 v235, v196, 0, vcc
	v_fma_f32 v196, v199, s42, -v235
	v_fma_f32 v199, v218, s42, -v235
	v_exp_f32_e32 v196, v196
	v_exp_f32_e32 v224, v199
	v_fma_f32 v199, v217, s42, -v235
	v_cvt_pk_bf16_f32 v220, v197, v237
	v_exp_f32_e32 v236, v199
	v_fma_f32 v199, v219, s42, -v235
	v_pk_add_f32 v[218:219], v[196:197], v[224:225]
	v_fma_f32 v197, v232, s42, -v235
	v_exp_f32_e32 v240, v197
	v_fma_f32 v197, v230, s42, -v235
	v_exp_f32_e32 v238, v199
	v_exp_f32_e32 v242, v197
	v_fma_f32 v197, v244, s42, -v235
	v_exp_f32_e32 v244, v197
	v_fma_f32 v197, v231, s42, -v235
	v_exp_f32_e32 v246, v197
	v_pk_add_f32 v[218:219], v[218:219], 0 op_sel_hi:[1,0]
	v_pk_add_f32 v[228:229], v[236:237], v[238:239]
	v_pk_mul_f32 v[130:131], v[130:131], v[216:217] op_sel_hi:[1,0]
	v_pk_mul_f32 v[128:129], v[128:129], v[216:217] op_sel_hi:[1,0]
	v_pk_mul_f32 v[126:127], v[126:127], v[216:217] op_sel_hi:[1,0]
	v_pk_mul_f32 v[124:125], v[124:125], v[216:217] op_sel_hi:[1,0]
	v_pk_mul_f32 v[138:139], v[138:139], v[216:217] op_sel_hi:[1,0]
	v_pk_mul_f32 v[136:137], v[136:137], v[216:217] op_sel_hi:[1,0]
	v_pk_mul_f32 v[146:147], v[146:147], v[216:217] op_sel_hi:[1,0]
	v_pk_mul_f32 v[144:145], v[144:145], v[216:217] op_sel_hi:[1,0]
	v_mov_b32_e32 v217, v198
	v_pk_add_f32 v[198:199], v[228:229], v[218:219]
	v_pk_add_f32 v[218:219], v[240:241], v[242:243]
	v_cvt_pk_bf16_f32 v221, v241, v245
	v_pk_add_f32 v[198:199], v[218:219], v[198:199]
	v_pk_add_f32 v[218:219], v[244:245], v[246:247]
	v_cvt_pk_bf16_f32 v222, v225, v239
	v_pk_add_f32 v[198:199], v[218:219], v[198:199]
	v_cvt_pk_bf16_f32 v223, v243, v247
	v_pk_fma_f32 v[202:203], v[202:203], v[216:217], v[198:199]
	v_cvt_pk_bf16_f32 v216, v196, v236
	v_cvt_pk_bf16_f32 v217, v240, v244
	v_cvt_pk_bf16_f32 v218, v224, v238
	v_cvt_pk_bf16_f32 v219, v242, v246
	s_setprio 1
	v_add3_u32 v196, v213, v248, v206
	ds_read_b64_tr_b16 v[230:231], v196 offset:11776
	ds_read_b64_tr_b16 v[228:229], v196 offset:9216
	ds_read_b64_tr_b16 v[236:237], v196 offset:9248
	ds_read_b64_tr_b16 v[238:239], v196 offset:11808
	s_waitcnt lgkmcnt(2)
	v_mfma_f32_16x16x32_bf16 v[160:163], v[228:231], v[220:223], v[160:163]
	v_mfma_f32_16x16x32_bf16 v[128:131], v[228:231], v[216:219], v[128:131]
	ds_read_b64_tr_b16 v[228:229], v196 offset:9280
	ds_read_b64_tr_b16 v[230:231], v196 offset:11840
	s_waitcnt lgkmcnt(0)
	v_mfma_f32_16x16x32_bf16 v[168:171], v[228:231], v[220:223], v[168:171]
	v_mfma_f32_16x16x32_bf16 v[136:139], v[228:231], v[216:219], v[136:139]
	ds_read_b64_tr_b16 v[228:229], v196 offset:9312
	ds_read_b64_tr_b16 v[230:231], v196 offset:11872
	v_mfma_f32_16x16x32_bf16 v[156:159], v[236:239], v[220:223], v[156:159]
	v_mfma_f32_16x16x32_bf16 v[124:127], v[236:239], v[216:219], v[124:127]
	s_waitcnt lgkmcnt(0)
	v_mfma_f32_16x16x32_bf16 v[176:179], v[228:231], v[220:223], v[176:179]
	v_mfma_f32_16x16x32_bf16 v[144:147], v[228:231], v[216:219], v[144:147]
	s_setprio 0
	s_mov_b32 s8, 32
	s_and_b64 vcc, exec, s[70:71]
	s_mov_b64 s[70:71], 0
	s_cbranch_vccnz .LBB0_1265
	s_mov_b64 s[12:13], 0

; template <int NT, int NKK, int NDT, int MODE, bool MASK> ...
;     ...
;     for (int jh = 0; jh < NT / JB; ++jh) {
;       int oz = 0; if (NT > JB) asm volatile("" : "+v"(oz));
;       f32x4 s[JB][2];
;       __builtin_amdgcn_s_setprio(1);
; #pragma unroll
;       for (int t = 0; t < 2; ++t)
; #pragma unroll
;         for (int kk = 0; kk < NKK; ++kk) {
;           const bf16x8 kf = *(LAS const bf16x8*)(Kl + oz + (32 * st + 16 * t + r) * KSTR + (32 * kk + 8 * lg) * 2);
; #pragma unroll
;           for (int jj = 0; jj < JB; ++jj) s[jj][t] = mfma16(kf, qf[jh * JB + jj][kk], kk == 0 ? (f32x4){0.f, 0.f, 0.f, 0.f} : s[jj][t]);
;         }
;       __builtin_amdgcn_s_setprio(0);
;       bf16x8 pf[JB];
;       if (NT > JB) __builtin_amdgcn_sched_barrier(0);
; #pragma unroll
;       for (int jj = 0; jj < JB; ++jj) {
;         const int j = jh * JB + jj;
;         float mx = -INFINITY;
; #pragma unroll
;         for (int t = 0; t < 2; ++t)
; #pragma unroll
;           for (int i = 0; i < 4; ++i) {
;             if (MASK) { const int kp = kpos0 + 32 * st + 16 * t + 4 * lg + i; if (!mask_ok<MODE>(tq[j], kp, W)) s[jj][t][i] = -INFINITY; }
;             mx = fmaxf(mx, s[jj][t][i]);
;           }
;         mx = max_x16_x32(mx);
;         if (NT > 2 || __any(mx > m[j] + 8.0f / c)) {
;           const float mnew = fmaxf(m[j], mx);
;           const float ms2 = (mnew == -INFINITY) ? 0.f : mnew;
;           const float alpha = ex2((m[j] - ms2) * c);
;           m[j] = mnew; l[j] *= alpha;
; #pragma unroll
;           for (int dt = 0; dt < NDT; ++dt) o[j][dt] *= alpha;
;         }
;         const float mc = ((m[j] == -INFINITY) ? 0.f : m[j]) * c;
;         float p0[4], p1[4], ps = 0.f;
; #pragma unroll
;         for (int i = 0; i < 4; ++i) { p0[i] = ex2(s[jj][0][i] * c - mc); p1[i] = ex2(s[jj][1][i] * c - mc); ps += p0[i] + p1[i]; }
;         l[j] += ps;
;         pf[jj] = pack8(p0, p1);
;       }
;       if (NT > JB) __builtin_amdgcn_sched_barrier(0);
;       __builtin_amdgcn_s_setprio(1);
; #pragma unroll
;       for (int dt = 0; dt < NDT; ++dt) {
;         const s16x4 v0 = ds_tr(Vl + oz + (32 * st + 4 * lg + vq) * VSTR + (16 * dt + 4 * vp) * 2);
;         const s16x4 v1 = ds_tr(Vl + oz + (32 * st + 16 + 4 * lg + vq) * VSTR + (16 * dt + 4 * vp) * 2);
;         const bf16x8 vf = (bf16x8){v0[0], v0[1], v0[2], v0[3], v1[0], v1[1], v1[2], v1[3]};
; #pragma unroll
.LBB0_1269:
	v_or_b32_e32 v1, s8, v204
	v_mov_b32_e32 v150, 0
	v_mov_b32_e32 v136, v190
	v_mov_b32_e32 v138, v191
	v_mov_b32_e32 v148, v192
	v_mov_b32_e32 v149, v193
	v_or_b32_e32 v116, s8, v183
	v_mad_u32_u24 v1, v1, s80, 0
	s_setprio 1
	v_mul_u32_u24_e32 v151, 0x90, v116
	v_add3_u32 v128, v207, v150, v151
	ds_read_b128 v[116:119], v128
	ds_read_b128 v[120:123], v128 offset:64
	s_waitcnt lgkmcnt(1)
	v_mfma_f32_16x16x32_bf16 v[124:127], v[116:119], v[12:15], 0
	v_mfma_f32_16x16x32_bf16 v[116:119], v[116:119], v[20:23], 0
	s_waitcnt lgkmcnt(0)
	v_mfma_f32_16x16x32_bf16 v[124:127], v[120:123], v[16:19], v[124:127]
	v_mfma_f32_16x16x32_bf16 v[116:119], v[120:123], v[24:27], v[116:119]
	ds_read_b128 v[120:123], v128 offset:2304
	ds_read_b128 v[128:131], v128 offset:2368
	s_waitcnt lgkmcnt(1)
	v_mfma_f32_16x16x32_bf16 v[132:135], v[120:123], v[12:15], 0
	v_mfma_f32_16x16x32_bf16 v[120:123], v[120:123], v[20:23], 0
	s_waitcnt lgkmcnt(0)
	v_mfma_f32_16x16x32_bf16 v[132:135], v[128:131], v[16:19], v[132:135]
	v_mfma_f32_16x16x32_bf16 v[120:123], v[128:131], v[24:27], v[120:123]
	s_setprio 0
	v_max3_f32 v128, v124, s81, v125
	v_max3_f32 v128, v128, v126, v127
	s_nop 3
	v_max3_f32 v128, v128, v132, v133
	v_max3_f32 v128, v128, v134, v135
	v_mov_b32_e32 v129, v128
	s_nop 1
	v_permlane16_swap_b32_e32 v128, v129
	v_max_f32_e32 v128, v128, v129
	v_mov_b32_e32 v129, v128
	s_nop 1
	v_permlane32_swap_b32_e32 v128, v129
	v_max3_f32 v190, v136, v128, v129
	v_cmp_eq_f32_e32 vcc, s81, v190
	s_nop 1
	v_cndmask_b32_e64 v128, v190, 0, vcc
	v_sub_f32_e32 v128, v136, v128
	v_mul_f32_e32 v128, 0x3e38aa3b, v128
	v_exp_f32_e32 v128, v128
	s_nop 0
	v_pk_mul_f32 v[106:107], v[106:107], v[128:129] op_sel_hi:[1,0]
	v_pk_mul_f32 v[104:105], v[104:105], v[128:129] op_sel_hi:[1,0]
	v_pk_mul_f32 v[102:103], v[102:103], v[128:129] op_sel_hi:[1,0]
	v_pk_mul_f32 v[100:101], v[100:101], v[128:129] op_sel_hi:[1,0]
	v_pk_mul_f32 v[110:111], v[110:111], v[128:129] op_sel_hi:[1,0]
	v_pk_mul_f32 v[108:109], v[108:109], v[128:129] op_sel_hi:[1,0]
	v_pk_mul_f32 v[114:115], v[114:115], v[128:129] op_sel_hi:[1,0]
	v_pk_mul_f32 v[112:113], v[112:113], v[128:129] op_sel_hi:[1,0]
	v_mul_f32_e32 v129, 0x3e38aa3b, v190
	v_cndmask_b32_e64 v129, v129, 0, vcc
	v_fma_f32 v124, v124, s42, -v129
	v_exp_f32_e32 v131, v124
	v_fma_f32 v124, v132, s42, -v129
	v_exp_f32_e32 v137, v124
	v_fma_f32 v124, v125, s42, -v129
	v_max3_f32 v125, v116, s81, v117
	v_max3_f32 v125, v125, v118, v119
	v_max3_f32 v125, v125, v120, v121
	v_exp_f32_e32 v139, v124
	v_fma_f32 v124, v133, s42, -v129
	v_max3_f32 v125, v125, v122, v123
	v_exp_f32_e32 v133, v124
	v_fma_f32 v124, v126, s42, -v129
	v_mov_b32_e32 v126, v125
	s_nop 1
	v_permlane16_swap_b32_e32 v125, v126
	v_max_f32_e32 v125, v125, v126
	v_mov_b32_e32 v126, v125
	v_exp_f32_e32 v141, v124
	v_fma_f32 v124, v134, s42, -v129
	v_permlane32_swap_b32_e32 v125, v126
	v_exp_f32_e32 v143, v124
	v_fma_f32 v124, v127, s42, -v129
	v_max3_f32 v191, v138, v125, v126
	v_exp_f32_e32 v145, v124
	v_fma_f32 v124, v135, s42, -v129
	v_cmp_eq_f32_e32 vcc, s81, v191
	v_mul_f32_e32 v129, 0x3e38aa3b, v191
	v_exp_f32_e32 v135, v124
	v_cndmask_b32_e64 v129, v129, 0, vcc
	v_fma_f32 v116, v116, s42, -v129
	v_exp_f32_e32 v130, v116
	v_fma_f32 v116, v120, s42, -v129
	v_cndmask_b32_e64 v125, v191, 0, vcc
	v_exp_f32_e32 v136, v116
	v_fma_f32 v116, v117, s42, -v129
	v_fma_f32 v118, v118, s42, -v129
	v_sub_f32_e32 v125, v138, v125
	v_exp_f32_e32 v138, v116
	v_fma_f32 v116, v121, s42, -v129
	v_exp_f32_e32 v140, v118
	v_fma_f32 v118, v122, s42, -v129
	v_exp_f32_e32 v132, v116
	v_exp_f32_e32 v142, v118
	v_fma_f32 v118, v119, s42, -v129
	v_exp_f32_e32 v144, v118
	v_fma_f32 v118, v123, s42, -v129
	v_mul_f32_e32 v125, 0x3e38aa3b, v125
	v_exp_f32_e32 v134, v118
	v_exp_f32_e32 v146, v125
	v_pk_add_f32 v[116:117], v[130:131], v[136:137]
	v_pk_add_f32 v[120:121], v[138:139], v[132:133]
	v_pk_add_f32 v[116:117], v[116:117], 0 op_sel_hi:[1,0]
	v_pk_add_f32 v[118:119], v[140:141], v[142:143]
	v_pk_add_f32 v[116:117], v[120:121], v[116:117]
	v_pk_mul_f32 v[74:75], v[74:75], v[146:147] op_sel_hi:[1,0]
	v_pk_add_f32 v[116:117], v[118:119], v[116:117]
	v_pk_add_f32 v[118:119], v[144:145], v[134:135]
	v_pk_mul_f32 v[72:73], v[72:73], v[146:147] op_sel_hi:[1,0]
	v_pk_mul_f32 v[70:71], v[70:71], v[146:147] op_sel_hi:[1,0]
	v_pk_mul_f32 v[68:69], v[68:69], v[146:147] op_sel_hi:[1,0]
	v_pk_mul_f32 v[78:79], v[78:79], v[146:147] op_sel_hi:[1,0]
	v_pk_mul_f32 v[76:77], v[76:77], v[146:147] op_sel_hi:[1,0]
	v_pk_mul_f32 v[82:83], v[82:83], v[146:147] op_sel_hi:[1,0]
	v_pk_mul_f32 v[80:81], v[80:81], v[146:147] op_sel_hi:[1,0]
	v_mov_b32_e32 v147, v128
	v_pk_add_f32 v[116:117], v[118:119], v[116:117]
	v_cvt_pk_bf16_f32 v124, v131, v139
	v_pk_fma_f32 v[2:3], v[2:3], v[146:147], v[116:117]
	v_cvt_pk_bf16_f32 v125, v141, v145
	v_cvt_pk_bf16_f32 v126, v137, v133
	v_cvt_pk_bf16_f32 v127, v143, v135
	v_cvt_pk_bf16_f32 v116, v130, v138
	v_cvt_pk_bf16_f32 v117, v140, v144
	v_cvt_pk_bf16_f32 v118, v136, v132
	v_cvt_pk_bf16_f32 v119, v142, v134
	s_setprio 1
	v_add3_u32 v132, v1, v150, v206
	ds_read_b64_tr_b16 v[122:123], v132 offset:11776
	ds_read_b64_tr_b16 v[120:121], v132 offset:9216
	ds_read_b64_tr_b16 v[128:129], v132 offset:9248
	ds_read_b64_tr_b16 v[130:131], v132 offset:11808
	s_waitcnt lgkmcnt(2)
	v_mfma_f32_16x16x32_bf16 v[104:107], v[120:123], v[124:127], v[104:107]
	v_mfma_f32_16x16x32_bf16 v[72:75], v[120:123], v[116:119], v[72:75]
	ds_read_b64_tr_b16 v[120:121], v132 offset:9280
	ds_read_b64_tr_b16 v[122:123], v132 offset:11840
	s_waitcnt lgkmcnt(0)
; template <int NT, int NKK, int NDT, int MODE, bool MASK> ...
;     ...
;     for (int jh = 0; jh < NT / JB; ++jh) {
;       int oz = 0; if (NT > JB) asm volatile("" : "+v"(oz));
;       f32x4 s[JB][2];
;       __builtin_amdgcn_s_setprio(1);
; #pragma unroll
;       for (int t = 0; t < 2; ++t)
; #pragma unroll
;         for (int kk = 0; kk < NKK; ++kk) {
;           const bf16x8 kf = *(LAS const bf16x8*)(Kl + oz + (32 * st + 16 * t + r) * KSTR + (32 * kk + 8 * lg) * 2);
; #pragma unroll
;           for (int jj = 0; jj < JB; ++jj) s[jj][t] = mfma16(kf, qf[jh * JB + jj][kk], kk == 0 ? (f32x4){0.f, 0.f, 0.f, 0.f} : s[jj][t]);
;         }
;       __builtin_amdgcn_s_setprio(0);
;       bf16x8 pf[JB];
;       if (NT > JB) __builtin_amdgcn_sched_barrier(0);
; #pragma unroll
;       for (int jj = 0; jj < JB; ++jj) {
;         const int j = jh * JB + jj;
;         float mx = -INFINITY;
; #pragma unroll
;         for (int t = 0; t < 2; ++t)
; #pragma unroll
;           for (int i = 0; i < 4; ++i) {
;             if (MASK) { const int kp = kpos0 + 32 * st + 16 * t + 4 * lg + i; if (!mask_ok<MODE>(tq[j], kp, W)) s[jj][t][i] = -INFINITY; }
;             mx = fmaxf(mx, s[jj][t][i]);
;           }
;         mx = max_x16_x32(mx);
;         if (NT > 2 || __any(mx > m[j] + 8.0f / c)) {
;           const float mnew = fmaxf(m[j], mx);
;           const float ms2 = (mnew == -INFINITY) ? 0.f : mnew;
;           const float alpha = ex2((m[j] - ms2) * c);
;           m[j] = mnew; l[j] *= alpha;
; #pragma unroll
;           for (int dt = 0; dt < NDT; ++dt) o[j][dt] *= alpha;
;         }
;         const float mc = ((m[j] == -INFINITY) ? 0.f : m[j]) * c;
;         float p0[4], p1[4], ps = 0.f;
; #pragma unroll
;         for (int i = 0; i < 4; ++i) { p0[i] = ex2(s[jj][0][i] * c - mc); p1[i] = ex2(s[jj][1][i] * c - mc); ps += p0[i] + p1[i]; }
;         l[j] += ps;
;         pf[jj] = pack8(p0, p1);
;       }
;       if (NT > JB) __builtin_amdgcn_sched_barrier(0);
;       __builtin_amdgcn_s_setprio(1);
; #pragma unroll
;       for (int dt = 0; dt < NDT; ++dt) {
;         const s16x4 v0 = ds_tr(Vl + oz + (32 * st + 4 * lg + vq) * VSTR + (16 * dt + 4 * vp) * 2);
;         const s16x4 v1 = ds_tr(Vl + oz + (32 * st + 16 + 4 * lg + vq) * VSTR + (16 * dt + 4 * vp) * 2);
;         const bf16x8 vf = (bf16x8){v0[0], v0[1], v0[2], v0[3], v1[0], v1[1], v1[2], v1[3]};
; #pragma unroll
	v_mfma_f32_16x16x32_bf16 v[108:111], v[120:123], v[124:127], v[108:111]
	v_mfma_f32_16x16x32_bf16 v[76:79], v[120:123], v[116:119], v[76:79]
	ds_read_b64_tr_b16 v[120:121], v132 offset:9312
	ds_read_b64_tr_b16 v[122:123], v132 offset:11872
	v_mfma_f32_16x16x32_bf16 v[100:103], v[128:131], v[124:127], v[100:103]
	v_mfma_f32_16x16x32_bf16 v[68:71], v[128:131], v[116:119], v[68:71]
	s_waitcnt lgkmcnt(0)
	v_mfma_f32_16x16x32_bf16 v[112:115], v[120:123], v[124:127], v[112:115]
	v_mfma_f32_16x16x32_bf16 v[80:83], v[120:123], v[116:119], v[80:83]
	s_setprio 0
	v_mov_b32_e32 v150, 0
	s_setprio 1
	v_add3_u32 v128, v207, v150, v151
	ds_read_b128 v[116:119], v128
	ds_read_b128 v[120:123], v128 offset:64
	s_waitcnt lgkmcnt(1)
	v_mfma_f32_16x16x32_bf16 v[124:127], v[116:119], v[28:31], 0
	v_mfma_f32_16x16x32_bf16 v[116:119], v[116:119], v[36:39], 0
	s_waitcnt lgkmcnt(0)
	v_mfma_f32_16x16x32_bf16 v[124:127], v[120:123], v[32:35], v[124:127]
	v_mfma_f32_16x16x32_bf16 v[116:119], v[120:123], v[40:43], v[116:119]
	ds_read_b128 v[120:123], v128 offset:2304
	ds_read_b128 v[128:131], v128 offset:2368
	s_waitcnt lgkmcnt(1)
	v_mfma_f32_16x16x32_bf16 v[132:135], v[120:123], v[28:31], 0
	v_mfma_f32_16x16x32_bf16 v[120:123], v[120:123], v[36:39], 0
	s_waitcnt lgkmcnt(0)
	v_mfma_f32_16x16x32_bf16 v[132:135], v[128:131], v[32:35], v[132:135]
	v_mfma_f32_16x16x32_bf16 v[120:123], v[128:131], v[40:43], v[120:123]
	s_setprio 0
	v_max3_f32 v128, v124, s81, v125
	v_max3_f32 v128, v128, v126, v127
	s_nop 3
	v_max3_f32 v128, v128, v132, v133
	v_max3_f32 v128, v128, v134, v135
	v_mov_b32_e32 v129, v128
	s_nop 1
	v_permlane16_swap_b32_e32 v128, v129
	v_max_f32_e32 v128, v128, v129
	v_mov_b32_e32 v129, v128
	s_nop 1
	v_permlane32_swap_b32_e32 v128, v129
	v_max3_f32 v192, v148, v128, v129
	v_cmp_eq_f32_e32 vcc, s81, v192
	s_nop 1
	v_cndmask_b32_e64 v128, v192, 0, vcc
	v_sub_f32_e32 v128, v148, v128
	v_mul_f32_e32 v128, 0x3e38aa3b, v128
	v_exp_f32_e32 v128, v128
	s_nop 0
	v_pk_mul_f32 v[90:91], v[90:91], v[128:129] op_sel_hi:[1,0]
	v_pk_mul_f32 v[88:89], v[88:89], v[128:129] op_sel_hi:[1,0]
	v_pk_mul_f32 v[86:87], v[86:87], v[128:129] op_sel_hi:[1,0]
	v_pk_mul_f32 v[84:85], v[84:85], v[128:129] op_sel_hi:[1,0]
	v_pk_mul_f32 v[94:95], v[94:95], v[128:129] op_sel_hi:[1,0]
	v_pk_mul_f32 v[92:93], v[92:93], v[128:129] op_sel_hi:[1,0]
	v_pk_mul_f32 v[98:99], v[98:99], v[128:129] op_sel_hi:[1,0]
	v_pk_mul_f32 v[96:97], v[96:97], v[128:129] op_sel_hi:[1,0]
	v_mul_f32_e32 v129, 0x3e38aa3b, v192
	v_cndmask_b32_e64 v129, v129, 0, vcc
	v_fma_f32 v124, v124, s42, -v129
	v_exp_f32_e32 v131, v124
	v_fma_f32 v124, v132, s42, -v129
	v_exp_f32_e32 v137, v124
	v_fma_f32 v124, v125, s42, -v129
	v_max3_f32 v125, v116, s81, v117
	v_max3_f32 v125, v125, v118, v119
	v_max3_f32 v125, v125, v120, v121
	v_exp_f32_e32 v139, v124
	v_fma_f32 v124, v133, s42, -v129
	v_max3_f32 v125, v125, v122, v123
	v_exp_f32_e32 v133, v124
	v_fma_f32 v124, v126, s42, -v129
	v_mov_b32_e32 v126, v125
	s_nop 1
	v_permlane16_swap_b32_e32 v125, v126
	v_max_f32_e32 v125, v125, v126
	v_mov_b32_e32 v126, v125
	v_exp_f32_e32 v141, v124
	v_fma_f32 v124, v134, s42, -v129
	v_permlane32_swap_b32_e32 v125, v126
	v_exp_f32_e32 v143, v124
	v_fma_f32 v124, v127, s42, -v129
	v_max3_f32 v193, v149, v125, v126
	v_exp_f32_e32 v145, v124
	v_fma_f32 v124, v135, s42, -v129
	v_cmp_eq_f32_e32 vcc, s81, v193
	v_mul_f32_e32 v129, 0x3e38aa3b, v193
	v_exp_f32_e32 v135, v124
	v_cndmask_b32_e64 v129, v129, 0, vcc
	v_fma_f32 v116, v116, s42, -v129
	v_exp_f32_e32 v130, v116
	v_fma_f32 v116, v120, s42, -v129
	v_exp_f32_e32 v136, v116
	v_fma_f32 v116, v117, s42, -v129
	v_fma_f32 v118, v118, s42, -v129
	v_exp_f32_e32 v138, v116
	v_fma_f32 v116, v121, s42, -v129
	v_exp_f32_e32 v140, v118
	v_fma_f32 v118, v122, s42, -v129
	v_cndmask_b32_e64 v125, v193, 0, vcc
	v_exp_f32_e32 v132, v116
	v_exp_f32_e32 v142, v118
	v_fma_f32 v118, v119, s42, -v129
	v_sub_f32_e32 v125, v149, v125
	v_exp_f32_e32 v144, v118
	v_fma_f32 v118, v123, s42, -v129
	v_mul_f32_e32 v125, 0x3e38aa3b, v125
	v_exp_f32_e32 v134, v118
	v_exp_f32_e32 v146, v125
	v_pk_add_f32 v[116:117], v[130:131], v[136:137]
	v_pk_add_f32 v[120:121], v[138:139], v[132:133]
	v_pk_add_f32 v[116:117], v[116:117], 0 op_sel_hi:[1,0]
	v_pk_add_f32 v[118:119], v[140:141], v[142:143]
	v_pk_add_f32 v[116:117], v[120:121], v[116:117]
	v_pk_mul_f32 v[58:59], v[58:59], v[146:147] op_sel_hi:[1,0]
	v_pk_add_f32 v[116:117], v[118:119], v[116:117]
	v_pk_add_f32 v[118:119], v[144:145], v[134:135]
	v_pk_mul_f32 v[56:57], v[56:57], v[146:147] op_sel_hi:[1,0]
	v_pk_mul_f32 v[54:55], v[54:55], v[146:147] op_sel_hi:[1,0]
	v_pk_mul_f32 v[52:53], v[52:53], v[146:147] op_sel_hi:[1,0]
	v_pk_mul_f32 v[62:63], v[62:63], v[146:147] op_sel_hi:[1,0]
	v_pk_mul_f32 v[60:61], v[60:61], v[146:147] op_sel_hi:[1,0]
	v_pk_mul_f32 v[66:67], v[66:67], v[146:147] op_sel_hi:[1,0]
	v_pk_mul_f32 v[64:65], v[64:65], v[146:147] op_sel_hi:[1,0]
	v_mov_b32_e32 v147, v128
	v_pk_add_f32 v[116:117], v[118:119], v[116:117]
	v_cvt_pk_bf16_f32 v124, v131, v139
	v_pk_fma_f32 v[184:185], v[184:185], v[146:147], v[116:117]
	v_cvt_pk_bf16_f32 v125, v141, v145
	v_cvt_pk_bf16_f32 v126, v137, v133
	v_cvt_pk_bf16_f32 v127, v143, v135
	v_cvt_pk_bf16_f32 v116, v130, v138
	v_cvt_pk_bf16_f32 v117, v140, v144
	v_cvt_pk_bf16_f32 v118, v136, v132
	v_cvt_pk_bf16_f32 v119, v142, v134
	s_setprio 1
	v_add3_u32 v1, v1, v150, v206
	ds_read_b64_tr_b16 v[122:123], v1 offset:11776
	ds_read_b64_tr_b16 v[120:121], v1 offset:9216
	ds_read_b64_tr_b16 v[128:129], v1 offset:9248
	ds_read_b64_tr_b16 v[130:131], v1 offset:11808
	s_waitcnt lgkmcnt(2)
	v_mfma_f32_16x16x32_bf16 v[88:91], v[120:123], v[124:127], v[88:91]
	v_mfma_f32_16x16x32_bf16 v[56:59], v[120:123], v[116:119], v[56:59]
	ds_read_b64_tr_b16 v[120:121], v1 offset:9280
	ds_read_b64_tr_b16 v[122:123], v1 offset:11840
	s_waitcnt lgkmcnt(0)
	v_mfma_f32_16x16x32_bf16 v[92:95], v[120:123], v[124:127], v[92:95]
	v_mfma_f32_16x16x32_bf16 v[60:63], v[120:123], v[116:119], v[60:63]
	ds_read_b64_tr_b16 v[120:121], v1 offset:9312
	ds_read_b64_tr_b16 v[122:123], v1 offset:11872
	v_mfma_f32_16x16x32_bf16 v[84:87], v[128:131], v[124:127], v[84:87]
	v_mfma_f32_16x16x32_bf16 v[52:55], v[128:131], v[116:119], v[52:55]
	s_waitcnt lgkmcnt(0)
	v_mfma_f32_16x16x32_bf16 v[96:99], v[120:123], v[124:127], v[96:99]
	v_mfma_f32_16x16x32_bf16 v[64:67], v[120:123], v[116:119], v[64:67]
	s_setprio 0
	s_mov_b32 s8, 32
	s_andn2_b64 vcc, exec, s[12:13]
	s_mov_b64 s[12:13], 0
	s_cbranch_vccz .LBB0_1269
; #define LAS __attribute__((address_space(3)))
; template <int NT, int DQK, int DV, int MODE, int PD, class Src> ...
;     ...
;     for (int u = 0; u < PD; ++u) {
;       const int kc = kcb + u;
;       if (kc < kc1) {
;         LAS unsigned char* buf = lds + ((kc - kc0) & 1) * BUF;
; #pragma unroll
;         for (int rr = 0; rr < NKR; ++rr) { const int idx = tid + 512 * rr; if (idx < NKI) { const int row = idx / KCH, ch = idx % KCH; *(LAS u32x4*)(buf + row * KSTR + ch * 16) = kreg[u][rr]; } }
; #pragma unroll
;         for (int rr = 0; rr < NVR; ++rr) { const int idx = tid + 512 * rr; if (idx < NVI) { const int row = idx / VCH, ch = idx % VCH; *(LAS u32x4*)(buf + KB + row * VSTR + ch * 16) = vreg[u][rr]; } }
	s_branch .Lrt_skip_2
	v_mov_b64_e32 v[154:155], v[106:107]
	v_mov_b64_e32 v[150:151], v[102:103]
	v_mov_b64_e32 v[166:167], v[110:111]
	v_mov_b64_e32 v[174:175], v[114:115]
	v_mov_b64_e32 v[122:123], v[74:75]
	v_mov_b64_e32 v[118:119], v[70:71]
	v_mov_b64_e32 v[134:135], v[78:79]
	v_mov_b64_e32 v[142:143], v[82:83]
	v_mov_b64_e32 v[162:163], v[90:91]
	v_mov_b64_e32 v[158:159], v[86:87]
	v_mov_b64_e32 v[170:171], v[94:95]
	v_mov_b64_e32 v[178:179], v[98:99]
	v_mov_b64_e32 v[130:131], v[58:59]
	v_mov_b64_e32 v[126:127], v[54:55]
	v_mov_b64_e32 v[138:139], v[62:63]
	v_mov_b64_e32 v[146:147], v[66:67]
	v_mov_b32_e32 v212, v191
	v_mov_b32_e32 v1, v190
	v_mov_b32_e32 v215, v193
	v_mov_b32_e32 v214, v192
	v_mov_b64_e32 v[194:195], v[2:3]
	v_mov_b64_e32 v[202:203], v[184:185]
	v_mov_b64_e32 v[152:153], v[104:105]
	v_mov_b64_e32 v[148:149], v[100:101]
	v_mov_b64_e32 v[164:165], v[108:109]
	v_mov_b64_e32 v[172:173], v[112:113]
	v_mov_b64_e32 v[120:121], v[72:73]
	v_mov_b64_e32 v[116:117], v[68:69]
	v_mov_b64_e32 v[132:133], v[76:77]
	v_mov_b64_e32 v[140:141], v[80:81]
	v_mov_b64_e32 v[160:161], v[88:89]
	v_mov_b64_e32 v[156:157], v[84:85]
	v_mov_b64_e32 v[168:169], v[92:93]
	v_mov_b64_e32 v[176:177], v[96:97]
	v_mov_b64_e32 v[128:129], v[56:57]
	v_mov_b64_e32 v[124:125], v[52:53]
	v_mov_b64_e32 v[136:137], v[60:61]
	v_mov_b64_e32 v[144:145], v[64:65]
.LBB0_1271:
	v_mov_b64_e32 v[64:65], v[144:145]
	v_mov_b64_e32 v[60:61], v[136:137]
	v_mov_b64_e32 v[52:53], v[124:125]
	v_mov_b64_e32 v[56:57], v[128:129]
	v_mov_b64_e32 v[96:97], v[176:177]
	v_mov_b64_e32 v[92:93], v[168:169]
	v_mov_b64_e32 v[84:85], v[156:157]
	v_mov_b64_e32 v[88:89], v[160:161]
	v_mov_b64_e32 v[80:81], v[140:141]
	v_mov_b64_e32 v[76:77], v[132:133]
	v_mov_b64_e32 v[68:69], v[116:117]
	v_mov_b64_e32 v[72:73], v[120:121]
	v_mov_b64_e32 v[112:113], v[172:173]
	v_mov_b64_e32 v[108:109], v[164:165]
	v_mov_b64_e32 v[100:101], v[148:149]
	v_mov_b64_e32 v[104:105], v[152:153]
	v_mov_b64_e32 v[66:67], v[146:147]
	v_mov_b64_e32 v[62:63], v[138:139]
	v_mov_b64_e32 v[54:55], v[126:127]
	v_mov_b64_e32 v[58:59], v[130:131]
	v_mov_b64_e32 v[98:99], v[178:179]
	v_mov_b64_e32 v[94:95], v[170:171]
	v_mov_b64_e32 v[86:87], v[158:159]
	v_mov_b64_e32 v[90:91], v[162:163]
	v_mov_b64_e32 v[82:83], v[142:143]
	v_mov_b64_e32 v[78:79], v[134:135]
	v_mov_b64_e32 v[70:71], v[118:119]
	v_mov_b64_e32 v[74:75], v[122:123]
	v_mov_b64_e32 v[114:115], v[174:175]
	v_mov_b64_e32 v[110:111], v[166:167]
	v_mov_b64_e32 v[102:103], v[150:151]
	v_mov_b64_e32 v[106:107], v[154:155]
	v_mov_b64_e32 v[184:185], v[202:203]
	v_mov_b64_e32 v[2:3], v[194:195]
	v_mov_b32_e32 v192, v214
	v_mov_b32_e32 v193, v215
	v_mov_b32_e32 v190, v1
	v_mov_b32_e32 v191, v212
.Lrt_skip_2:
	s_and_saveexec_b64 s[12:13], s[10:11]
	s_cbranch_execz .LBB0_1262
.LBB0_1272:
	s_waitcnt vmcnt(0)
	ds_write_b128 v209, v[8:11] offset:19456
	ds_write_b128 v210, v[48:51] offset:28672
	s_or_b64 exec, exec, s[12:13]
	s_andn2_b64 vcc, exec, s[64:65]
	s_cbranch_vccnz .LBB0_1278

; #define LAS __attribute__((address_space(3)))
; __device__ __forceinline__ float ex2(float x) { return __builtin_amdgcn_exp2f(x); }
; __device__ __forceinline__ f32x4 mfma16(bf16x8 a, bf16x8 b, f32x4 c) { return __builtin_amdgcn_mfma_f32_16x16x32_bf16(a, b, c, 0, 0, 0); }
;   __device__ __forceinline__ bf16_t* W() const { return (bf16_t*)(ws + WS_W); }
; template <int NT, int NKK, int NDT, int MODE, bool MASK> ...
;     ...
; #pragma unroll
;       for (int t = 0; t < 2; ++t)
; #pragma unroll
;         for (int kk = 0; kk < NKK; ++kk) {
;           const bf16x8 kf = *(LAS const bf16x8*)(Kl + oz + (32 * st + 16 * t + r) * KSTR + (32 * kk + 8 * lg) * 2);
; #pragma unroll
;           for (int jj = 0; jj < JB; ++jj) s[jj][t] = mfma16(kf, qf[jh * JB + jj][kk], kk == 0 ? (f32x4){0.f, 0.f, 0.f, 0.f} : s[jj][t]);
;         }
;       __builtin_amdgcn_s_setprio(0);
;       bf16x8 pf[JB];
;       if (NT > JB) __builtin_amdgcn_sched_barrier(0);
; #pragma unroll
;       for (int jj = 0; jj < JB; ++jj) {
;         const int j = jh * JB + jj;
;         float mx = -INFINITY;
; #pragma unroll
;         for (int t = 0; t < 2; ++t)
; #pragma unroll
;           for (int i = 0; i < 4; ++i) {
;             if (MASK) { const int kp = kpos0 + 32 * st + 16 * t + 4 * lg + i; if (!mask_ok<MODE>(tq[j], kp, W)) s[jj][t][i] = -INFINITY; }
;             mx = fmaxf(mx, s[jj][t][i]);
;           }
;         mx = max_x16_x32(mx);
;         if (NT > 2 || __any(mx > m[j] + 8.0f / c)) {
;           const float mnew = fmaxf(m[j], mx);
;           const float ms2 = (mnew == -INFINITY) ? 0.f : mnew;
;           const float alpha = ex2((m[j] - ms2) * c);
;           m[j] = mnew; l[j] *= alpha;
; #pragma unroll
;           for (int dt = 0; dt < NDT; ++dt) o[j][dt] *= alpha;
;         }
;         const float mc = ((m[j] == -INFINITY) ? 0.f : m[j]) * c;
;         float p0[4], p1[4], ps = 0.f;
; #pragma unroll
;         for (int i = 0; i < 4; ++i) { p0[i] = ex2(s[jj][0][i] * c - mc); p1[i] = ex2(s[jj][1][i] * c - mc); ps += p0[i] + p1[i]; }
;         l[j] += ps;
;         pf[jj] = pack8(p0, p1);
.LBB0_1281:
	v_mov_b32_e32 v197, v1
	v_or_b32_e32 v1, s8, v211
	v_cmp_le_i32_e32 vcc, v1, v182
	v_cmp_gt_i32_e64 s[12:13], v1, v208
	s_and_b64 vcc, vcc, s[12:13]
	v_cmp_lt_i32_e64 s[12:13], v1, v182
	v_cmp_ge_i32_e64 s[14:15], v1, v208
	v_or_b32_e32 v196, 2, v1
	s_and_b64 s[12:13], s[12:13], s[14:15]
	v_cmp_le_i32_e64 s[14:15], v196, v182
	v_cmp_gt_i32_e64 s[16:17], v196, v208
	v_or_b32_e32 v196, 3, v1
	s_and_b64 s[14:15], s[14:15], s[16:17]
	v_cmp_le_i32_e64 s[16:17], v196, v182
	v_cmp_gt_i32_e64 s[18:19], v196, v208
	v_or_b32_e32 v196, 16, v1
	s_and_b64 s[16:17], s[16:17], s[18:19]
	v_cmp_le_i32_e64 s[18:19], v196, v182
	v_cmp_gt_i32_e64 s[20:21], v196, v208
	v_or_b32_e32 v196, 17, v1
	s_and_b64 s[18:19], s[18:19], s[20:21]
	v_cmp_le_i32_e64 s[20:21], v196, v182
	v_cmp_gt_i32_e64 s[22:23], v196, v208
	v_or_b32_e32 v196, 18, v1
	s_and_b64 s[20:21], s[20:21], s[22:23]
	v_cmp_le_i32_e64 s[22:23], v196, v182
	v_cmp_gt_i32_e64 s[24:25], v196, v208
	v_or_b32_e32 v1, 19, v1
	s_and_b64 s[22:23], s[22:23], s[24:25]
	v_cmp_le_i32_e64 s[24:25], v1, v182
	v_cmp_gt_i32_e64 s[28:29], v1, v208
	v_or_b32_e32 v1, s8, v183
	v_or_b32_e32 v196, s8, v204
	v_mov_b32_e32 v246, 0
	v_mov_b32_e32 v199, v212
	v_mov_b32_e32 v232, v214
	v_mov_b32_e32 v235, v215
	s_and_b64 s[24:25], s[24:25], s[28:29]
	v_mad_u32_u24 v213, v196, s80, 0
	s_setprio 1
	v_mul_u32_u24_e32 v247, 0x90, v1
	v_add3_u32 v1, v207, v246, v247
	ds_read_b128 v[214:217], v1 offset:19456
	ds_read_b128 v[218:221], v1 offset:19520
	s_waitcnt lgkmcnt(1)
	v_mfma_f32_16x16x32_bf16 v[222:225], v[214:217], v[12:15], 0
	v_mfma_f32_16x16x32_bf16 v[214:217], v[214:217], v[20:23], 0
	s_waitcnt lgkmcnt(0)
	v_mfma_f32_16x16x32_bf16 v[222:225], v[218:221], v[16:19], v[222:225]
	v_mfma_f32_16x16x32_bf16 v[214:217], v[218:221], v[24:27], v[214:217]
	ds_read_b128 v[218:221], v1 offset:21760
	ds_read_b128 v[228:231], v1 offset:21824
	s_waitcnt lgkmcnt(1)
	v_mfma_f32_16x16x32_bf16 v[236:239], v[218:221], v[12:15], 0
	v_mfma_f32_16x16x32_bf16 v[218:221], v[218:221], v[20:23], 0
	s_waitcnt lgkmcnt(0)
	v_mfma_f32_16x16x32_bf16 v[236:239], v[228:231], v[16:19], v[236:239]
	v_mfma_f32_16x16x32_bf16 v[218:221], v[228:231], v[24:27], v[218:221]
	s_setprio 0
	v_mov_b32_e32 v196, s81
	v_cndmask_b32_e32 v212, v196, v222, vcc
	v_cndmask_b32_e64 v222, v200, v223, s[12:13]
	v_max3_f32 v1, v212, s81, v222
	v_cndmask_b32_e64 v223, v200, v224, s[14:15]
	v_cndmask_b32_e64 v224, v200, v225, s[16:17]
	v_max3_f32 v1, v1, v223, v224
	v_cndmask_b32_e64 v196, v196, v236, s[18:19]
	v_cndmask_b32_e64 v225, v200, v237, s[20:21]
	v_max3_f32 v1, v1, v196, v225
	v_cndmask_b32_e64 v228, v200, v238, s[22:23]
	v_cndmask_b32_e64 v230, v200, v239, s[24:25]
	v_max3_f32 v1, v1, v228, v230
	v_mov_b32_e32 v198, v1
	s_nop 1
	v_permlane16_swap_b32_e32 v1, v198
	v_max_f32_e32 v1, v1, v198
	v_mov_b32_e32 v198, v1
	s_nop 1
	v_permlane32_swap_b32_e32 v1, v198
	v_max3_f32 v1, v197, v1, v198
	v_cmp_eq_f32_e64 s[28:29], s81, v1
	v_cndmask_b32_e64 v215, v200, v215, s[12:13]
	v_cndmask_b32_e64 v216, v200, v216, s[14:15]
	v_cndmask_b32_e64 v198, v1, 0, s[28:29]
	v_sub_f32_e32 v197, v197, v198
	v_mul_f32_e32 v197, 0x3e38aa3b, v197
	v_exp_f32_e32 v198, v197
	v_mul_f32_e32 v197, 0x3e38aa3b, v1
	v_cndmask_b32_e64 v236, v197, 0, s[28:29]
	v_fma_f32 v196, v196, s42, -v236
	v_exp_f32_e32 v229, v196
	v_fma_f32 v196, v222, s42, -v236
	v_exp_f32_e32 v231, v196
	v_fma_f32 v196, v225, s42, -v236
	v_exp_f32_e32 v237, v196
	v_fma_f32 v196, v223, s42, -v236
	v_exp_f32_e32 v239, v196
	v_fma_f32 v196, v228, s42, -v236
	v_exp_f32_e32 v241, v196
	v_fma_f32 v196, v224, s42, -v236
	v_exp_f32_e32 v243, v196
	v_fma_f32 v196, v230, s42, -v236
	v_exp_f32_e32 v245, v196
	v_mov_b32_e32 v196, s81
	v_cndmask_b32_e32 v228, v196, v214, vcc
	v_max3_f32 v196, v228, s81, v215
	v_cndmask_b32_e64 v217, v200, v217, s[16:17]
	v_fma_f32 v197, v212, s42, -v236
	v_max3_f32 v212, v196, v216, v217
	v_mov_b32_e32 v196, s81
	v_cndmask_b32_e64 v218, v196, v218, s[18:19]
	v_cndmask_b32_e64 v219, v200, v219, s[20:21]
	v_max3_f32 v196, v212, v218, v219
	v_cndmask_b32_e64 v220, v200, v220, s[22:23]
	v_cndmask_b32_e64 v221, v200, v221, s[24:25]
	v_max3_f32 v196, v196, v220, v221
	v_mov_b32_e32 v212, v196
	s_nop 1
	v_permlane16_swap_b32_e32 v196, v212
	v_max_f32_e32 v196, v196, v212
	v_mov_b32_e32 v212, v196
	s_nop 1
	v_permlane32_swap_b32_e32 v196, v212
	v_max3_f32 v212, v199, v196, v212
	v_cmp_eq_f32_e64 s[28:29], s81, v212
	v_pk_mul_f32 v[154:155], v[154:155], v[198:199] op_sel_hi:[1,0]
	v_pk_mul_f32 v[152:153], v[152:153], v[198:199] op_sel_hi:[1,0]
	v_cndmask_b32_e64 v196, v212, 0, s[28:29]
	v_sub_f32_e32 v196, v199, v196
	v_mul_f32_e32 v196, 0x3e38aa3b, v196
	v_exp_f32_e32 v214, v196
	v_mul_f32_e32 v196, 0x3e38aa3b, v212
	v_pk_mul_f32 v[150:151], v[150:151], v[198:199] op_sel_hi:[1,0]
	v_pk_mul_f32 v[148:149], v[148:149], v[198:199] op_sel_hi:[1,0]
	v_pk_mul_f32 v[166:167], v[166:167], v[198:199] op_sel_hi:[1,0]
	v_pk_mul_f32 v[164:165], v[164:165], v[198:199] op_sel_hi:[1,0]
	v_pk_mul_f32 v[174:175], v[174:175], v[198:199] op_sel_hi:[1,0]
	v_pk_mul_f32 v[172:173], v[172:173], v[198:199] op_sel_hi:[1,0]
	v_cndmask_b32_e64 v199, v196, 0, s[28:29]
	v_pk_mul_f32 v[122:123], v[122:123], v[214:215] op_sel_hi:[1,0]
	v_pk_mul_f32 v[120:121], v[120:121], v[214:215] op_sel_hi:[1,0]
	v_pk_mul_f32 v[118:119], v[118:119], v[214:215] op_sel_hi:[1,0]
	v_pk_mul_f32 v[116:117], v[116:117], v[214:215] op_sel_hi:[1,0]
	v_pk_mul_f32 v[134:135], v[134:135], v[214:215] op_sel_hi:[1,0]
	v_pk_mul_f32 v[132:133], v[132:133], v[214:215] op_sel_hi:[1,0]
	v_pk_mul_f32 v[142:143], v[142:143], v[214:215] op_sel_hi:[1,0]
; __device__ __forceinline__ float ex2(float x) { return __builtin_amdgcn_exp2f(x); }
; __device__ __forceinline__ f32x4 mfma16(bf16x8 a, bf16x8 b, f32x4 c) { return __builtin_amdgcn_mfma_f32_16x16x32_bf16(a, b, c, 0, 0, 0); }
; __device__ __forceinline__ s16x4 ds_tr(LAS const unsigned char* p) { return __builtin_bit_cast(s16x4, __builtin_amdgcn_ds_read_tr16_b64_v4i16((LAS v4i16_t*)p)); }
; template <int NT, int NKK, int NDT, int MODE, bool MASK> ...
;     ...
;           m[j] = mnew; l[j] *= alpha;
; #pragma unroll
;           for (int dt = 0; dt < NDT; ++dt) o[j][dt] *= alpha;
;         }
;         const float mc = ((m[j] == -INFINITY) ? 0.f : m[j]) * c;
;         float p0[4], p1[4], ps = 0.f;
; #pragma unroll
;         for (int i = 0; i < 4; ++i) { p0[i] = ex2(s[jj][0][i] * c - mc); p1[i] = ex2(s[jj][1][i] * c - mc); ps += p0[i] + p1[i]; }
;         l[j] += ps;
;         pf[jj] = pack8(p0, p1);
;       }
;       if (NT > JB) __builtin_amdgcn_sched_barrier(0);
;       __builtin_amdgcn_s_setprio(1);
; #pragma unroll
;       for (int dt = 0; dt < NDT; ++dt) {
;         const s16x4 v0 = ds_tr(Vl + oz + (32 * st + 4 * lg + vq) * VSTR + (16 * dt + 4 * vp) * 2);
;         const s16x4 v1 = ds_tr(Vl + oz + (32 * st + 16 + 4 * lg + vq) * VSTR + (16 * dt + 4 * vp) * 2);
;         const bf16x8 vf = (bf16x8){v0[0], v0[1], v0[2], v0[3], v1[0], v1[1], v1[2], v1[3]};
; #pragma unroll
;         for (int jj = 0; jj < JB; ++jj) o[jh * JB + jj][dt] = mfma16(vf, pf[jj], o[jh * JB + jj][dt]);
	v_pk_mul_f32 v[140:141], v[140:141], v[214:215] op_sel_hi:[1,0]
	v_fma_f32 v215, v215, s42, -v199
	v_fma_f32 v196, v228, s42, -v199
	v_fma_f32 v218, v218, s42, -v199
	v_exp_f32_e32 v230, v215
	v_fma_f32 v215, v219, s42, -v199
	v_exp_f32_e32 v197, v197
	v_exp_f32_e32 v196, v196
	v_exp_f32_e32 v228, v218
	v_exp_f32_e32 v236, v215
	v_fma_f32 v215, v216, s42, -v199
	v_exp_f32_e32 v238, v215
	v_fma_f32 v215, v220, s42, -v199
	v_exp_f32_e32 v240, v215
	v_fma_f32 v215, v217, s42, -v199
	v_fma_f32 v199, v221, s42, -v199
	v_exp_f32_e32 v242, v215
	v_exp_f32_e32 v244, v199
	v_mov_b32_e32 v215, v198
	v_pk_add_f32 v[198:199], v[196:197], v[228:229]
	v_pk_add_f32 v[216:217], v[230:231], v[236:237]
	v_pk_add_f32 v[198:199], v[198:199], 0 op_sel_hi:[1,0]
	v_cvt_pk_bf16_f32 v222, v197, v231
	v_pk_add_f32 v[198:199], v[216:217], v[198:199]
	v_pk_add_f32 v[216:217], v[238:239], v[240:241]
	v_cvt_pk_bf16_f32 v223, v239, v243
	v_pk_add_f32 v[198:199], v[216:217], v[198:199]
	v_pk_add_f32 v[216:217], v[242:243], v[244:245]
	v_cvt_pk_bf16_f32 v224, v229, v237
	v_pk_add_f32 v[198:199], v[216:217], v[198:199]
	v_cvt_pk_bf16_f32 v225, v241, v245
	v_pk_fma_f32 v[194:195], v[194:195], v[214:215], v[198:199]
	v_cvt_pk_bf16_f32 v214, v196, v230
	v_cvt_pk_bf16_f32 v215, v238, v242
	v_cvt_pk_bf16_f32 v216, v228, v236
	v_cvt_pk_bf16_f32 v217, v240, v244
	s_setprio 1
	v_add3_u32 v196, v213, v246, v206
	ds_read_b64_tr_b16 v[220:221], v196 offset:31232
	ds_read_b64_tr_b16 v[218:219], v196 offset:28672
	ds_read_b64_tr_b16 v[228:229], v196 offset:28704
	ds_read_b64_tr_b16 v[230:231], v196 offset:31264
	s_waitcnt lgkmcnt(2)
	v_mfma_f32_16x16x32_bf16 v[152:155], v[218:221], v[222:225], v[152:155]
	v_mfma_f32_16x16x32_bf16 v[120:123], v[218:221], v[214:217], v[120:123]
	ds_read_b64_tr_b16 v[218:219], v196 offset:28736
	ds_read_b64_tr_b16 v[220:221], v196 offset:31296
	s_waitcnt lgkmcnt(0)
	v_mfma_f32_16x16x32_bf16 v[164:167], v[218:221], v[222:225], v[164:167]
	v_mfma_f32_16x16x32_bf16 v[132:135], v[218:221], v[214:217], v[132:135]
	ds_read_b64_tr_b16 v[218:219], v196 offset:28768
	ds_read_b64_tr_b16 v[220:221], v196 offset:31328
	v_mfma_f32_16x16x32_bf16 v[148:151], v[228:231], v[222:225], v[148:151]
	v_mfma_f32_16x16x32_bf16 v[116:119], v[228:231], v[214:217], v[116:119]
	s_waitcnt lgkmcnt(0)
	v_mfma_f32_16x16x32_bf16 v[172:175], v[218:221], v[222:225], v[172:175]
	v_mfma_f32_16x16x32_bf16 v[140:143], v[218:221], v[214:217], v[140:143]
	s_setprio 0
	v_mov_b32_e32 v248, 0
	s_setprio 1
	v_add3_u32 v196, v207, v248, v247
	ds_read_b128 v[214:217], v196 offset:19456
	ds_read_b128 v[218:221], v196 offset:19520
	ds_read_b128 v[228:231], v196 offset:21760
	ds_read_b128 v[236:239], v196 offset:21824
	s_waitcnt lgkmcnt(3)
	v_mfma_f32_16x16x32_bf16 v[222:225], v[214:217], v[28:31], 0
	v_mfma_f32_16x16x32_bf16 v[214:217], v[214:217], v[36:39], 0
	s_waitcnt lgkmcnt(1)
	v_mfma_f32_16x16x32_bf16 v[240:243], v[228:231], v[28:31], 0
	v_mfma_f32_16x16x32_bf16 v[228:231], v[228:231], v[36:39], 0
	v_mfma_f32_16x16x32_bf16 v[222:225], v[218:221], v[32:35], v[222:225]
	v_mfma_f32_16x16x32_bf16 v[216:219], v[218:221], v[40:43], v[214:217]
	s_waitcnt lgkmcnt(0)
; __device__ __forceinline__ float ex2(float x) { return __builtin_amdgcn_exp2f(x); }
; __device__ __forceinline__ f32x4 mfma16(bf16x8 a, bf16x8 b, f32x4 c) { return __builtin_amdgcn_mfma_f32_16x16x32_bf16(a, b, c, 0, 0, 0); }
; __device__ __forceinline__ s16x4 ds_tr(LAS const unsigned char* p) { return __builtin_bit_cast(s16x4, __builtin_amdgcn_ds_read_tr16_b64_v4i16((LAS v4i16_t*)p)); }
;   __device__ __forceinline__ bf16_t* W() const { return (bf16_t*)(ws + WS_W); }
; template <int NT, int NKK, int NDT, int MODE, bool MASK> ...
;     ...
;       for (int jj = 0; jj < JB; ++jj) {
;         const int j = jh * JB + jj;
;         float mx = -INFINITY;
; #pragma unroll
;         for (int t = 0; t < 2; ++t)
; #pragma unroll
;           for (int i = 0; i < 4; ++i) {
;             if (MASK) { const int kp = kpos0 + 32 * st + 16 * t + 4 * lg + i; if (!mask_ok<MODE>(tq[j], kp, W)) s[jj][t][i] = -INFINITY; }
;             mx = fmaxf(mx, s[jj][t][i]);
;           }
;         mx = max_x16_x32(mx);
;         if (NT > 2 || __any(mx > m[j] + 8.0f / c)) {
;           const float mnew = fmaxf(m[j], mx);
;           const float ms2 = (mnew == -INFINITY) ? 0.f : mnew;
;           const float alpha = ex2((m[j] - ms2) * c);
;           m[j] = mnew; l[j] *= alpha;
; #pragma unroll
;           for (int dt = 0; dt < NDT; ++dt) o[j][dt] *= alpha;
;         }
;         const float mc = ((m[j] == -INFINITY) ? 0.f : m[j]) * c;
;         float p0[4], p1[4], ps = 0.f;
; #pragma unroll
;         for (int i = 0; i < 4; ++i) { p0[i] = ex2(s[jj][0][i] * c - mc); p1[i] = ex2(s[jj][1][i] * c - mc); ps += p0[i] + p1[i]; }
;         l[j] += ps;
;         pf[jj] = pack8(p0, p1);
;       }
;       if (NT > JB) __builtin_amdgcn_sched_barrier(0);
;       __builtin_amdgcn_s_setprio(1);
; #pragma unroll
;       for (int dt = 0; dt < NDT; ++dt) {
;         const s16x4 v0 = ds_tr(Vl + oz + (32 * st + 4 * lg + vq) * VSTR + (16 * dt + 4 * vp) * 2);
;         const s16x4 v1 = ds_tr(Vl + oz + (32 * st + 16 + 4 * lg + vq) * VSTR + (16 * dt + 4 * vp) * 2);
;         const bf16x8 vf = (bf16x8){v0[0], v0[1], v0[2], v0[3], v1[0], v1[1], v1[2], v1[3]};
; #pragma unroll
;         for (int jj = 0; jj < JB; ++jj) o[jh * JB + jj][dt] = mfma16(vf, pf[jj], o[jh * JB + jj][dt]);
;       }
;       __builtin_amdgcn_s_setprio(0);
;       if (NT > JB) __builtin_amdgcn_sched_barrier(0);
	v_mfma_f32_16x16x32_bf16 v[240:243], v[236:239], v[32:35], v[240:243]
	v_mfma_f32_16x16x32_bf16 v[228:231], v[236:239], v[40:43], v[228:231]
	s_setprio 0
	v_mov_b32_e32 v196, s81
	s_nop 0
	v_cndmask_b32_e32 v197, v196, v222, vcc
	v_cndmask_b32_e64 v199, v200, v223, s[12:13]
	v_max3_f32 v196, v197, s81, v199
	v_cndmask_b32_e64 v215, v200, v224, s[14:15]
	v_cndmask_b32_e64 v220, v200, v225, s[16:17]
	v_max3_f32 v198, v196, v215, v220
	v_mov_b32_e32 v196, s81
	v_cndmask_b32_e64 v196, v196, v240, s[18:19]
	v_cndmask_b32_e64 v221, v200, v241, s[20:21]
	v_max3_f32 v198, v198, v196, v221
	v_cndmask_b32_e64 v222, v200, v242, s[22:23]
	v_cndmask_b32_e64 v223, v200, v243, s[24:25]
	v_max3_f32 v198, v198, v222, v223
	v_mov_b32_e32 v214, v198
	s_nop 1
	v_permlane16_swap_b32_e32 v198, v214
	v_max_f32_e32 v198, v198, v214
	v_mov_b32_e32 v214, v198
	s_nop 1
	v_permlane32_swap_b32_e32 v198, v214
	v_max3_f32 v214, v232, v198, v214
	v_cmp_eq_f32_e64 s[28:29], s81, v214
	v_mul_f32_e32 v224, 0x3e38aa3b, v214
	v_cndmask_b32_e64 v217, v200, v217, s[12:13]
	v_cndmask_b32_e64 v224, v224, 0, s[28:29]
	v_fma_f32 v196, v196, s42, -v224
	v_cndmask_b32_e64 v198, v214, 0, s[28:29]
	v_exp_f32_e32 v225, v196
	v_fma_f32 v196, v199, s42, -v224
	v_sub_f32_e32 v198, v232, v198
	v_exp_f32_e32 v237, v196
	v_fma_f32 v196, v221, s42, -v224
	v_mul_f32_e32 v198, 0x3e38aa3b, v198
	v_exp_f32_e32 v239, v196
	v_fma_f32 v196, v215, s42, -v224
	v_exp_f32_e32 v198, v198
	v_exp_f32_e32 v241, v196
	v_fma_f32 v196, v222, s42, -v224
	v_exp_f32_e32 v243, v196
	v_fma_f32 v196, v220, s42, -v224
	v_exp_f32_e32 v245, v196
	v_fma_f32 v196, v223, s42, -v224
	v_exp_f32_e32 v247, v196
	v_mov_b32_e32 v196, s81
	v_pk_mul_f32 v[162:163], v[162:163], v[198:199] op_sel_hi:[1,0]
	v_pk_mul_f32 v[160:161], v[160:161], v[198:199] op_sel_hi:[1,0]
	v_pk_mul_f32 v[158:159], v[158:159], v[198:199] op_sel_hi:[1,0]
	v_pk_mul_f32 v[156:157], v[156:157], v[198:199] op_sel_hi:[1,0]
	v_pk_mul_f32 v[170:171], v[170:171], v[198:199] op_sel_hi:[1,0]
	v_pk_mul_f32 v[168:169], v[168:169], v[198:199] op_sel_hi:[1,0]
	v_pk_mul_f32 v[178:179], v[178:179], v[198:199] op_sel_hi:[1,0]
	v_pk_mul_f32 v[176:177], v[176:177], v[198:199] op_sel_hi:[1,0]
	v_cndmask_b32_e32 v199, v196, v216, vcc
	v_max3_f32 v196, v199, s81, v217
	v_cndmask_b32_e64 v218, v200, v218, s[14:15]
	v_cndmask_b32_e64 v219, v200, v219, s[16:17]
	v_max3_f32 v215, v196, v218, v219
	v_mov_b32_e32 v196, s81
	v_fma_f32 v197, v197, s42, -v224
	v_cndmask_b32_e64 v224, v196, v228, s[18:19]
	v_cndmask_b32_e64 v228, v200, v229, s[20:21]
	v_max3_f32 v196, v215, v224, v228
	v_cndmask_b32_e64 v229, v200, v230, s[22:23]
	v_cndmask_b32_e64 v230, v200, v231, s[24:25]
	v_max3_f32 v196, v196, v229, v230
	v_mov_b32_e32 v215, v196
	s_nop 1
	v_permlane16_swap_b32_e32 v196, v215
	v_max_f32_e32 v196, v196, v215
	v_mov_b32_e32 v215, v196
	s_nop 1
	v_permlane32_swap_b32_e32 v196, v215
	v_max3_f32 v215, v235, v196, v215
	v_cmp_eq_f32_e32 vcc, s81, v215
	v_exp_f32_e32 v197, v197
	v_cvt_pk_bf16_f32 v221, v241, v245
	v_cndmask_b32_e64 v196, v215, 0, vcc
	v_sub_f32_e32 v196, v235, v196
	v_mul_f32_e32 v196, 0x3e38aa3b, v196
	v_exp_f32_e32 v216, v196
	v_mul_f32_e32 v196, 0x3e38aa3b, v215
	v_cndmask_b32_e64 v231, v196, 0, vcc
	v_fma_f32 v196, v199, s42, -v231
	v_fma_f32 v199, v224, s42, -v231
	v_exp_f32_e32 v224, v199
	v_fma_f32 v199, v217, s42, -v231
	v_exp_f32_e32 v236, v199
	v_fma_f32 v199, v228, s42, -v231
	v_exp_f32_e32 v238, v199
	v_fma_f32 v199, v218, s42, -v231
	v_exp_f32_e32 v196, v196
	v_exp_f32_e32 v240, v199
	v_fma_f32 v199, v229, s42, -v231
	v_exp_f32_e32 v242, v199
	v_fma_f32 v199, v219, s42, -v231
	v_exp_f32_e32 v244, v199
	v_fma_f32 v199, v230, s42, -v231
	v_exp_f32_e32 v246, v199
	v_pk_mul_f32 v[130:131], v[130:131], v[216:217] op_sel_hi:[1,0]
	v_pk_mul_f32 v[128:129], v[128:129], v[216:217] op_sel_hi:[1,0]
	v_pk_mul_f32 v[126:127], v[126:127], v[216:217] op_sel_hi:[1,0]
	v_pk_mul_f32 v[124:125], v[124:125], v[216:217] op_sel_hi:[1,0]
	v_pk_mul_f32 v[138:139], v[138:139], v[216:217] op_sel_hi:[1,0]
	v_pk_mul_f32 v[136:137], v[136:137], v[216:217] op_sel_hi:[1,0]
	v_pk_mul_f32 v[146:147], v[146:147], v[216:217] op_sel_hi:[1,0]
	v_pk_mul_f32 v[144:145], v[144:145], v[216:217] op_sel_hi:[1,0]
	v_mov_b32_e32 v217, v198
	v_pk_add_f32 v[198:199], v[196:197], v[224:225]
	v_pk_add_f32 v[218:219], v[236:237], v[238:239]
	v_pk_add_f32 v[198:199], v[198:199], 0 op_sel_hi:[1,0]
	v_cvt_pk_bf16_f32 v220, v197, v237
	v_pk_add_f32 v[198:199], v[218:219], v[198:199]
	v_pk_add_f32 v[218:219], v[240:241], v[242:243]
	v_cvt_pk_bf16_f32 v222, v225, v239
	v_pk_add_f32 v[198:199], v[218:219], v[198:199]
	v_pk_add_f32 v[218:219], v[244:245], v[246:247]
	v_cvt_pk_bf16_f32 v223, v243, v247
	v_pk_add_f32 v[198:199], v[218:219], v[198:199]
	v_cvt_pk_bf16_f32 v218, v224, v238
	v_pk_fma_f32 v[202:203], v[202:203], v[216:217], v[198:199]
	v_cvt_pk_bf16_f32 v216, v196, v236
	v_cvt_pk_bf16_f32 v217, v240, v244
	v_cvt_pk_bf16_f32 v219, v242, v246
	s_setprio 1
	v_add3_u32 v196, v213, v248, v206
	ds_read_b64_tr_b16 v[230:231], v196 offset:31232
	ds_read_b64_tr_b16 v[228:229], v196 offset:28672
	ds_read_b64_tr_b16 v[236:237], v196 offset:28704
	ds_read_b64_tr_b16 v[238:239], v196 offset:31264
	s_waitcnt lgkmcnt(2)
	v_mfma_f32_16x16x32_bf16 v[160:163], v[228:231], v[220:223], v[160:163]
	v_mfma_f32_16x16x32_bf16 v[128:131], v[228:231], v[216:219], v[128:131]
	ds_read_b64_tr_b16 v[228:229], v196 offset:28736
	ds_read_b64_tr_b16 v[230:231], v196 offset:31296
	s_waitcnt lgkmcnt(0)
	v_mfma_f32_16x16x32_bf16 v[168:171], v[228:231], v[220:223], v[168:171]
	v_mfma_f32_16x16x32_bf16 v[136:139], v[228:231], v[216:219], v[136:139]
	ds_read_b64_tr_b16 v[228:229], v196 offset:28768
	ds_read_b64_tr_b16 v[230:231], v196 offset:31328
	v_mfma_f32_16x16x32_bf16 v[156:159], v[236:239], v[220:223], v[156:159]
	v_mfma_f32_16x16x32_bf16 v[124:127], v[236:239], v[216:219], v[124:127]
	s_waitcnt lgkmcnt(0)
	v_mfma_f32_16x16x32_bf16 v[176:179], v[228:231], v[220:223], v[176:179]
	v_mfma_f32_16x16x32_bf16 v[144:147], v[228:231], v[216:219], v[144:147]
	s_setprio 0
	s_mov_b32 s8, 32
	s_andn2_b64 vcc, exec, s[64:65]
	s_mov_b64 s[64:65], 0
	s_cbranch_vccz .LBB0_1281
	s_mov_b64 s[12:13], 0

; template <int NT, int NKK, int NDT, int MODE, bool MASK> ...
;     ...
;     for (int jh = 0; jh < NT / JB; ++jh) {
;       int oz = 0; if (NT > JB) asm volatile("" : "+v"(oz));
;       f32x4 s[JB][2];
;       __builtin_amdgcn_s_setprio(1);
; #pragma unroll
;       for (int t = 0; t < 2; ++t)
; #pragma unroll
;         for (int kk = 0; kk < NKK; ++kk) {
;           const bf16x8 kf = *(LAS const bf16x8*)(Kl + oz + (32 * st + 16 * t + r) * KSTR + (32 * kk + 8 * lg) * 2);
; #pragma unroll
;           for (int jj = 0; jj < JB; ++jj) s[jj][t] = mfma16(kf, qf[jh * JB + jj][kk], kk == 0 ? (f32x4){0.f, 0.f, 0.f, 0.f} : s[jj][t]);
;         }
;       __builtin_amdgcn_s_setprio(0);
;       bf16x8 pf[JB];
;       if (NT > JB) __builtin_amdgcn_sched_barrier(0);
; #pragma unroll
;       for (int jj = 0; jj < JB; ++jj) {
;         const int j = jh * JB + jj;
;         float mx = -INFINITY;
; #pragma unroll
;         for (int t = 0; t < 2; ++t)
; #pragma unroll
;           for (int i = 0; i < 4; ++i) {
;             if (MASK) { const int kp = kpos0 + 32 * st + 16 * t + 4 * lg + i; if (!mask_ok<MODE>(tq[j], kp, W)) s[jj][t][i] = -INFINITY; }
;             mx = fmaxf(mx, s[jj][t][i]);
;           }
;         mx = max_x16_x32(mx);
;         if (NT > 2 || __any(mx > m[j] + 8.0f / c)) {
;           const float mnew = fmaxf(m[j], mx);
;           const float ms2 = (mnew == -INFINITY) ? 0.f : mnew;
;           const float alpha = ex2((m[j] - ms2) * c);
;           m[j] = mnew; l[j] *= alpha;
; #pragma unroll
;           for (int dt = 0; dt < NDT; ++dt) o[j][dt] *= alpha;
;         }
;         const float mc = ((m[j] == -INFINITY) ? 0.f : m[j]) * c;
;         float p0[4], p1[4], ps = 0.f;
; #pragma unroll
;         for (int i = 0; i < 4; ++i) { p0[i] = ex2(s[jj][0][i] * c - mc); p1[i] = ex2(s[jj][1][i] * c - mc); ps += p0[i] + p1[i]; }
;         l[j] += ps;
;         pf[jj] = pack8(p0, p1);
;       }
;       if (NT > JB) __builtin_amdgcn_sched_barrier(0);
;       __builtin_amdgcn_s_setprio(1);
; #pragma unroll
;       for (int dt = 0; dt < NDT; ++dt) {
;         const s16x4 v0 = ds_tr(Vl + oz + (32 * st + 4 * lg + vq) * VSTR + (16 * dt + 4 * vp) * 2);
;         const s16x4 v1 = ds_tr(Vl + oz + (32 * st + 16 + 4 * lg + vq) * VSTR + (16 * dt + 4 * vp) * 2);
;         const bf16x8 vf = (bf16x8){v0[0], v0[1], v0[2], v0[3], v1[0], v1[1], v1[2], v1[3]};
; #pragma unroll
.LBB0_1285:
	v_or_b32_e32 v1, s8, v204
	v_mov_b32_e32 v150, 0
	v_mov_b32_e32 v136, v190
	v_mov_b32_e32 v138, v191
	v_mov_b32_e32 v148, v192
	v_mov_b32_e32 v149, v193
	v_or_b32_e32 v116, s8, v183
	v_mad_u32_u24 v1, v1, s80, 0
	s_setprio 1
	v_mul_u32_u24_e32 v151, 0x90, v116
	v_add3_u32 v128, v207, v150, v151
	ds_read_b128 v[116:119], v128 offset:19456
	ds_read_b128 v[120:123], v128 offset:19520
	s_waitcnt lgkmcnt(1)
	v_mfma_f32_16x16x32_bf16 v[124:127], v[116:119], v[12:15], 0
	v_mfma_f32_16x16x32_bf16 v[116:119], v[116:119], v[20:23], 0
	s_waitcnt lgkmcnt(0)
	v_mfma_f32_16x16x32_bf16 v[124:127], v[120:123], v[16:19], v[124:127]
	v_mfma_f32_16x16x32_bf16 v[116:119], v[120:123], v[24:27], v[116:119]
	ds_read_b128 v[120:123], v128 offset:21760
	ds_read_b128 v[128:131], v128 offset:21824
	s_waitcnt lgkmcnt(1)
	v_mfma_f32_16x16x32_bf16 v[132:135], v[120:123], v[12:15], 0
	v_mfma_f32_16x16x32_bf16 v[120:123], v[120:123], v[20:23], 0
	s_waitcnt lgkmcnt(0)
	v_mfma_f32_16x16x32_bf16 v[132:135], v[128:131], v[16:19], v[132:135]
	v_mfma_f32_16x16x32_bf16 v[120:123], v[128:131], v[24:27], v[120:123]
	s_setprio 0
	v_max3_f32 v128, v124, s81, v125
	v_max3_f32 v128, v128, v126, v127
	s_nop 3
	v_max3_f32 v128, v128, v132, v133
	v_max3_f32 v128, v128, v134, v135
	v_mov_b32_e32 v129, v128
	s_nop 1
	v_permlane16_swap_b32_e32 v128, v129
	v_max_f32_e32 v128, v128, v129
	v_mov_b32_e32 v129, v128
	s_nop 1
	v_permlane32_swap_b32_e32 v128, v129
	v_max3_f32 v190, v136, v128, v129
	v_cmp_eq_f32_e32 vcc, s81, v190
	s_nop 1
	v_cndmask_b32_e64 v128, v190, 0, vcc
	v_sub_f32_e32 v128, v136, v128
	v_mul_f32_e32 v128, 0x3e38aa3b, v128
	v_exp_f32_e32 v128, v128
	s_nop 0
	v_pk_mul_f32 v[106:107], v[106:107], v[128:129] op_sel_hi:[1,0]
	v_pk_mul_f32 v[104:105], v[104:105], v[128:129] op_sel_hi:[1,0]
	v_pk_mul_f32 v[102:103], v[102:103], v[128:129] op_sel_hi:[1,0]
	v_pk_mul_f32 v[100:101], v[100:101], v[128:129] op_sel_hi:[1,0]
	v_pk_mul_f32 v[110:111], v[110:111], v[128:129] op_sel_hi:[1,0]
	v_pk_mul_f32 v[108:109], v[108:109], v[128:129] op_sel_hi:[1,0]
	v_pk_mul_f32 v[114:115], v[114:115], v[128:129] op_sel_hi:[1,0]
	v_pk_mul_f32 v[112:113], v[112:113], v[128:129] op_sel_hi:[1,0]
	v_mul_f32_e32 v129, 0x3e38aa3b, v190
	v_cndmask_b32_e64 v129, v129, 0, vcc
	v_fma_f32 v124, v124, s42, -v129
	v_exp_f32_e32 v131, v124
	v_fma_f32 v124, v132, s42, -v129
	v_exp_f32_e32 v137, v124
	v_fma_f32 v124, v125, s42, -v129
	v_max3_f32 v125, v116, s81, v117
	v_max3_f32 v125, v125, v118, v119
	v_max3_f32 v125, v125, v120, v121
	v_exp_f32_e32 v139, v124
	v_fma_f32 v124, v133, s42, -v129
	v_max3_f32 v125, v125, v122, v123
	v_exp_f32_e32 v133, v124
	v_fma_f32 v124, v126, s42, -v129
	v_mov_b32_e32 v126, v125
	s_nop 1
	v_permlane16_swap_b32_e32 v125, v126
	v_max_f32_e32 v125, v125, v126
	v_mov_b32_e32 v126, v125
	v_exp_f32_e32 v141, v124
	v_fma_f32 v124, v134, s42, -v129
	v_permlane32_swap_b32_e32 v125, v126
	v_exp_f32_e32 v143, v124
	v_fma_f32 v124, v127, s42, -v129
	v_max3_f32 v191, v138, v125, v126
	v_exp_f32_e32 v145, v124
	v_fma_f32 v124, v135, s42, -v129
	v_cmp_eq_f32_e32 vcc, s81, v191
	v_mul_f32_e32 v129, 0x3e38aa3b, v191
	v_exp_f32_e32 v135, v124
	v_cndmask_b32_e64 v129, v129, 0, vcc
	v_fma_f32 v116, v116, s42, -v129
	v_exp_f32_e32 v130, v116
	v_fma_f32 v116, v120, s42, -v129
	v_cndmask_b32_e64 v125, v191, 0, vcc
	v_exp_f32_e32 v136, v116
	v_fma_f32 v116, v117, s42, -v129
	v_sub_f32_e32 v125, v138, v125
	v_exp_f32_e32 v138, v116
	v_fma_f32 v116, v121, s42, -v129
	v_exp_f32_e32 v132, v116
	v_fma_f32 v116, v118, s42, -v129
	v_exp_f32_e32 v140, v116
	v_fma_f32 v116, v122, s42, -v129
	v_exp_f32_e32 v142, v116
	v_fma_f32 v116, v119, s42, -v129
	v_exp_f32_e32 v144, v116
	v_fma_f32 v116, v123, s42, -v129
	v_mul_f32_e32 v125, 0x3e38aa3b, v125
	v_exp_f32_e32 v134, v116
	v_exp_f32_e32 v146, v125
	v_pk_add_f32 v[116:117], v[130:131], v[136:137]
	v_pk_add_f32 v[118:119], v[138:139], v[132:133]
	v_pk_add_f32 v[116:117], v[116:117], 0 op_sel_hi:[1,0]
	v_pk_mul_f32 v[74:75], v[74:75], v[146:147] op_sel_hi:[1,0]
	v_pk_add_f32 v[116:117], v[118:119], v[116:117]
	v_pk_add_f32 v[118:119], v[140:141], v[142:143]
	v_pk_mul_f32 v[72:73], v[72:73], v[146:147] op_sel_hi:[1,0]
	v_pk_add_f32 v[116:117], v[118:119], v[116:117]
	v_pk_add_f32 v[118:119], v[144:145], v[134:135]
	v_pk_mul_f32 v[70:71], v[70:71], v[146:147] op_sel_hi:[1,0]
	v_pk_mul_f32 v[68:69], v[68:69], v[146:147] op_sel_hi:[1,0]
	v_pk_mul_f32 v[78:79], v[78:79], v[146:147] op_sel_hi:[1,0]
	v_pk_mul_f32 v[76:77], v[76:77], v[146:147] op_sel_hi:[1,0]
	v_pk_mul_f32 v[82:83], v[82:83], v[146:147] op_sel_hi:[1,0]
	v_pk_mul_f32 v[80:81], v[80:81], v[146:147] op_sel_hi:[1,0]
	v_mov_b32_e32 v147, v128
	v_pk_add_f32 v[116:117], v[118:119], v[116:117]
	v_cvt_pk_bf16_f32 v124, v131, v139
	v_pk_fma_f32 v[2:3], v[2:3], v[146:147], v[116:117]
	v_cvt_pk_bf16_f32 v125, v141, v145
	v_cvt_pk_bf16_f32 v126, v137, v133
	v_cvt_pk_bf16_f32 v127, v143, v135
	v_cvt_pk_bf16_f32 v116, v130, v138
	v_cvt_pk_bf16_f32 v117, v140, v144
	v_cvt_pk_bf16_f32 v118, v136, v132
	v_cvt_pk_bf16_f32 v119, v142, v134
	s_setprio 1
	v_add3_u32 v132, v1, v150, v206
	ds_read_b64_tr_b16 v[122:123], v132 offset:31232
	ds_read_b64_tr_b16 v[120:121], v132 offset:28672
	ds_read_b64_tr_b16 v[128:129], v132 offset:28704
	ds_read_b64_tr_b16 v[130:131], v132 offset:31264
	s_waitcnt lgkmcnt(2)
	v_mfma_f32_16x16x32_bf16 v[104:107], v[120:123], v[124:127], v[104:107]
	v_mfma_f32_16x16x32_bf16 v[72:75], v[120:123], v[116:119], v[72:75]
	ds_read_b64_tr_b16 v[120:121], v132 offset:28736
	ds_read_b64_tr_b16 v[122:123], v132 offset:31296
	s_waitcnt lgkmcnt(0)
; template <int NT, int NKK, int NDT, int MODE, bool MASK> ...
;     ...
;     for (int jh = 0; jh < NT / JB; ++jh) {
;       int oz = 0; if (NT > JB) asm volatile("" : "+v"(oz));
;       f32x4 s[JB][2];
;       __builtin_amdgcn_s_setprio(1);
; #pragma unroll
;       for (int t = 0; t < 2; ++t)
; #pragma unroll
;         for (int kk = 0; kk < NKK; ++kk) {
;           const bf16x8 kf = *(LAS const bf16x8*)(Kl + oz + (32 * st + 16 * t + r) * KSTR + (32 * kk + 8 * lg) * 2);
; #pragma unroll
;           for (int jj = 0; jj < JB; ++jj) s[jj][t] = mfma16(kf, qf[jh * JB + jj][kk], kk == 0 ? (f32x4){0.f, 0.f, 0.f, 0.f} : s[jj][t]);
;         }
;       __builtin_amdgcn_s_setprio(0);
;       bf16x8 pf[JB];
;       if (NT > JB) __builtin_amdgcn_sched_barrier(0);
; #pragma unroll
;       for (int jj = 0; jj < JB; ++jj) {
;         const int j = jh * JB + jj;
;         float mx = -INFINITY;
; #pragma unroll
;         for (int t = 0; t < 2; ++t)
; #pragma unroll
;           for (int i = 0; i < 4; ++i) {
;             if (MASK) { const int kp = kpos0 + 32 * st + 16 * t + 4 * lg + i; if (!mask_ok<MODE>(tq[j], kp, W)) s[jj][t][i] = -INFINITY; }
;             mx = fmaxf(mx, s[jj][t][i]);
;           }
;         mx = max_x16_x32(mx);
;         if (NT > 2 || __any(mx > m[j] + 8.0f / c)) {
;           const float mnew = fmaxf(m[j], mx);
;           const float ms2 = (mnew == -INFINITY) ? 0.f : mnew;
;           const float alpha = ex2((m[j] - ms2) * c);
;           m[j] = mnew; l[j] *= alpha;
; #pragma unroll
;           for (int dt = 0; dt < NDT; ++dt) o[j][dt] *= alpha;
;         }
;         const float mc = ((m[j] == -INFINITY) ? 0.f : m[j]) * c;
;         float p0[4], p1[4], ps = 0.f;
; #pragma unroll
;         for (int i = 0; i < 4; ++i) { p0[i] = ex2(s[jj][0][i] * c - mc); p1[i] = ex2(s[jj][1][i] * c - mc); ps += p0[i] + p1[i]; }
;         l[j] += ps;
;         pf[jj] = pack8(p0, p1);
;       }
;       if (NT > JB) __builtin_amdgcn_sched_barrier(0);
;       __builtin_amdgcn_s_setprio(1);
; #pragma unroll
;       for (int dt = 0; dt < NDT; ++dt) {
;         const s16x4 v0 = ds_tr(Vl + oz + (32 * st + 4 * lg + vq) * VSTR + (16 * dt + 4 * vp) * 2);
;         const s16x4 v1 = ds_tr(Vl + oz + (32 * st + 16 + 4 * lg + vq) * VSTR + (16 * dt + 4 * vp) * 2);
;         const bf16x8 vf = (bf16x8){v0[0], v0[1], v0[2], v0[3], v1[0], v1[1], v1[2], v1[3]};
; #pragma unroll
	v_mfma_f32_16x16x32_bf16 v[108:111], v[120:123], v[124:127], v[108:111]
	v_mfma_f32_16x16x32_bf16 v[76:79], v[120:123], v[116:119], v[76:79]
	ds_read_b64_tr_b16 v[120:121], v132 offset:28768
	ds_read_b64_tr_b16 v[122:123], v132 offset:31328
	v_mfma_f32_16x16x32_bf16 v[100:103], v[128:131], v[124:127], v[100:103]
	v_mfma_f32_16x16x32_bf16 v[68:71], v[128:131], v[116:119], v[68:71]
	s_waitcnt lgkmcnt(0)
	v_mfma_f32_16x16x32_bf16 v[112:115], v[120:123], v[124:127], v[112:115]
	v_mfma_f32_16x16x32_bf16 v[80:83], v[120:123], v[116:119], v[80:83]
	s_setprio 0
	v_mov_b32_e32 v150, 0
	s_setprio 1
	v_add3_u32 v128, v207, v150, v151
	ds_read_b128 v[116:119], v128 offset:19456
	ds_read_b128 v[120:123], v128 offset:19520
	s_waitcnt lgkmcnt(1)
	v_mfma_f32_16x16x32_bf16 v[124:127], v[116:119], v[28:31], 0
	v_mfma_f32_16x16x32_bf16 v[116:119], v[116:119], v[36:39], 0
	s_waitcnt lgkmcnt(0)
	v_mfma_f32_16x16x32_bf16 v[124:127], v[120:123], v[32:35], v[124:127]
	v_mfma_f32_16x16x32_bf16 v[116:119], v[120:123], v[40:43], v[116:119]
	ds_read_b128 v[120:123], v128 offset:21760
	ds_read_b128 v[128:131], v128 offset:21824
	s_waitcnt lgkmcnt(1)
	v_mfma_f32_16x16x32_bf16 v[132:135], v[120:123], v[28:31], 0
	v_mfma_f32_16x16x32_bf16 v[120:123], v[120:123], v[36:39], 0
	s_waitcnt lgkmcnt(0)
	v_mfma_f32_16x16x32_bf16 v[132:135], v[128:131], v[32:35], v[132:135]
	v_mfma_f32_16x16x32_bf16 v[120:123], v[128:131], v[40:43], v[120:123]
	s_setprio 0
	v_max3_f32 v128, v124, s81, v125
	v_max3_f32 v128, v128, v126, v127
	s_nop 3
	v_max3_f32 v128, v128, v132, v133
	v_max3_f32 v128, v128, v134, v135
	v_mov_b32_e32 v129, v128
	s_nop 1
	v_permlane16_swap_b32_e32 v128, v129
	v_max_f32_e32 v128, v128, v129
	v_mov_b32_e32 v129, v128
	s_nop 1
	v_permlane32_swap_b32_e32 v128, v129
	v_max3_f32 v192, v148, v128, v129
	v_cmp_eq_f32_e32 vcc, s81, v192
	s_nop 1
	v_cndmask_b32_e64 v128, v192, 0, vcc
	v_sub_f32_e32 v128, v148, v128
	v_mul_f32_e32 v128, 0x3e38aa3b, v128
	v_exp_f32_e32 v128, v128
	s_nop 0
	v_pk_mul_f32 v[90:91], v[90:91], v[128:129] op_sel_hi:[1,0]
	v_pk_mul_f32 v[88:89], v[88:89], v[128:129] op_sel_hi:[1,0]
	v_pk_mul_f32 v[86:87], v[86:87], v[128:129] op_sel_hi:[1,0]
	v_pk_mul_f32 v[84:85], v[84:85], v[128:129] op_sel_hi:[1,0]
	v_pk_mul_f32 v[94:95], v[94:95], v[128:129] op_sel_hi:[1,0]
	v_pk_mul_f32 v[92:93], v[92:93], v[128:129] op_sel_hi:[1,0]
	v_pk_mul_f32 v[98:99], v[98:99], v[128:129] op_sel_hi:[1,0]
	v_pk_mul_f32 v[96:97], v[96:97], v[128:129] op_sel_hi:[1,0]
	v_mul_f32_e32 v129, 0x3e38aa3b, v192
	v_cndmask_b32_e64 v129, v129, 0, vcc
	v_fma_f32 v124, v124, s42, -v129
	v_exp_f32_e32 v131, v124
	v_fma_f32 v124, v132, s42, -v129
	v_exp_f32_e32 v137, v124
	v_fma_f32 v124, v125, s42, -v129
	v_max3_f32 v125, v116, s81, v117
	v_max3_f32 v125, v125, v118, v119
	v_max3_f32 v125, v125, v120, v121
	v_exp_f32_e32 v139, v124
	v_fma_f32 v124, v133, s42, -v129
	v_max3_f32 v125, v125, v122, v123
	v_exp_f32_e32 v133, v124
	v_fma_f32 v124, v126, s42, -v129
	v_mov_b32_e32 v126, v125
	s_nop 1
	v_permlane16_swap_b32_e32 v125, v126
	v_max_f32_e32 v125, v125, v126
	v_mov_b32_e32 v126, v125
	v_exp_f32_e32 v141, v124
	v_fma_f32 v124, v134, s42, -v129
	v_permlane32_swap_b32_e32 v125, v126
	v_exp_f32_e32 v143, v124
	v_fma_f32 v124, v127, s42, -v129
	v_max3_f32 v193, v149, v125, v126
	v_exp_f32_e32 v145, v124
	v_fma_f32 v124, v135, s42, -v129
	v_cmp_eq_f32_e32 vcc, s81, v193
	v_mul_f32_e32 v129, 0x3e38aa3b, v193
	v_exp_f32_e32 v135, v124
	v_cndmask_b32_e64 v129, v129, 0, vcc
	v_fma_f32 v116, v116, s42, -v129
	v_exp_f32_e32 v130, v116
	v_fma_f32 v116, v120, s42, -v129
	v_exp_f32_e32 v136, v116
	v_fma_f32 v116, v117, s42, -v129
	v_exp_f32_e32 v138, v116
	v_fma_f32 v116, v121, s42, -v129
	v_exp_f32_e32 v132, v116
	v_fma_f32 v116, v118, s42, -v129
	v_exp_f32_e32 v140, v116
	v_fma_f32 v116, v122, s42, -v129
	v_cndmask_b32_e64 v125, v193, 0, vcc
	v_exp_f32_e32 v142, v116
	v_fma_f32 v116, v119, s42, -v129
	v_sub_f32_e32 v125, v149, v125
	v_exp_f32_e32 v144, v116
	v_fma_f32 v116, v123, s42, -v129
	v_mul_f32_e32 v125, 0x3e38aa3b, v125
	v_exp_f32_e32 v134, v116
	v_exp_f32_e32 v146, v125
	v_pk_add_f32 v[116:117], v[130:131], v[136:137]
	v_pk_add_f32 v[118:119], v[138:139], v[132:133]
	v_pk_add_f32 v[116:117], v[116:117], 0 op_sel_hi:[1,0]
	v_pk_mul_f32 v[58:59], v[58:59], v[146:147] op_sel_hi:[1,0]
	v_pk_add_f32 v[116:117], v[118:119], v[116:117]
	v_pk_add_f32 v[118:119], v[140:141], v[142:143]
	v_pk_mul_f32 v[56:57], v[56:57], v[146:147] op_sel_hi:[1,0]
	v_pk_add_f32 v[116:117], v[118:119], v[116:117]
	v_pk_add_f32 v[118:119], v[144:145], v[134:135]
	v_pk_mul_f32 v[54:55], v[54:55], v[146:147] op_sel_hi:[1,0]
	v_pk_mul_f32 v[52:53], v[52:53], v[146:147] op_sel_hi:[1,0]
	v_pk_mul_f32 v[62:63], v[62:63], v[146:147] op_sel_hi:[1,0]
	v_pk_mul_f32 v[60:61], v[60:61], v[146:147] op_sel_hi:[1,0]
	v_pk_mul_f32 v[66:67], v[66:67], v[146:147] op_sel_hi:[1,0]
	v_pk_mul_f32 v[64:65], v[64:65], v[146:147] op_sel_hi:[1,0]
	v_mov_b32_e32 v147, v128
	v_pk_add_f32 v[116:117], v[118:119], v[116:117]
	v_cvt_pk_bf16_f32 v124, v131, v139
	v_pk_fma_f32 v[184:185], v[184:185], v[146:147], v[116:117]
	v_cvt_pk_bf16_f32 v125, v141, v145
	v_cvt_pk_bf16_f32 v126, v137, v133
	v_cvt_pk_bf16_f32 v127, v143, v135
	v_cvt_pk_bf16_f32 v116, v130, v138
	v_cvt_pk_bf16_f32 v117, v140, v144
	v_cvt_pk_bf16_f32 v118, v136, v132
	v_cvt_pk_bf16_f32 v119, v142, v134
	s_setprio 1
	v_add3_u32 v1, v1, v150, v206
	ds_read_b64_tr_b16 v[122:123], v1 offset:31232
	ds_read_b64_tr_b16 v[120:121], v1 offset:28672
	ds_read_b64_tr_b16 v[128:129], v1 offset:28704
	ds_read_b64_tr_b16 v[130:131], v1 offset:31264
	s_waitcnt lgkmcnt(2)
	v_mfma_f32_16x16x32_bf16 v[88:91], v[120:123], v[124:127], v[88:91]
	v_mfma_f32_16x16x32_bf16 v[56:59], v[120:123], v[116:119], v[56:59]
	ds_read_b64_tr_b16 v[120:121], v1 offset:28736
	ds_read_b64_tr_b16 v[122:123], v1 offset:31296
	s_waitcnt lgkmcnt(0)
	v_mfma_f32_16x16x32_bf16 v[92:95], v[120:123], v[124:127], v[92:95]
	v_mfma_f32_16x16x32_bf16 v[60:63], v[120:123], v[116:119], v[60:63]
	ds_read_b64_tr_b16 v[120:121], v1 offset:28768
	ds_read_b64_tr_b16 v[122:123], v1 offset:31328
	v_mfma_f32_16x16x32_bf16 v[84:87], v[128:131], v[124:127], v[84:87]
	v_mfma_f32_16x16x32_bf16 v[52:55], v[128:131], v[116:119], v[52:55]
	s_waitcnt lgkmcnt(0)
	v_mfma_f32_16x16x32_bf16 v[96:99], v[120:123], v[124:127], v[96:99]
	v_mfma_f32_16x16x32_bf16 v[64:67], v[120:123], v[116:119], v[64:67]
	s_setprio 0
	s_mov_b32 s8, 32
	s_andn2_b64 vcc, exec, s[12:13]
	s_mov_b64 s[12:13], 0
	s_cbranch_vccz .LBB0_1285
; #define LAS __attribute__((address_space(3)))
; #define LBAR() asm volatile("s_waitcnt lgkmcnt(0)\n\ts_barrier" ::: "memory")
;   __device__ __forceinline__ bf16_t* W() const { return (bf16_t*)(ws + WS_W); }
; template <int NT, int DQK, int DV, int MODE, int PD, class Src> ...
;     ...
;   for (int kcb = kc0; kcb < kc1; kcb += PD) {
; #pragma unroll
;     for (int u = 0; u < PD; ++u) {
;       const int kc = kcb + u;
;       if (kc < kc1) {
;         LAS unsigned char* buf = lds + ((kc - kc0) & 1) * BUF;
; #pragma unroll
;         for (int rr = 0; rr < NKR; ++rr) { const int idx = tid + 512 * rr; if (idx < NKI) { const int row = idx / KCH, ch = idx % KCH; *(LAS u32x4*)(buf + row * KSTR + ch * 16) = kreg[u][rr]; } }
; #pragma unroll
;         for (int rr = 0; rr < NVR; ++rr) { const int idx = tid + 512 * rr; if (idx < NVI) { const int row = idx / VCH, ch = idx % VCH; *(LAS u32x4*)(buf + KB + row * VSTR + ch * 16) = vreg[u][rr]; } }
;         if (kc + PD < kc1) ABL_LOAD(u, kc + PD);
;         LBAR();
;         const int lo = kbase + 64 * kc, hi = lo + 63;
;         bool rel = true, full = true;
;         if (MODE == MODE_CAUSAL) { rel = lo <= tq_max; full = hi <= tq_min; }
;         if (MODE == MODE_WINDOW) { rel = (lo <= tq_max) && (hi > tq_min - W); full = (hi <= tq_min) && (lo > tq_max - W); }
;         if (MODE == MODE_CMP) { rel = 16 * lo + 31 <= tq_max; full = 16 * hi + 31 <= tq_min; }
;         if (rel) {
;           if (NT <= 2) {
;             if (full) attn_chunk_wide<NT, DQK / 32, DV / 16, MODE, false>(o, m, l, qf, buf, KSTR, buf + KB, VSTR, lo, tq, c, W, lane);
;             else attn_chunk_wide<NT, DQK / 32, DV / 16, MODE, true>(o, m, l, qf, buf, KSTR, buf + KB, VSTR, lo, tq, c, W, lane);
;           } else {
;             if (full) attn_chunk<NT, DQK / 32, DV / 16, MODE, false>(o, m, l, qf, buf, KSTR, buf + KB, VSTR, lo, tq, c, W, lane);
;             else attn_chunk<NT, DQK / 32, DV / 16, MODE, true>(o, m, l, qf, buf, KSTR, buf + KB, VSTR, lo, tq, c, W, lane);
;           }
;         }
;       }
;     }
;   }
	v_mov_b64_e32 v[154:155], v[106:107]
	v_mov_b64_e32 v[150:151], v[102:103]
	v_mov_b64_e32 v[166:167], v[110:111]
	v_mov_b64_e32 v[174:175], v[114:115]
	v_mov_b64_e32 v[122:123], v[74:75]
	v_mov_b64_e32 v[118:119], v[70:71]
	v_mov_b64_e32 v[134:135], v[78:79]
	v_mov_b64_e32 v[142:143], v[82:83]
	v_mov_b64_e32 v[162:163], v[90:91]
	v_mov_b64_e32 v[158:159], v[86:87]
	v_mov_b64_e32 v[170:171], v[94:95]
	v_mov_b64_e32 v[178:179], v[98:99]
	v_mov_b64_e32 v[130:131], v[58:59]
	v_mov_b64_e32 v[126:127], v[54:55]
	v_mov_b64_e32 v[138:139], v[62:63]
	v_mov_b64_e32 v[146:147], v[66:67]
	v_mov_b32_e32 v212, v191
	v_mov_b32_e32 v1, v190
	v_mov_b32_e32 v215, v193
	v_mov_b32_e32 v214, v192
	v_mov_b64_e32 v[194:195], v[2:3]
	v_mov_b64_e32 v[202:203], v[184:185]
	v_mov_b64_e32 v[152:153], v[104:105]
	v_mov_b64_e32 v[148:149], v[100:101]
	v_mov_b64_e32 v[164:165], v[108:109]
	v_mov_b64_e32 v[172:173], v[112:113]
	v_mov_b64_e32 v[120:121], v[72:73]
	v_mov_b64_e32 v[116:117], v[68:69]
	v_mov_b64_e32 v[132:133], v[76:77]
	v_mov_b64_e32 v[140:141], v[80:81]
	v_mov_b64_e32 v[160:161], v[88:89]
	v_mov_b64_e32 v[156:157], v[84:85]
	v_mov_b64_e32 v[168:169], v[92:93]
	v_mov_b64_e32 v[176:177], v[96:97]
	v_mov_b64_e32 v[128:129], v[56:57]
	v_mov_b64_e32 v[124:125], v[52:53]
	v_mov_b64_e32 v[136:137], v[60:61]
	v_mov_b64_e32 v[144:145], v[64:65]
	s_branch .LBB0_1250

; __device__ __forceinline__ float ex2(float x) { return __builtin_amdgcn_exp2f(x); }
; __device__ __forceinline__ long as_long(unsigned lo, unsigned hi) { return (long)(((unsigned long long)hi << 32) | (unsigned long long)lo); }
; __device__ __forceinline__ f32x4 mfma16_fp8(long a, long b, f32x4 c) { return __builtin_amdgcn_mfma_f32_16x16x32_fp8_fp8(a, b, c, 0, 0, 0); }
; __device__ __forceinline__ void sel_compute(const SelFrag& F, const long (&qs)[2], f32x4 (&os)[4], float& m, float& l, int blk, int cur, int t, int lg, float c) {
;     ...
;   for (int t4 = 0; t4 < 4; ++t4) { s[t4] = mfma16_fp8(as_long(F.kf[t4].x, F.kf[t4].y), qs[0], (f32x4){0.f, 0.f, 0.f, 0.f}); s[t4] = mfma16_fp8(as_long(F.kf[t4].z, F.kf[t4].w), qs[1], s[t4]); }
;   float mx = -INFINITY;
; #pragma unroll
;   for (int t4 = 0; t4 < 4; ++t4)
; #pragma unroll
;     for (int i = 0; i < 4; ++i) { if (blk == cur) { const int key = 64 * blk + 16 * t4 + 4 * lg + i; if (key > t) s[t4][i] = -INFINITY; } mx = fmaxf(mx, s[t4][i]); }
;   mx = max_x16_x32(mx);
;   if (__any(mx > m + 8.0f / c)) {
;     const float mnew = fmaxf(m, mx), ms2 = (mnew == -INFINITY) ? 0.f : mnew, alpha = ex2((m - ms2) * c);
;     m = mnew; l *= alpha;
; #pragma unroll
;     for (int dt = 0; dt < 4; ++dt) os[dt] *= alpha;
;   }
.LBB0_1348:
	v_mfma_f32_16x16x32_fp8_fp8 v[110:113], v[18:19], v[100:101], 0
	s_cmp_eq_u32 s65, s59
	v_lshl_or_b32 v138, s65, 6, v92
	s_cselect_b64 s[46:47], -1, 0
	v_mfma_f32_16x16x32_fp8_fp8 v[110:113], v[20:21], v[102:103], v[110:113]
	v_cmp_lt_i32_e32 vcc, s29, v138
	s_and_b64 vcc, s[46:47], vcc
	v_or_b32_e32 v116, 16, v138
	v_mfma_f32_16x16x32_fp8_fp8 v[120:123], v[22:23], v[100:101], 0
	v_mfma_f32_16x16x32_fp8_fp8 v[126:129], v[24:25], v[102:103], v[120:123]
	s_nop 2
	v_cndmask_b32_e32 v115, v110, v200, vcc
	v_cmp_le_i32_e32 vcc, s29, v138
	s_and_b64 vcc, s[46:47], vcc
	v_mfma_f32_16x16x32_fp8_fp8 v[122:125], v[26:27], v[100:101], 0
	v_cndmask_b32_e32 v118, v111, v200, vcc
	v_or_b32_e32 v111, 2, v138
	v_cmp_lt_i32_e32 vcc, s29, v111
	s_and_b64 vcc, s[46:47], vcc
	v_or_b32_e32 v111, 3, v138
	v_cndmask_b32_e32 v121, v112, v200, vcc
	v_cmp_lt_i32_e32 vcc, s29, v111
	s_and_b64 vcc, s[46:47], vcc
	v_max3_f32 v110, v115, s81, v118
	v_mfma_f32_16x16x32_fp8_fp8 v[130:133], v[28:29], v[102:103], v[122:125]
	s_nop 2
	v_cndmask_b32_e32 v123, v113, v200, vcc
	v_max3_f32 v114, v110, v121, v123
	v_mfma_f32_16x16x32_fp8_fp8 v[110:113], v[30:31], v[100:101], 0
	v_cmp_lt_i32_e32 vcc, s29, v116
	s_and_b64 vcc, s[46:47], vcc
	v_mfma_f32_16x16x32_fp8_fp8 v[134:137], v[32:33], v[102:103], v[110:113]
	v_cndmask_b32_e32 v125, v126, v200, vcc
	s_nop 3
	v_or_b32_e32 v110, 17, v138
	v_cmp_lt_i32_e32 vcc, s29, v110
	s_and_b64 vcc, s[46:47], vcc
	v_or_b32_e32 v111, 18, v138
	v_cndmask_b32_e32 v126, v127, v200, vcc
	v_cmp_lt_i32_e32 vcc, s29, v111
	s_and_b64 vcc, s[46:47], vcc
	v_or_b32_e32 v111, 19, v138
	v_cndmask_b32_e32 v124, v128, v200, vcc
	v_cmp_lt_i32_e32 vcc, s29, v111
	s_and_b64 vcc, s[46:47], vcc
	v_or_b32_e32 v111, 32, v138
	v_cndmask_b32_e32 v122, v129, v200, vcc
	v_cmp_lt_i32_e32 vcc, s29, v111
	s_and_b64 vcc, s[46:47], vcc
	v_or_b32_e32 v111, 33, v138
	v_cndmask_b32_e32 v120, v130, v200, vcc
	v_cmp_lt_i32_e32 vcc, s29, v111
	s_and_b64 vcc, s[46:47], vcc
	v_or_b32_e32 v111, 34, v138
	v_cndmask_b32_e32 v119, v131, v200, vcc
	v_cmp_lt_i32_e32 vcc, s29, v111
	s_and_b64 vcc, s[46:47], vcc
	v_or_b32_e32 v111, 35, v138
	v_cndmask_b32_e32 v117, v132, v200, vcc
	v_cmp_lt_i32_e32 vcc, s29, v111
	s_and_b64 vcc, s[46:47], vcc
	v_or_b32_e32 v111, 48, v138
	v_cndmask_b32_e32 v116, v133, v200, vcc
	v_cmp_lt_i32_e32 vcc, s29, v111
	s_and_b64 vcc, s[46:47], vcc
	v_or_b32_e32 v111, 49, v138
	v_max3_f32 v110, v114, v125, v126
	v_cndmask_b32_e32 v114, v134, v200, vcc
	v_cmp_lt_i32_e32 vcc, s29, v111
	s_and_b64 vcc, s[46:47], vcc
	v_or_b32_e32 v111, 50, v138
	v_cndmask_b32_e32 v113, v135, v200, vcc
	v_cmp_lt_i32_e32 vcc, s29, v111
	v_max3_f32 v110, v110, v124, v122
	s_and_b64 vcc, s[46:47], vcc
	v_or_b32_e32 v112, 51, v138
	v_max3_f32 v110, v110, v120, v119
	v_cndmask_b32_e32 v111, v136, v200, vcc
	v_cmp_lt_i32_e32 vcc, s29, v112
	v_max3_f32 v110, v110, v117, v116
	s_and_b64 vcc, s[46:47], vcc
	v_max3_f32 v110, v110, v114, v113
	v_cndmask_b32_e32 v112, v137, v200, vcc
	v_max3_f32 v110, v110, v111, v112
	v_mov_b32_e32 v127, v110
	s_nop 1
	v_permlane16_swap_b32_e32 v110, v127
	v_max_f32_e32 v110, v110, v127
	v_mov_b32_e32 v127, v110
	s_nop 1
	v_permlane32_swap_b32_e32 v110, v127
	v_max_f32_e32 v110, v110, v127
	v_add_f32_e32 v127, 0x42317218, v109
	v_cmp_gt_f32_e32 vcc, v110, v127
	s_cbranch_vccz .LBB0_1350
	v_max_f32_e32 v110, v110, v110
	v_max_f32_e32 v127, v109, v109
	v_max_f32_e32 v127, v127, v110
	v_cmp_neq_f32_e32 vcc, s81, v127
	s_nop 1
	v_cndmask_b32_e32 v110, 0, v127, vcc
	v_sub_f32_e32 v109, v109, v110
	v_mul_f32_e32 v109, 0x3e38aa3b, v109
	v_exp_f32_e32 v110, v109
	v_mov_b32_e32 v109, v127
	v_mul_f32_e32 v99, v99, v110
	v_pk_mul_f32 v[88:89], v[88:89], v[110:111] op_sel_hi:[1,0]
	v_pk_mul_f32 v[86:87], v[86:87], v[110:111] op_sel_hi:[1,0]
	v_pk_mul_f32 v[76:77], v[76:77], v[110:111] op_sel_hi:[1,0]
	v_pk_mul_f32 v[74:75], v[74:75], v[110:111] op_sel_hi:[1,0]
	v_pk_mul_f32 v[80:81], v[80:81], v[110:111] op_sel_hi:[1,0]
	v_pk_mul_f32 v[78:79], v[78:79], v[110:111] op_sel_hi:[1,0]
	v_pk_mul_f32 v[84:85], v[84:85], v[110:111] op_sel_hi:[1,0]
	v_pk_mul_f32 v[82:83], v[82:83], v[110:111] op_sel_hi:[1,0]

; __device__ __forceinline__ float ex2(float x) { return __builtin_amdgcn_exp2f(x); }
; __device__ __forceinline__ long as_long(unsigned lo, unsigned hi) { return (long)(((unsigned long long)hi << 32) | (unsigned long long)lo); }
; __device__ __forceinline__ f32x4 mfma16_fp8(long a, long b, f32x4 c) { return __builtin_amdgcn_mfma_f32_16x16x32_fp8_fp8(a, b, c, 0, 0, 0); }
; __device__ __forceinline__ void sel_load(SelFrag& F, const bf16_t* kst, const bf16_t* vst, int blk, int cq, int lg) {
;   const unsigned char* kp = (const unsigned char*)kst + (size_t)blk * 4096 + (cq * 4 + lg) * 16;
;   const unsigned char* vp = (const unsigned char*)vst + (size_t)blk * 4096 + (cq * 4 + lg) * 16;
; #pragma unroll
;   for (int t4 = 0; t4 < 4; ++t4) F.kf[t4] = *(const u32x4*)(kp + t4 * 1024);
; #pragma unroll
;   for (int dt = 0; dt < 4; ++dt) F.vf[dt] = *(const u32x4*)(vp + dt * 1024);
; }
; __device__ __forceinline__ void sel_compute(const SelFrag& F, const long (&qs)[2], f32x4 (&os)[4], float& m, float& l, int blk, int cur, int t, int lg, float c) {
;     ...
;   for (int t4 = 0; t4 < 4; ++t4) { s[t4] = mfma16_fp8(as_long(F.kf[t4].x, F.kf[t4].y), qs[0], (f32x4){0.f, 0.f, 0.f, 0.f}); s[t4] = mfma16_fp8(as_long(F.kf[t4].z, F.kf[t4].w), qs[1], s[t4]); }
;   float mx = -INFINITY;
; #pragma unroll
;   for (int t4 = 0; t4 < 4; ++t4)
; #pragma unroll
;     for (int i = 0; i < 4; ++i) { if (blk == cur) { const int key = 64 * blk + 16 * t4 + 4 * lg + i; if (key > t) s[t4][i] = -INFINITY; } mx = fmaxf(mx, s[t4][i]); }
;   mx = max_x16_x32(mx);
;   if (__any(mx > m + 8.0f / c)) {
;     const float mnew = fmaxf(m, mx), ms2 = (mnew == -INFINITY) ? 0.f : mnew, alpha = ex2((m - ms2) * c);
;     m = mnew; l *= alpha;
; #pragma unroll
;     for (int dt = 0; dt < 4; ++dt) os[dt] *= alpha;
;   }
.LBB0_1353:
	s_waitcnt vmcnt(15)
	v_mfma_f32_16x16x32_fp8_fp8 v[112:115], v[34:35], v[100:101], 0
	s_cmp_eq_u32 s69, s59
	v_lshl_or_b32 v138, s69, 6, v92
	s_cselect_b64 s[38:39], -1, 0
	v_mfma_f32_16x16x32_fp8_fp8 v[120:123], v[36:37], v[102:103], v[112:115]
	v_cmp_lt_i32_e32 vcc, s29, v138
	s_and_b64 vcc, s[38:39], vcc
	s_waitcnt vmcnt(14)
	v_mfma_f32_16x16x32_fp8_fp8 v[124:127], v[38:39], v[100:101], 0
	v_or_b32_e32 v112, 2, v138
	s_nop 2
	v_cndmask_b32_e32 v115, v120, v200, vcc
	v_cmp_le_i32_e32 vcc, s29, v138
	s_and_b64 vcc, s[38:39], vcc
	v_mfma_f32_16x16x32_fp8_fp8 v[126:129], v[40:41], v[102:103], v[124:127]
	v_cndmask_b32_e32 v118, v121, v200, vcc
	v_cmp_lt_i32_e32 vcc, s29, v112
	s_and_b64 vcc, s[38:39], vcc
	v_or_b32_e32 v112, 3, v138
	v_cndmask_b32_e32 v121, v122, v200, vcc
	v_cmp_lt_i32_e32 vcc, s29, v112
	s_and_b64 vcc, s[38:39], vcc
	v_or_b32_e32 v112, 16, v138
	v_cndmask_b32_e32 v123, v123, v200, vcc
	v_cmp_lt_i32_e32 vcc, s29, v112
	s_and_b64 vcc, s[38:39], vcc
	v_or_b32_e32 v112, 17, v138
	s_waitcnt vmcnt(13)
	v_mfma_f32_16x16x32_fp8_fp8 v[130:133], v[42:43], v[100:101], 0
	v_cndmask_b32_e32 v125, v126, v200, vcc
	v_cmp_lt_i32_e32 vcc, s29, v112
	s_and_b64 vcc, s[38:39], vcc
	v_or_b32_e32 v112, 18, v138
	v_cndmask_b32_e32 v126, v127, v200, vcc
	v_cmp_lt_i32_e32 vcc, s29, v112
	s_and_b64 vcc, s[38:39], vcc
	v_or_b32_e32 v112, 19, v138
	v_mfma_f32_16x16x32_fp8_fp8 v[130:133], v[44:45], v[102:103], v[130:133]
	v_cndmask_b32_e32 v124, v128, v200, vcc
	v_cmp_lt_i32_e32 vcc, s29, v112
	s_and_b64 vcc, s[38:39], vcc
	v_or_b32_e32 v112, 32, v138
	v_cndmask_b32_e32 v122, v129, v200, vcc
	v_cmp_lt_i32_e32 vcc, s29, v112
	s_and_b64 vcc, s[38:39], vcc
	v_or_b32_e32 v112, 33, v138
	s_waitcnt vmcnt(12)
	v_mfma_f32_16x16x32_fp8_fp8 v[134:137], v[46:47], v[100:101], 0
	v_cndmask_b32_e32 v120, v130, v200, vcc
	v_cmp_lt_i32_e32 vcc, s29, v112
	s_and_b64 vcc, s[38:39], vcc
	v_or_b32_e32 v112, 34, v138
	v_cndmask_b32_e32 v119, v131, v200, vcc
	v_cmp_lt_i32_e32 vcc, s29, v112
	s_and_b64 vcc, s[38:39], vcc
	v_or_b32_e32 v112, 35, v138
	v_mfma_f32_16x16x32_fp8_fp8 v[134:137], v[48:49], v[102:103], v[134:137]
	v_cndmask_b32_e32 v117, v132, v200, vcc
	v_cmp_lt_i32_e32 vcc, s29, v112
	v_max3_f32 v111, v115, s81, v118
	s_and_b64 vcc, s[38:39], vcc
	v_or_b32_e32 v112, 48, v138
	v_max3_f32 v111, v111, v121, v123
	v_cndmask_b32_e32 v116, v133, v200, vcc
	v_cmp_lt_i32_e32 vcc, s29, v112
	v_max3_f32 v111, v111, v125, v126
	s_and_b64 vcc, s[38:39], vcc
	v_or_b32_e32 v112, 49, v138
	v_max3_f32 v111, v111, v124, v122
	v_cndmask_b32_e32 v114, v134, v200, vcc
	v_cmp_lt_i32_e32 vcc, s29, v112
	v_max3_f32 v111, v111, v120, v119
	s_and_b64 vcc, s[38:39], vcc
	v_max3_f32 v111, v111, v117, v116
	v_cndmask_b32_e32 v113, v135, v200, vcc
	v_max3_f32 v127, v111, v114, v113
	v_or_b32_e32 v111, 50, v138
	v_cmp_lt_i32_e32 vcc, s29, v111
	s_and_b64 vcc, s[38:39], vcc
	v_or_b32_e32 v112, 51, v138
	v_cndmask_b32_e32 v111, v136, v200, vcc
	v_cmp_lt_i32_e32 vcc, s29, v112
	s_and_b64 vcc, s[38:39], vcc
	s_nop 0
	v_cndmask_b32_e32 v112, v137, v200, vcc
	v_max3_f32 v127, v127, v111, v112
	v_mov_b32_e32 v128, v127
	s_nop 1
	v_permlane16_swap_b32_e32 v127, v128
	v_max_f32_e32 v127, v127, v128
	v_mov_b32_e32 v128, v127
	s_nop 1
	v_permlane32_swap_b32_e32 v127, v128
	v_max_f32_e32 v127, v127, v128
	v_add_f32_e32 v128, 0x42317218, v109
	v_cmp_gt_f32_e32 vcc, v127, v128
	s_cbranch_vccz .LBB0_1355
	v_max_f32_e32 v110, v127, v127
	v_max_f32_e32 v127, v109, v109
	v_max_f32_e32 v127, v127, v110
	v_cmp_eq_f32_e32 vcc, s81, v127
	s_nop 1
	v_cndmask_b32_e64 v110, v127, 0, vcc
	v_sub_f32_e32 v109, v109, v110
	v_mul_f32_e32 v109, 0x3e38aa3b, v109
	v_exp_f32_e32 v110, v109
	v_mul_f32_e32 v109, 0x3e38aa3b, v127
	v_mul_f32_e32 v99, v99, v110
	v_pk_mul_f32 v[88:89], v[88:89], v[110:111] op_sel_hi:[1,0]
	v_pk_mul_f32 v[86:87], v[86:87], v[110:111] op_sel_hi:[1,0]
	v_pk_mul_f32 v[76:77], v[76:77], v[110:111] op_sel_hi:[1,0]
	v_pk_mul_f32 v[74:75], v[74:75], v[110:111] op_sel_hi:[1,0]
	v_pk_mul_f32 v[80:81], v[80:81], v[110:111] op_sel_hi:[1,0]
	v_pk_mul_f32 v[78:79], v[78:79], v[110:111] op_sel_hi:[1,0]
	v_pk_mul_f32 v[84:85], v[84:85], v[110:111] op_sel_hi:[1,0]
	v_pk_mul_f32 v[82:83], v[82:83], v[110:111] op_sel_hi:[1,0]
	v_cndmask_b32_e64 v110, v109, 0, vcc
	v_mov_b32_e32 v109, v127

; #define LAS __attribute__((address_space(3)))
; __device__ __forceinline__ float ex2(float x) { return __builtin_amdgcn_exp2f(x); }
; #define LBAR() asm volatile("s_waitcnt lgkmcnt(0)\n\ts_barrier" ::: "memory")
; __device__ __forceinline__ f32x4 mfma16(bf16x8 a, bf16x8 b, f32x4 c) { return __builtin_amdgcn_mfma_f32_16x16x32_bf16(a, b, c, 0, 0, 0); }
;   __device__ __forceinline__ bf16_t* W() const { return (bf16_t*)(ws + WS_W); }
; template <int NT, int NKK, int NDT, int MODE, bool MASK> ...
;     ...
;   f32x4 s[NT][4];
;   __builtin_amdgcn_s_setprio(1);
; #pragma unroll
;   for (int t = 0; t < 4; ++t)
; #pragma unroll
;     for (int kk = 0; kk < NKK; ++kk) {
;       const bf16x8 kf = *(LAS const bf16x8*)(Kl + (16 * t + r) * KSTR + (32 * kk + 8 * lg) * 2);
; #pragma unroll
;       for (int j = 0; j < NT; ++j) s[j][t] = mfma16(kf, qf[j][kk], kk == 0 ? (f32x4){0.f, 0.f, 0.f, 0.f} : s[j][t]);
;     }
;   __builtin_amdgcn_s_setprio(0);
;   bf16x8 pf[NT][2];
; #pragma unroll
;   for (int j = 0; j < NT; ++j) {
;     float mx = -INFINITY;
; #pragma unroll
;     for (int t = 0; t < 4; ++t)
; #pragma unroll
;       for (int i = 0; i < 4; ++i) {
;         if (MASK) { const int kp = kpos0 + 16 * t + 4 * lg + i; if (!mask_ok<MODE>(tq[j], kp, W)) s[j][t][i] = -INFINITY; }
;         mx = fmaxf(mx, s[j][t][i]);
;       }
;     mx = max_x16_x32(mx);
;     if (__any(mx > m[j] + 8.0f / c)) {
;       const float mnew = fmaxf(m[j], mx);
;       const float ms2 = (mnew == -INFINITY) ? 0.f : mnew;
;       const float alpha = ex2((m[j] - ms2) * c);
;       m[j] = mnew; l[j] *= alpha;
; #pragma unroll
;       for (int dt = 0; dt < NDT; ++dt) o[j][dt] *= alpha;
;     }
; template <int NT, int DQK, int DV, int MODE, int PD, class Src> ...
;     ...
;         LBAR();
.LBB0_1788:
	s_waitcnt lgkmcnt(0)
	s_barrier
	s_xor_b64 s[16:17], s[18:19], -1
	s_setprio 1
	ds_read_b128 v[132:135], v193
	ds_read_b128 v[140:143], v193 offset:64
	s_waitcnt vmcnt(7) lgkmcnt(1)
	v_mfma_f32_16x16x32_bf16 v[136:139], v[132:135], v[4:7], 0
	ds_read_b128 v[144:147], v193 offset:192
	ds_read_b128 v[148:151], v193 offset:4416
	ds_read_b128 v[152:155], v193 offset:4544
	s_waitcnt vmcnt(3)
	v_mfma_f32_16x16x32_bf16 v[132:135], v[132:135], v[20:23], 0
	ds_read_b128 v[156:159], v193 offset:8768
	ds_read_b128 v[160:163], v193 offset:8896
	ds_read_b128 v[206:209], v194 offset:64
	s_waitcnt lgkmcnt(6)
	v_mfma_f32_16x16x32_bf16 v[136:139], v[140:143], v[8:11], v[136:139]
	s_waitcnt vmcnt(2)
	v_mfma_f32_16x16x32_bf16 v[132:135], v[140:143], v[24:27], v[132:135]
	ds_read_b128 v[140:143], v193 offset:128
	s_waitcnt lgkmcnt(0)
	v_mfma_f32_16x16x32_bf16 v[136:139], v[140:143], v[12:15], v[136:139]
	s_waitcnt vmcnt(1)
	v_mfma_f32_16x16x32_bf16 v[132:135], v[140:143], v[28:31], v[132:135]
	v_mfma_f32_16x16x32_bf16 v[140:143], v[144:147], v[16:19], v[136:139]
	s_nop 4
	ds_read_b128 v[136:139], v193 offset:4352
	s_waitcnt vmcnt(0)
	v_mfma_f32_16x16x32_bf16 v[132:135], v[144:147], v[32:35], v[132:135]
	s_waitcnt lgkmcnt(0)
	v_mfma_f32_16x16x32_bf16 v[144:147], v[136:139], v[4:7], 0
	v_mfma_f32_16x16x32_bf16 v[136:139], v[136:139], v[20:23], 0
	v_mfma_f32_16x16x32_bf16 v[144:147], v[148:151], v[8:11], v[144:147]
	v_mfma_f32_16x16x32_bf16 v[136:139], v[148:151], v[24:27], v[136:139]
	ds_read_b128 v[148:151], v193 offset:4480
	s_waitcnt lgkmcnt(0)
	v_mfma_f32_16x16x32_bf16 v[144:147], v[148:151], v[12:15], v[144:147]
	v_mfma_f32_16x16x32_bf16 v[136:139], v[148:151], v[28:31], v[136:139]
	v_mfma_f32_16x16x32_bf16 v[148:151], v[152:155], v[16:19], v[144:147]
	s_nop 5
	ds_read_b128 v[144:147], v193 offset:8704
	v_mfma_f32_16x16x32_bf16 v[136:139], v[152:155], v[32:35], v[136:139]
	s_waitcnt lgkmcnt(0)
	v_mfma_f32_16x16x32_bf16 v[152:155], v[144:147], v[4:7], 0
	v_mfma_f32_16x16x32_bf16 v[144:147], v[144:147], v[20:23], 0
	v_mfma_f32_16x16x32_bf16 v[152:155], v[156:159], v[8:11], v[152:155]
	v_mfma_f32_16x16x32_bf16 v[144:147], v[156:159], v[24:27], v[144:147]
	ds_read_b128 v[156:159], v193 offset:8832
	s_waitcnt lgkmcnt(0)
	v_mfma_f32_16x16x32_bf16 v[152:155], v[156:159], v[12:15], v[152:155]
	v_mfma_f32_16x16x32_bf16 v[144:147], v[156:159], v[28:31], v[144:147]
	v_mfma_f32_16x16x32_bf16 v[156:159], v[160:163], v[16:19], v[152:155]
	s_nop 5
	ds_read_b128 v[152:155], v194
	v_mfma_f32_16x16x32_bf16 v[144:147], v[160:163], v[32:35], v[144:147]
	s_waitcnt lgkmcnt(0)
	v_mfma_f32_16x16x32_bf16 v[160:163], v[152:155], v[4:7], 0
	v_mfma_f32_16x16x32_bf16 v[152:155], v[152:155], v[20:23], 0
	v_mfma_f32_16x16x32_bf16 v[160:163], v[206:209], v[8:11], v[160:163]
	v_mfma_f32_16x16x32_bf16 v[152:155], v[206:209], v[24:27], v[152:155]
	ds_read_b128 v[206:209], v194 offset:128
	s_waitcnt lgkmcnt(0)
	v_mfma_f32_16x16x32_bf16 v[160:163], v[206:209], v[12:15], v[160:163]
	v_mfma_f32_16x16x32_bf16 v[152:155], v[206:209], v[28:31], v[152:155]
	ds_read_b128 v[206:209], v194 offset:192
	s_waitcnt lgkmcnt(0)
	v_mfma_f32_16x16x32_bf16 v[160:163], v[206:209], v[16:19], v[160:163]
	v_mfma_f32_16x16x32_bf16 v[152:155], v[206:209], v[32:35], v[152:155]
	s_setprio 0
	v_max3_f32 v3, v140, s81, v141
	v_max3_f32 v3, v3, v142, v143
	v_max3_f32 v3, v3, v148, v149
	v_max3_f32 v3, v3, v150, v151
	v_max3_f32 v3, v3, v156, v157
	v_max3_f32 v3, v3, v158, v159
	v_max3_f32 v3, v3, v160, v161
	v_max3_f32 v3, v3, v162, v163
	v_mov_b32_e32 v196, v3
	s_nop 1
	v_permlane16_swap_b32_e32 v3, v196
	v_max_f32_e32 v3, v3, v196
	v_mov_b32_e32 v196, v3
	s_nop 1
	v_permlane32_swap_b32_e32 v3, v196
	v_max_f32_e32 v3, v3, v196
	v_add_f32_e32 v196, 0x427af232, v1
	v_cmp_gt_f32_e32 vcc, v3, v196
	s_cbranch_vccz .LBB0_1790
	v_max_f32_e32 v3, v3, v3
	v_max_f32_e32 v196, v1, v1
	v_max_f32_e32 v3, v196, v3
	v_cmp_neq_f32_e32 vcc, s81, v3
	s_nop 1
	v_cndmask_b32_e32 v196, 0, v3, vcc
	v_sub_f32_e32 v1, v1, v196
	v_mul_f32_e32 v1, 0x3e0293ee, v1
	v_exp_f32_e32 v196, v1
	v_mov_b32_e32 v1, v3
	v_mul_f32_e32 v2, v2, v196
	v_pk_mul_f32 v[126:127], v[126:127], v[196:197] op_sel_hi:[1,0]
	v_pk_mul_f32 v[124:125], v[124:125], v[196:197] op_sel_hi:[1,0]
	v_pk_mul_f32 v[130:131], v[130:131], v[196:197] op_sel_hi:[1,0]
	v_pk_mul_f32 v[128:129], v[128:129], v[196:197] op_sel_hi:[1,0]
	v_pk_mul_f32 v[122:123], v[122:123], v[196:197] op_sel_hi:[1,0]
	v_pk_mul_f32 v[120:121], v[120:121], v[196:197] op_sel_hi:[1,0]
	v_pk_mul_f32 v[118:119], v[118:119], v[196:197] op_sel_hi:[1,0]
	v_pk_mul_f32 v[116:117], v[116:117], v[196:197] op_sel_hi:[1,0]
	v_pk_mul_f32 v[114:115], v[114:115], v[196:197] op_sel_hi:[1,0]
	v_pk_mul_f32 v[112:113], v[112:113], v[196:197] op_sel_hi:[1,0]
	v_pk_mul_f32 v[110:111], v[110:111], v[196:197] op_sel_hi:[1,0]
	v_pk_mul_f32 v[108:109], v[108:109], v[196:197] op_sel_hi:[1,0]
	v_pk_mul_f32 v[106:107], v[106:107], v[196:197] op_sel_hi:[1,0]
	v_pk_mul_f32 v[104:105], v[104:105], v[196:197] op_sel_hi:[1,0]
	v_pk_mul_f32 v[102:103], v[102:103], v[196:197] op_sel_hi:[1,0]
	v_pk_mul_f32 v[100:101], v[100:101], v[196:197] op_sel_hi:[1,0]
.LBB0_1790:
	v_max3_f32 v3, v132, s81, v133
	v_max3_f32 v3, v3, v134, v135
	v_max3_f32 v3, v3, v136, v137
	v_max3_f32 v3, v3, v138, v139
	v_max3_f32 v3, v3, v144, v145
	v_max3_f32 v3, v3, v146, v147
	v_max3_f32 v3, v3, v152, v153
	v_max3_f32 v3, v3, v154, v155
	v_mov_b32_e32 v196, v3
	s_nop 1
	v_permlane16_swap_b32_e32 v3, v196
	v_max_f32_e32 v3, v3, v196
	v_mov_b32_e32 v196, v3
	s_nop 1
	v_permlane32_swap_b32_e32 v3, v196
	v_max_f32_e32 v3, v3, v196
	v_add_f32_e32 v196, 0x427af232, v201
	v_cmp_gt_f32_e32 vcc, v3, v196
	s_cbranch_vccz .LBB0_1792
	v_max_f32_e32 v3, v3, v3
	v_max_f32_e32 v196, v201, v201
	v_max_f32_e32 v3, v196, v3
	v_cmp_neq_f32_e32 vcc, s81, v3
	s_nop 1
	v_cndmask_b32_e32 v196, 0, v3, vcc
	v_sub_f32_e32 v196, v201, v196
	v_mul_f32_e32 v196, 0x3e0293ee, v196
	v_exp_f32_e32 v196, v196
	v_mov_b32_e32 v201, v3
	v_mul_f32_e32 v195, v195, v196
	v_pk_mul_f32 v[94:95], v[94:95], v[196:197] op_sel_hi:[1,0]
	v_pk_mul_f32 v[92:93], v[92:93], v[196:197] op_sel_hi:[1,0]
	v_pk_mul_f32 v[98:99], v[98:99], v[196:197] op_sel_hi:[1,0]
	v_pk_mul_f32 v[96:97], v[96:97], v[196:197] op_sel_hi:[1,0]
	v_pk_mul_f32 v[90:91], v[90:91], v[196:197] op_sel_hi:[1,0]
	v_pk_mul_f32 v[88:89], v[88:89], v[196:197] op_sel_hi:[1,0]
	v_pk_mul_f32 v[86:87], v[86:87], v[196:197] op_sel_hi:[1,0]
	v_pk_mul_f32 v[84:85], v[84:85], v[196:197] op_sel_hi:[1,0]
	v_pk_mul_f32 v[82:83], v[82:83], v[196:197] op_sel_hi:[1,0]
	v_pk_mul_f32 v[80:81], v[80:81], v[196:197] op_sel_hi:[1,0]
	v_pk_mul_f32 v[78:79], v[78:79], v[196:197] op_sel_hi:[1,0]
	v_pk_mul_f32 v[76:77], v[76:77], v[196:197] op_sel_hi:[1,0]
	v_pk_mul_f32 v[74:75], v[74:75], v[196:197] op_sel_hi:[1,0]
	v_pk_mul_f32 v[72:73], v[72:73], v[196:197] op_sel_hi:[1,0]
	v_pk_mul_f32 v[70:71], v[70:71], v[196:197] op_sel_hi:[1,0]
	v_pk_mul_f32 v[68:69], v[68:69], v[196:197] op_sel_hi:[1,0]

; #define LAS __attribute__((address_space(3)))
; __device__ __forceinline__ float ex2(float x) { return __builtin_amdgcn_exp2f(x); }
; __device__ __forceinline__ f32x4 mfma16(bf16x8 a, bf16x8 b, f32x4 c) { return __builtin_amdgcn_mfma_f32_16x16x32_bf16(a, b, c, 0, 0, 0); }
;   __device__ __forceinline__ bf16_t* W() const { return (bf16_t*)(ws + WS_W); }
; template <int NT, int NKK, int NDT, int MODE, bool MASK> ...
;     ...
;   f32x4 s[NT][4];
;   __builtin_amdgcn_s_setprio(1);
; #pragma unroll
;   for (int t = 0; t < 4; ++t)
; #pragma unroll
;     for (int kk = 0; kk < NKK; ++kk) {
;       const bf16x8 kf = *(LAS const bf16x8*)(Kl + (16 * t + r) * KSTR + (32 * kk + 8 * lg) * 2);
; #pragma unroll
;       for (int j = 0; j < NT; ++j) s[j][t] = mfma16(kf, qf[j][kk], kk == 0 ? (f32x4){0.f, 0.f, 0.f, 0.f} : s[j][t]);
;     }
;   __builtin_amdgcn_s_setprio(0);
;   bf16x8 pf[NT][2];
; #pragma unroll
;   for (int j = 0; j < NT; ++j) {
;     float mx = -INFINITY;
; #pragma unroll
;     for (int t = 0; t < 4; ++t)
; #pragma unroll
;       for (int i = 0; i < 4; ++i) {
;         if (MASK) { const int kp = kpos0 + 16 * t + 4 * lg + i; if (!mask_ok<MODE>(tq[j], kp, W)) s[j][t][i] = -INFINITY; }
;         mx = fmaxf(mx, s[j][t][i]);
;       }
;     mx = max_x16_x32(mx);
;     if (__any(mx > m[j] + 8.0f / c)) {
;       const float mnew = fmaxf(m[j], mx);
;       const float ms2 = (mnew == -INFINITY) ? 0.f : mnew;
;       const float alpha = ex2((m[j] - ms2) * c);
;       m[j] = mnew; l[j] *= alpha;
; #pragma unroll
;       for (int dt = 0; dt < NDT; ++dt) o[j][dt] *= alpha;
;     }
;     ...
;       for (int i = 0; i < 4; ++i) { p[t][i] = ex2(s[j][t][i] * c - mc); ps += p[t][i]; }
;     l[j] += ps;
.LBB0_1807:
	v_add_f32_e32 v132, 0, v221
	v_add_f32_e32 v132, v222, v132
	v_add_f32_e32 v132, v223, v132
	v_add_f32_e32 v132, v224, v132
	v_add_f32_e32 v132, v148, v132
	v_add_f32_e32 v132, v149, v132
	v_add_f32_e32 v132, v150, v132
	v_add_f32_e32 v132, v151, v132
	v_add_f32_e32 v132, v156, v132
	v_add_f32_e32 v132, v157, v132
	v_add_f32_e32 v132, v158, v132
	v_add_f32_e32 v132, v159, v132
	v_add_f32_e32 v132, v160, v132
	v_add_f32_e32 v132, v161, v132
	v_add_f32_e32 v132, v162, v132
	s_waitcnt lgkmcnt(0)
	s_barrier
	v_add_f32_e32 v132, v163, v132
	v_add_f32_e32 v2, v2, v132
	s_setprio 1
	ds_read_b128 v[132:135], v193 offset:35840
	ds_read_b128 v[140:143], v193 offset:35904
	s_waitcnt lgkmcnt(1)
	v_mfma_f32_16x16x32_bf16 v[136:139], v[132:135], v[4:7], 0
	ds_read_b128 v[144:147], v193 offset:40256
	ds_read_b128 v[156:159], v193 offset:44608
	ds_read_b128 v[160:163], v193 offset:44736
	v_mfma_f32_16x16x32_bf16 v[132:135], v[132:135], v[20:23], 0
	ds_read_b128 v[222:225], v194 offset:35904
	s_waitcnt lgkmcnt(4)
	v_mfma_f32_16x16x32_bf16 v[136:139], v[140:143], v[8:11], v[136:139]
	v_mfma_f32_16x16x32_bf16 v[132:135], v[140:143], v[24:27], v[132:135]
	ds_read_b128 v[140:143], v193 offset:35968
	s_waitcnt lgkmcnt(0)
	v_mfma_f32_16x16x32_bf16 v[136:139], v[140:143], v[12:15], v[136:139]
	v_mfma_f32_16x16x32_bf16 v[132:135], v[140:143], v[28:31], v[132:135]
	ds_read_b128 v[140:143], v193 offset:36032
	s_waitcnt lgkmcnt(0)
	v_mfma_f32_16x16x32_bf16 v[148:151], v[140:143], v[16:19], v[136:139]
	s_nop 3
	ds_read_b128 v[136:139], v193 offset:40192
	v_mfma_f32_16x16x32_bf16 v[132:135], v[140:143], v[32:35], v[132:135]
	s_waitcnt lgkmcnt(0)
	v_mfma_f32_16x16x32_bf16 v[140:143], v[136:139], v[4:7], 0
	v_mfma_f32_16x16x32_bf16 v[136:139], v[136:139], v[20:23], 0
	v_mfma_f32_16x16x32_bf16 v[140:143], v[144:147], v[8:11], v[140:143]
	v_mfma_f32_16x16x32_bf16 v[136:139], v[144:147], v[24:27], v[136:139]
	ds_read_b128 v[144:147], v193 offset:40320
	s_waitcnt lgkmcnt(0)
	v_mfma_f32_16x16x32_bf16 v[140:143], v[144:147], v[12:15], v[140:143]
	v_mfma_f32_16x16x32_bf16 v[136:139], v[144:147], v[28:31], v[136:139]
	ds_read_b128 v[144:147], v193 offset:40384
	s_waitcnt lgkmcnt(0)
	v_mfma_f32_16x16x32_bf16 v[152:155], v[144:147], v[16:19], v[140:143]
	s_nop 3
	ds_read_b128 v[140:143], v193 offset:44544
	v_mfma_f32_16x16x32_bf16 v[136:139], v[144:147], v[32:35], v[136:139]
	s_waitcnt lgkmcnt(0)
	v_mfma_f32_16x16x32_bf16 v[144:147], v[140:143], v[4:7], 0
	v_mfma_f32_16x16x32_bf16 v[140:143], v[140:143], v[20:23], 0
	v_mfma_f32_16x16x32_bf16 v[144:147], v[156:159], v[8:11], v[144:147]
	v_mfma_f32_16x16x32_bf16 v[140:143], v[156:159], v[24:27], v[140:143]
	ds_read_b128 v[156:159], v193 offset:44672
	s_waitcnt lgkmcnt(0)
	v_mfma_f32_16x16x32_bf16 v[144:147], v[156:159], v[12:15], v[144:147]
	v_mfma_f32_16x16x32_bf16 v[140:143], v[156:159], v[28:31], v[140:143]
	v_mfma_f32_16x16x32_bf16 v[156:159], v[160:163], v[16:19], v[144:147]
	s_nop 5
	ds_read_b128 v[144:147], v194 offset:35840
	v_mfma_f32_16x16x32_bf16 v[140:143], v[160:163], v[32:35], v[140:143]
	s_waitcnt lgkmcnt(0)
	v_mfma_f32_16x16x32_bf16 v[160:163], v[144:147], v[4:7], 0
	v_mfma_f32_16x16x32_bf16 v[144:147], v[144:147], v[20:23], 0
	v_mfma_f32_16x16x32_bf16 v[160:163], v[222:225], v[8:11], v[160:163]
	v_mfma_f32_16x16x32_bf16 v[144:147], v[222:225], v[24:27], v[144:147]
	ds_read_b128 v[222:225], v194 offset:35968
	s_waitcnt lgkmcnt(0)
	v_mfma_f32_16x16x32_bf16 v[160:163], v[222:225], v[12:15], v[160:163]
	v_mfma_f32_16x16x32_bf16 v[144:147], v[222:225], v[28:31], v[144:147]
	ds_read_b128 v[222:225], v194 offset:36032
	s_waitcnt lgkmcnt(0)
	v_mfma_f32_16x16x32_bf16 v[160:163], v[222:225], v[16:19], v[160:163]
	v_mfma_f32_16x16x32_bf16 v[144:147], v[222:225], v[32:35], v[144:147]
	s_setprio 0
	v_max3_f32 v196, v148, s81, v149
	v_max3_f32 v196, v196, v150, v151
	v_max3_f32 v196, v196, v152, v153
	v_max3_f32 v196, v196, v154, v155
	v_max3_f32 v196, v196, v156, v157
	v_max3_f32 v196, v196, v158, v159
	v_max3_f32 v196, v196, v160, v161
	v_max3_f32 v196, v196, v162, v163
	v_mov_b32_e32 v197, v196
	s_nop 1
	v_permlane16_swap_b32_e32 v196, v197
	v_max_f32_e32 v196, v196, v197
	v_mov_b32_e32 v197, v196
	s_nop 1
	v_permlane32_swap_b32_e32 v196, v197
	v_max_f32_e32 v196, v196, v197
	v_add_f32_e32 v197, 0x427af232, v1
	v_cmp_gt_f32_e32 vcc, v196, v197
	s_cbranch_vccz .LBB0_1809
	v_max_f32_e32 v196, v196, v196
	v_max_f32_e32 v197, v1, v1
	v_max_f32_e32 v197, v197, v196
	v_cmp_eq_f32_e32 vcc, s81, v197
	s_nop 1
	v_cndmask_b32_e64 v196, v197, 0, vcc
	v_sub_f32_e32 v1, v1, v196
	v_mul_f32_e32 v1, 0x3e0293ee, v1
	v_exp_f32_e32 v196, v1
	v_mul_f32_e32 v1, 0x3e0293ee, v197
	v_cndmask_b32_e64 v202, v1, 0, vcc
	v_mov_b32_e32 v1, v197
	v_mul_f32_e32 v2, v2, v196
	v_pk_mul_f32 v[70:71], v[70:71], v[196:197] op_sel_hi:[1,0]
	v_pk_mul_f32 v[68:69], v[68:69], v[196:197] op_sel_hi:[1,0]
	v_pk_mul_f32 v[126:127], v[126:127], v[196:197] op_sel_hi:[1,0]
	v_pk_mul_f32 v[124:125], v[124:125], v[196:197] op_sel_hi:[1,0]
	v_pk_mul_f32 v[98:99], v[98:99], v[196:197] op_sel_hi:[1,0]
	v_pk_mul_f32 v[96:97], v[96:97], v[196:197] op_sel_hi:[1,0]
	v_pk_mul_f32 v[94:95], v[94:95], v[196:197] op_sel_hi:[1,0]
	v_pk_mul_f32 v[92:93], v[92:93], v[196:197] op_sel_hi:[1,0]
	v_pk_mul_f32 v[90:91], v[90:91], v[196:197] op_sel_hi:[1,0]
	v_pk_mul_f32 v[88:89], v[88:89], v[196:197] op_sel_hi:[1,0]
	v_pk_mul_f32 v[86:87], v[86:87], v[196:197] op_sel_hi:[1,0]
	v_pk_mul_f32 v[84:85], v[84:85], v[196:197] op_sel_hi:[1,0]
	v_pk_mul_f32 v[82:83], v[82:83], v[196:197] op_sel_hi:[1,0]
	v_pk_mul_f32 v[80:81], v[80:81], v[196:197] op_sel_hi:[1,0]
	v_pk_mul_f32 v[78:79], v[78:79], v[196:197] op_sel_hi:[1,0]
	v_pk_mul_f32 v[76:77], v[76:77], v[196:197] op_sel_hi:[1,0]
; __device__ __forceinline__ float ex2(float x) { return __builtin_amdgcn_exp2f(x); }
;   __device__ __forceinline__ bf16_t* W() const { return (bf16_t*)(ws + WS_W); }
; template <int NT, int NKK, int NDT, int MODE, bool MASK> ...
;     ...
;   for (int j = 0; j < NT; ++j) {
;     float mx = -INFINITY;
; #pragma unroll
;     for (int t = 0; t < 4; ++t)
; #pragma unroll
;       for (int i = 0; i < 4; ++i) {
;         if (MASK) { const int kp = kpos0 + 16 * t + 4 * lg + i; if (!mask_ok<MODE>(tq[j], kp, W)) s[j][t][i] = -INFINITY; }
;         mx = fmaxf(mx, s[j][t][i]);
;       }
;     mx = max_x16_x32(mx);
;     if (__any(mx > m[j] + 8.0f / c)) {
;       const float mnew = fmaxf(m[j], mx);
;       const float ms2 = (mnew == -INFINITY) ? 0.f : mnew;
;       const float alpha = ex2((m[j] - ms2) * c);
;       m[j] = mnew; l[j] *= alpha;
; #pragma unroll
;       for (int dt = 0; dt < NDT; ++dt) o[j][dt] *= alpha;
;     }
;     ...
;       for (int i = 0; i < 4; ++i) { p[t][i] = ex2(s[j][t][i] * c - mc); ps += p[t][i]; }
;     l[j] += ps;
.LBB0_1809:
	v_add_f32_e32 v196, 0, v205
	v_add_f32_e32 v196, v206, v196
	v_add_f32_e32 v196, v207, v196
	v_add_f32_e32 v196, v208, v196
	v_add_f32_e32 v196, v209, v196
	v_add_f32_e32 v196, v210, v196
	v_add_f32_e32 v196, v211, v196
	v_add_f32_e32 v196, v212, v196
	v_add_f32_e32 v196, v213, v196
	v_add_f32_e32 v196, v214, v196
	v_add_f32_e32 v196, v215, v196
	v_add_f32_e32 v196, v216, v196
	v_add_f32_e32 v196, v217, v196
	v_add_f32_e32 v196, v218, v196
	v_add_f32_e32 v196, v219, v196
	v_add_f32_e32 v196, v220, v196
	v_add_f32_e32 v195, v195, v196
	v_max3_f32 v196, v132, s81, v133
	v_max3_f32 v196, v196, v134, v135
	v_max3_f32 v196, v196, v136, v137
	v_max3_f32 v196, v196, v138, v139
	v_max3_f32 v196, v196, v140, v141
	v_max3_f32 v196, v196, v142, v143
	v_max3_f32 v196, v196, v144, v145
	v_max3_f32 v196, v196, v146, v147
	v_mov_b32_e32 v197, v196
	s_nop 1
	v_permlane16_swap_b32_e32 v196, v197
	v_max_f32_e32 v196, v196, v197
	v_mov_b32_e32 v197, v196
	s_nop 1
	v_permlane32_swap_b32_e32 v196, v197
	v_max_f32_e32 v196, v196, v197
	v_add_f32_e32 v197, 0x427af232, v201
	v_cmp_gt_f32_e32 vcc, v196, v197
	s_cbranch_vccz .LBB0_1772
	v_max_f32_e32 v3, v196, v196
	v_max_f32_e32 v196, v201, v201
	v_max_f32_e32 v197, v196, v3
	v_cmp_eq_f32_e32 vcc, s81, v197
	s_nop 1
	v_cndmask_b32_e64 v3, v197, 0, vcc
	v_sub_f32_e32 v3, v201, v3
	v_mul_f32_e32 v3, 0x3e0293ee, v3
	v_exp_f32_e32 v196, v3
	v_mul_f32_e32 v3, 0x3e0293ee, v197
	v_cndmask_b32_e64 v3, v3, 0, vcc
	v_mov_b32_e32 v201, v197
	v_mul_f32_e32 v195, v195, v196
	v_pk_mul_f32 v[74:75], v[74:75], v[196:197] op_sel_hi:[1,0]
	v_pk_mul_f32 v[72:73], v[72:73], v[196:197] op_sel_hi:[1,0]
	v_pk_mul_f32 v[130:131], v[130:131], v[196:197] op_sel_hi:[1,0]
	v_pk_mul_f32 v[128:129], v[128:129], v[196:197] op_sel_hi:[1,0]
	v_pk_mul_f32 v[122:123], v[122:123], v[196:197] op_sel_hi:[1,0]
	v_pk_mul_f32 v[120:121], v[120:121], v[196:197] op_sel_hi:[1,0]
	v_pk_mul_f32 v[118:119], v[118:119], v[196:197] op_sel_hi:[1,0]
	v_pk_mul_f32 v[116:117], v[116:117], v[196:197] op_sel_hi:[1,0]
	v_pk_mul_f32 v[114:115], v[114:115], v[196:197] op_sel_hi:[1,0]
	v_pk_mul_f32 v[112:113], v[112:113], v[196:197] op_sel_hi:[1,0]
	v_pk_mul_f32 v[110:111], v[110:111], v[196:197] op_sel_hi:[1,0]
	v_pk_mul_f32 v[108:109], v[108:109], v[196:197] op_sel_hi:[1,0]
	v_pk_mul_f32 v[106:107], v[106:107], v[196:197] op_sel_hi:[1,0]
	v_pk_mul_f32 v[104:105], v[104:105], v[196:197] op_sel_hi:[1,0]
	v_pk_mul_f32 v[102:103], v[102:103], v[196:197] op_sel_hi:[1,0]
	v_pk_mul_f32 v[100:101], v[100:101], v[196:197] op_sel_hi:[1,0]
	s_branch .LBB0_1772
